# K-loop LDS-DMA waits relaxed to counted vmcnt(10) placed one phase before each consumer (P4/P1/P2) on top of the tightened barrier hand-off
# speedup vs baseline: 1.0255x; 1.0071x over previous
.LBB0_287:
	s_add_u32 s0, s22, 0xfffc0080
	s_addc_u32 s1, s23, -1
	s_add_i32 s72, 0, 0x10000
	v_add_u32_e32 v80, s72, v163
	ds_read_b128 v[68:71], v80
	ds_read_b128 v[72:75], v80 offset:1024
	ds_read_b128 v[76:79], v80 offset:2048
	ds_read_b128 v[80:83], v80 offset:3072
	s_cmp_eq_u32 s69, 12
	s_cselect_b32 s27, s18, s1
	s_cselect_b32 s26, s19, s0
	s_cselect_b32 s25, s45, s68
	s_cselect_b32 s24, s47, s59
	v_lshl_add_u64 v[202:203], s[22:23], 0, v[154:155]
	s_add_i32 m0, s53, 0xc000
	ds_read_b128 v[158:161], v165
	ds_read_b128 v[174:177], v165 offset:1024
	ds_read_b128 v[178:181], v165 offset:2048
	ds_read_b128 v[182:185], v165 offset:3072
	ds_read_b128 v[186:189], v165 offset:4096
	ds_read_b128 v[190:193], v165 offset:5120
	ds_read_b128 v[194:197], v165 offset:6144
	ds_read_b128 v[198:201], v165 offset:7168
	global_load_lds_dwordx4 v[202:203], off
	v_lshl_add_u64 v[202:203], s[22:23], 0, v[156:157]
	s_add_i32 m0, s53, 0xe000
	s_nop 0
	global_load_lds_dwordx4 v[202:203], off
	s_waitcnt vmcnt(10) lgkmcnt(8)
	s_setprio 1
	s_barrier
	s_waitcnt lgkmcnt(0)
	v_mfma_f32_16x16x32_bf16 v[144:147], v[68:71], v[158:161], v[144:147]
	v_mfma_f32_16x16x32_bf16 v[140:143], v[76:79], v[158:161], v[140:143]
	v_mfma_f32_16x16x32_bf16 v[128:131], v[68:71], v[178:181], v[128:131]
	v_mfma_f32_16x16x32_bf16 v[124:127], v[76:79], v[178:181], v[124:127]
	v_mfma_f32_16x16x32_bf16 v[112:115], v[68:71], v[186:189], v[112:115]
	v_mfma_f32_16x16x32_bf16 v[108:111], v[76:79], v[186:189], v[108:111]
	v_mfma_f32_16x16x32_bf16 v[96:99], v[68:71], v[194:197], v[96:99]
	v_mfma_f32_16x16x32_bf16 v[92:95], v[76:79], v[194:197], v[92:95]
	v_mfma_f32_16x16x32_bf16 v[144:147], v[72:75], v[174:177], v[144:147]
	v_mfma_f32_16x16x32_bf16 v[140:143], v[80:83], v[174:177], v[140:143]
	v_mfma_f32_16x16x32_bf16 v[128:131], v[72:75], v[182:185], v[128:131]
	v_mfma_f32_16x16x32_bf16 v[124:127], v[80:83], v[182:185], v[124:127]
	v_mfma_f32_16x16x32_bf16 v[112:115], v[72:75], v[190:193], v[112:115]
	v_mfma_f32_16x16x32_bf16 v[108:111], v[80:83], v[190:193], v[108:111]
	v_mfma_f32_16x16x32_bf16 v[96:99], v[72:75], v[198:201], v[96:99]
	v_mfma_f32_16x16x32_bf16 v[92:95], v[80:83], v[198:201], v[92:95]
	s_barrier
	s_setprio 0
	s_add_i32 s73, 0, 0x14000
	s_add_i32 s0, s72, s52
	v_add_u32_e32 v166, s73, v163
	v_lshl_add_u64 v[218:219], s[24:25], 0, v[26:27]
	s_mov_b32 m0, s0
	ds_read_b128 v[202:205], v166
	ds_read_b128 v[206:209], v166 offset:1024
	ds_read_b128 v[210:213], v166 offset:2048
	ds_read_b128 v[214:217], v166 offset:3072
	global_load_lds_dwordx4 v[218:219], off
	v_lshl_add_u64 v[220:221], s[24:25], 0, v[148:149]
	s_add_i32 m0, s0, 0x2000
	s_nop 0
	global_load_lds_dwordx4 v[220:221], off
	s_waitcnt vmcnt(10)
	s_setprio 1
	s_barrier
	s_waitcnt lgkmcnt(0)
	v_mfma_f32_16x16x32_bf16 v[136:139], v[202:205], v[158:161], v[136:139]
	v_mfma_f32_16x16x32_bf16 v[132:135], v[210:213], v[158:161], v[132:135]
	v_mfma_f32_16x16x32_bf16 v[120:123], v[202:205], v[178:181], v[120:123]
	v_mfma_f32_16x16x32_bf16 v[116:119], v[210:213], v[178:181], v[116:119]
	v_mfma_f32_16x16x32_bf16 v[104:107], v[202:205], v[186:189], v[104:107]
	v_mfma_f32_16x16x32_bf16 v[100:103], v[210:213], v[186:189], v[100:103]
	v_mfma_f32_16x16x32_bf16 v[88:91], v[202:205], v[194:197], v[88:91]
	v_mfma_f32_16x16x32_bf16 v[84:87], v[210:213], v[194:197], v[84:87]
	v_mfma_f32_16x16x32_bf16 v[136:139], v[206:209], v[174:177], v[136:139]
	v_mfma_f32_16x16x32_bf16 v[132:135], v[214:217], v[174:177], v[132:135]
	v_mfma_f32_16x16x32_bf16 v[120:123], v[206:209], v[182:185], v[120:123]
	v_mfma_f32_16x16x32_bf16 v[116:119], v[214:217], v[182:185], v[116:119]
	v_mfma_f32_16x16x32_bf16 v[104:107], v[206:209], v[190:193], v[104:107]
	v_mfma_f32_16x16x32_bf16 v[100:103], v[214:217], v[190:193], v[100:103]
	v_mfma_f32_16x16x32_bf16 v[88:91], v[206:209], v[198:201], v[88:91]
	v_mfma_f32_16x16x32_bf16 v[84:87], v[214:217], v[198:201], v[84:87]
	s_barrier
	s_setprio 0
	s_mov_b32 m0, s53
	v_lshl_add_u64 v[222:223], s[26:27], 0, v[152:153]
	ds_read_b128 v[158:161], v165 offset:16384
	ds_read_b128 v[174:177], v165 offset:17408
	ds_read_b128 v[178:181], v165 offset:18432
	ds_read_b128 v[182:185], v165 offset:19456
	ds_read_b128 v[186:189], v165 offset:20480
	ds_read_b128 v[190:193], v165 offset:21504
	ds_read_b128 v[194:197], v165 offset:22528
	ds_read_b128 v[198:201], v165 offset:23552
	global_load_lds_dwordx4 v[222:223], off
	v_lshl_add_u64 v[224:225], s[26:27], 0, v[150:151]
	s_mov_b32 m0, s54
	s_nop 0
	global_load_lds_dwordx4 v[224:225], off
	s_setprio 1
	s_barrier
	s_waitcnt lgkmcnt(0)
	v_mfma_f32_16x16x32_bf16 v[64:67], v[68:71], v[158:161], v[64:67]
	v_mfma_f32_16x16x32_bf16 v[60:63], v[76:79], v[158:161], v[60:63]
	v_mfma_f32_16x16x32_bf16 v[48:51], v[68:71], v[178:181], v[48:51]
	v_mfma_f32_16x16x32_bf16 v[44:47], v[76:79], v[178:181], v[44:47]
	v_mfma_f32_16x16x32_bf16 v[32:35], v[68:71], v[186:189], v[32:35]
	v_mfma_f32_16x16x32_bf16 v[28:31], v[76:79], v[186:189], v[28:31]
	v_mfma_f32_16x16x32_bf16 v[14:17], v[68:71], v[194:197], v[14:17]
	v_mfma_f32_16x16x32_bf16 v[10:13], v[76:79], v[194:197], v[10:13]
	v_mfma_f32_16x16x32_bf16 v[64:67], v[72:75], v[174:177], v[64:67]
	v_mfma_f32_16x16x32_bf16 v[60:63], v[80:83], v[174:177], v[60:63]
	v_mfma_f32_16x16x32_bf16 v[48:51], v[72:75], v[182:185], v[48:51]
	v_mfma_f32_16x16x32_bf16 v[44:47], v[80:83], v[182:185], v[44:47]
	v_mfma_f32_16x16x32_bf16 v[32:35], v[72:75], v[190:193], v[32:35]
	v_mfma_f32_16x16x32_bf16 v[28:31], v[80:83], v[190:193], v[28:31]
	v_mfma_f32_16x16x32_bf16 v[14:17], v[72:75], v[198:201], v[14:17]
	v_mfma_f32_16x16x32_bf16 v[10:13], v[80:83], v[198:201], v[10:13]
	s_barrier
	s_setprio 0
	s_add_u32 s0, s24, 0x40000
	s_addc_u32 s1, s25, 0
	s_add_i32 s72, s73, s52
	v_lshl_add_u64 v[68:69], s[0:1], 0, v[26:27]
	s_mov_b32 m0, s72
	s_nop 0
	global_load_lds_dwordx4 v[68:69], off
	v_lshl_add_u64 v[68:69], s[0:1], 0, v[148:149]
	s_add_i32 m0, s72, 0x2000
	s_nop 0
	global_load_lds_dwordx4 v[68:69], off
	s_waitcnt vmcnt(10)
	s_setprio 1
	s_barrier
	v_mfma_f32_16x16x32_bf16 v[56:59], v[202:205], v[158:161], v[56:59]
	v_mfma_f32_16x16x32_bf16 v[52:55], v[210:213], v[158:161], v[52:55]
	v_mfma_f32_16x16x32_bf16 v[40:43], v[202:205], v[178:181], v[40:43]
	v_mfma_f32_16x16x32_bf16 v[36:39], v[210:213], v[178:181], v[36:39]
	v_mfma_f32_16x16x32_bf16 v[22:25], v[202:205], v[186:189], v[22:25]
	v_mfma_f32_16x16x32_bf16 v[18:21], v[210:213], v[186:189], v[18:21]
	v_mfma_f32_16x16x32_bf16 v[6:9], v[202:205], v[194:197], v[6:9]
	v_mfma_f32_16x16x32_bf16 v[2:5], v[210:213], v[194:197], v[2:5]
	v_mfma_f32_16x16x32_bf16 v[56:59], v[206:209], v[174:177], v[56:59]
	v_mfma_f32_16x16x32_bf16 v[52:55], v[214:217], v[174:177], v[52:55]
	v_mfma_f32_16x16x32_bf16 v[40:43], v[206:209], v[182:185], v[40:43]
	v_mfma_f32_16x16x32_bf16 v[36:39], v[214:217], v[182:185], v[36:39]
	v_mfma_f32_16x16x32_bf16 v[22:25], v[206:209], v[190:193], v[22:25]
	v_mfma_f32_16x16x32_bf16 v[18:21], v[214:217], v[190:193], v[18:21]
	v_mfma_f32_16x16x32_bf16 v[6:9], v[206:209], v[198:201], v[6:9]
	v_mfma_f32_16x16x32_bf16 v[2:5], v[214:217], v[198:201], v[2:5]
	s_barrier
	s_setprio 0
	s_add_i32 s72, 0, 0x18000
	v_add_u32_e32 v80, s72, v163
	ds_read_b128 v[68:71], v80
	ds_read_b128 v[72:75], v80 offset:1024
	ds_read_b128 v[76:79], v80 offset:2048
	ds_read_b128 v[80:83], v80 offset:3072
	s_add_u32 s0, s26, 0x40000
	s_addc_u32 s1, s27, 0
	s_mov_b32 m0, s55
	v_lshl_add_u64 v[202:203], s[0:1], 0, v[152:153]
	ds_read_b128 v[158:161], v165 offset:32768
	ds_read_b128 v[174:177], v165 offset:33792
	ds_read_b128 v[178:181], v165 offset:34816
	ds_read_b128 v[182:185], v165 offset:35840
	ds_read_b128 v[186:189], v165 offset:36864
	ds_read_b128 v[190:193], v165 offset:37888
	ds_read_b128 v[194:197], v165 offset:38912
	ds_read_b128 v[198:201], v165 offset:39936
	global_load_lds_dwordx4 v[202:203], off
	v_lshl_add_u64 v[202:203], s[0:1], 0, v[150:151]
	s_mov_b32 m0, s56
	s_nop 0
	global_load_lds_dwordx4 v[202:203], off
	s_waitcnt vmcnt(10) lgkmcnt(8)
	s_setprio 1
	s_barrier
	s_waitcnt lgkmcnt(0)
	v_mfma_f32_16x16x32_bf16 v[144:147], v[68:71], v[158:161], v[144:147]
	v_mfma_f32_16x16x32_bf16 v[140:143], v[76:79], v[158:161], v[140:143]
	v_mfma_f32_16x16x32_bf16 v[128:131], v[68:71], v[178:181], v[128:131]
	v_mfma_f32_16x16x32_bf16 v[124:127], v[76:79], v[178:181], v[124:127]
	v_mfma_f32_16x16x32_bf16 v[112:115], v[68:71], v[186:189], v[112:115]
	v_mfma_f32_16x16x32_bf16 v[108:111], v[76:79], v[186:189], v[108:111]
	v_mfma_f32_16x16x32_bf16 v[96:99], v[68:71], v[194:197], v[96:99]
	v_mfma_f32_16x16x32_bf16 v[92:95], v[76:79], v[194:197], v[92:95]
	v_mfma_f32_16x16x32_bf16 v[144:147], v[72:75], v[174:177], v[144:147]
	v_mfma_f32_16x16x32_bf16 v[140:143], v[80:83], v[174:177], v[140:143]
	v_mfma_f32_16x16x32_bf16 v[128:131], v[72:75], v[182:185], v[128:131]
	v_mfma_f32_16x16x32_bf16 v[124:127], v[80:83], v[182:185], v[124:127]
	v_mfma_f32_16x16x32_bf16 v[112:115], v[72:75], v[190:193], v[112:115]
	v_mfma_f32_16x16x32_bf16 v[108:111], v[80:83], v[190:193], v[108:111]
	v_mfma_f32_16x16x32_bf16 v[96:99], v[72:75], v[198:201], v[96:99]
	v_mfma_f32_16x16x32_bf16 v[92:95], v[80:83], v[198:201], v[92:95]
	s_barrier
	s_setprio 0
	s_add_i32 s26, 0, 0x1c000
	s_add_i32 s0, s72, s52
	v_add_u32_e32 v166, s26, v163
	v_lshl_add_u64 v[218:219], v[218:219], 0, s[12:13]
	s_mov_b32 m0, s0
	ds_read_b128 v[202:205], v166
	ds_read_b128 v[206:209], v166 offset:1024
	ds_read_b128 v[210:213], v166 offset:2048
	ds_read_b128 v[214:217], v166 offset:3072
	global_load_lds_dwordx4 v[218:219], off
	v_lshl_add_u64 v[218:219], v[220:221], 0, s[12:13]
	s_add_i32 m0, s0, 0x2000
	s_nop 0
	global_load_lds_dwordx4 v[218:219], off
	s_waitcnt vmcnt(10)
	s_setprio 1
	s_barrier
	s_waitcnt lgkmcnt(0)
	v_mfma_f32_16x16x32_bf16 v[136:139], v[202:205], v[158:161], v[136:139]
	v_mfma_f32_16x16x32_bf16 v[132:135], v[210:213], v[158:161], v[132:135]
	v_mfma_f32_16x16x32_bf16 v[120:123], v[202:205], v[178:181], v[120:123]
	v_mfma_f32_16x16x32_bf16 v[116:119], v[210:213], v[178:181], v[116:119]
	v_mfma_f32_16x16x32_bf16 v[104:107], v[202:205], v[186:189], v[104:107]
	v_mfma_f32_16x16x32_bf16 v[100:103], v[210:213], v[186:189], v[100:103]
	v_mfma_f32_16x16x32_bf16 v[88:91], v[202:205], v[194:197], v[88:91]
	v_mfma_f32_16x16x32_bf16 v[84:87], v[210:213], v[194:197], v[84:87]
	v_mfma_f32_16x16x32_bf16 v[136:139], v[206:209], v[174:177], v[136:139]
	v_mfma_f32_16x16x32_bf16 v[132:135], v[214:217], v[174:177], v[132:135]
	v_mfma_f32_16x16x32_bf16 v[120:123], v[206:209], v[182:185], v[120:123]
	v_mfma_f32_16x16x32_bf16 v[116:119], v[214:217], v[182:185], v[116:119]
	v_mfma_f32_16x16x32_bf16 v[104:107], v[206:209], v[190:193], v[104:107]
	v_mfma_f32_16x16x32_bf16 v[100:103], v[214:217], v[190:193], v[100:103]
	v_mfma_f32_16x16x32_bf16 v[88:91], v[206:209], v[198:201], v[88:91]
	v_mfma_f32_16x16x32_bf16 v[84:87], v[214:217], v[198:201], v[84:87]
	s_barrier
	s_setprio 0
	s_mov_b32 m0, s30
	v_lshl_add_u64 v[218:219], v[222:223], 0, s[12:13]
	ds_read_b128 v[158:161], v165 offset:49152
	ds_read_b128 v[174:177], v165 offset:50176
	ds_read_b128 v[178:181], v165 offset:51200
	ds_read_b128 v[182:185], v165 offset:52224
	ds_read_b128 v[186:189], v165 offset:53248
	ds_read_b128 v[190:193], v165 offset:54272
	ds_read_b128 v[194:197], v165 offset:55296
	ds_read_b128 v[198:201], v165 offset:56320
	global_load_lds_dwordx4 v[218:219], off
	v_lshl_add_u64 v[218:219], v[224:225], 0, s[12:13]
	s_mov_b32 m0, s31
	s_nop 0
	global_load_lds_dwordx4 v[218:219], off
	s_setprio 1
	s_barrier
	s_waitcnt lgkmcnt(0)
	v_mfma_f32_16x16x32_bf16 v[64:67], v[68:71], v[158:161], v[64:67]
	v_mfma_f32_16x16x32_bf16 v[60:63], v[76:79], v[158:161], v[60:63]
	v_mfma_f32_16x16x32_bf16 v[48:51], v[68:71], v[178:181], v[48:51]
	v_mfma_f32_16x16x32_bf16 v[44:47], v[76:79], v[178:181], v[44:47]
	v_mfma_f32_16x16x32_bf16 v[32:35], v[68:71], v[186:189], v[32:35]
	v_mfma_f32_16x16x32_bf16 v[28:31], v[76:79], v[186:189], v[28:31]
	v_mfma_f32_16x16x32_bf16 v[14:17], v[68:71], v[194:197], v[14:17]
	v_mfma_f32_16x16x32_bf16 v[10:13], v[76:79], v[194:197], v[10:13]
	v_mfma_f32_16x16x32_bf16 v[64:67], v[72:75], v[174:177], v[64:67]
	v_mfma_f32_16x16x32_bf16 v[60:63], v[80:83], v[174:177], v[60:63]
	v_mfma_f32_16x16x32_bf16 v[48:51], v[72:75], v[182:185], v[48:51]
	v_mfma_f32_16x16x32_bf16 v[44:47], v[80:83], v[182:185], v[44:47]
	v_mfma_f32_16x16x32_bf16 v[32:35], v[72:75], v[190:193], v[32:35]
	v_mfma_f32_16x16x32_bf16 v[28:31], v[80:83], v[190:193], v[28:31]
	v_mfma_f32_16x16x32_bf16 v[14:17], v[72:75], v[198:201], v[14:17]
	v_mfma_f32_16x16x32_bf16 v[10:13], v[80:83], v[198:201], v[10:13]
	s_barrier
	s_setprio 0
	s_add_u32 s0, s24, 0x40080
	s_addc_u32 s1, s25, 0
	s_add_i32 s24, s26, s52
	v_lshl_add_u64 v[68:69], s[0:1], 0, v[26:27]
	s_mov_b32 m0, s24
	s_nop 0
	global_load_lds_dwordx4 v[68:69], off
	v_lshl_add_u64 v[68:69], s[0:1], 0, v[148:149]
	s_add_i32 m0, s24, 0x2000
	s_nop 0
	global_load_lds_dwordx4 v[68:69], off
	s_waitcnt vmcnt(10)
	s_setprio 1
	s_barrier
	v_mfma_f32_16x16x32_bf16 v[56:59], v[202:205], v[158:161], v[56:59]
	v_mfma_f32_16x16x32_bf16 v[52:55], v[210:213], v[158:161], v[52:55]
	v_mfma_f32_16x16x32_bf16 v[40:43], v[202:205], v[178:181], v[40:43]
	v_mfma_f32_16x16x32_bf16 v[36:39], v[210:213], v[178:181], v[36:39]
	v_mfma_f32_16x16x32_bf16 v[22:25], v[202:205], v[186:189], v[22:25]
	v_mfma_f32_16x16x32_bf16 v[18:21], v[210:213], v[186:189], v[18:21]
	v_mfma_f32_16x16x32_bf16 v[6:9], v[202:205], v[194:197], v[6:9]
	v_mfma_f32_16x16x32_bf16 v[2:5], v[210:213], v[194:197], v[2:5]
	v_mfma_f32_16x16x32_bf16 v[56:59], v[206:209], v[174:177], v[56:59]
	v_mfma_f32_16x16x32_bf16 v[52:55], v[214:217], v[174:177], v[52:55]
	v_mfma_f32_16x16x32_bf16 v[40:43], v[206:209], v[182:185], v[40:43]
	v_mfma_f32_16x16x32_bf16 v[36:39], v[214:217], v[182:185], v[36:39]
	v_mfma_f32_16x16x32_bf16 v[22:25], v[206:209], v[190:193], v[22:25]
	v_mfma_f32_16x16x32_bf16 v[18:21], v[214:217], v[190:193], v[18:21]
	v_mfma_f32_16x16x32_bf16 v[6:9], v[206:209], v[198:201], v[6:9]
	v_mfma_f32_16x16x32_bf16 v[2:5], v[214:217], v[198:201], v[2:5]
	s_barrier
	s_setprio 0
	s_add_i32 s69, s69, 2
	s_add_u32 s22, s22, 0x100
	s_addc_u32 s23, s23, 0
	s_add_u32 s59, s59, 0x100
	s_addc_u32 s68, s68, 0
	s_cmp_gt_u32 s69, 13
	s_cbranch_scc0 .LBB0_287
	s_cmpk_gt_i32 s58, 0xff
	s_mov_b64 s[18:19], 0xb000
	s_cbranch_scc1 .LBB0_283
	s_ashr_i32 s0, s58, 5
	s_mul_hi_i32 s19, s0, 0x1600
	s_mul_i32 s18, s0, 0x1600
	s_branch .LBB0_283

.LBB0_361:
	s_add_u32 s28, s26, 0x100
	s_addc_u32 s29, s27, 0
	s_add_i32 s0, 0, 0x10000
	v_add_u32_e32 v160, s0, v222
	ds_read_b128 v[132:135], v160
	ds_read_b128 v[136:139], v160 offset:1024
	ds_read_b128 v[156:159], v160 offset:2048
	ds_read_b128 v[160:163], v160 offset:3072
	s_cmp_eq_u32 s46, 40
	s_cselect_b32 s35, s45, s29
	s_cselect_b32 s34, s44, s28
	s_cselect_b32 s31, s23, s19
	s_cselect_b32 s30, s22, s18
	v_lshl_add_u64 v[164:165], s[26:27], 0, v[152:153]
	s_add_i32 m0, s20, 0xc000
	ds_read_b128 v[172:175], v224
	ds_read_b128 v[176:179], v224 offset:1024
	ds_read_b128 v[180:183], v224 offset:2048
	ds_read_b128 v[184:187], v224 offset:3072
	ds_read_b128 v[188:191], v224 offset:4096
	ds_read_b128 v[192:195], v224 offset:5120
	ds_read_b128 v[196:199], v224 offset:6144
	ds_read_b128 v[200:203], v224 offset:7168
	global_load_lds_dwordx4 v[164:165], off
	v_lshl_add_u64 v[164:165], s[26:27], 0, v[154:155]
	s_add_i32 m0, s20, 0xe000
	s_nop 0
	global_load_lds_dwordx4 v[164:165], off
	s_waitcnt vmcnt(10) lgkmcnt(8)
	s_setprio 1
	s_barrier
	s_waitcnt lgkmcnt(0)
	v_mfma_f32_16x16x32_bf16 v[128:131], v[132:135], v[172:175], v[128:131]
	v_mfma_f32_16x16x32_bf16 v[124:127], v[156:159], v[172:175], v[124:127]
	v_mfma_f32_16x16x32_bf16 v[120:123], v[132:135], v[180:183], v[120:123]
	v_mfma_f32_16x16x32_bf16 v[116:119], v[156:159], v[180:183], v[116:119]
	v_mfma_f32_16x16x32_bf16 v[112:115], v[132:135], v[188:191], v[112:115]
	v_mfma_f32_16x16x32_bf16 v[108:111], v[156:159], v[188:191], v[108:111]
	v_mfma_f32_16x16x32_bf16 v[104:107], v[132:135], v[196:199], v[104:107]
	v_mfma_f32_16x16x32_bf16 v[100:103], v[156:159], v[196:199], v[100:103]
	v_mfma_f32_16x16x32_bf16 v[128:131], v[136:139], v[176:179], v[128:131]
	v_mfma_f32_16x16x32_bf16 v[124:127], v[160:163], v[176:179], v[124:127]
	v_mfma_f32_16x16x32_bf16 v[120:123], v[136:139], v[184:187], v[120:123]
	v_mfma_f32_16x16x32_bf16 v[116:119], v[160:163], v[184:187], v[116:119]
	v_mfma_f32_16x16x32_bf16 v[112:115], v[136:139], v[192:195], v[112:115]
	v_mfma_f32_16x16x32_bf16 v[108:111], v[160:163], v[192:195], v[108:111]
	v_mfma_f32_16x16x32_bf16 v[104:107], v[136:139], v[200:203], v[104:107]
	v_mfma_f32_16x16x32_bf16 v[100:103], v[160:163], v[200:203], v[100:103]
	s_barrier
	s_setprio 0
	s_add_i32 s26, 0, 0x14000
	v_add_u32_e32 v164, s26, v222
	s_add_i32 s0, s0, s17
	ds_read_b128 v[204:207], v164
	ds_read_b128 v[208:211], v164 offset:1024
	ds_read_b128 v[212:215], v164 offset:2048
	ds_read_b128 v[216:219], v164 offset:3072
	v_lshl_add_u64 v[164:165], s[30:31], 0, v[26:27]
	s_mov_b32 m0, s0
	v_lshl_add_u64 v[166:167], s[30:31], 0, v[140:141]
	global_load_lds_dwordx4 v[164:165], off
	s_add_i32 m0, s0, 0x2000
	s_nop 0
	global_load_lds_dwordx4 v[166:167], off
	s_waitcnt vmcnt(10)
	s_setprio 1
	s_barrier
	s_waitcnt lgkmcnt(0)
	v_mfma_f32_16x16x32_bf16 v[64:67], v[204:207], v[172:175], v[64:67]
	v_mfma_f32_16x16x32_bf16 v[60:63], v[212:215], v[172:175], v[60:63]
	v_mfma_f32_16x16x32_bf16 v[56:59], v[204:207], v[180:183], v[56:59]
	v_mfma_f32_16x16x32_bf16 v[52:55], v[212:215], v[180:183], v[52:55]
	v_mfma_f32_16x16x32_bf16 v[48:51], v[204:207], v[188:191], v[48:51]
	v_mfma_f32_16x16x32_bf16 v[44:47], v[212:215], v[188:191], v[44:47]
	v_mfma_f32_16x16x32_bf16 v[40:43], v[204:207], v[196:199], v[40:43]
	v_mfma_f32_16x16x32_bf16 v[36:39], v[212:215], v[196:199], v[36:39]
	v_mfma_f32_16x16x32_bf16 v[64:67], v[208:211], v[176:179], v[64:67]
	v_mfma_f32_16x16x32_bf16 v[60:63], v[216:219], v[176:179], v[60:63]
	v_mfma_f32_16x16x32_bf16 v[56:59], v[208:211], v[184:187], v[56:59]
	v_mfma_f32_16x16x32_bf16 v[52:55], v[216:219], v[184:187], v[52:55]
	v_mfma_f32_16x16x32_bf16 v[48:51], v[208:211], v[192:195], v[48:51]
	v_mfma_f32_16x16x32_bf16 v[44:47], v[216:219], v[192:195], v[44:47]
	v_mfma_f32_16x16x32_bf16 v[40:43], v[208:211], v[200:203], v[40:43]
	v_mfma_f32_16x16x32_bf16 v[36:39], v[216:219], v[200:203], v[36:39]
	s_barrier
	s_setprio 0
	s_mov_b32 m0, s20
	v_lshl_add_u64 v[168:169], s[34:35], 0, v[144:145]
	ds_read_b128 v[172:175], v224 offset:16384
	ds_read_b128 v[176:179], v224 offset:17408
	ds_read_b128 v[180:183], v224 offset:18432
	ds_read_b128 v[184:187], v224 offset:19456
	ds_read_b128 v[188:191], v224 offset:20480
	ds_read_b128 v[192:195], v224 offset:21504
	ds_read_b128 v[196:199], v224 offset:22528
	ds_read_b128 v[200:203], v224 offset:23552
	global_load_lds_dwordx4 v[168:169], off
	v_lshl_add_u64 v[220:221], s[34:35], 0, v[142:143]
	s_mov_b32 m0, s21
	s_nop 0
	global_load_lds_dwordx4 v[220:221], off
	s_setprio 1
	s_barrier
	s_waitcnt lgkmcnt(0)
	v_mfma_f32_16x16x32_bf16 v[96:99], v[132:135], v[172:175], v[96:99]
	v_mfma_f32_16x16x32_bf16 v[92:95], v[156:159], v[172:175], v[92:95]
	v_mfma_f32_16x16x32_bf16 v[88:91], v[132:135], v[180:183], v[88:91]
	v_mfma_f32_16x16x32_bf16 v[84:87], v[156:159], v[180:183], v[84:87]
	v_mfma_f32_16x16x32_bf16 v[80:83], v[132:135], v[188:191], v[80:83]
	v_mfma_f32_16x16x32_bf16 v[76:79], v[156:159], v[188:191], v[76:79]
	v_mfma_f32_16x16x32_bf16 v[72:75], v[132:135], v[196:199], v[72:75]
	v_mfma_f32_16x16x32_bf16 v[68:71], v[156:159], v[196:199], v[68:71]
	v_mfma_f32_16x16x32_bf16 v[96:99], v[136:139], v[176:179], v[96:99]
	v_mfma_f32_16x16x32_bf16 v[92:95], v[160:163], v[176:179], v[92:95]
	v_mfma_f32_16x16x32_bf16 v[88:91], v[136:139], v[184:187], v[88:91]
	v_mfma_f32_16x16x32_bf16 v[84:87], v[160:163], v[184:187], v[84:87]
	v_mfma_f32_16x16x32_bf16 v[80:83], v[136:139], v[192:195], v[80:83]
	v_mfma_f32_16x16x32_bf16 v[76:79], v[160:163], v[192:195], v[76:79]
	v_mfma_f32_16x16x32_bf16 v[72:75], v[136:139], v[200:203], v[72:75]
	v_mfma_f32_16x16x32_bf16 v[68:71], v[160:163], v[200:203], v[68:71]
	s_barrier
	s_setprio 0
	s_add_u32 s0, s30, 0xb0000
	s_addc_u32 s1, s31, 0
	s_add_i32 s26, s26, s17
	v_lshl_add_u64 v[132:133], s[0:1], 0, v[26:27]
	s_mov_b32 m0, s26
	s_nop 0
	global_load_lds_dwordx4 v[132:133], off
	v_lshl_add_u64 v[132:133], s[0:1], 0, v[140:141]
	s_add_i32 m0, s26, 0x2000
	s_nop 0
	global_load_lds_dwordx4 v[132:133], off
	s_waitcnt vmcnt(10)
	s_setprio 1
	s_barrier
	v_mfma_f32_16x16x32_bf16 v[32:35], v[204:207], v[172:175], v[32:35]
	v_mfma_f32_16x16x32_bf16 v[28:31], v[212:215], v[172:175], v[28:31]
	v_mfma_f32_16x16x32_bf16 v[22:25], v[204:207], v[180:183], v[22:25]
	v_mfma_f32_16x16x32_bf16 v[18:21], v[212:215], v[180:183], v[18:21]
	v_mfma_f32_16x16x32_bf16 v[14:17], v[204:207], v[188:191], v[14:17]
	v_mfma_f32_16x16x32_bf16 v[10:13], v[212:215], v[188:191], v[10:13]
	v_mfma_f32_16x16x32_bf16 v[6:9], v[204:207], v[196:199], v[6:9]
	v_mfma_f32_16x16x32_bf16 v[2:5], v[212:215], v[196:199], v[2:5]
	v_mfma_f32_16x16x32_bf16 v[32:35], v[208:211], v[176:179], v[32:35]
	v_mfma_f32_16x16x32_bf16 v[28:31], v[216:219], v[176:179], v[28:31]
	v_mfma_f32_16x16x32_bf16 v[22:25], v[208:211], v[184:187], v[22:25]
	v_mfma_f32_16x16x32_bf16 v[18:21], v[216:219], v[184:187], v[18:21]
	v_mfma_f32_16x16x32_bf16 v[14:17], v[208:211], v[192:195], v[14:17]
	v_mfma_f32_16x16x32_bf16 v[10:13], v[216:219], v[192:195], v[10:13]
	v_mfma_f32_16x16x32_bf16 v[6:9], v[208:211], v[200:203], v[6:9]
	v_mfma_f32_16x16x32_bf16 v[2:5], v[216:219], v[200:203], v[2:5]
	s_barrier
	s_setprio 0
	s_add_i32 s26, 0, 0x18000
	v_add_u32_e32 v160, s26, v222
	ds_read_b128 v[132:135], v160
	ds_read_b128 v[136:139], v160 offset:1024
	ds_read_b128 v[156:159], v160 offset:2048
	ds_read_b128 v[160:163], v160 offset:3072
	s_add_u32 s0, s34, 0xb0000
	s_addc_u32 s1, s35, 0
	s_mov_b32 m0, s36
	v_lshl_add_u64 v[204:205], s[0:1], 0, v[144:145]
	ds_read_b128 v[172:175], v224 offset:32768
	ds_read_b128 v[176:179], v224 offset:33792
	ds_read_b128 v[180:183], v224 offset:34816
	ds_read_b128 v[184:187], v224 offset:35840
	ds_read_b128 v[188:191], v224 offset:36864
	ds_read_b128 v[192:195], v224 offset:37888
	ds_read_b128 v[196:199], v224 offset:38912
	ds_read_b128 v[200:203], v224 offset:39936
	global_load_lds_dwordx4 v[204:205], off
	v_lshl_add_u64 v[204:205], s[0:1], 0, v[142:143]
	s_mov_b32 m0, s37
	s_nop 0
	global_load_lds_dwordx4 v[204:205], off
	s_waitcnt vmcnt(10) lgkmcnt(8)
	s_setprio 1
	s_barrier
	s_waitcnt lgkmcnt(0)
	v_mfma_f32_16x16x32_bf16 v[128:131], v[132:135], v[172:175], v[128:131]
	v_mfma_f32_16x16x32_bf16 v[124:127], v[156:159], v[172:175], v[124:127]
	v_mfma_f32_16x16x32_bf16 v[120:123], v[132:135], v[180:183], v[120:123]
	v_mfma_f32_16x16x32_bf16 v[116:119], v[156:159], v[180:183], v[116:119]
	v_mfma_f32_16x16x32_bf16 v[112:115], v[132:135], v[188:191], v[112:115]
	v_mfma_f32_16x16x32_bf16 v[108:111], v[156:159], v[188:191], v[108:111]
	v_mfma_f32_16x16x32_bf16 v[104:107], v[132:135], v[196:199], v[104:107]
	v_mfma_f32_16x16x32_bf16 v[100:103], v[156:159], v[196:199], v[100:103]
	v_mfma_f32_16x16x32_bf16 v[128:131], v[136:139], v[176:179], v[128:131]
	v_mfma_f32_16x16x32_bf16 v[124:127], v[160:163], v[176:179], v[124:127]
	v_mfma_f32_16x16x32_bf16 v[120:123], v[136:139], v[184:187], v[120:123]
	v_mfma_f32_16x16x32_bf16 v[116:119], v[160:163], v[184:187], v[116:119]
	v_mfma_f32_16x16x32_bf16 v[112:115], v[136:139], v[192:195], v[112:115]
	v_mfma_f32_16x16x32_bf16 v[108:111], v[160:163], v[192:195], v[108:111]
	v_mfma_f32_16x16x32_bf16 v[104:107], v[136:139], v[200:203], v[104:107]
	v_mfma_f32_16x16x32_bf16 v[100:103], v[160:163], v[200:203], v[100:103]
	s_barrier
	s_setprio 0
	s_add_i32 s27, 0, 0x1c000
	s_add_i32 s0, s26, s17
	v_add_u32_e32 v216, s27, v222
	v_lshl_add_u64 v[164:165], v[164:165], 0, s[12:13]
	s_mov_b32 m0, s0
	ds_read_b128 v[204:207], v216
	ds_read_b128 v[208:211], v216 offset:1024
	ds_read_b128 v[212:215], v216 offset:2048
	ds_read_b128 v[216:219], v216 offset:3072
	global_load_lds_dwordx4 v[164:165], off
	v_lshl_add_u64 v[164:165], v[166:167], 0, s[12:13]
	s_add_i32 m0, s0, 0x2000
	s_nop 0
	global_load_lds_dwordx4 v[164:165], off
	s_waitcnt vmcnt(10)
	s_setprio 1
	s_barrier
	s_waitcnt lgkmcnt(0)
	v_mfma_f32_16x16x32_bf16 v[64:67], v[204:207], v[172:175], v[64:67]
	v_mfma_f32_16x16x32_bf16 v[60:63], v[212:215], v[172:175], v[60:63]
	v_mfma_f32_16x16x32_bf16 v[56:59], v[204:207], v[180:183], v[56:59]
	v_mfma_f32_16x16x32_bf16 v[52:55], v[212:215], v[180:183], v[52:55]
	v_mfma_f32_16x16x32_bf16 v[48:51], v[204:207], v[188:191], v[48:51]
	v_mfma_f32_16x16x32_bf16 v[44:47], v[212:215], v[188:191], v[44:47]
	v_mfma_f32_16x16x32_bf16 v[40:43], v[204:207], v[196:199], v[40:43]
	v_mfma_f32_16x16x32_bf16 v[36:39], v[212:215], v[196:199], v[36:39]
	v_mfma_f32_16x16x32_bf16 v[64:67], v[208:211], v[176:179], v[64:67]
	v_mfma_f32_16x16x32_bf16 v[60:63], v[216:219], v[176:179], v[60:63]
	v_mfma_f32_16x16x32_bf16 v[56:59], v[208:211], v[184:187], v[56:59]
	v_mfma_f32_16x16x32_bf16 v[52:55], v[216:219], v[184:187], v[52:55]
	v_mfma_f32_16x16x32_bf16 v[48:51], v[208:211], v[192:195], v[48:51]
	v_mfma_f32_16x16x32_bf16 v[44:47], v[216:219], v[192:195], v[44:47]
	v_mfma_f32_16x16x32_bf16 v[40:43], v[208:211], v[200:203], v[40:43]
	v_mfma_f32_16x16x32_bf16 v[36:39], v[216:219], v[200:203], v[36:39]
	s_barrier
	s_setprio 0
	s_mov_b32 m0, s59
	v_lshl_add_u64 v[164:165], v[168:169], 0, s[12:13]
	ds_read_b128 v[172:175], v224 offset:49152
	ds_read_b128 v[176:179], v224 offset:50176
	ds_read_b128 v[180:183], v224 offset:51200
	ds_read_b128 v[184:187], v224 offset:52224
	ds_read_b128 v[188:191], v224 offset:53248
	ds_read_b128 v[192:195], v224 offset:54272
	ds_read_b128 v[196:199], v224 offset:55296
	ds_read_b128 v[200:203], v224 offset:56320
	global_load_lds_dwordx4 v[164:165], off
	v_lshl_add_u64 v[164:165], v[220:221], 0, s[12:13]
	s_mov_b32 m0, s68
	s_nop 0
	global_load_lds_dwordx4 v[164:165], off
	s_setprio 1
	s_barrier
	s_waitcnt lgkmcnt(0)
	v_mfma_f32_16x16x32_bf16 v[96:99], v[132:135], v[172:175], v[96:99]
	v_mfma_f32_16x16x32_bf16 v[92:95], v[156:159], v[172:175], v[92:95]
	v_mfma_f32_16x16x32_bf16 v[88:91], v[132:135], v[180:183], v[88:91]
	v_mfma_f32_16x16x32_bf16 v[84:87], v[156:159], v[180:183], v[84:87]
	v_mfma_f32_16x16x32_bf16 v[80:83], v[132:135], v[188:191], v[80:83]
	v_mfma_f32_16x16x32_bf16 v[76:79], v[156:159], v[188:191], v[76:79]
	v_mfma_f32_16x16x32_bf16 v[72:75], v[132:135], v[196:199], v[72:75]
	v_mfma_f32_16x16x32_bf16 v[68:71], v[156:159], v[196:199], v[68:71]
	v_mfma_f32_16x16x32_bf16 v[96:99], v[136:139], v[176:179], v[96:99]
	v_mfma_f32_16x16x32_bf16 v[92:95], v[160:163], v[176:179], v[92:95]
	v_mfma_f32_16x16x32_bf16 v[88:91], v[136:139], v[184:187], v[88:91]
	v_mfma_f32_16x16x32_bf16 v[84:87], v[160:163], v[184:187], v[84:87]
	v_mfma_f32_16x16x32_bf16 v[80:83], v[136:139], v[192:195], v[80:83]
	v_mfma_f32_16x16x32_bf16 v[76:79], v[160:163], v[192:195], v[76:79]
	v_mfma_f32_16x16x32_bf16 v[72:75], v[136:139], v[200:203], v[72:75]
	v_mfma_f32_16x16x32_bf16 v[68:71], v[160:163], v[200:203], v[68:71]
	s_barrier
	s_setprio 0
	s_add_u32 s0, s30, 0xb0080
	s_addc_u32 s1, s31, 0
	s_add_i32 s26, s27, s17
	v_lshl_add_u64 v[132:133], s[0:1], 0, v[26:27]
	s_mov_b32 m0, s26
	s_nop 0
	global_load_lds_dwordx4 v[132:133], off
	v_lshl_add_u64 v[132:133], s[0:1], 0, v[140:141]
	s_add_i32 m0, s26, 0x2000
	s_nop 0
	global_load_lds_dwordx4 v[132:133], off
	s_waitcnt vmcnt(10)
	s_setprio 1
	s_barrier
	v_mfma_f32_16x16x32_bf16 v[32:35], v[204:207], v[172:175], v[32:35]
	v_mfma_f32_16x16x32_bf16 v[28:31], v[212:215], v[172:175], v[28:31]
	v_mfma_f32_16x16x32_bf16 v[22:25], v[204:207], v[180:183], v[22:25]
	v_mfma_f32_16x16x32_bf16 v[18:21], v[212:215], v[180:183], v[18:21]
	v_mfma_f32_16x16x32_bf16 v[14:17], v[204:207], v[188:191], v[14:17]
	v_mfma_f32_16x16x32_bf16 v[10:13], v[212:215], v[188:191], v[10:13]
	v_mfma_f32_16x16x32_bf16 v[6:9], v[204:207], v[196:199], v[6:9]
	v_mfma_f32_16x16x32_bf16 v[2:5], v[212:215], v[196:199], v[2:5]
	v_mfma_f32_16x16x32_bf16 v[32:35], v[208:211], v[176:179], v[32:35]
	v_mfma_f32_16x16x32_bf16 v[28:31], v[216:219], v[176:179], v[28:31]
	v_mfma_f32_16x16x32_bf16 v[22:25], v[208:211], v[184:187], v[22:25]
	v_mfma_f32_16x16x32_bf16 v[18:21], v[216:219], v[184:187], v[18:21]
	v_mfma_f32_16x16x32_bf16 v[14:17], v[208:211], v[192:195], v[14:17]
	v_mfma_f32_16x16x32_bf16 v[10:13], v[216:219], v[192:195], v[10:13]
	v_mfma_f32_16x16x32_bf16 v[6:9], v[208:211], v[200:203], v[6:9]
	v_mfma_f32_16x16x32_bf16 v[2:5], v[216:219], v[200:203], v[2:5]
	s_barrier
	s_setprio 0
	s_add_i32 s46, s46, 2
	s_add_u32 s18, s18, 0x100
	s_addc_u32 s19, s19, 0
	s_cmp_gt_u32 s46, 41
	s_mov_b64 s[26:27], s[28:29]
	s_cbranch_scc0 .LBB0_361
	s_min_i32 s0, s24, 0x100
	s_ashr_i32 s0, s0, 5
	s_ashr_i32 s1, s0, 31
	s_add_i32 s18, s24, 0xffffff00
	s_cmpk_lt_i32 s24, 0x100
	s_cselect_b32 s18, s24, s18
	s_cselect_b32 s27, 0, s58
	s_cselect_b32 s26, 0, s57
	s_ashr_i32 s19, s18, 31
	s_lshl_b64 s[18:19], s[18:19], 19
	s_add_u32 s26, s50, s26
	v_lshl_or_b32 v178, s25, 8, v223
	s_addc_u32 s27, s51, s27
	s_ashr_i32 s25, s24, 31
	v_lshl_add_u64 v[132:133], s[18:19], 0, v[146:147]
	s_lshl_b64 s[18:19], s[24:25], 19
	v_lshl_add_u64 v[184:185], v[148:149], 0, s[18:19]
	s_lshl_b64 s[24:25], s[24:25], 10
	s_mul_i32 s18, s0, 0x9000
	v_ashrrev_i32_e32 v179, 31, v178
	s_mul_hi_i32 s19, s0, 0x9000
	s_add_u32 s18, s48, s18
	s_addc_u32 s19, s49, s19
	v_lshlrev_b64 v[186:187], 2, v[178:179]
	v_lshl_add_u64 v[156:157], s[18:19], 0, v[186:187]
	v_lshl_add_u64 v[180:181], v[132:133], 0, v[178:179]
	v_lshl_add_u64 v[182:183], v[132:133], 1, s[26:27]
	global_load_dwordx4 v[132:135], v[156:157], off offset:16
	global_load_dwordx4 v[136:139], v[156:157], off
	s_lshl_b64 s[0:1], s[0:1], 12
	s_add_u32 s28, s52, s0
	s_addc_u32 s29, s53, s1
	v_lshl_add_u64 v[196:197], v[180:181], 1, s[26:27]
	v_lshl_add_u64 v[180:181], s[28:29], 0, v[186:187]
	v_add_co_u32_e32 v210, vcc, s65, v196
	v_lshlrev_b64 v[188:189], 1, v[178:179]
	s_nop 0
	v_addc_co_u32_e32 v211, vcc, 0, v197, vcc
	s_mov_b32 s1, 0x20000
	v_lshl_add_u64 v[178:179], v[184:185], 0, v[188:189]
	v_add_co_u32_e32 v184, vcc, s1, v196
	s_mov_b32 s18, 0x30000
	s_nop 0
	v_addc_co_u32_e32 v185, vcc, 0, v197, vcc
	v_lshl_add_u64 v[182:183], v[182:183], 0, v[188:189]
	v_add_co_u32_e32 v188, vcc, s18, v196
	s_mov_b32 s0, 0x8000
	s_nop 0
	v_addc_co_u32_e32 v189, vcc, 0, v197, vcc
	s_mov_b32 s19, 0x80000
	s_mov_b32 s26, 0x90000
	s_waitcnt vmcnt(0)
	v_pk_mul_f32 v[172:173], v[134:135], 0.5 op_sel_hi:[1,0]
	v_pk_mul_f32 v[176:177], v[138:139], 0.5 op_sel_hi:[1,0]
	v_pk_mul_f32 v[174:175], v[136:137], 0.5 op_sel_hi:[1,0]
	v_pk_mul_f32 v[164:165], v[132:133], 0.5 op_sel_hi:[1,0]
	global_load_dwordx4 v[132:135], v[156:157], off offset:528
	global_load_dwordx4 v[136:139], v[156:157], off offset:512
	s_waitcnt vmcnt(0)
	v_pk_mul_f32 v[158:159], v[134:135], 0.5 op_sel_hi:[1,0]
	v_pk_mul_f32 v[162:163], v[138:139], 0.5 op_sel_hi:[1,0]
	v_pk_mul_f32 v[160:161], v[136:137], 0.5 op_sel_hi:[1,0]
	v_pk_mul_f32 v[156:157], v[132:133], 0.5 op_sel_hi:[1,0]
	global_load_dwordx4 v[132:135], v[180:181], off offset:16
	global_load_dwordx4 v[136:139], v[180:181], off
	global_load_dwordx4 v[190:193], v[196:197], off offset:2048
	global_load_dwordx4 v[198:201], v[210:211], off offset:2048
	global_load_dwordx4 v[202:205], v[184:185], off offset:2048
	global_load_dwordx4 v[206:209], v[188:189], off offset:2048
	s_waitcnt vmcnt(0)
	v_lshlrev_b32_e32 v186, 16, v190
	v_and_b32_e32 v187, 0xffff0000, v190
	v_lshlrev_b32_e32 v190, 16, v191
	v_and_b32_e32 v191, 0xffff0000, v191
	v_lshlrev_b32_e32 v194, 16, v192
	v_and_b32_e32 v195, 0xffff0000, v192
	v_lshlrev_b32_e32 v192, 16, v193
	v_and_b32_e32 v193, 0xffff0000, v193
	v_pk_fma_f32 v[130:131], v[130:131], v[176:177], v[190:191]
	v_pk_fma_f32 v[128:129], v[128:129], v[174:175], v[186:187]
	v_pk_fma_f32 v[126:127], v[126:127], v[172:173], v[192:193]
	v_pk_fma_f32 v[124:125], v[124:125], v[164:165], v[194:195]
	v_cvt_pk_bf16_f32 v190, v128, v129
	v_cvt_pk_bf16_f32 v191, v130, v131
	v_cvt_pk_bf16_f32 v192, v124, v125
	v_cvt_pk_bf16_f32 v193, v126, v127
	v_lshlrev_b32_e32 v130, 16, v190
	v_and_b32_e32 v131, 0xffff0000, v190
	v_lshlrev_b32_e32 v128, 16, v191
	v_and_b32_e32 v129, 0xffff0000, v191
	v_lshlrev_b32_e32 v126, 16, v192
	v_and_b32_e32 v127, 0xffff0000, v192
	v_lshlrev_b32_e32 v124, 16, v193
	v_and_b32_e32 v125, 0xffff0000, v193
	v_lshlrev_b32_e32 v212, 16, v198
	v_and_b32_e32 v213, 0xffff0000, v198
	v_lshlrev_b32_e32 v198, 16, v199
	v_and_b32_e32 v199, 0xffff0000, v199
	global_store_dwordx4 v[182:183], v[190:193], off offset:2048
	v_pk_mul_f32 v[186:187], v[138:139], v[128:129]
	v_pk_mul_f32 v[194:195], v[134:135], v[124:125]
	v_pk_mul_f32 v[190:191], v[136:137], v[130:131]
	v_pk_mul_f32 v[192:193], v[132:133], v[126:127]
	v_lshlrev_b32_e32 v214, 16, v200
	v_and_b32_e32 v215, 0xffff0000, v200
	v_lshlrev_b32_e32 v200, 16, v201
	v_and_b32_e32 v201, 0xffff0000, v201
	v_cvt_pk_bf16_f32 v190, v190, v191
	v_cvt_pk_bf16_f32 v191, v186, v187
	v_cvt_pk_bf16_f32 v192, v192, v193
	v_cvt_pk_bf16_f32 v193, v194, v195
	v_pk_fma_f32 v[122:123], v[122:123], v[176:177], v[198:199]
	v_pk_fma_f32 v[120:121], v[120:121], v[174:175], v[212:213]
	global_store_dwordx4 v[178:179], v[190:193], off
	v_pk_fma_f32 v[118:119], v[118:119], v[172:173], v[200:201]
	v_pk_fma_f32 v[116:117], v[116:117], v[164:165], v[214:215]
	v_cvt_pk_bf16_f32 v190, v120, v121
	v_cvt_pk_bf16_f32 v191, v122, v123
	v_add_co_u32_e32 v186, vcc, s65, v182
	v_cvt_pk_bf16_f32 v192, v116, v117
	v_cvt_pk_bf16_f32 v193, v118, v119
	v_addc_co_u32_e32 v187, vcc, 0, v183, vcc
	v_lshlrev_b32_e32 v122, 16, v190
	v_and_b32_e32 v123, 0xffff0000, v190
	v_lshlrev_b32_e32 v120, 16, v191
	v_and_b32_e32 v121, 0xffff0000, v191
	global_store_dwordx4 v[186:187], v[190:193], off offset:2048
	v_lshlrev_b32_e32 v118, 16, v192
	v_and_b32_e32 v119, 0xffff0000, v192
	v_lshlrev_b32_e32 v116, 16, v193
	v_and_b32_e32 v117, 0xffff0000, v193
	v_pk_mul_f32 v[190:191], v[138:139], v[120:121]
	v_pk_mul_f32 v[192:193], v[136:137], v[122:123]
	v_pk_mul_f32 v[198:199], v[134:135], v[116:117]
	v_pk_mul_f32 v[194:195], v[132:133], v[118:119]
	v_cvt_pk_bf16_f32 v192, v192, v193
	v_cvt_pk_bf16_f32 v193, v190, v191
	v_add_co_u32_e32 v190, vcc, s0, v178
	v_cvt_pk_bf16_f32 v194, v194, v195
	v_cvt_pk_bf16_f32 v195, v198, v199
	v_addc_co_u32_e32 v191, vcc, 0, v179, vcc
	global_store_dwordx4 v[190:191], v[192:195], off
	v_lshlrev_b32_e32 v198, 16, v202
	v_and_b32_e32 v199, 0xffff0000, v202
	v_add_co_u32_e32 v192, vcc, s19, v196
	v_lshlrev_b32_e32 v200, 16, v203
	s_nop 0
	v_addc_co_u32_e32 v193, vcc, 0, v197, vcc
	v_add_co_u32_e32 v194, vcc, s26, v196
	v_and_b32_e32 v201, 0xffff0000, v203
	global_load_dwordx4 v[212:215], v[192:193], off offset:2048
	v_addc_co_u32_e32 v195, vcc, 0, v197, vcc
	v_lshlrev_b32_e32 v202, 16, v204
	v_and_b32_e32 v203, 0xffff0000, v204
	v_lshlrev_b32_e32 v204, 16, v205
	v_and_b32_e32 v205, 0xffff0000, v205
	v_pk_fma_f32 v[114:115], v[114:115], v[176:177], v[200:201]
	v_pk_fma_f32 v[112:113], v[112:113], v[174:175], v[198:199]
	v_pk_fma_f32 v[110:111], v[110:111], v[172:173], v[204:205]
	v_pk_fma_f32 v[108:109], v[108:109], v[164:165], v[202:203]
	v_cvt_pk_bf16_f32 v200, v112, v113
	v_cvt_pk_bf16_f32 v201, v114, v115
	v_add_co_u32_e32 v198, vcc, s1, v182
	v_cvt_pk_bf16_f32 v202, v108, v109
	v_cvt_pk_bf16_f32 v203, v110, v111
	v_addc_co_u32_e32 v199, vcc, 0, v183, vcc
	v_lshlrev_b32_e32 v114, 16, v200
	v_and_b32_e32 v115, 0xffff0000, v200
	v_lshlrev_b32_e32 v112, 16, v201
	v_and_b32_e32 v113, 0xffff0000, v201
	global_load_dwordx4 v[216:219], v[194:195], off offset:2048
	v_lshlrev_b32_e32 v110, 16, v202
	global_store_dwordx4 v[198:199], v[200:203], off offset:2048
	v_and_b32_e32 v111, 0xffff0000, v202
	v_lshlrev_b32_e32 v108, 16, v203
	v_and_b32_e32 v109, 0xffff0000, v203
	v_pk_mul_f32 v[200:201], v[138:139], v[112:113]
	v_pk_mul_f32 v[202:203], v[136:137], v[114:115]
	v_lshlrev_b32_e32 v220, 16, v206
	v_and_b32_e32 v221, 0xffff0000, v206
	v_lshlrev_b32_e32 v206, 16, v207
	v_and_b32_e32 v207, 0xffff0000, v207
	v_pk_mul_f32 v[238:239], v[134:135], v[108:109]
	v_pk_mul_f32 v[204:205], v[132:133], v[110:111]
	v_cvt_pk_bf16_f32 v202, v202, v203
	v_cvt_pk_bf16_f32 v203, v200, v201
	v_add_co_u32_e32 v200, vcc, s65, v178
	v_lshlrev_b32_e32 v234, 16, v208
	v_and_b32_e32 v235, 0xffff0000, v208
	v_lshlrev_b32_e32 v208, 16, v209
	v_and_b32_e32 v209, 0xffff0000, v209
	v_cvt_pk_bf16_f32 v204, v204, v205
	v_cvt_pk_bf16_f32 v205, v238, v239
	v_addc_co_u32_e32 v201, vcc, 0, v179, vcc
	v_pk_fma_f32 v[106:107], v[106:107], v[176:177], v[206:207]
	v_pk_fma_f32 v[104:105], v[104:105], v[174:175], v[220:221]
	global_store_dwordx4 v[200:201], v[202:205], off
	v_pk_fma_f32 v[102:103], v[102:103], v[172:173], v[208:209]
	v_pk_fma_f32 v[100:101], v[100:101], v[164:165], v[234:235]
	v_cvt_pk_bf16_f32 v204, v104, v105
	v_cvt_pk_bf16_f32 v205, v106, v107
	v_add_co_u32_e32 v202, vcc, s18, v182
	v_cvt_pk_bf16_f32 v206, v100, v101
	v_cvt_pk_bf16_f32 v207, v102, v103
	v_addc_co_u32_e32 v203, vcc, 0, v183, vcc
	v_lshlrev_b32_e32 v106, 16, v204
	v_and_b32_e32 v107, 0xffff0000, v204
	v_lshlrev_b32_e32 v104, 16, v205
	v_and_b32_e32 v105, 0xffff0000, v205
	global_store_dwordx4 v[202:203], v[204:207], off offset:2048
	v_lshlrev_b32_e32 v102, 16, v206
	v_and_b32_e32 v103, 0xffff0000, v206
	v_lshlrev_b32_e32 v100, 16, v207
	v_and_b32_e32 v101, 0xffff0000, v207
	v_pk_mul_f32 v[204:205], v[138:139], v[104:105]
	v_pk_mul_f32 v[206:207], v[136:137], v[106:107]
	s_mov_b32 s0, 0x18000
	v_pk_mul_f32 v[220:221], v[134:135], v[100:101]
	v_pk_mul_f32 v[208:209], v[132:133], v[102:103]
	v_cvt_pk_bf16_f32 v206, v206, v207
	v_cvt_pk_bf16_f32 v207, v204, v205
	v_add_co_u32_e32 v204, vcc, s0, v178
	v_cvt_pk_bf16_f32 v208, v208, v209
	v_cvt_pk_bf16_f32 v209, v220, v221
	v_addc_co_u32_e32 v205, vcc, 0, v179, vcc
	global_store_dwordx4 v[204:205], v[206:209], off
	s_mov_b32 s0, 0xb0000
	s_waitcnt vmcnt(0)
	v_lshlrev_b32_e32 v220, 16, v212
	v_add_co_u32_e32 v206, vcc, s76, v196
	v_and_b32_e32 v221, 0xffff0000, v212
	s_nop 0
	v_addc_co_u32_e32 v207, vcc, 0, v197, vcc
	global_load_dwordx4 v[238:241], v[206:207], off offset:2048
	v_add_co_u32_e32 v208, vcc, s0, v196
	v_lshlrev_b32_e32 v212, 16, v213
	s_nop 0
	v_addc_co_u32_e32 v209, vcc, 0, v197, vcc
	global_load_dwordx4 v[242:245], v[208:209], off offset:2048
	v_and_b32_e32 v213, 0xffff0000, v213
	v_lshlrev_b32_e32 v234, 16, v214
	v_and_b32_e32 v235, 0xffff0000, v214
	v_lshlrev_b32_e32 v214, 16, v215
	v_and_b32_e32 v215, 0xffff0000, v215
	v_pk_fma_f32 v[98:99], v[98:99], v[176:177], v[212:213]
	v_pk_fma_f32 v[96:97], v[96:97], v[174:175], v[220:221]
	v_pk_fma_f32 v[94:95], v[94:95], v[172:173], v[214:215]
	v_pk_fma_f32 v[92:93], v[92:93], v[164:165], v[234:235]
	v_cvt_pk_bf16_f32 v214, v96, v97
	v_cvt_pk_bf16_f32 v215, v98, v99
	v_add_co_u32_e32 v212, vcc, s19, v182
	v_lshlrev_b32_e32 v246, 16, v216
	v_and_b32_e32 v247, 0xffff0000, v216
	v_lshlrev_b32_e32 v248, 16, v217
	v_and_b32_e32 v249, 0xffff0000, v217
	v_cvt_pk_bf16_f32 v216, v92, v93
	v_cvt_pk_bf16_f32 v217, v94, v95
	v_addc_co_u32_e32 v213, vcc, 0, v183, vcc
	v_lshlrev_b32_e32 v98, 16, v214
	v_and_b32_e32 v99, 0xffff0000, v214
	v_lshlrev_b32_e32 v96, 16, v215
	v_and_b32_e32 v97, 0xffff0000, v215
	global_store_dwordx4 v[212:213], v[214:217], off offset:2048
	v_lshlrev_b32_e32 v94, 16, v216
	v_and_b32_e32 v95, 0xffff0000, v216
	v_lshlrev_b32_e32 v92, 16, v217
	v_and_b32_e32 v93, 0xffff0000, v217
	v_pk_mul_f32 v[214:215], v[138:139], v[96:97]
	v_pk_mul_f32 v[216:217], v[136:137], v[98:99]
	s_mov_b32 s1, 0x40000
	v_lshlrev_b32_e32 v250, 16, v218
	v_and_b32_e32 v251, 0xffff0000, v218
	v_lshlrev_b32_e32 v252, 16, v219
	v_and_b32_e32 v253, 0xffff0000, v219
	v_pk_mul_f32 v[220:221], v[134:135], v[92:93]
	v_pk_mul_f32 v[218:219], v[132:133], v[94:95]
	v_cvt_pk_bf16_f32 v216, v216, v217
	v_cvt_pk_bf16_f32 v217, v214, v215
	v_add_co_u32_e32 v214, vcc, s1, v178
	v_cvt_pk_bf16_f32 v218, v218, v219
	v_cvt_pk_bf16_f32 v219, v220, v221
	v_addc_co_u32_e32 v215, vcc, 0, v179, vcc
	v_pk_fma_f32 v[90:91], v[90:91], v[176:177], v[248:249]
	global_store_dwordx4 v[214:215], v[216:219], off
	v_pk_fma_f32 v[88:89], v[88:89], v[174:175], v[246:247]
	v_pk_fma_f32 v[86:87], v[86:87], v[172:173], v[252:253]
	v_pk_fma_f32 v[84:85], v[84:85], v[164:165], v[250:251]
	v_cvt_pk_bf16_f32 v219, v90, v91
	v_add_co_u32_e32 v216, vcc, s26, v182
	v_cvt_pk_bf16_f32 v218, v88, v89
	v_cvt_pk_bf16_f32 v220, v84, v85
	v_cvt_pk_bf16_f32 v221, v86, v87
	v_addc_co_u32_e32 v217, vcc, 0, v183, vcc
	v_lshlrev_b32_e32 v88, 16, v219
	v_and_b32_e32 v89, 0xffff0000, v219
	global_store_dwordx4 v[216:217], v[218:221], off offset:2048
	v_lshlrev_b32_e32 v90, 16, v218
	v_and_b32_e32 v91, 0xffff0000, v218
	v_lshlrev_b32_e32 v86, 16, v220
	v_and_b32_e32 v87, 0xffff0000, v220
	v_lshlrev_b32_e32 v84, 16, v221
	v_and_b32_e32 v85, 0xffff0000, v221
	v_pk_mul_f32 v[218:219], v[138:139], v[88:89]
	s_mov_b32 s1, 0x48000
	v_pk_mul_f32 v[220:221], v[136:137], v[90:91]
	v_pk_mul_f32 v[234:235], v[134:135], v[84:85]
	v_pk_mul_f32 v[248:249], v[132:133], v[86:87]
	v_cvt_pk_bf16_f32 v247, v218, v219
	v_add_co_u32_e32 v218, vcc, s1, v178
	v_cvt_pk_bf16_f32 v246, v220, v221
	v_cvt_pk_bf16_f32 v248, v248, v249
	v_cvt_pk_bf16_f32 v249, v234, v235
	v_addc_co_u32_e32 v219, vcc, 0, v179, vcc
	global_store_dwordx4 v[218:219], v[246:249], off
	global_load_dwordx4 v[246:249], v[196:197], off offset:2304
	s_nop 0
	global_load_dwordx4 v[250:253], v[210:211], off offset:2304
	s_waitcnt vmcnt(0)
	v_lshlrev_b32_e32 v210, 16, v239
	v_and_b32_e32 v211, 0xffff0000, v239
	v_lshlrev_b32_e32 v196, 16, v238
	v_and_b32_e32 v197, 0xffff0000, v238
	v_pk_fma_f32 v[82:83], v[82:83], v[176:177], v[210:211]
	v_lshlrev_b32_e32 v220, 16, v240
	v_and_b32_e32 v221, 0xffff0000, v240
	v_lshlrev_b32_e32 v234, 16, v241
	v_and_b32_e32 v235, 0xffff0000, v241
	v_pk_fma_f32 v[80:81], v[80:81], v[174:175], v[196:197]
	v_cvt_pk_bf16_f32 v239, v82, v83
	v_pk_fma_f32 v[78:79], v[78:79], v[172:173], v[234:235]
	v_pk_fma_f32 v[76:77], v[76:77], v[164:165], v[220:221]
	v_cvt_pk_bf16_f32 v238, v80, v81
	v_add_co_u32_e32 v196, vcc, s76, v182
	v_lshlrev_b32_e32 v80, 16, v239
	v_and_b32_e32 v81, 0xffff0000, v239
	v_cvt_pk_bf16_f32 v240, v76, v77
	v_cvt_pk_bf16_f32 v241, v78, v79
	v_addc_co_u32_e32 v197, vcc, 0, v183, vcc
	v_pk_mul_f32 v[210:211], v[138:139], v[80:81]
	v_lshlrev_b32_e32 v166, 16, v242
	v_and_b32_e32 v167, 0xffff0000, v242
	v_lshlrev_b32_e32 v242, 16, v243
	v_and_b32_e32 v243, 0xffff0000, v243
	v_lshlrev_b32_e32 v168, 16, v244
	v_and_b32_e32 v169, 0xffff0000, v244
	v_lshlrev_b32_e32 v244, 16, v245
	v_and_b32_e32 v245, 0xffff0000, v245
	global_store_dwordx4 v[196:197], v[238:241], off offset:2048
	v_lshlrev_b32_e32 v82, 16, v238
	v_and_b32_e32 v83, 0xffff0000, v238
	v_cvt_pk_bf16_f32 v239, v210, v211
	v_add_co_u32_e32 v210, vcc, s77, v178
	v_lshlrev_b32_e32 v78, 16, v240
	v_and_b32_e32 v79, 0xffff0000, v240
	v_lshlrev_b32_e32 v76, 16, v241
	v_and_b32_e32 v77, 0xffff0000, v241
	v_pk_mul_f32 v[220:221], v[136:137], v[82:83]
	v_addc_co_u32_e32 v211, vcc, 0, v179, vcc
	v_pk_fma_f32 v[74:75], v[74:75], v[176:177], v[242:243]
	v_pk_fma_f32 v[72:73], v[72:73], v[174:175], v[166:167]
	v_pk_fma_f32 v[166:167], v[70:71], v[172:173], v[244:245]
	v_pk_fma_f32 v[70:71], v[68:69], v[164:165], v[168:169]
	v_pk_mul_f32 v[234:235], v[134:135], v[76:77]
	v_pk_mul_f32 v[240:241], v[132:133], v[78:79]
	v_cvt_pk_bf16_f32 v238, v220, v221
	v_cvt_pk_bf16_f32 v68, v72, v73
	v_cvt_pk_bf16_f32 v69, v74, v75
	v_cvt_pk_bf16_f32 v70, v70, v71
	v_cvt_pk_bf16_f32 v71, v166, v167
	v_add_co_u32_e32 v220, vcc, s0, v182
	v_cvt_pk_bf16_f32 v240, v240, v241
	v_cvt_pk_bf16_f32 v241, v234, v235
	v_addc_co_u32_e32 v221, vcc, 0, v183, vcc
	v_lshlrev_b32_e32 v176, 16, v68
	v_and_b32_e32 v177, 0xffff0000, v68
	v_lshlrev_b32_e32 v174, 16, v69
	v_and_b32_e32 v175, 0xffff0000, v69
	v_lshlrev_b32_e32 v172, 16, v70
	v_and_b32_e32 v173, 0xffff0000, v70
	v_lshlrev_b32_e32 v164, 16, v71
	v_and_b32_e32 v165, 0xffff0000, v71
	s_mov_b32 s0, 0x58000
	global_store_dwordx4 v[210:211], v[238:241], off
	global_store_dwordx4 v[220:221], v[68:71], off offset:2048
	v_pk_mul_f32 v[72:73], v[134:135], v[164:165]
	v_pk_mul_f32 v[74:75], v[132:133], v[172:173]
	v_pk_mul_f32 v[70:71], v[138:139], v[174:175]
	v_pk_mul_f32 v[68:69], v[136:137], v[176:177]
	v_add_co_u32_e32 v132, vcc, s0, v178
	v_cvt_pk_bf16_f32 v68, v68, v69
	v_cvt_pk_bf16_f32 v69, v70, v71
	v_cvt_pk_bf16_f32 v70, v74, v75
	v_cvt_pk_bf16_f32 v71, v72, v73
	v_addc_co_u32_e32 v133, vcc, 0, v179, vcc
	global_store_dwordx4 v[132:133], v[68:71], off
	global_load_dwordx4 v[134:137], v[184:185], off offset:2304
	global_load_dwordx4 v[238:241], v[188:189], off offset:2304
	s_nop 0
	global_load_dwordx4 v[68:71], v[180:181], off offset:528
	global_load_dwordx4 v[72:75], v[180:181], off offset:512
	v_lshlrev_b32_e32 v138, 16, v246
	v_and_b32_e32 v139, 0xffff0000, v246
	v_lshlrev_b32_e32 v166, 16, v247
	v_and_b32_e32 v167, 0xffff0000, v247
	v_lshlrev_b32_e32 v168, 16, v248
	v_and_b32_e32 v169, 0xffff0000, v248
	v_lshlrev_b32_e32 v180, 16, v249
	v_and_b32_e32 v181, 0xffff0000, v249
	v_pk_fma_f32 v[66:67], v[66:67], v[162:163], v[166:167]
	v_pk_fma_f32 v[64:65], v[64:65], v[160:161], v[138:139]
	v_pk_fma_f32 v[62:63], v[62:63], v[158:159], v[180:181]
	v_pk_fma_f32 v[60:61], v[60:61], v[156:157], v[168:169]
	v_cvt_pk_bf16_f32 v242, v64, v65
	v_cvt_pk_bf16_f32 v243, v66, v67
	v_cvt_pk_bf16_f32 v244, v60, v61
	v_cvt_pk_bf16_f32 v245, v62, v63
	v_lshlrev_b32_e32 v66, 16, v242
	v_and_b32_e32 v67, 0xffff0000, v242
	v_lshlrev_b32_e32 v64, 16, v243
	v_and_b32_e32 v65, 0xffff0000, v243
	v_lshlrev_b32_e32 v62, 16, v244
	v_and_b32_e32 v63, 0xffff0000, v244
	v_lshlrev_b32_e32 v60, 16, v245
	v_and_b32_e32 v61, 0xffff0000, v245
	v_lshlrev_b32_e32 v184, 16, v250
	v_and_b32_e32 v185, 0xffff0000, v250
	v_lshlrev_b32_e32 v188, 16, v251
	v_and_b32_e32 v189, 0xffff0000, v251
	v_lshlrev_b32_e32 v234, 16, v252
	v_and_b32_e32 v235, 0xffff0000, v252
	v_lshlrev_b32_e32 v246, 16, v253
	v_and_b32_e32 v247, 0xffff0000, v253
	global_store_dwordx4 v[182:183], v[242:245], off offset:2304
	v_pk_fma_f32 v[58:59], v[58:59], v[162:163], v[188:189]
	v_pk_fma_f32 v[56:57], v[56:57], v[160:161], v[184:185]
	v_pk_fma_f32 v[54:55], v[54:55], v[158:159], v[246:247]
	v_pk_fma_f32 v[52:53], v[52:53], v[156:157], v[234:235]
	s_waitcnt vmcnt(0)
	v_lshlrev_b32_e32 v188, 16, v240
	v_pk_mul_f32 v[168:169], v[70:71], v[60:61]
	v_pk_mul_f32 v[138:139], v[74:75], v[64:65]
	v_pk_mul_f32 v[166:167], v[72:73], v[66:67]
	v_pk_mul_f32 v[182:183], v[68:69], v[62:63]
	v_cvt_pk_bf16_f32 v180, v166, v167
	v_cvt_pk_bf16_f32 v181, v138, v139
	v_cvt_pk_bf16_f32 v182, v182, v183
	v_cvt_pk_bf16_f32 v183, v168, v169
	global_store_dwordx4 v[178:179], v[180:183], off offset:256
	v_cvt_pk_bf16_f32 v178, v56, v57
	v_cvt_pk_bf16_f32 v179, v58, v59
	v_cvt_pk_bf16_f32 v180, v52, v53
	v_cvt_pk_bf16_f32 v181, v54, v55
	v_lshlrev_b32_e32 v58, 16, v178
	v_and_b32_e32 v59, 0xffff0000, v178
	v_lshlrev_b32_e32 v56, 16, v179
	v_and_b32_e32 v57, 0xffff0000, v179
	v_lshlrev_b32_e32 v54, 16, v180
	v_and_b32_e32 v55, 0xffff0000, v180
	v_lshlrev_b32_e32 v52, 16, v181
	v_and_b32_e32 v53, 0xffff0000, v181
	global_store_dwordx4 v[186:187], v[178:181], off offset:2304
	v_pk_mul_f32 v[138:139], v[74:75], v[56:57]
	v_pk_mul_f32 v[166:167], v[72:73], v[58:59]
	v_pk_mul_f32 v[168:169], v[70:71], v[52:53]
	v_pk_mul_f32 v[180:181], v[68:69], v[54:55]
	v_cvt_pk_bf16_f32 v178, v166, v167
	v_cvt_pk_bf16_f32 v179, v138, v139
	v_cvt_pk_bf16_f32 v180, v180, v181
	v_cvt_pk_bf16_f32 v181, v168, v169
	v_lshlrev_b32_e32 v138, 16, v134
	v_and_b32_e32 v139, 0xffff0000, v134
	v_lshlrev_b32_e32 v134, 16, v135
	v_and_b32_e32 v135, 0xffff0000, v135
	v_lshlrev_b32_e32 v166, 16, v136
	v_and_b32_e32 v167, 0xffff0000, v136
	v_lshlrev_b32_e32 v136, 16, v137
	v_and_b32_e32 v137, 0xffff0000, v137
	global_store_dwordx4 v[190:191], v[178:181], off offset:256
	v_pk_fma_f32 v[50:51], v[50:51], v[162:163], v[134:135]
	v_pk_fma_f32 v[48:49], v[48:49], v[160:161], v[138:139]
	v_pk_fma_f32 v[46:47], v[46:47], v[158:159], v[136:137]
	v_pk_fma_f32 v[44:45], v[44:45], v[156:157], v[166:167]
	global_load_dwordx4 v[178:181], v[192:193], off offset:2304
	global_load_dwordx4 v[182:185], v[194:195], off offset:2304
	v_cvt_pk_bf16_f32 v134, v48, v49
	v_cvt_pk_bf16_f32 v135, v50, v51
	v_cvt_pk_bf16_f32 v136, v44, v45
	v_cvt_pk_bf16_f32 v137, v46, v47
	v_lshlrev_b32_e32 v50, 16, v134
	v_and_b32_e32 v51, 0xffff0000, v134
	v_lshlrev_b32_e32 v48, 16, v135
	v_and_b32_e32 v49, 0xffff0000, v135
	v_lshlrev_b32_e32 v46, 16, v136
	v_and_b32_e32 v47, 0xffff0000, v136
	v_lshlrev_b32_e32 v44, 16, v137
	v_and_b32_e32 v45, 0xffff0000, v137
	v_lshlrev_b32_e32 v168, 16, v238
	v_and_b32_e32 v169, 0xffff0000, v238
	v_lshlrev_b32_e32 v186, 16, v239
	v_and_b32_e32 v187, 0xffff0000, v239
	v_and_b32_e32 v189, 0xffff0000, v240
	v_lshlrev_b32_e32 v190, 16, v241
	v_and_b32_e32 v191, 0xffff0000, v241
	global_store_dwordx4 v[198:199], v[134:137], off offset:2304
	v_pk_mul_f32 v[138:139], v[70:71], v[44:45]
	v_pk_mul_f32 v[166:167], v[68:69], v[46:47]
	v_pk_mul_f32 v[136:137], v[74:75], v[48:49]
	v_pk_mul_f32 v[134:135], v[72:73], v[50:51]
	v_pk_fma_f32 v[42:43], v[42:43], v[162:163], v[186:187]
	v_cvt_pk_bf16_f32 v134, v134, v135
	v_cvt_pk_bf16_f32 v135, v136, v137
	v_cvt_pk_bf16_f32 v136, v166, v167
	v_cvt_pk_bf16_f32 v137, v138, v139
	v_pk_fma_f32 v[40:41], v[40:41], v[160:161], v[168:169]
	v_pk_fma_f32 v[38:39], v[38:39], v[158:159], v[190:191]
	v_pk_fma_f32 v[36:37], v[36:37], v[156:157], v[188:189]
	global_store_dwordx4 v[200:201], v[134:137], off offset:256
	v_mul_f32_e32 v67, v67, v67
	v_mul_f32_e32 v65, v65, v65
	v_cvt_pk_bf16_f32 v134, v40, v41
	v_cvt_pk_bf16_f32 v135, v42, v43
	v_cvt_pk_bf16_f32 v136, v36, v37
	v_cvt_pk_bf16_f32 v137, v38, v39
	v_lshlrev_b32_e32 v42, 16, v134
	v_and_b32_e32 v43, 0xffff0000, v134
	v_lshlrev_b32_e32 v40, 16, v135
	v_and_b32_e32 v41, 0xffff0000, v135
	v_lshlrev_b32_e32 v38, 16, v136
	v_and_b32_e32 v39, 0xffff0000, v136
	v_lshlrev_b32_e32 v36, 16, v137
	v_and_b32_e32 v37, 0xffff0000, v137
	global_store_dwordx4 v[202:203], v[134:137], off offset:2304
	v_pk_mul_f32 v[138:139], v[70:71], v[36:37]
	v_pk_mul_f32 v[166:167], v[68:69], v[38:39]
	v_pk_mul_f32 v[136:137], v[74:75], v[40:41]
	v_pk_mul_f32 v[134:135], v[72:73], v[42:43]
	v_fmac_f32_e32 v67, v66, v66
	v_cvt_pk_bf16_f32 v134, v134, v135
	v_cvt_pk_bf16_f32 v135, v136, v137
	v_cvt_pk_bf16_f32 v136, v166, v167
	v_cvt_pk_bf16_f32 v137, v138, v139
	global_store_dwordx4 v[204:205], v[134:137], off offset:256
	global_load_dwordx4 v[134:137], v[206:207], off offset:2304
	s_nop 0
	global_load_dwordx4 v[186:189], v[208:209], off offset:2304
	v_fmac_f32_e32 v65, v64, v64
	v_mul_f32_e32 v63, v63, v63
	v_mul_f32_e32 v61, v61, v61
	v_add_f32_e32 v64, v67, v65
	v_fmac_f32_e32 v63, v62, v62
	v_fmac_f32_e32 v61, v60, v60
	v_add_f32_e32 v60, v63, v61
	s_waitcnt vmcnt(0)
	v_lshlrev_b32_e32 v138, 16, v178
	v_and_b32_e32 v139, 0xffff0000, v178
	v_lshlrev_b32_e32 v166, 16, v179
	v_and_b32_e32 v167, 0xffff0000, v179
	v_lshlrev_b32_e32 v168, 16, v180
	v_and_b32_e32 v169, 0xffff0000, v180
	v_lshlrev_b32_e32 v178, 16, v181
	v_and_b32_e32 v179, 0xffff0000, v181
	v_pk_fma_f32 v[34:35], v[34:35], v[162:163], v[166:167]
	v_pk_fma_f32 v[32:33], v[32:33], v[160:161], v[138:139]
	v_pk_fma_f32 v[30:31], v[30:31], v[158:159], v[178:179]
	v_pk_fma_f32 v[28:29], v[28:29], v[156:157], v[168:169]
	v_cvt_pk_bf16_f32 v178, v32, v33
	v_cvt_pk_bf16_f32 v179, v34, v35
	v_cvt_pk_bf16_f32 v180, v28, v29
	v_cvt_pk_bf16_f32 v181, v30, v31
	v_lshlrev_b32_e32 v34, 16, v178
	v_and_b32_e32 v35, 0xffff0000, v178
	v_lshlrev_b32_e32 v32, 16, v179
	v_and_b32_e32 v33, 0xffff0000, v179
	v_lshlrev_b32_e32 v30, 16, v180
	v_and_b32_e32 v31, 0xffff0000, v180
	v_lshlrev_b32_e32 v28, 16, v181
	v_and_b32_e32 v29, 0xffff0000, v181
	v_lshlrev_b32_e32 v190, 16, v182
	v_and_b32_e32 v191, 0xffff0000, v182
	v_lshlrev_b32_e32 v182, 16, v183
	v_and_b32_e32 v183, 0xffff0000, v183
	global_store_dwordx4 v[212:213], v[178:181], off offset:2304
	v_pk_mul_f32 v[138:139], v[74:75], v[32:33]
	v_pk_mul_f32 v[166:167], v[72:73], v[34:35]
	v_pk_mul_f32 v[168:169], v[70:71], v[28:29]
	v_pk_mul_f32 v[180:181], v[68:69], v[30:31]
	v_cvt_pk_bf16_f32 v178, v166, v167
	v_cvt_pk_bf16_f32 v179, v138, v139
	v_cvt_pk_bf16_f32 v180, v180, v181
	v_cvt_pk_bf16_f32 v181, v168, v169
	v_pk_fma_f32 v[24:25], v[24:25], v[162:163], v[182:183]
	v_pk_fma_f32 v[22:23], v[22:23], v[160:161], v[190:191]
	v_lshlrev_b32_e32 v192, 16, v184
	v_and_b32_e32 v193, 0xffff0000, v184
	v_lshlrev_b32_e32 v184, 16, v185
	v_and_b32_e32 v185, 0xffff0000, v185
	global_store_dwordx4 v[214:215], v[178:181], off offset:256
	v_pk_fma_f32 v[20:21], v[20:21], v[158:159], v[184:185]
	v_pk_fma_f32 v[18:19], v[18:19], v[156:157], v[192:193]
	v_cvt_pk_bf16_f32 v178, v22, v23
	v_cvt_pk_bf16_f32 v179, v24, v25
	v_lshlrev_b32_e32 v24, 16, v178
	v_and_b32_e32 v25, 0xffff0000, v178
	v_lshlrev_b32_e32 v22, 16, v179
	v_and_b32_e32 v23, 0xffff0000, v179
	v_cvt_pk_bf16_f32 v180, v18, v19
	v_cvt_pk_bf16_f32 v181, v20, v21
	v_pk_mul_f32 v[138:139], v[74:75], v[22:23]
	v_pk_mul_f32 v[166:167], v[72:73], v[24:25]
	global_store_dwordx4 v[216:217], v[178:181], off offset:2304
	v_lshlrev_b32_e32 v20, 16, v180
	v_and_b32_e32 v21, 0xffff0000, v180
	v_cvt_pk_bf16_f32 v178, v166, v167
	v_cvt_pk_bf16_f32 v179, v138, v139
	v_lshlrev_b32_e32 v138, 16, v134
	v_and_b32_e32 v139, 0xffff0000, v134
	v_lshlrev_b32_e32 v134, 16, v135
	v_and_b32_e32 v135, 0xffff0000, v135
	v_lshlrev_b32_e32 v166, 16, v136
	v_and_b32_e32 v167, 0xffff0000, v136
	v_lshlrev_b32_e32 v136, 16, v137
	v_and_b32_e32 v137, 0xffff0000, v137
	v_lshlrev_b32_e32 v18, 16, v181
	v_and_b32_e32 v19, 0xffff0000, v181
	v_pk_fma_f32 v[16:17], v[16:17], v[162:163], v[134:135]
	v_pk_fma_f32 v[14:15], v[14:15], v[160:161], v[138:139]
	v_pk_fma_f32 v[12:13], v[12:13], v[158:159], v[136:137]
	v_pk_fma_f32 v[10:11], v[10:11], v[156:157], v[166:167]
	v_pk_mul_f32 v[168:169], v[70:71], v[18:19]
	v_pk_mul_f32 v[180:181], v[68:69], v[20:21]
	v_cvt_pk_bf16_f32 v134, v14, v15
	v_cvt_pk_bf16_f32 v135, v16, v17
	v_cvt_pk_bf16_f32 v136, v10, v11
	v_cvt_pk_bf16_f32 v137, v12, v13
	v_cvt_pk_bf16_f32 v180, v180, v181
	v_cvt_pk_bf16_f32 v181, v168, v169
	v_lshlrev_b32_e32 v16, 16, v134
	v_and_b32_e32 v17, 0xffff0000, v134
	v_lshlrev_b32_e32 v14, 16, v135
	v_and_b32_e32 v15, 0xffff0000, v135
	v_lshlrev_b32_e32 v12, 16, v136
	v_and_b32_e32 v13, 0xffff0000, v136
	v_lshlrev_b32_e32 v10, 16, v137
	v_and_b32_e32 v11, 0xffff0000, v137
	global_store_dwordx4 v[218:219], v[178:181], off offset:256
	v_lshlrev_b32_e32 v168, 16, v186
	v_and_b32_e32 v169, 0xffff0000, v186
	v_lshlrev_b32_e32 v178, 16, v187
	v_and_b32_e32 v179, 0xffff0000, v187
	v_lshlrev_b32_e32 v180, 16, v188
	v_and_b32_e32 v181, 0xffff0000, v188
	v_lshlrev_b32_e32 v182, 16, v189
	v_and_b32_e32 v183, 0xffff0000, v189
	global_store_dwordx4 v[196:197], v[134:137], off offset:2304
	v_pk_mul_f32 v[138:139], v[70:71], v[10:11]
	v_pk_mul_f32 v[166:167], v[68:69], v[12:13]
	v_pk_mul_f32 v[136:137], v[74:75], v[14:15]
	v_pk_mul_f32 v[134:135], v[72:73], v[16:17]
	v_pk_fma_f32 v[8:9], v[8:9], v[162:163], v[178:179]
	v_cvt_pk_bf16_f32 v134, v134, v135
	v_cvt_pk_bf16_f32 v135, v136, v137
	v_cvt_pk_bf16_f32 v136, v166, v167
	v_cvt_pk_bf16_f32 v137, v138, v139
	v_pk_fma_f32 v[6:7], v[6:7], v[160:161], v[168:169]
	v_pk_fma_f32 v[4:5], v[4:5], v[158:159], v[182:183]
	v_pk_fma_f32 v[2:3], v[2:3], v[156:157], v[180:181]
	global_store_dwordx4 v[210:211], v[134:137], off offset:256
	s_nop 1
	v_cvt_pk_bf16_f32 v134, v6, v7
	v_cvt_pk_bf16_f32 v135, v8, v9
	v_cvt_pk_bf16_f32 v136, v2, v3
	v_cvt_pk_bf16_f32 v137, v4, v5
	v_lshlrev_b32_e32 v8, 16, v134
	v_and_b32_e32 v9, 0xffff0000, v134
	v_lshlrev_b32_e32 v6, 16, v135
	v_and_b32_e32 v7, 0xffff0000, v135
	v_lshlrev_b32_e32 v4, 16, v136
	v_and_b32_e32 v5, 0xffff0000, v136
	v_lshlrev_b32_e32 v2, 16, v137
	v_and_b32_e32 v3, 0xffff0000, v137
	global_store_dwordx4 v[220:221], v[134:137], off offset:2304
	v_pk_mul_f32 v[74:75], v[74:75], v[6:7]
	v_pk_mul_f32 v[72:73], v[72:73], v[8:9]
	v_pk_mul_f32 v[134:135], v[70:71], v[2:3]
	v_pk_mul_f32 v[70:71], v[68:69], v[4:5]
	v_cvt_pk_bf16_f32 v68, v72, v73
	v_cvt_pk_bf16_f32 v69, v74, v75
	v_cvt_pk_bf16_f32 v70, v70, v71
	v_cvt_pk_bf16_f32 v71, v134, v135
	global_store_dwordx4 v[132:133], v[68:71], off offset:256
	v_xor_b32_e32 v72, 32, v227
	v_mul_f32_e32 v73, v129, v129
	v_and_b32_e32 v71, 64, v227
	v_xor_b32_e32 v70, 16, v227
	v_add_u32_e32 v71, 64, v71
	v_cmp_lt_i32_e32 vcc, v70, v71
	v_fmac_f32_e32 v73, v128, v128
	v_mul_f32_e32 v74, v125, v125
	v_cndmask_b32_e32 v70, v227, v70, vcc
	v_cmp_lt_i32_e32 vcc, v72, v71
	v_fmac_f32_e32 v74, v124, v124
	v_lshlrev_b32_e32 v70, 2, v70
	v_cndmask_b32_e32 v71, v227, v72, vcc
	v_mul_f32_e32 v72, v131, v131
	v_fmac_f32_e32 v72, v130, v130
	v_add_f32_e32 v72, v72, v73
	v_mul_f32_e32 v73, v127, v127
	v_fmac_f32_e32 v73, v126, v126
	v_add_f32_e32 v73, v73, v74
	v_add_f32_e32 v72, v72, v73
	v_add_f32_e32 v64, v72, v64
	v_add_f32_e32 v60, v60, v64
	ds_bpermute_b32 v61, v70, v60
	v_lshlrev_b32_e32 v71, 2, v71
	v_lshl_add_u64 v[68:69], v[150:151], 0, s[24:25]
	s_waitcnt lgkmcnt(0)
	v_add_f32_e32 v60, v60, v61
	ds_bpermute_b32 v61, v71, v60
	s_and_saveexec_b64 s[18:19], s[40:41]
	s_cbranch_execz .LBB0_364
	s_waitcnt lgkmcnt(0)
	v_add_f32_e32 v60, v60, v61
	global_atomic_add_f32 v[68:69], v60, off

.LBB0_395:
	s_add_u32 s26, s24, 0x100
	s_addc_u32 s27, s25, 0
	s_add_i32 s0, 0, 0x10000
	v_add_u32_e32 v160, s0, v233
	ds_read_b128 v[100:103], v160
	ds_read_b128 v[104:107], v160 offset:1024
	ds_read_b128 v[156:159], v160 offset:2048
	ds_read_b128 v[160:163], v160 offset:3072
	s_cmp_eq_u32 s52, 40
	s_cselect_b32 s31, s43, s27
	s_cselect_b32 s30, s42, s26
	s_cselect_b32 s29, s45, s19
	s_cselect_b32 s28, s44, s18
	v_lshl_add_u64 v[164:165], s[24:25], 0, v[152:153]
	s_add_i32 m0, s69, 0xc000
	ds_read_b128 v[172:175], v235
	ds_read_b128 v[176:179], v235 offset:1024
	ds_read_b128 v[180:183], v235 offset:2048
	ds_read_b128 v[184:187], v235 offset:3072
	ds_read_b128 v[188:191], v235 offset:4096
	ds_read_b128 v[192:195], v235 offset:5120
	ds_read_b128 v[196:199], v235 offset:6144
	ds_read_b128 v[200:203], v235 offset:7168
	global_load_lds_dwordx4 v[164:165], off
	v_lshl_add_u64 v[164:165], s[24:25], 0, v[154:155]
	s_add_i32 m0, s69, 0xe000
	s_nop 0
	global_load_lds_dwordx4 v[164:165], off
	s_waitcnt vmcnt(10) lgkmcnt(8)
	s_setprio 1
	s_barrier
	s_waitcnt lgkmcnt(0)
	v_mfma_f32_16x16x32_bf16 v[136:139], v[100:103], v[172:175], v[136:139]
	v_mfma_f32_16x16x32_bf16 v[132:135], v[156:159], v[172:175], v[132:135]
	v_mfma_f32_16x16x32_bf16 v[128:131], v[100:103], v[180:183], v[128:131]
	v_mfma_f32_16x16x32_bf16 v[124:127], v[156:159], v[180:183], v[124:127]
	v_mfma_f32_16x16x32_bf16 v[120:123], v[100:103], v[188:191], v[120:123]
	v_mfma_f32_16x16x32_bf16 v[116:119], v[156:159], v[188:191], v[116:119]
	v_mfma_f32_16x16x32_bf16 v[112:115], v[100:103], v[196:199], v[112:115]
	v_mfma_f32_16x16x32_bf16 v[108:111], v[156:159], v[196:199], v[108:111]
	v_mfma_f32_16x16x32_bf16 v[136:139], v[104:107], v[176:179], v[136:139]
	v_mfma_f32_16x16x32_bf16 v[132:135], v[160:163], v[176:179], v[132:135]
	v_mfma_f32_16x16x32_bf16 v[128:131], v[104:107], v[184:187], v[128:131]
	v_mfma_f32_16x16x32_bf16 v[124:127], v[160:163], v[184:187], v[124:127]
	v_mfma_f32_16x16x32_bf16 v[120:123], v[104:107], v[192:195], v[120:123]
	v_mfma_f32_16x16x32_bf16 v[116:119], v[160:163], v[192:195], v[116:119]
	v_mfma_f32_16x16x32_bf16 v[112:115], v[104:107], v[200:203], v[112:115]
	v_mfma_f32_16x16x32_bf16 v[108:111], v[160:163], v[200:203], v[108:111]
	s_barrier
	s_setprio 0
	s_add_i32 s24, 0, 0x14000
	v_add_u32_e32 v164, s24, v233
	s_add_i32 s0, s0, s68
	ds_read_b128 v[204:207], v164
	ds_read_b128 v[208:211], v164 offset:1024
	ds_read_b128 v[212:215], v164 offset:2048
	ds_read_b128 v[216:219], v164 offset:3072
	v_lshl_add_u64 v[164:165], s[28:29], 0, v[26:27]
	s_mov_b32 m0, s0
	v_lshl_add_u64 v[220:221], s[28:29], 0, v[140:141]
	global_load_lds_dwordx4 v[164:165], off
	s_add_i32 m0, s0, 0x2000
	s_nop 0
	global_load_lds_dwordx4 v[220:221], off
	s_waitcnt vmcnt(10)
	s_setprio 1
	s_barrier
	s_waitcnt lgkmcnt(0)
	v_mfma_f32_16x16x32_bf16 v[64:67], v[204:207], v[172:175], v[64:67]
	v_mfma_f32_16x16x32_bf16 v[60:63], v[212:215], v[172:175], v[60:63]
	v_mfma_f32_16x16x32_bf16 v[56:59], v[204:207], v[180:183], v[56:59]
	v_mfma_f32_16x16x32_bf16 v[52:55], v[212:215], v[180:183], v[52:55]
	v_mfma_f32_16x16x32_bf16 v[48:51], v[204:207], v[188:191], v[48:51]
	v_mfma_f32_16x16x32_bf16 v[44:47], v[212:215], v[188:191], v[44:47]
	v_mfma_f32_16x16x32_bf16 v[40:43], v[204:207], v[196:199], v[40:43]
	v_mfma_f32_16x16x32_bf16 v[36:39], v[212:215], v[196:199], v[36:39]
	v_mfma_f32_16x16x32_bf16 v[64:67], v[208:211], v[176:179], v[64:67]
	v_mfma_f32_16x16x32_bf16 v[60:63], v[216:219], v[176:179], v[60:63]
	v_mfma_f32_16x16x32_bf16 v[56:59], v[208:211], v[184:187], v[56:59]
	v_mfma_f32_16x16x32_bf16 v[52:55], v[216:219], v[184:187], v[52:55]
	v_mfma_f32_16x16x32_bf16 v[48:51], v[208:211], v[192:195], v[48:51]
	v_mfma_f32_16x16x32_bf16 v[44:47], v[216:219], v[192:195], v[44:47]
	v_mfma_f32_16x16x32_bf16 v[40:43], v[208:211], v[200:203], v[40:43]
	v_mfma_f32_16x16x32_bf16 v[36:39], v[216:219], v[200:203], v[36:39]
	s_barrier
	s_setprio 0
	s_mov_b32 m0, s69
	v_lshl_add_u64 v[222:223], s[30:31], 0, v[144:145]
	ds_read_b128 v[172:175], v235 offset:16384
	ds_read_b128 v[176:179], v235 offset:17408
	ds_read_b128 v[180:183], v235 offset:18432
	ds_read_b128 v[184:187], v235 offset:19456
	ds_read_b128 v[188:191], v235 offset:20480
	ds_read_b128 v[192:195], v235 offset:21504
	ds_read_b128 v[196:199], v235 offset:22528
	ds_read_b128 v[200:203], v235 offset:23552
	global_load_lds_dwordx4 v[222:223], off
	v_lshl_add_u64 v[224:225], s[30:31], 0, v[142:143]
	s_mov_b32 m0, s72
	s_nop 0
	global_load_lds_dwordx4 v[224:225], off
	s_setprio 1
	s_barrier
	s_waitcnt lgkmcnt(0)
	v_mfma_f32_16x16x32_bf16 v[96:99], v[100:103], v[172:175], v[96:99]
	v_mfma_f32_16x16x32_bf16 v[92:95], v[156:159], v[172:175], v[92:95]
	v_mfma_f32_16x16x32_bf16 v[88:91], v[100:103], v[180:183], v[88:91]
	v_mfma_f32_16x16x32_bf16 v[84:87], v[156:159], v[180:183], v[84:87]
	v_mfma_f32_16x16x32_bf16 v[80:83], v[100:103], v[188:191], v[80:83]
	v_mfma_f32_16x16x32_bf16 v[76:79], v[156:159], v[188:191], v[76:79]
	v_mfma_f32_16x16x32_bf16 v[72:75], v[100:103], v[196:199], v[72:75]
	v_mfma_f32_16x16x32_bf16 v[68:71], v[156:159], v[196:199], v[68:71]
	v_mfma_f32_16x16x32_bf16 v[96:99], v[104:107], v[176:179], v[96:99]
	v_mfma_f32_16x16x32_bf16 v[92:95], v[160:163], v[176:179], v[92:95]
	v_mfma_f32_16x16x32_bf16 v[88:91], v[104:107], v[184:187], v[88:91]
	v_mfma_f32_16x16x32_bf16 v[84:87], v[160:163], v[184:187], v[84:87]
	v_mfma_f32_16x16x32_bf16 v[80:83], v[104:107], v[192:195], v[80:83]
	v_mfma_f32_16x16x32_bf16 v[76:79], v[160:163], v[192:195], v[76:79]
	v_mfma_f32_16x16x32_bf16 v[72:75], v[104:107], v[200:203], v[72:75]
	v_mfma_f32_16x16x32_bf16 v[68:71], v[160:163], v[200:203], v[68:71]
	s_barrier
	s_setprio 0
	s_add_u32 s0, s28, 0xb0000
	s_addc_u32 s1, s29, 0
	s_add_i32 s24, s24, s68
	v_lshl_add_u64 v[100:101], s[0:1], 0, v[26:27]
	s_mov_b32 m0, s24
	s_nop 0
	global_load_lds_dwordx4 v[100:101], off
	v_lshl_add_u64 v[100:101], s[0:1], 0, v[140:141]
	s_add_i32 m0, s24, 0x2000
	s_nop 0
	global_load_lds_dwordx4 v[100:101], off
	s_waitcnt vmcnt(10)
	s_setprio 1
	s_barrier
	v_mfma_f32_16x16x32_bf16 v[32:35], v[204:207], v[172:175], v[32:35]
	v_mfma_f32_16x16x32_bf16 v[28:31], v[212:215], v[172:175], v[28:31]
	v_mfma_f32_16x16x32_bf16 v[22:25], v[204:207], v[180:183], v[22:25]
	v_mfma_f32_16x16x32_bf16 v[18:21], v[212:215], v[180:183], v[18:21]
	v_mfma_f32_16x16x32_bf16 v[14:17], v[204:207], v[188:191], v[14:17]
	v_mfma_f32_16x16x32_bf16 v[10:13], v[212:215], v[188:191], v[10:13]
	v_mfma_f32_16x16x32_bf16 v[6:9], v[204:207], v[196:199], v[6:9]
	v_mfma_f32_16x16x32_bf16 v[2:5], v[212:215], v[196:199], v[2:5]
	v_mfma_f32_16x16x32_bf16 v[32:35], v[208:211], v[176:179], v[32:35]
	v_mfma_f32_16x16x32_bf16 v[28:31], v[216:219], v[176:179], v[28:31]
	v_mfma_f32_16x16x32_bf16 v[22:25], v[208:211], v[184:187], v[22:25]
	v_mfma_f32_16x16x32_bf16 v[18:21], v[216:219], v[184:187], v[18:21]
	v_mfma_f32_16x16x32_bf16 v[14:17], v[208:211], v[192:195], v[14:17]
	v_mfma_f32_16x16x32_bf16 v[10:13], v[216:219], v[192:195], v[10:13]
	v_mfma_f32_16x16x32_bf16 v[6:9], v[208:211], v[200:203], v[6:9]
	v_mfma_f32_16x16x32_bf16 v[2:5], v[216:219], v[200:203], v[2:5]
	s_barrier
	s_setprio 0
	s_add_i32 s24, 0, 0x18000
	v_add_u32_e32 v160, s24, v233
	ds_read_b128 v[100:103], v160
	ds_read_b128 v[104:107], v160 offset:1024
	ds_read_b128 v[156:159], v160 offset:2048
	ds_read_b128 v[160:163], v160 offset:3072
	s_add_u32 s0, s30, 0xb0000
	s_addc_u32 s1, s31, 0
	s_mov_b32 m0, s73
	v_lshl_add_u64 v[204:205], s[0:1], 0, v[144:145]
	ds_read_b128 v[172:175], v235 offset:32768
	ds_read_b128 v[176:179], v235 offset:33792
	ds_read_b128 v[180:183], v235 offset:34816
	ds_read_b128 v[184:187], v235 offset:35840
	ds_read_b128 v[188:191], v235 offset:36864
	ds_read_b128 v[192:195], v235 offset:37888
	ds_read_b128 v[196:199], v235 offset:38912
	ds_read_b128 v[200:203], v235 offset:39936
	global_load_lds_dwordx4 v[204:205], off
	v_lshl_add_u64 v[204:205], s[0:1], 0, v[142:143]
	s_mov_b32 m0, s81
	s_nop 0
	global_load_lds_dwordx4 v[204:205], off
	s_waitcnt vmcnt(10) lgkmcnt(8)
	s_setprio 1
	s_barrier
	s_waitcnt lgkmcnt(0)
	v_mfma_f32_16x16x32_bf16 v[136:139], v[100:103], v[172:175], v[136:139]
	v_mfma_f32_16x16x32_bf16 v[132:135], v[156:159], v[172:175], v[132:135]
	v_mfma_f32_16x16x32_bf16 v[128:131], v[100:103], v[180:183], v[128:131]
	v_mfma_f32_16x16x32_bf16 v[124:127], v[156:159], v[180:183], v[124:127]
	v_mfma_f32_16x16x32_bf16 v[120:123], v[100:103], v[188:191], v[120:123]
	v_mfma_f32_16x16x32_bf16 v[116:119], v[156:159], v[188:191], v[116:119]
	v_mfma_f32_16x16x32_bf16 v[112:115], v[100:103], v[196:199], v[112:115]
	v_mfma_f32_16x16x32_bf16 v[108:111], v[156:159], v[196:199], v[108:111]
	v_mfma_f32_16x16x32_bf16 v[136:139], v[104:107], v[176:179], v[136:139]
	v_mfma_f32_16x16x32_bf16 v[132:135], v[160:163], v[176:179], v[132:135]
	v_mfma_f32_16x16x32_bf16 v[128:131], v[104:107], v[184:187], v[128:131]
	v_mfma_f32_16x16x32_bf16 v[124:127], v[160:163], v[184:187], v[124:127]
	v_mfma_f32_16x16x32_bf16 v[120:123], v[104:107], v[192:195], v[120:123]
	v_mfma_f32_16x16x32_bf16 v[116:119], v[160:163], v[192:195], v[116:119]
	v_mfma_f32_16x16x32_bf16 v[112:115], v[104:107], v[200:203], v[112:115]
	v_mfma_f32_16x16x32_bf16 v[108:111], v[160:163], v[200:203], v[108:111]
	s_barrier
	s_setprio 0
	s_add_i32 s25, 0, 0x1c000
	s_add_i32 s0, s24, s68
	v_add_u32_e32 v166, s25, v233
	v_lshl_add_u64 v[164:165], v[164:165], 0, s[12:13]
	s_mov_b32 m0, s0
	ds_read_b128 v[204:207], v166
	ds_read_b128 v[208:211], v166 offset:1024
	ds_read_b128 v[212:215], v166 offset:2048
	ds_read_b128 v[216:219], v166 offset:3072
	global_load_lds_dwordx4 v[164:165], off
	v_lshl_add_u64 v[164:165], v[220:221], 0, s[12:13]
	s_add_i32 m0, s0, 0x2000
	s_nop 0
	global_load_lds_dwordx4 v[164:165], off
	s_waitcnt vmcnt(10)
	s_setprio 1
	s_barrier
	s_waitcnt lgkmcnt(0)
	v_mfma_f32_16x16x32_bf16 v[64:67], v[204:207], v[172:175], v[64:67]
	v_mfma_f32_16x16x32_bf16 v[60:63], v[212:215], v[172:175], v[60:63]
	v_mfma_f32_16x16x32_bf16 v[56:59], v[204:207], v[180:183], v[56:59]
	v_mfma_f32_16x16x32_bf16 v[52:55], v[212:215], v[180:183], v[52:55]
	v_mfma_f32_16x16x32_bf16 v[48:51], v[204:207], v[188:191], v[48:51]
	v_mfma_f32_16x16x32_bf16 v[44:47], v[212:215], v[188:191], v[44:47]
	v_mfma_f32_16x16x32_bf16 v[40:43], v[204:207], v[196:199], v[40:43]
	v_mfma_f32_16x16x32_bf16 v[36:39], v[212:215], v[196:199], v[36:39]
	v_mfma_f32_16x16x32_bf16 v[64:67], v[208:211], v[176:179], v[64:67]
	v_mfma_f32_16x16x32_bf16 v[60:63], v[216:219], v[176:179], v[60:63]
	v_mfma_f32_16x16x32_bf16 v[56:59], v[208:211], v[184:187], v[56:59]
	v_mfma_f32_16x16x32_bf16 v[52:55], v[216:219], v[184:187], v[52:55]
	v_mfma_f32_16x16x32_bf16 v[48:51], v[208:211], v[192:195], v[48:51]
	v_mfma_f32_16x16x32_bf16 v[44:47], v[216:219], v[192:195], v[44:47]
	v_mfma_f32_16x16x32_bf16 v[40:43], v[208:211], v[200:203], v[40:43]
	v_mfma_f32_16x16x32_bf16 v[36:39], v[216:219], v[200:203], v[36:39]
	s_barrier
	s_setprio 0
	s_mov_b32 m0, s21
	v_lshl_add_u64 v[164:165], v[222:223], 0, s[12:13]
	ds_read_b128 v[172:175], v235 offset:49152
	ds_read_b128 v[176:179], v235 offset:50176
	ds_read_b128 v[180:183], v235 offset:51200
	ds_read_b128 v[184:187], v235 offset:52224
	ds_read_b128 v[188:191], v235 offset:53248
	ds_read_b128 v[192:195], v235 offset:54272
	ds_read_b128 v[196:199], v235 offset:55296
	ds_read_b128 v[200:203], v235 offset:56320
	global_load_lds_dwordx4 v[164:165], off
	v_lshl_add_u64 v[164:165], v[224:225], 0, s[12:13]
	s_mov_b32 m0, s48
	s_nop 0
	global_load_lds_dwordx4 v[164:165], off
	s_setprio 1
	s_barrier
	s_waitcnt lgkmcnt(0)
	v_mfma_f32_16x16x32_bf16 v[96:99], v[100:103], v[172:175], v[96:99]
	v_mfma_f32_16x16x32_bf16 v[92:95], v[156:159], v[172:175], v[92:95]
	v_mfma_f32_16x16x32_bf16 v[88:91], v[100:103], v[180:183], v[88:91]
	v_mfma_f32_16x16x32_bf16 v[84:87], v[156:159], v[180:183], v[84:87]
	v_mfma_f32_16x16x32_bf16 v[80:83], v[100:103], v[188:191], v[80:83]
	v_mfma_f32_16x16x32_bf16 v[76:79], v[156:159], v[188:191], v[76:79]
	v_mfma_f32_16x16x32_bf16 v[72:75], v[100:103], v[196:199], v[72:75]
	v_mfma_f32_16x16x32_bf16 v[68:71], v[156:159], v[196:199], v[68:71]
	v_mfma_f32_16x16x32_bf16 v[96:99], v[104:107], v[176:179], v[96:99]
	v_mfma_f32_16x16x32_bf16 v[92:95], v[160:163], v[176:179], v[92:95]
	v_mfma_f32_16x16x32_bf16 v[88:91], v[104:107], v[184:187], v[88:91]
	v_mfma_f32_16x16x32_bf16 v[84:87], v[160:163], v[184:187], v[84:87]
	v_mfma_f32_16x16x32_bf16 v[80:83], v[104:107], v[192:195], v[80:83]
	v_mfma_f32_16x16x32_bf16 v[76:79], v[160:163], v[192:195], v[76:79]
	v_mfma_f32_16x16x32_bf16 v[72:75], v[104:107], v[200:203], v[72:75]
	v_mfma_f32_16x16x32_bf16 v[68:71], v[160:163], v[200:203], v[68:71]
	s_barrier
	s_setprio 0
	s_add_u32 s0, s28, 0xb0080
	s_addc_u32 s1, s29, 0
	s_add_i32 s24, s25, s68
	v_lshl_add_u64 v[100:101], s[0:1], 0, v[26:27]
	s_mov_b32 m0, s24
	s_nop 0
	global_load_lds_dwordx4 v[100:101], off
	v_lshl_add_u64 v[100:101], s[0:1], 0, v[140:141]
	s_add_i32 m0, s24, 0x2000
	s_nop 0
	global_load_lds_dwordx4 v[100:101], off
	s_waitcnt vmcnt(10)
	s_setprio 1
	s_barrier
	v_mfma_f32_16x16x32_bf16 v[32:35], v[204:207], v[172:175], v[32:35]
	v_mfma_f32_16x16x32_bf16 v[28:31], v[212:215], v[172:175], v[28:31]
	v_mfma_f32_16x16x32_bf16 v[22:25], v[204:207], v[180:183], v[22:25]
	v_mfma_f32_16x16x32_bf16 v[18:21], v[212:215], v[180:183], v[18:21]
	v_mfma_f32_16x16x32_bf16 v[14:17], v[204:207], v[188:191], v[14:17]
	v_mfma_f32_16x16x32_bf16 v[10:13], v[212:215], v[188:191], v[10:13]
	v_mfma_f32_16x16x32_bf16 v[6:9], v[204:207], v[196:199], v[6:9]
	v_mfma_f32_16x16x32_bf16 v[2:5], v[212:215], v[196:199], v[2:5]
	v_mfma_f32_16x16x32_bf16 v[32:35], v[208:211], v[176:179], v[32:35]
	v_mfma_f32_16x16x32_bf16 v[28:31], v[216:219], v[176:179], v[28:31]
	v_mfma_f32_16x16x32_bf16 v[22:25], v[208:211], v[184:187], v[22:25]
	v_mfma_f32_16x16x32_bf16 v[18:21], v[216:219], v[184:187], v[18:21]
	v_mfma_f32_16x16x32_bf16 v[14:17], v[208:211], v[192:195], v[14:17]
	v_mfma_f32_16x16x32_bf16 v[10:13], v[216:219], v[192:195], v[10:13]
	v_mfma_f32_16x16x32_bf16 v[6:9], v[208:211], v[200:203], v[6:9]
	v_mfma_f32_16x16x32_bf16 v[2:5], v[216:219], v[200:203], v[2:5]
	s_barrier
	s_setprio 0
	s_add_i32 s52, s52, 2
	s_add_u32 s18, s18, 0x100
	s_addc_u32 s19, s19, 0
	s_cmp_gt_u32 s52, 41
	s_mov_b64 s[24:25], s[26:27]
	s_cbranch_scc0 .LBB0_395
	s_min_i32 s0, s22, 0x100
	s_ashr_i32 s0, s0, 5
	s_ashr_i32 s1, s0, 31
	s_add_i32 s18, s22, 0xffffff00
	s_cmpk_lt_i32 s22, 0x100
	s_cselect_b32 s18, s22, s18
	s_cselect_b32 s25, 0, s35
	s_cselect_b32 s24, 0, s34
	s_cselect_b32 s26, 0, s57
	s_cselect_b32 s27, 0, s58
	s_ashr_i32 s19, s18, 31
	s_add_u32 s24, s46, s24
	s_addc_u32 s25, s47, s25
	s_lshl_b64 s[18:19], s[18:19], 20
	v_lshl_add_u64 v[100:101], s[18:19], 0, v[146:147]
	s_add_u32 s18, s50, s26
	v_lshl_or_b32 v172, s23, 8, v234
	s_addc_u32 s19, s51, s27
	s_ashr_i32 s23, s22, 31
	v_lshl_add_u64 v[180:181], s[18:19], 0, v[100:101]
	s_lshl_b64 s[18:19], s[22:23], 19
	v_lshl_add_u64 v[184:185], v[148:149], 0, s[18:19]
	s_lshl_b64 s[52:53], s[22:23], 10
	s_mul_i32 s18, s0, 0x9000
	v_ashrrev_i32_e32 v173, 31, v172
	s_mul_hi_i32 s19, s0, 0x9000
	s_add_u32 s18, s36, s18
	s_addc_u32 s19, s37, s19
	v_lshlrev_b64 v[186:187], 2, v[172:173]
	v_lshl_add_u64 v[156:157], s[18:19], 0, v[186:187]
	v_lshl_add_u64 v[164:165], s[24:25], 0, v[100:101]
	global_load_dwordx4 v[100:103], v[156:157], off offset:16
	global_load_dwordx4 v[104:107], v[156:157], off
	s_lshl_b64 s[0:1], s[0:1], 12
	s_add_u32 s0, s59, s0
	s_addc_u32 s1, s20, s1
	v_lshl_add_u64 v[164:165], v[164:165], 0, v[186:187]
	s_mov_b32 s18, 0x20000
	s_waitcnt vmcnt(0)
	v_pk_mul_f32 v[178:179], v[102:103], 0.5 op_sel_hi:[1,0]
	v_pk_mul_f32 v[174:175], v[106:107], 0.5 op_sel_hi:[1,0]
	v_pk_mul_f32 v[176:177], v[104:105], 0.5 op_sel_hi:[1,0]
	v_pk_mul_f32 v[210:211], v[100:101], 0.5 op_sel_hi:[1,0]
	global_load_dwordx4 v[100:103], v[156:157], off offset:528
	global_load_dwordx4 v[104:107], v[156:157], off offset:512
	s_waitcnt vmcnt(0)
	v_pk_mul_f32 v[162:163], v[100:101], 0.5 op_sel_hi:[1,0]
	v_lshlrev_b64 v[100:101], 1, v[172:173]
	v_lshl_add_u64 v[182:183], v[180:181], 0, v[100:101]
	v_lshl_add_u64 v[180:181], v[184:185], 0, v[100:101]
	v_lshl_add_u64 v[184:185], s[0:1], 0, v[186:187]
	v_pk_mul_f32 v[156:157], v[106:107], 0.5 op_sel_hi:[1,0]
	v_pk_mul_f32 v[158:159], v[104:105], 0.5 op_sel_hi:[1,0]
	v_pk_mul_f32 v[160:161], v[102:103], 0.5 op_sel_hi:[1,0]
	global_load_dwordx4 v[100:103], v[184:185], off offset:16
	global_load_dwordx4 v[104:107], v[184:185], off
	global_load_dwordx4 v[188:191], v[164:165], off offset:16
	global_load_dwordx4 v[192:195], v[164:165], off
	v_add_co_u32_e32 v186, vcc, s65, v164
	s_mov_b64 s[0:1], 0x10000
	s_nop 0
	v_addc_co_u32_e32 v187, vcc, 0, v165, vcc
	v_lshl_add_u64 v[172:173], v[164:165], 0, s[0:1]
	global_load_dwordx4 v[196:199], v[186:187], off
	global_load_dwordx4 v[200:203], v[172:173], off offset:16
	s_mov_b32 s0, 0x8000
	s_waitcnt vmcnt(0)
	v_pk_fma_f32 v[134:135], v[134:135], v[178:179], v[190:191]
	v_pk_fma_f32 v[138:139], v[138:139], v[174:175], v[194:195]
	v_pk_fma_f32 v[136:137], v[136:137], v[176:177], v[192:193]
	v_pk_fma_f32 v[132:133], v[132:133], v[210:211], v[188:189]
	v_cvt_pk_bf16_f32 v188, v136, v137
	v_cvt_pk_bf16_f32 v189, v138, v139
	v_cvt_pk_bf16_f32 v190, v132, v133
	v_cvt_pk_bf16_f32 v191, v134, v135
	v_lshlrev_b32_e32 v138, 16, v188
	v_and_b32_e32 v139, 0xffff0000, v188
	v_lshlrev_b32_e32 v136, 16, v189
	v_and_b32_e32 v137, 0xffff0000, v189
	global_store_dwordx4 v[182:183], v[188:191], off offset:2048
	v_lshlrev_b32_e32 v134, 16, v190
	v_and_b32_e32 v135, 0xffff0000, v190
	v_lshlrev_b32_e32 v132, 16, v191
	v_and_b32_e32 v133, 0xffff0000, v191
	v_pk_mul_f32 v[172:173], v[106:107], v[136:137]
	v_pk_mul_f32 v[188:189], v[104:105], v[138:139]
	v_pk_mul_f32 v[192:193], v[102:103], v[132:133]
	v_pk_mul_f32 v[190:191], v[100:101], v[134:135]
	v_cvt_pk_bf16_f32 v188, v188, v189
	v_cvt_pk_bf16_f32 v189, v172, v173
	v_pk_fma_f32 v[130:131], v[130:131], v[174:175], v[198:199]
	v_pk_fma_f32 v[128:129], v[128:129], v[176:177], v[196:197]
	v_pk_fma_f32 v[172:173], v[126:127], v[178:179], v[202:203]
	v_pk_fma_f32 v[126:127], v[124:125], v[210:211], v[200:201]
	v_add_co_u32_e32 v202, vcc, s65, v182
	v_cvt_pk_bf16_f32 v190, v190, v191
	v_cvt_pk_bf16_f32 v191, v192, v193
	v_cvt_pk_bf16_f32 v124, v128, v129
	v_cvt_pk_bf16_f32 v125, v130, v131
	v_cvt_pk_bf16_f32 v126, v126, v127
	v_cvt_pk_bf16_f32 v127, v172, v173
	v_addc_co_u32_e32 v203, vcc, 0, v183, vcc
	global_store_dwordx4 v[180:181], v[188:191], off
	global_store_dwordx4 v[202:203], v[124:127], off offset:2048
	v_lshlrev_b32_e32 v128, 16, v124
	v_and_b32_e32 v129, 0xffff0000, v124
	v_lshlrev_b32_e32 v124, 16, v125
	v_and_b32_e32 v125, 0xffff0000, v125
	v_lshlrev_b32_e32 v130, 16, v126
	v_and_b32_e32 v131, 0xffff0000, v126
	v_lshlrev_b32_e32 v126, 16, v127
	v_and_b32_e32 v127, 0xffff0000, v127
	v_pk_mul_f32 v[172:173], v[106:107], v[124:125]
	v_pk_mul_f32 v[188:189], v[104:105], v[128:129]
	v_pk_mul_f32 v[192:193], v[102:103], v[126:127]
	v_pk_mul_f32 v[190:191], v[100:101], v[130:131]
	v_add_co_u32_e32 v220, vcc, s0, v180
	v_cvt_pk_bf16_f32 v188, v188, v189
	v_cvt_pk_bf16_f32 v189, v172, v173
	v_cvt_pk_bf16_f32 v190, v190, v191
	v_cvt_pk_bf16_f32 v191, v192, v193
	v_addc_co_u32_e32 v221, vcc, 0, v181, vcc
	global_store_dwordx4 v[220:221], v[188:191], off
	s_mov_b64 s[0:1], 0x20000
	v_lshl_add_u64 v[172:173], v[164:165], 0, s[0:1]
	v_add_co_u32_e32 v188, vcc, s18, v164
	s_mov_b64 s[0:1], 0x30000
	s_nop 0
	v_addc_co_u32_e32 v189, vcc, 0, v165, vcc
	global_load_dwordx4 v[192:195], v[188:189], off
	global_load_dwordx4 v[196:199], v[172:173], off offset:16
	v_lshl_add_u64 v[172:173], v[164:165], 0, s[0:1]
	s_mov_b32 s0, 0x30000
	v_add_co_u32_e32 v190, vcc, s0, v164
	s_waitcnt vmcnt(0)
	v_pk_fma_f32 v[120:121], v[120:121], v[176:177], v[192:193]
	v_addc_co_u32_e32 v191, vcc, 0, v165, vcc
	global_load_dwordx4 v[204:207], v[190:191], off
	global_load_dwordx4 v[212:215], v[172:173], off offset:16
	v_pk_fma_f32 v[122:123], v[122:123], v[174:175], v[194:195]
	v_pk_fma_f32 v[118:119], v[118:119], v[178:179], v[198:199]
	v_pk_fma_f32 v[116:117], v[116:117], v[210:211], v[196:197]
	v_cvt_pk_bf16_f32 v194, v120, v121
	v_add_co_u32_e32 v192, vcc, s18, v182
	v_cvt_pk_bf16_f32 v195, v122, v123
	v_cvt_pk_bf16_f32 v196, v116, v117
	v_cvt_pk_bf16_f32 v197, v118, v119
	v_addc_co_u32_e32 v193, vcc, 0, v183, vcc
	v_lshlrev_b32_e32 v122, 16, v194
	v_and_b32_e32 v123, 0xffff0000, v194
	global_store_dwordx4 v[192:193], v[194:197], off offset:2048
	v_lshlrev_b32_e32 v120, 16, v195
	v_and_b32_e32 v121, 0xffff0000, v195
	v_pk_mul_f32 v[194:195], v[104:105], v[122:123]
	v_lshlrev_b32_e32 v118, 16, v196
	v_and_b32_e32 v119, 0xffff0000, v196
	v_cvt_pk_bf16_f32 v196, v194, v195
	v_add_co_u32_e32 v194, vcc, s65, v180
	v_lshlrev_b32_e32 v116, 16, v197
	v_and_b32_e32 v117, 0xffff0000, v197
	v_pk_mul_f32 v[172:173], v[106:107], v[120:121]
	v_addc_co_u32_e32 v195, vcc, 0, v181, vcc
	v_pk_mul_f32 v[200:201], v[102:103], v[116:117]
	v_pk_mul_f32 v[198:199], v[100:101], v[118:119]
	v_cvt_pk_bf16_f32 v197, v172, v173
	v_cvt_pk_bf16_f32 v198, v198, v199
	v_cvt_pk_bf16_f32 v199, v200, v201
	global_store_dwordx4 v[194:195], v[196:199], off
	s_mov_b32 s18, 0x80000
	s_waitcnt vmcnt(0)
	v_pk_fma_f32 v[114:115], v[114:115], v[174:175], v[206:207]
	v_pk_fma_f32 v[112:113], v[112:113], v[176:177], v[204:205]
	v_pk_fma_f32 v[172:173], v[110:111], v[178:179], v[214:215]
	v_pk_fma_f32 v[110:111], v[108:109], v[210:211], v[212:213]
	v_add_co_u32_e32 v212, vcc, s0, v182
	v_cvt_pk_bf16_f32 v108, v112, v113
	v_cvt_pk_bf16_f32 v109, v114, v115
	v_cvt_pk_bf16_f32 v110, v110, v111
	v_cvt_pk_bf16_f32 v111, v172, v173
	v_addc_co_u32_e32 v213, vcc, 0, v183, vcc
	global_store_dwordx4 v[212:213], v[108:111], off offset:2048
	v_lshlrev_b32_e32 v112, 16, v108
	v_and_b32_e32 v113, 0xffff0000, v108
	v_lshlrev_b32_e32 v172, 16, v109
	v_and_b32_e32 v173, 0xffff0000, v109
	v_lshlrev_b32_e32 v114, 16, v110
	v_and_b32_e32 v115, 0xffff0000, v110
	v_lshlrev_b32_e32 v108, 16, v111
	v_and_b32_e32 v109, 0xffff0000, v111
	s_mov_b32 s0, 0x18000
	v_pk_mul_f32 v[110:111], v[106:107], v[172:173]
	v_pk_mul_f32 v[196:197], v[104:105], v[112:113]
	v_pk_mul_f32 v[200:201], v[102:103], v[108:109]
	v_pk_mul_f32 v[198:199], v[100:101], v[114:115]
	v_add_co_u32_e32 v222, vcc, s0, v180
	v_cvt_pk_bf16_f32 v196, v196, v197
	v_cvt_pk_bf16_f32 v197, v110, v111
	v_cvt_pk_bf16_f32 v198, v198, v199
	v_cvt_pk_bf16_f32 v199, v200, v201
	v_addc_co_u32_e32 v223, vcc, 0, v181, vcc
	global_store_dwordx4 v[222:223], v[196:199], off
	s_mov_b64 s[0:1], 0x80000
	v_lshl_add_u64 v[110:111], v[164:165], 0, s[0:1]
	v_add_co_u32_e32 v196, vcc, s18, v164
	s_mov_b64 s[0:1], 0x90000
	s_nop 0
	v_addc_co_u32_e32 v197, vcc, 0, v165, vcc
	global_load_dwordx4 v[204:207], v[196:197], off
	global_load_dwordx4 v[214:217], v[110:111], off offset:16
	v_lshl_add_u64 v[110:111], v[164:165], 0, s[0:1]
	s_mov_b32 s0, 0x90000
	v_add_co_u32_e32 v198, vcc, s0, v164
	s_mov_b32 s1, 0x40000
	s_nop 0
	v_addc_co_u32_e32 v199, vcc, 0, v165, vcc
	global_load_dwordx4 v[238:241], v[198:199], off
	global_load_dwordx4 v[242:245], v[110:111], off offset:16
	v_add_co_u32_e32 v200, vcc, s18, v182
	s_waitcnt vmcnt(0)
	v_pk_fma_f32 v[96:97], v[96:97], v[176:177], v[204:205]
	v_pk_fma_f32 v[98:99], v[98:99], v[174:175], v[206:207]
	v_pk_fma_f32 v[94:95], v[94:95], v[178:179], v[216:217]
	v_pk_fma_f32 v[92:93], v[92:93], v[210:211], v[214:215]
	v_cvt_pk_bf16_f32 v204, v96, v97
	v_cvt_pk_bf16_f32 v205, v98, v99
	v_cvt_pk_bf16_f32 v206, v92, v93
	v_cvt_pk_bf16_f32 v207, v94, v95
	v_addc_co_u32_e32 v201, vcc, 0, v183, vcc
	v_lshlrev_b32_e32 v98, 16, v204
	v_and_b32_e32 v99, 0xffff0000, v204
	global_store_dwordx4 v[200:201], v[204:207], off offset:2048
	v_lshlrev_b32_e32 v96, 16, v205
	v_and_b32_e32 v97, 0xffff0000, v205
	v_pk_mul_f32 v[204:205], v[104:105], v[98:99]
	v_lshlrev_b32_e32 v94, 16, v206
	v_and_b32_e32 v95, 0xffff0000, v206
	v_cvt_pk_bf16_f32 v206, v204, v205
	v_add_co_u32_e32 v204, vcc, s1, v180
	v_lshlrev_b32_e32 v92, 16, v207
	v_and_b32_e32 v93, 0xffff0000, v207
	v_pk_mul_f32 v[110:111], v[106:107], v[96:97]
	v_addc_co_u32_e32 v205, vcc, 0, v181, vcc
	v_pk_mul_f32 v[214:215], v[102:103], v[92:93]
	v_pk_mul_f32 v[208:209], v[100:101], v[94:95]
	v_cvt_pk_bf16_f32 v207, v110, v111
	v_pk_fma_f32 v[90:91], v[90:91], v[174:175], v[240:241]
	v_pk_fma_f32 v[88:89], v[88:89], v[176:177], v[238:239]
	v_pk_fma_f32 v[110:111], v[86:87], v[178:179], v[244:245]
	v_pk_fma_f32 v[86:87], v[84:85], v[210:211], v[242:243]
	v_add_co_u32_e32 v218, vcc, s0, v182
	v_cvt_pk_bf16_f32 v208, v208, v209
	v_cvt_pk_bf16_f32 v209, v214, v215
	v_cvt_pk_bf16_f32 v84, v88, v89
	v_cvt_pk_bf16_f32 v85, v90, v91
	v_cvt_pk_bf16_f32 v86, v86, v87
	v_cvt_pk_bf16_f32 v87, v110, v111
	v_addc_co_u32_e32 v219, vcc, 0, v183, vcc
	global_store_dwordx4 v[204:205], v[206:209], off
	global_store_dwordx4 v[218:219], v[84:87], off offset:2048
	v_lshlrev_b32_e32 v88, 16, v84
	v_and_b32_e32 v89, 0xffff0000, v84
	v_lshlrev_b32_e32 v110, 16, v85
	v_and_b32_e32 v111, 0xffff0000, v85
	v_lshlrev_b32_e32 v90, 16, v86
	v_and_b32_e32 v91, 0xffff0000, v86
	v_lshlrev_b32_e32 v84, 16, v87
	v_and_b32_e32 v85, 0xffff0000, v87
	s_mov_b32 s0, 0x48000
	v_pk_mul_f32 v[86:87], v[106:107], v[110:111]
	v_pk_mul_f32 v[206:207], v[104:105], v[88:89]
	v_pk_mul_f32 v[214:215], v[102:103], v[84:85]
	v_pk_mul_f32 v[208:209], v[100:101], v[90:91]
	v_add_co_u32_e32 v224, vcc, s0, v180
	v_cvt_pk_bf16_f32 v206, v206, v207
	v_cvt_pk_bf16_f32 v207, v86, v87
	v_cvt_pk_bf16_f32 v208, v208, v209
	v_cvt_pk_bf16_f32 v209, v214, v215
	v_addc_co_u32_e32 v225, vcc, 0, v181, vcc
	global_store_dwordx4 v[224:225], v[206:209], off
	s_mov_b64 s[0:1], 0xa0000
	v_lshl_add_u64 v[86:87], v[164:165], 0, s[0:1]
	v_add_co_u32_e32 v206, vcc, s76, v164
	s_mov_b64 s[0:1], 0xb0000
	s_nop 0
	v_addc_co_u32_e32 v207, vcc, 0, v165, vcc
	global_load_dwordx4 v[214:217], v[206:207], off
	global_load_dwordx4 v[238:241], v[86:87], off offset:16
	v_lshl_add_u64 v[86:87], v[164:165], 0, s[0:1]
	s_mov_b32 s0, 0xb0000
	v_add_co_u32_e32 v208, vcc, s0, v164
	s_waitcnt vmcnt(0)
	v_pk_fma_f32 v[80:81], v[80:81], v[176:177], v[214:215]
	v_addc_co_u32_e32 v209, vcc, 0, v165, vcc
	global_load_dwordx4 v[242:245], v[208:209], off
	global_load_dwordx4 v[246:249], v[86:87], off offset:16
	v_pk_fma_f32 v[82:83], v[82:83], v[174:175], v[216:217]
	v_pk_fma_f32 v[76:77], v[76:77], v[210:211], v[238:239]
	v_cvt_pk_bf16_f32 v238, v80, v81
	v_pk_fma_f32 v[78:79], v[78:79], v[178:179], v[240:241]
	v_cvt_pk_bf16_f32 v239, v82, v83
	v_add_co_u32_e32 v214, vcc, s76, v182
	v_lshlrev_b32_e32 v82, 16, v238
	v_and_b32_e32 v83, 0xffff0000, v238
	v_cvt_pk_bf16_f32 v240, v76, v77
	v_cvt_pk_bf16_f32 v241, v78, v79
	v_addc_co_u32_e32 v215, vcc, 0, v183, vcc
	v_lshlrev_b32_e32 v80, 16, v239
	v_and_b32_e32 v81, 0xffff0000, v239
	v_pk_mul_f32 v[216:217], v[104:105], v[82:83]
	global_store_dwordx4 v[214:215], v[238:241], off offset:2048
	v_pk_mul_f32 v[86:87], v[106:107], v[80:81]
	v_lshlrev_b32_e32 v78, 16, v240
	v_cvt_pk_bf16_f32 v238, v216, v217
	v_add_co_u32_e32 v216, vcc, s77, v180
	v_and_b32_e32 v79, 0xffff0000, v240
	v_lshlrev_b32_e32 v76, 16, v241
	v_and_b32_e32 v77, 0xffff0000, v241
	v_cvt_pk_bf16_f32 v239, v86, v87
	v_addc_co_u32_e32 v217, vcc, 0, v181, vcc
	v_pk_mul_f32 v[250:251], v[102:103], v[76:77]
	v_pk_mul_f32 v[240:241], v[100:101], v[78:79]
	s_waitcnt vmcnt(0)
	v_pk_fma_f32 v[74:75], v[74:75], v[174:175], v[244:245]
	v_pk_fma_f32 v[72:73], v[72:73], v[176:177], v[242:243]
	v_pk_fma_f32 v[86:87], v[70:71], v[178:179], v[248:249]
	v_pk_fma_f32 v[70:71], v[68:69], v[210:211], v[246:247]
	v_cvt_pk_bf16_f32 v68, v72, v73
	v_cvt_pk_bf16_f32 v69, v74, v75
	v_cvt_pk_bf16_f32 v70, v70, v71
	v_cvt_pk_bf16_f32 v71, v86, v87
	v_add_co_u32_e32 v210, vcc, s0, v182
	v_cvt_pk_bf16_f32 v240, v240, v241
	v_cvt_pk_bf16_f32 v241, v250, v251
	v_addc_co_u32_e32 v211, vcc, 0, v183, vcc
	v_lshlrev_b32_e32 v86, 16, v68
	v_and_b32_e32 v87, 0xffff0000, v68
	v_lshlrev_b32_e32 v178, 16, v69
	v_and_b32_e32 v179, 0xffff0000, v69
	v_lshlrev_b32_e32 v176, 16, v70
	v_and_b32_e32 v177, 0xffff0000, v70
	v_lshlrev_b32_e32 v174, 16, v71
	v_and_b32_e32 v175, 0xffff0000, v71
	s_mov_b32 s0, 0x58000
	global_store_dwordx4 v[216:217], v[238:241], off
	global_store_dwordx4 v[210:211], v[68:71], off offset:2048
	v_pk_mul_f32 v[72:73], v[102:103], v[174:175]
	v_pk_mul_f32 v[74:75], v[100:101], v[176:177]
	v_pk_mul_f32 v[70:71], v[106:107], v[178:179]
	v_pk_mul_f32 v[68:69], v[104:105], v[86:87]
	v_add_co_u32_e32 v100, vcc, s0, v180
	v_cvt_pk_bf16_f32 v68, v68, v69
	v_cvt_pk_bf16_f32 v69, v70, v71
	v_cvt_pk_bf16_f32 v70, v74, v75
	v_cvt_pk_bf16_f32 v71, v72, v73
	v_addc_co_u32_e32 v101, vcc, 0, v181, vcc
	global_store_dwordx4 v[100:101], v[68:71], off
	global_load_dwordx4 v[68:71], v[184:185], off offset:528
	s_nop 0
	global_load_dwordx4 v[72:75], v[184:185], off offset:512
	global_load_dwordx4 v[102:105], v[164:165], off offset:528
	global_load_dwordx4 v[238:241], v[164:165], off offset:512
	s_mov_b64 s[0:1], 0x10200
	v_lshl_add_u64 v[106:107], v[164:165], 0, s[0:1]
	global_load_dwordx4 v[184:187], v[186:187], off offset:512
	s_nop 0
	global_load_dwordx4 v[242:245], v[106:107], off offset:16
	s_mov_b64 s[0:1], 0x20200
	s_waitcnt vmcnt(0)
	v_pk_fma_f32 v[62:63], v[62:63], v[160:161], v[104:105]
	v_pk_fma_f32 v[66:67], v[66:67], v[156:157], v[240:241]
	v_pk_fma_f32 v[64:65], v[64:65], v[158:159], v[238:239]
	v_pk_fma_f32 v[60:61], v[60:61], v[162:163], v[102:103]
	v_cvt_pk_bf16_f32 v102, v64, v65
	v_cvt_pk_bf16_f32 v103, v66, v67
	v_cvt_pk_bf16_f32 v104, v60, v61
	v_cvt_pk_bf16_f32 v105, v62, v63
	v_lshlrev_b32_e32 v66, 16, v102
	v_and_b32_e32 v67, 0xffff0000, v102
	v_lshlrev_b32_e32 v64, 16, v103
	v_and_b32_e32 v65, 0xffff0000, v103
	v_lshlrev_b32_e32 v62, 16, v104
	v_and_b32_e32 v63, 0xffff0000, v104
	v_lshlrev_b32_e32 v60, 16, v105
	v_and_b32_e32 v61, 0xffff0000, v105
	global_store_dwordx4 v[182:183], v[102:105], off offset:2304
	v_pk_mul_f32 v[106:107], v[70:71], v[60:61]
	v_pk_mul_f32 v[182:183], v[68:69], v[62:63]
	v_pk_mul_f32 v[104:105], v[74:75], v[64:65]
	v_pk_mul_f32 v[102:103], v[72:73], v[66:67]
	v_pk_fma_f32 v[58:59], v[58:59], v[156:157], v[186:187]
	v_cvt_pk_bf16_f32 v102, v102, v103
	v_cvt_pk_bf16_f32 v103, v104, v105
	v_cvt_pk_bf16_f32 v104, v182, v183
	v_cvt_pk_bf16_f32 v105, v106, v107
	v_pk_fma_f32 v[56:57], v[56:57], v[158:159], v[184:185]
	v_pk_fma_f32 v[54:55], v[54:55], v[160:161], v[244:245]
	v_pk_fma_f32 v[52:53], v[52:53], v[162:163], v[242:243]
	global_store_dwordx4 v[180:181], v[102:105], off offset:256
	v_mul_f32_e32 v67, v67, v67
	v_mul_f32_e32 v65, v65, v65
	v_cvt_pk_bf16_f32 v102, v56, v57
	v_cvt_pk_bf16_f32 v103, v58, v59
	v_cvt_pk_bf16_f32 v104, v52, v53
	v_cvt_pk_bf16_f32 v105, v54, v55
	v_lshlrev_b32_e32 v58, 16, v102
	v_and_b32_e32 v59, 0xffff0000, v102
	v_lshlrev_b32_e32 v56, 16, v103
	v_and_b32_e32 v57, 0xffff0000, v103
	v_lshlrev_b32_e32 v54, 16, v104
	v_and_b32_e32 v55, 0xffff0000, v104
	v_lshlrev_b32_e32 v52, 16, v105
	v_and_b32_e32 v53, 0xffff0000, v105
	global_store_dwordx4 v[202:203], v[102:105], off offset:2304
	v_pk_mul_f32 v[106:107], v[70:71], v[52:53]
	v_pk_mul_f32 v[180:181], v[68:69], v[54:55]
	v_pk_mul_f32 v[104:105], v[74:75], v[56:57]
	v_pk_mul_f32 v[102:103], v[72:73], v[58:59]
	v_fmac_f32_e32 v67, v66, v66
	v_cvt_pk_bf16_f32 v102, v102, v103
	v_cvt_pk_bf16_f32 v103, v104, v105
	v_cvt_pk_bf16_f32 v104, v180, v181
	v_cvt_pk_bf16_f32 v105, v106, v107
	global_store_dwordx4 v[220:221], v[102:105], off offset:256
	v_lshl_add_u64 v[106:107], v[164:165], 0, s[0:1]
	global_load_dwordx4 v[102:105], v[188:189], off offset:512
	global_load_dwordx4 v[180:183], v[106:107], off offset:16
	s_mov_b64 s[0:1], 0x30200
	v_lshl_add_u64 v[106:107], v[164:165], 0, s[0:1]
	global_load_dwordx4 v[184:187], v[190:191], off offset:512
	s_nop 0
	global_load_dwordx4 v[188:191], v[106:107], off offset:16
	s_mov_b64 s[0:1], 0x80200
	v_fmac_f32_e32 v65, v64, v64
	v_mul_f32_e32 v63, v63, v63
	v_mul_f32_e32 v61, v61, v61
	v_add_f32_e32 v64, v67, v65
	v_fmac_f32_e32 v63, v62, v62
	v_fmac_f32_e32 v61, v60, v60
	v_add_f32_e32 v60, v63, v61
	s_waitcnt vmcnt(0)
	v_pk_fma_f32 v[50:51], v[50:51], v[156:157], v[104:105]
	v_pk_fma_f32 v[48:49], v[48:49], v[158:159], v[102:103]
	v_pk_fma_f32 v[46:47], v[46:47], v[160:161], v[182:183]
	v_pk_fma_f32 v[44:45], v[44:45], v[162:163], v[180:181]
	v_cvt_pk_bf16_f32 v102, v48, v49
	v_cvt_pk_bf16_f32 v103, v50, v51
	v_cvt_pk_bf16_f32 v104, v44, v45
	v_cvt_pk_bf16_f32 v105, v46, v47
	v_lshlrev_b32_e32 v50, 16, v102
	v_and_b32_e32 v51, 0xffff0000, v102
	v_lshlrev_b32_e32 v48, 16, v103
	v_and_b32_e32 v49, 0xffff0000, v103
	v_lshlrev_b32_e32 v46, 16, v104
	v_and_b32_e32 v47, 0xffff0000, v104
	v_lshlrev_b32_e32 v44, 16, v105
	v_and_b32_e32 v45, 0xffff0000, v105
	global_store_dwordx4 v[192:193], v[102:105], off offset:2304
	v_pk_mul_f32 v[106:107], v[70:71], v[44:45]
	v_pk_mul_f32 v[180:181], v[68:69], v[46:47]
	v_pk_mul_f32 v[104:105], v[74:75], v[48:49]
	v_pk_mul_f32 v[102:103], v[72:73], v[50:51]
	v_pk_fma_f32 v[42:43], v[42:43], v[156:157], v[186:187]
	v_cvt_pk_bf16_f32 v102, v102, v103
	v_cvt_pk_bf16_f32 v103, v104, v105
	v_cvt_pk_bf16_f32 v104, v180, v181
	v_cvt_pk_bf16_f32 v105, v106, v107
	v_pk_fma_f32 v[40:41], v[40:41], v[158:159], v[184:185]
	v_pk_fma_f32 v[38:39], v[38:39], v[160:161], v[190:191]
	v_pk_fma_f32 v[36:37], v[36:37], v[162:163], v[188:189]
	global_store_dwordx4 v[194:195], v[102:105], off offset:256
	s_nop 1
	v_cvt_pk_bf16_f32 v102, v40, v41
	v_cvt_pk_bf16_f32 v103, v42, v43
	v_cvt_pk_bf16_f32 v104, v36, v37
	v_cvt_pk_bf16_f32 v105, v38, v39
	v_lshlrev_b32_e32 v42, 16, v102
	v_and_b32_e32 v43, 0xffff0000, v102
	v_lshlrev_b32_e32 v40, 16, v103
	v_and_b32_e32 v41, 0xffff0000, v103
	v_lshlrev_b32_e32 v38, 16, v104
	v_and_b32_e32 v39, 0xffff0000, v104
	v_lshlrev_b32_e32 v36, 16, v105
	v_and_b32_e32 v37, 0xffff0000, v105
	global_store_dwordx4 v[212:213], v[102:105], off offset:2304
	v_pk_mul_f32 v[106:107], v[70:71], v[36:37]
	v_pk_mul_f32 v[180:181], v[68:69], v[38:39]
	v_pk_mul_f32 v[104:105], v[74:75], v[40:41]
	v_pk_mul_f32 v[102:103], v[72:73], v[42:43]
	s_nop 0
	v_cvt_pk_bf16_f32 v102, v102, v103
	v_cvt_pk_bf16_f32 v103, v104, v105
	v_cvt_pk_bf16_f32 v104, v180, v181
	v_cvt_pk_bf16_f32 v105, v106, v107
	global_store_dwordx4 v[222:223], v[102:105], off offset:256
	v_lshl_add_u64 v[106:107], v[164:165], 0, s[0:1]
	global_load_dwordx4 v[102:105], v[196:197], off offset:512
	global_load_dwordx4 v[180:183], v[106:107], off offset:16
	s_mov_b64 s[0:1], 0x90200
	v_lshl_add_u64 v[106:107], v[164:165], 0, s[0:1]
	global_load_dwordx4 v[184:187], v[198:199], off offset:512
	global_load_dwordx4 v[188:191], v[106:107], off offset:16
	s_mov_b64 s[0:1], 0xa0200
	s_waitcnt vmcnt(0)
	v_pk_fma_f32 v[34:35], v[34:35], v[156:157], v[104:105]
	v_pk_fma_f32 v[32:33], v[32:33], v[158:159], v[102:103]
	v_pk_fma_f32 v[30:31], v[30:31], v[160:161], v[182:183]
	v_pk_fma_f32 v[28:29], v[28:29], v[162:163], v[180:181]
	v_cvt_pk_bf16_f32 v102, v32, v33
	v_cvt_pk_bf16_f32 v103, v34, v35
	v_cvt_pk_bf16_f32 v104, v28, v29
	v_cvt_pk_bf16_f32 v105, v30, v31
	v_lshlrev_b32_e32 v34, 16, v102
	v_and_b32_e32 v35, 0xffff0000, v102
	v_lshlrev_b32_e32 v32, 16, v103
	v_and_b32_e32 v33, 0xffff0000, v103
	v_lshlrev_b32_e32 v30, 16, v104
	v_and_b32_e32 v31, 0xffff0000, v104
	v_lshlrev_b32_e32 v28, 16, v105
	v_and_b32_e32 v29, 0xffff0000, v105
	global_store_dwordx4 v[200:201], v[102:105], off offset:2304
	v_pk_mul_f32 v[106:107], v[70:71], v[28:29]
	v_pk_mul_f32 v[180:181], v[68:69], v[30:31]
	v_pk_mul_f32 v[104:105], v[74:75], v[32:33]
	v_pk_mul_f32 v[102:103], v[72:73], v[34:35]
	v_pk_fma_f32 v[24:25], v[24:25], v[156:157], v[186:187]
	v_cvt_pk_bf16_f32 v102, v102, v103
	v_cvt_pk_bf16_f32 v103, v104, v105
	v_cvt_pk_bf16_f32 v104, v180, v181
	v_cvt_pk_bf16_f32 v105, v106, v107
	v_pk_fma_f32 v[22:23], v[22:23], v[158:159], v[184:185]
	v_pk_fma_f32 v[20:21], v[20:21], v[160:161], v[190:191]
	v_pk_fma_f32 v[18:19], v[18:19], v[162:163], v[188:189]
	global_store_dwordx4 v[204:205], v[102:105], off offset:256
	s_nop 1
	v_cvt_pk_bf16_f32 v102, v22, v23
	v_cvt_pk_bf16_f32 v103, v24, v25
	v_cvt_pk_bf16_f32 v104, v18, v19
	v_cvt_pk_bf16_f32 v105, v20, v21
	v_lshlrev_b32_e32 v24, 16, v102
	v_and_b32_e32 v25, 0xffff0000, v102
	v_lshlrev_b32_e32 v22, 16, v103
	v_and_b32_e32 v23, 0xffff0000, v103
	v_lshlrev_b32_e32 v20, 16, v104
	v_and_b32_e32 v21, 0xffff0000, v104
	v_lshlrev_b32_e32 v18, 16, v105
	v_and_b32_e32 v19, 0xffff0000, v105
	global_store_dwordx4 v[218:219], v[102:105], off offset:2304
	v_pk_mul_f32 v[106:107], v[70:71], v[18:19]
	v_pk_mul_f32 v[180:181], v[68:69], v[20:21]
	v_pk_mul_f32 v[104:105], v[74:75], v[22:23]
	v_pk_mul_f32 v[102:103], v[72:73], v[24:25]
	s_nop 0
	v_cvt_pk_bf16_f32 v102, v102, v103
	v_cvt_pk_bf16_f32 v103, v104, v105
	v_cvt_pk_bf16_f32 v104, v180, v181
	v_cvt_pk_bf16_f32 v105, v106, v107
	global_store_dwordx4 v[224:225], v[102:105], off offset:256
	v_lshl_add_u64 v[106:107], v[164:165], 0, s[0:1]
	global_load_dwordx4 v[102:105], v[206:207], off offset:512
	global_load_dwordx4 v[180:183], v[106:107], off offset:16
	s_mov_b64 s[0:1], 0xb0200
	v_lshl_add_u64 v[106:107], v[164:165], 0, s[0:1]
	global_load_dwordx4 v[184:187], v[208:209], off offset:512
	global_load_dwordx4 v[188:191], v[106:107], off offset:16
	s_waitcnt vmcnt(0)
	v_pk_fma_f32 v[16:17], v[16:17], v[156:157], v[104:105]
	v_pk_fma_f32 v[14:15], v[14:15], v[158:159], v[102:103]
	v_pk_fma_f32 v[102:103], v[12:13], v[160:161], v[182:183]
	v_pk_fma_f32 v[12:13], v[10:11], v[162:163], v[180:181]
	v_cvt_pk_bf16_f32 v10, v14, v15
	v_cvt_pk_bf16_f32 v11, v16, v17
	v_cvt_pk_bf16_f32 v12, v12, v13
	v_cvt_pk_bf16_f32 v13, v102, v103
	v_lshlrev_b32_e32 v102, 16, v10
	v_and_b32_e32 v103, 0xffff0000, v10
	v_lshlrev_b32_e32 v16, 16, v11
	v_and_b32_e32 v17, 0xffff0000, v11
	global_store_dwordx4 v[214:215], v[10:13], off offset:2304
	v_lshlrev_b32_e32 v14, 16, v12
	v_and_b32_e32 v15, 0xffff0000, v12
	v_lshlrev_b32_e32 v12, 16, v13
	v_and_b32_e32 v13, 0xffff0000, v13
	v_pk_mul_f32 v[10:11], v[74:75], v[16:17]
	v_pk_mul_f32 v[104:105], v[72:73], v[102:103]
	v_pk_mul_f32 v[164:165], v[70:71], v[12:13]
	v_pk_mul_f32 v[106:107], v[68:69], v[14:15]
	v_cvt_pk_bf16_f32 v104, v104, v105
	v_cvt_pk_bf16_f32 v105, v10, v11
	v_pk_fma_f32 v[8:9], v[8:9], v[156:157], v[186:187]
	v_pk_fma_f32 v[6:7], v[6:7], v[158:159], v[184:185]
	v_pk_fma_f32 v[10:11], v[4:5], v[160:161], v[190:191]
	v_pk_fma_f32 v[4:5], v[2:3], v[162:163], v[188:189]
	v_cvt_pk_bf16_f32 v106, v106, v107
	v_cvt_pk_bf16_f32 v107, v164, v165
	v_cvt_pk_bf16_f32 v2, v6, v7
	v_cvt_pk_bf16_f32 v3, v8, v9
	v_cvt_pk_bf16_f32 v4, v4, v5
	v_cvt_pk_bf16_f32 v5, v10, v11
	global_store_dwordx4 v[216:217], v[104:107], off offset:256
	global_store_dwordx4 v[210:211], v[2:5], off offset:2304
	v_lshlrev_b32_e32 v10, 16, v2
	v_and_b32_e32 v11, 0xffff0000, v2
	v_lshlrev_b32_e32 v8, 16, v3
	v_and_b32_e32 v9, 0xffff0000, v3
	v_lshlrev_b32_e32 v6, 16, v4
	v_and_b32_e32 v7, 0xffff0000, v4
	v_lshlrev_b32_e32 v4, 16, v5
	v_and_b32_e32 v5, 0xffff0000, v5
	v_pk_mul_f32 v[2:3], v[74:75], v[8:9]
	v_pk_mul_f32 v[72:73], v[72:73], v[10:11]
	v_pk_mul_f32 v[74:75], v[70:71], v[4:5]
	v_pk_mul_f32 v[70:71], v[68:69], v[6:7]
	v_cvt_pk_bf16_f32 v68, v72, v73
	v_cvt_pk_bf16_f32 v69, v2, v3
	v_cvt_pk_bf16_f32 v70, v70, v71
	v_cvt_pk_bf16_f32 v71, v74, v75
	global_store_dwordx4 v[100:101], v[68:71], off offset:256
	v_mul_f32_e32 v72, v133, v133
	v_fmac_f32_e32 v72, v132, v132
	v_and_b32_e32 v69, 64, v227
	v_xor_b32_e32 v68, 16, v227
	v_add_u32_e32 v69, 64, v69
	v_cmp_lt_i32_e32 vcc, v68, v69
	v_xor_b32_e32 v70, 32, v227
	v_mul_f32_e32 v71, v137, v137
	v_cndmask_b32_e32 v68, v227, v68, vcc
	v_cmp_lt_i32_e32 vcc, v70, v69
	v_fmac_f32_e32 v71, v136, v136
	v_lshlrev_b32_e32 v68, 2, v68
	v_cndmask_b32_e32 v69, v227, v70, vcc
	v_mul_f32_e32 v70, v139, v139
	v_fmac_f32_e32 v70, v138, v138
	v_add_f32_e32 v70, v70, v71
	v_mul_f32_e32 v71, v135, v135
	v_fmac_f32_e32 v71, v134, v134
	v_add_f32_e32 v71, v71, v72
	v_add_f32_e32 v70, v70, v71
	v_add_f32_e32 v64, v70, v64
	v_add_f32_e32 v60, v64, v60
	ds_bpermute_b32 v61, v68, v60
	v_lshlrev_b32_e32 v69, 2, v69
	v_lshl_add_u64 v[2:3], v[150:151], 0, s[52:53]
	s_waitcnt lgkmcnt(0)
	v_add_f32_e32 v60, v60, v61
	ds_bpermute_b32 v61, v69, v60
	s_and_saveexec_b64 s[18:19], s[38:39]
	s_cbranch_execz .LBB0_398
	s_waitcnt lgkmcnt(0)
	v_add_f32_e32 v60, v60, v61
	global_atomic_add_f32 v[2:3], v60, off

.LBB0_479:
	s_add_u32 s0, s22, 0xfffc0080
	s_addc_u32 s1, s23, -1
	s_add_i32 s69, 0, 0x10000
	v_add_u32_e32 v154, s69, v163
	ds_read_b128 v[100:103], v154
	ds_read_b128 v[104:107], v154 offset:1024
	ds_read_b128 v[150:153], v154 offset:2048
	ds_read_b128 v[154:157], v154 offset:3072
	s_cmp_eq_u32 s68, 12
	s_cselect_b32 s27, s35, s1
	s_cselect_b32 s26, s40, s0
	s_cselect_b32 s25, s41, s59
	s_cselect_b32 s24, s49, s51
	v_lshl_add_u64 v[166:167], s[22:23], 0, v[146:147]
	s_add_i32 m0, s37, 0xc000
	ds_read_b128 v[158:161], v165
	ds_read_b128 v[172:175], v165 offset:1024
	ds_read_b128 v[176:179], v165 offset:2048
	ds_read_b128 v[180:183], v165 offset:3072
	ds_read_b128 v[184:187], v165 offset:4096
	ds_read_b128 v[188:191], v165 offset:5120
	ds_read_b128 v[192:195], v165 offset:6144
	ds_read_b128 v[196:199], v165 offset:7168
	global_load_lds_dwordx4 v[166:167], off
	v_lshl_add_u64 v[166:167], s[22:23], 0, v[148:149]
	s_add_i32 m0, s37, 0xe000
	s_nop 0
	global_load_lds_dwordx4 v[166:167], off
	s_waitcnt vmcnt(10) lgkmcnt(8)
	s_setprio 1
	s_barrier
	s_waitcnt lgkmcnt(0)
	v_mfma_f32_16x16x32_bf16 v[136:139], v[100:103], v[158:161], v[136:139]
	v_mfma_f32_16x16x32_bf16 v[132:135], v[150:153], v[158:161], v[132:135]
	v_mfma_f32_16x16x32_bf16 v[128:131], v[100:103], v[176:179], v[128:131]
	v_mfma_f32_16x16x32_bf16 v[124:127], v[150:153], v[176:179], v[124:127]
	v_mfma_f32_16x16x32_bf16 v[120:123], v[100:103], v[184:187], v[120:123]
	v_mfma_f32_16x16x32_bf16 v[116:119], v[150:153], v[184:187], v[116:119]
	v_mfma_f32_16x16x32_bf16 v[112:115], v[100:103], v[192:195], v[112:115]
	v_mfma_f32_16x16x32_bf16 v[108:111], v[150:153], v[192:195], v[108:111]
	v_mfma_f32_16x16x32_bf16 v[136:139], v[104:107], v[172:175], v[136:139]
	v_mfma_f32_16x16x32_bf16 v[132:135], v[154:157], v[172:175], v[132:135]
	v_mfma_f32_16x16x32_bf16 v[128:131], v[104:107], v[180:183], v[128:131]
	v_mfma_f32_16x16x32_bf16 v[124:127], v[154:157], v[180:183], v[124:127]
	v_mfma_f32_16x16x32_bf16 v[120:123], v[104:107], v[188:191], v[120:123]
	v_mfma_f32_16x16x32_bf16 v[116:119], v[154:157], v[188:191], v[116:119]
	v_mfma_f32_16x16x32_bf16 v[112:115], v[104:107], v[196:199], v[112:115]
	v_mfma_f32_16x16x32_bf16 v[108:111], v[154:157], v[196:199], v[108:111]
	s_barrier
	s_setprio 0
	s_add_i32 s72, 0, 0x14000
	v_add_u32_e32 v166, s72, v163
	s_add_i32 s0, s69, s36
	ds_read_b128 v[200:203], v166
	ds_read_b128 v[204:207], v166 offset:1024
	ds_read_b128 v[208:211], v166 offset:2048
	ds_read_b128 v[212:215], v166 offset:3072
	v_lshl_add_u64 v[166:167], s[24:25], 0, v[26:27]
	s_mov_b32 m0, s0
	v_lshl_add_u64 v[168:169], s[24:25], 0, v[140:141]
	global_load_lds_dwordx4 v[166:167], off
	s_add_i32 m0, s0, 0x2000
	s_nop 0
	global_load_lds_dwordx4 v[168:169], off
	s_waitcnt vmcnt(10)
	s_setprio 1
	s_barrier
	s_waitcnt lgkmcnt(0)
	v_mfma_f32_16x16x32_bf16 v[64:67], v[200:203], v[158:161], v[64:67]
	v_mfma_f32_16x16x32_bf16 v[60:63], v[208:211], v[158:161], v[60:63]
	v_mfma_f32_16x16x32_bf16 v[56:59], v[200:203], v[176:179], v[56:59]
	v_mfma_f32_16x16x32_bf16 v[52:55], v[208:211], v[176:179], v[52:55]
	v_mfma_f32_16x16x32_bf16 v[48:51], v[200:203], v[184:187], v[48:51]
	v_mfma_f32_16x16x32_bf16 v[44:47], v[208:211], v[184:187], v[44:47]
	v_mfma_f32_16x16x32_bf16 v[40:43], v[200:203], v[192:195], v[40:43]
	v_mfma_f32_16x16x32_bf16 v[36:39], v[208:211], v[192:195], v[36:39]
	v_mfma_f32_16x16x32_bf16 v[64:67], v[204:207], v[172:175], v[64:67]
	v_mfma_f32_16x16x32_bf16 v[60:63], v[212:215], v[172:175], v[60:63]
	v_mfma_f32_16x16x32_bf16 v[56:59], v[204:207], v[180:183], v[56:59]
	v_mfma_f32_16x16x32_bf16 v[52:55], v[212:215], v[180:183], v[52:55]
	v_mfma_f32_16x16x32_bf16 v[48:51], v[204:207], v[188:191], v[48:51]
	v_mfma_f32_16x16x32_bf16 v[44:47], v[212:215], v[188:191], v[44:47]
	v_mfma_f32_16x16x32_bf16 v[40:43], v[204:207], v[196:199], v[40:43]
	v_mfma_f32_16x16x32_bf16 v[36:39], v[212:215], v[196:199], v[36:39]
	s_barrier
	s_setprio 0
	s_mov_b32 m0, s37
	v_lshl_add_u64 v[216:217], s[26:27], 0, v[144:145]
	ds_read_b128 v[158:161], v165 offset:16384
	ds_read_b128 v[172:175], v165 offset:17408
	ds_read_b128 v[176:179], v165 offset:18432
	ds_read_b128 v[180:183], v165 offset:19456
	ds_read_b128 v[184:187], v165 offset:20480
	ds_read_b128 v[188:191], v165 offset:21504
	ds_read_b128 v[192:195], v165 offset:22528
	ds_read_b128 v[196:199], v165 offset:23552
	global_load_lds_dwordx4 v[216:217], off
	v_lshl_add_u64 v[218:219], s[26:27], 0, v[142:143]
	s_mov_b32 m0, s56
	s_nop 0
	global_load_lds_dwordx4 v[218:219], off
	s_setprio 1
	s_barrier
	s_waitcnt lgkmcnt(0)
	v_mfma_f32_16x16x32_bf16 v[96:99], v[100:103], v[158:161], v[96:99]
	v_mfma_f32_16x16x32_bf16 v[92:95], v[150:153], v[158:161], v[92:95]
	v_mfma_f32_16x16x32_bf16 v[88:91], v[100:103], v[176:179], v[88:91]
	v_mfma_f32_16x16x32_bf16 v[84:87], v[150:153], v[176:179], v[84:87]
	v_mfma_f32_16x16x32_bf16 v[80:83], v[100:103], v[184:187], v[80:83]
	v_mfma_f32_16x16x32_bf16 v[76:79], v[150:153], v[184:187], v[76:79]
	v_mfma_f32_16x16x32_bf16 v[72:75], v[100:103], v[192:195], v[72:75]
	v_mfma_f32_16x16x32_bf16 v[68:71], v[150:153], v[192:195], v[68:71]
	v_mfma_f32_16x16x32_bf16 v[96:99], v[104:107], v[172:175], v[96:99]
	v_mfma_f32_16x16x32_bf16 v[92:95], v[154:157], v[172:175], v[92:95]
	v_mfma_f32_16x16x32_bf16 v[88:91], v[104:107], v[180:183], v[88:91]
	v_mfma_f32_16x16x32_bf16 v[84:87], v[154:157], v[180:183], v[84:87]
	v_mfma_f32_16x16x32_bf16 v[80:83], v[104:107], v[188:191], v[80:83]
	v_mfma_f32_16x16x32_bf16 v[76:79], v[154:157], v[188:191], v[76:79]
	v_mfma_f32_16x16x32_bf16 v[72:75], v[104:107], v[196:199], v[72:75]
	v_mfma_f32_16x16x32_bf16 v[68:71], v[154:157], v[196:199], v[68:71]
	s_barrier
	s_setprio 0
	s_add_u32 s0, s24, 0x40000
	s_addc_u32 s1, s25, 0
	s_add_i32 s69, s72, s36
	v_lshl_add_u64 v[100:101], s[0:1], 0, v[26:27]
	s_mov_b32 m0, s69
	s_nop 0
	global_load_lds_dwordx4 v[100:101], off
	v_lshl_add_u64 v[100:101], s[0:1], 0, v[140:141]
	s_add_i32 m0, s69, 0x2000
	s_nop 0
	global_load_lds_dwordx4 v[100:101], off
	s_waitcnt vmcnt(10)
	s_setprio 1
	s_barrier
	v_mfma_f32_16x16x32_bf16 v[32:35], v[200:203], v[158:161], v[32:35]
	v_mfma_f32_16x16x32_bf16 v[28:31], v[208:211], v[158:161], v[28:31]
	v_mfma_f32_16x16x32_bf16 v[22:25], v[200:203], v[176:179], v[22:25]
	v_mfma_f32_16x16x32_bf16 v[18:21], v[208:211], v[176:179], v[18:21]
	v_mfma_f32_16x16x32_bf16 v[14:17], v[200:203], v[184:187], v[14:17]
	v_mfma_f32_16x16x32_bf16 v[10:13], v[208:211], v[184:187], v[10:13]
	v_mfma_f32_16x16x32_bf16 v[6:9], v[200:203], v[192:195], v[6:9]
	v_mfma_f32_16x16x32_bf16 v[2:5], v[208:211], v[192:195], v[2:5]
	v_mfma_f32_16x16x32_bf16 v[32:35], v[204:207], v[172:175], v[32:35]
	v_mfma_f32_16x16x32_bf16 v[28:31], v[212:215], v[172:175], v[28:31]
	v_mfma_f32_16x16x32_bf16 v[22:25], v[204:207], v[180:183], v[22:25]
	v_mfma_f32_16x16x32_bf16 v[18:21], v[212:215], v[180:183], v[18:21]
	v_mfma_f32_16x16x32_bf16 v[14:17], v[204:207], v[188:191], v[14:17]
	v_mfma_f32_16x16x32_bf16 v[10:13], v[212:215], v[188:191], v[10:13]
	v_mfma_f32_16x16x32_bf16 v[6:9], v[204:207], v[196:199], v[6:9]
	v_mfma_f32_16x16x32_bf16 v[2:5], v[212:215], v[196:199], v[2:5]
	s_barrier
	s_setprio 0
	s_add_i32 s69, 0, 0x18000
	v_add_u32_e32 v154, s69, v163
	ds_read_b128 v[100:103], v154
	ds_read_b128 v[104:107], v154 offset:1024
	ds_read_b128 v[150:153], v154 offset:2048
	ds_read_b128 v[154:157], v154 offset:3072
	s_add_u32 s0, s26, 0x40000
	s_addc_u32 s1, s27, 0
	s_mov_b32 m0, s57
	v_lshl_add_u64 v[200:201], s[0:1], 0, v[144:145]
	ds_read_b128 v[158:161], v165 offset:32768
	ds_read_b128 v[172:175], v165 offset:33792
	ds_read_b128 v[176:179], v165 offset:34816
	ds_read_b128 v[180:183], v165 offset:35840
	ds_read_b128 v[184:187], v165 offset:36864
	ds_read_b128 v[188:191], v165 offset:37888
	ds_read_b128 v[192:195], v165 offset:38912
	ds_read_b128 v[196:199], v165 offset:39936
	global_load_lds_dwordx4 v[200:201], off
	v_lshl_add_u64 v[200:201], s[0:1], 0, v[142:143]
	s_mov_b32 m0, s58
	s_nop 0
	global_load_lds_dwordx4 v[200:201], off
	s_waitcnt vmcnt(10) lgkmcnt(8)
	s_setprio 1
	s_barrier
	s_waitcnt lgkmcnt(0)
	v_mfma_f32_16x16x32_bf16 v[136:139], v[100:103], v[158:161], v[136:139]
	v_mfma_f32_16x16x32_bf16 v[132:135], v[150:153], v[158:161], v[132:135]
	v_mfma_f32_16x16x32_bf16 v[128:131], v[100:103], v[176:179], v[128:131]
	v_mfma_f32_16x16x32_bf16 v[124:127], v[150:153], v[176:179], v[124:127]
	v_mfma_f32_16x16x32_bf16 v[120:123], v[100:103], v[184:187], v[120:123]
	v_mfma_f32_16x16x32_bf16 v[116:119], v[150:153], v[184:187], v[116:119]
	v_mfma_f32_16x16x32_bf16 v[112:115], v[100:103], v[192:195], v[112:115]
	v_mfma_f32_16x16x32_bf16 v[108:111], v[150:153], v[192:195], v[108:111]
	v_mfma_f32_16x16x32_bf16 v[136:139], v[104:107], v[172:175], v[136:139]
	v_mfma_f32_16x16x32_bf16 v[132:135], v[154:157], v[172:175], v[132:135]
	v_mfma_f32_16x16x32_bf16 v[128:131], v[104:107], v[180:183], v[128:131]
	v_mfma_f32_16x16x32_bf16 v[124:127], v[154:157], v[180:183], v[124:127]
	v_mfma_f32_16x16x32_bf16 v[120:123], v[104:107], v[188:191], v[120:123]
	v_mfma_f32_16x16x32_bf16 v[116:119], v[154:157], v[188:191], v[116:119]
	v_mfma_f32_16x16x32_bf16 v[112:115], v[104:107], v[196:199], v[112:115]
	v_mfma_f32_16x16x32_bf16 v[108:111], v[154:157], v[196:199], v[108:111]
	s_barrier
	s_setprio 0
	s_add_i32 s26, 0, 0x1c000
	s_add_i32 s0, s69, s36
	v_add_u32_e32 v212, s26, v163
	v_lshl_add_u64 v[166:167], v[166:167], 0, s[12:13]
	s_mov_b32 m0, s0
	ds_read_b128 v[200:203], v212
	ds_read_b128 v[204:207], v212 offset:1024
	ds_read_b128 v[208:211], v212 offset:2048
	ds_read_b128 v[212:215], v212 offset:3072
	global_load_lds_dwordx4 v[166:167], off
	v_lshl_add_u64 v[166:167], v[168:169], 0, s[12:13]
	s_add_i32 m0, s0, 0x2000
	s_nop 0
	global_load_lds_dwordx4 v[166:167], off
	s_waitcnt vmcnt(10)
	s_setprio 1
	s_barrier
	s_waitcnt lgkmcnt(0)
	v_mfma_f32_16x16x32_bf16 v[64:67], v[200:203], v[158:161], v[64:67]
	v_mfma_f32_16x16x32_bf16 v[60:63], v[208:211], v[158:161], v[60:63]
	v_mfma_f32_16x16x32_bf16 v[56:59], v[200:203], v[176:179], v[56:59]
	v_mfma_f32_16x16x32_bf16 v[52:55], v[208:211], v[176:179], v[52:55]
	v_mfma_f32_16x16x32_bf16 v[48:51], v[200:203], v[184:187], v[48:51]
	v_mfma_f32_16x16x32_bf16 v[44:47], v[208:211], v[184:187], v[44:47]
	v_mfma_f32_16x16x32_bf16 v[40:43], v[200:203], v[192:195], v[40:43]
	v_mfma_f32_16x16x32_bf16 v[36:39], v[208:211], v[192:195], v[36:39]
	v_mfma_f32_16x16x32_bf16 v[64:67], v[204:207], v[172:175], v[64:67]
	v_mfma_f32_16x16x32_bf16 v[60:63], v[212:215], v[172:175], v[60:63]
	v_mfma_f32_16x16x32_bf16 v[56:59], v[204:207], v[180:183], v[56:59]
	v_mfma_f32_16x16x32_bf16 v[52:55], v[212:215], v[180:183], v[52:55]
	v_mfma_f32_16x16x32_bf16 v[48:51], v[204:207], v[188:191], v[48:51]
	v_mfma_f32_16x16x32_bf16 v[44:47], v[212:215], v[188:191], v[44:47]
	v_mfma_f32_16x16x32_bf16 v[40:43], v[204:207], v[196:199], v[40:43]
	v_mfma_f32_16x16x32_bf16 v[36:39], v[212:215], v[196:199], v[36:39]
	s_barrier
	s_setprio 0
	s_mov_b32 m0, s28
	v_lshl_add_u64 v[166:167], v[216:217], 0, s[12:13]
	ds_read_b128 v[158:161], v165 offset:49152
	ds_read_b128 v[172:175], v165 offset:50176
	ds_read_b128 v[176:179], v165 offset:51200
	ds_read_b128 v[180:183], v165 offset:52224
	ds_read_b128 v[184:187], v165 offset:53248
	ds_read_b128 v[188:191], v165 offset:54272
	ds_read_b128 v[192:195], v165 offset:55296
	ds_read_b128 v[196:199], v165 offset:56320
	global_load_lds_dwordx4 v[166:167], off
	v_lshl_add_u64 v[166:167], v[218:219], 0, s[12:13]
	s_mov_b32 m0, s29
	s_nop 0
	global_load_lds_dwordx4 v[166:167], off
	s_setprio 1
	s_barrier
	s_waitcnt lgkmcnt(0)
	v_mfma_f32_16x16x32_bf16 v[96:99], v[100:103], v[158:161], v[96:99]
	v_mfma_f32_16x16x32_bf16 v[92:95], v[150:153], v[158:161], v[92:95]
	v_mfma_f32_16x16x32_bf16 v[88:91], v[100:103], v[176:179], v[88:91]
	v_mfma_f32_16x16x32_bf16 v[84:87], v[150:153], v[176:179], v[84:87]
	v_mfma_f32_16x16x32_bf16 v[80:83], v[100:103], v[184:187], v[80:83]
	v_mfma_f32_16x16x32_bf16 v[76:79], v[150:153], v[184:187], v[76:79]
	v_mfma_f32_16x16x32_bf16 v[72:75], v[100:103], v[192:195], v[72:75]
	v_mfma_f32_16x16x32_bf16 v[68:71], v[150:153], v[192:195], v[68:71]
	v_mfma_f32_16x16x32_bf16 v[96:99], v[104:107], v[172:175], v[96:99]
	v_mfma_f32_16x16x32_bf16 v[92:95], v[154:157], v[172:175], v[92:95]
	v_mfma_f32_16x16x32_bf16 v[88:91], v[104:107], v[180:183], v[88:91]
	v_mfma_f32_16x16x32_bf16 v[84:87], v[154:157], v[180:183], v[84:87]
	v_mfma_f32_16x16x32_bf16 v[80:83], v[104:107], v[188:191], v[80:83]
	v_mfma_f32_16x16x32_bf16 v[76:79], v[154:157], v[188:191], v[76:79]
	v_mfma_f32_16x16x32_bf16 v[72:75], v[104:107], v[196:199], v[72:75]
	v_mfma_f32_16x16x32_bf16 v[68:71], v[154:157], v[196:199], v[68:71]
	s_barrier
	s_setprio 0
	s_add_u32 s0, s24, 0x40080
	s_addc_u32 s1, s25, 0
	s_add_i32 s24, s26, s36
	v_lshl_add_u64 v[100:101], s[0:1], 0, v[26:27]
	s_mov_b32 m0, s24
	s_nop 0
	global_load_lds_dwordx4 v[100:101], off
	v_lshl_add_u64 v[100:101], s[0:1], 0, v[140:141]
	s_add_i32 m0, s24, 0x2000
	s_nop 0
	global_load_lds_dwordx4 v[100:101], off
	s_waitcnt vmcnt(10)
	s_setprio 1
	s_barrier
	v_mfma_f32_16x16x32_bf16 v[32:35], v[200:203], v[158:161], v[32:35]
	v_mfma_f32_16x16x32_bf16 v[28:31], v[208:211], v[158:161], v[28:31]
	v_mfma_f32_16x16x32_bf16 v[22:25], v[200:203], v[176:179], v[22:25]
	v_mfma_f32_16x16x32_bf16 v[18:21], v[208:211], v[176:179], v[18:21]
	v_mfma_f32_16x16x32_bf16 v[14:17], v[200:203], v[184:187], v[14:17]
	v_mfma_f32_16x16x32_bf16 v[10:13], v[208:211], v[184:187], v[10:13]
	v_mfma_f32_16x16x32_bf16 v[6:9], v[200:203], v[192:195], v[6:9]
	v_mfma_f32_16x16x32_bf16 v[2:5], v[208:211], v[192:195], v[2:5]
	v_mfma_f32_16x16x32_bf16 v[32:35], v[204:207], v[172:175], v[32:35]
	v_mfma_f32_16x16x32_bf16 v[28:31], v[212:215], v[172:175], v[28:31]
	v_mfma_f32_16x16x32_bf16 v[22:25], v[204:207], v[180:183], v[22:25]
	v_mfma_f32_16x16x32_bf16 v[18:21], v[212:215], v[180:183], v[18:21]
	v_mfma_f32_16x16x32_bf16 v[14:17], v[204:207], v[188:191], v[14:17]
	v_mfma_f32_16x16x32_bf16 v[10:13], v[212:215], v[188:191], v[10:13]
	v_mfma_f32_16x16x32_bf16 v[6:9], v[204:207], v[196:199], v[6:9]
	v_mfma_f32_16x16x32_bf16 v[2:5], v[212:215], v[196:199], v[2:5]
	s_barrier
	s_setprio 0
	s_add_i32 s68, s68, 2
	s_add_u32 s22, s22, 0x100
	s_addc_u32 s23, s23, 0
	s_add_u32 s51, s51, 0x100
	s_addc_u32 s59, s59, 0
	s_cmp_gt_u32 s68, 13
	s_cbranch_scc0 .LBB0_479
	s_cmpk_gt_i32 s34, 0xff
	s_mov_b64 s[22:23], 0xb000
	s_cbranch_scc1 .LBB0_482
	s_ashr_i32 s0, s34, 5
	s_mul_hi_i32 s23, s0, 0x1600
	s_mul_i32 s22, s0, 0x1600

.LBB0_887:
	s_add_u32 s24, s22, 0x100
	s_addc_u32 s25, s23, 0
	s_add_i32 s0, 0, 0x10000
	v_add_u32_e32 v26, s0, v191
	ds_read_b128 v[134:137], v26
	ds_read_b128 v[138:141], v26 offset:1024
	ds_read_b128 v[142:145], v26 offset:2048
	ds_read_b128 v[146:149], v26 offset:3072
	s_cmp_eq_u32 s51, 4
	s_cselect_b32 s29, s47, s25
	s_cselect_b32 s28, s46, s24
	s_cselect_b32 s27, s18, s50
	s_cselect_b32 s26, s19, s45
	v_lshl_add_u64 v[28:29], s[22:23], 0, v[180:181]
	s_add_i32 m0, s58, 0xc000
	ds_read_b128 v[150:153], v193
	ds_read_b128 v[154:157], v193 offset:1024
	ds_read_b128 v[158:161], v193 offset:2048
	ds_read_b128 v[162:165], v193 offset:3072
	ds_read_b128 v[184:187], v193 offset:4096
	ds_read_b128 v[194:197], v193 offset:5120
	ds_read_b128 v[198:201], v193 offset:6144
	ds_read_b128 v[202:205], v193 offset:7168
	global_load_lds_dwordx4 v[28:29], off
	v_lshl_add_u64 v[28:29], s[22:23], 0, v[182:183]
	s_add_i32 m0, s58, 0xe000
	s_nop 0
	global_load_lds_dwordx4 v[28:29], off
	s_waitcnt vmcnt(10) lgkmcnt(8)
	s_setprio 1
	s_barrier
	s_waitcnt lgkmcnt(0)
	v_mfma_f32_16x16x32_bf16 v[130:133], v[134:137], v[150:153], v[130:133]
	v_mfma_f32_16x16x32_bf16 v[126:129], v[142:145], v[150:153], v[126:129]
	v_mfma_f32_16x16x32_bf16 v[122:125], v[134:137], v[158:161], v[122:125]
	v_mfma_f32_16x16x32_bf16 v[118:121], v[142:145], v[158:161], v[118:121]
	v_mfma_f32_16x16x32_bf16 v[114:117], v[134:137], v[184:187], v[114:117]
	v_mfma_f32_16x16x32_bf16 v[110:113], v[142:145], v[184:187], v[110:113]
	v_mfma_f32_16x16x32_bf16 v[106:109], v[134:137], v[198:201], v[106:109]
	v_mfma_f32_16x16x32_bf16 v[102:105], v[142:145], v[198:201], v[102:105]
	v_mfma_f32_16x16x32_bf16 v[130:133], v[138:141], v[154:157], v[130:133]
	v_mfma_f32_16x16x32_bf16 v[126:129], v[146:149], v[154:157], v[126:129]
	v_mfma_f32_16x16x32_bf16 v[122:125], v[138:141], v[162:165], v[122:125]
	v_mfma_f32_16x16x32_bf16 v[118:121], v[146:149], v[162:165], v[118:121]
	v_mfma_f32_16x16x32_bf16 v[114:117], v[138:141], v[194:197], v[114:117]
	v_mfma_f32_16x16x32_bf16 v[110:113], v[146:149], v[194:197], v[110:113]
	v_mfma_f32_16x16x32_bf16 v[106:109], v[138:141], v[202:205], v[106:109]
	v_mfma_f32_16x16x32_bf16 v[102:105], v[146:149], v[202:205], v[102:105]
	s_barrier
	s_setprio 0
	s_add_i32 s22, 0, 0x14000
	s_add_i32 s0, s0, s55
	v_add_u32_e32 v26, s22, v191
	v_lshl_add_u64 v[166:167], s[26:27], 0, v[176:177]
	s_mov_b32 m0, s0
	ds_read_b128 v[206:209], v26
	ds_read_b128 v[210:213], v26 offset:1024
	ds_read_b128 v[214:217], v26 offset:2048
	ds_read_b128 v[218:221], v26 offset:3072
	global_load_lds_dwordx4 v[166:167], off
	v_lshl_add_u64 v[168:169], s[26:27], 0, v[172:173]
	s_add_i32 m0, s0, 0x2000
	s_nop 0
	global_load_lds_dwordx4 v[168:169], off
	s_waitcnt vmcnt(10)
	s_setprio 1
	s_barrier
	s_waitcnt lgkmcnt(0)
	v_mfma_f32_16x16x32_bf16 v[98:101], v[206:209], v[150:153], v[98:101]
	v_mfma_f32_16x16x32_bf16 v[94:97], v[214:217], v[150:153], v[94:97]
	v_mfma_f32_16x16x32_bf16 v[90:93], v[206:209], v[158:161], v[90:93]
	v_mfma_f32_16x16x32_bf16 v[86:89], v[214:217], v[158:161], v[86:89]
	v_mfma_f32_16x16x32_bf16 v[82:85], v[206:209], v[184:187], v[82:85]
	v_mfma_f32_16x16x32_bf16 v[78:81], v[214:217], v[184:187], v[78:81]
	v_mfma_f32_16x16x32_bf16 v[74:77], v[206:209], v[198:201], v[74:77]
	v_mfma_f32_16x16x32_bf16 v[70:73], v[214:217], v[198:201], v[70:73]
	v_mfma_f32_16x16x32_bf16 v[98:101], v[210:213], v[154:157], v[98:101]
	v_mfma_f32_16x16x32_bf16 v[94:97], v[218:221], v[154:157], v[94:97]
	v_mfma_f32_16x16x32_bf16 v[90:93], v[210:213], v[162:165], v[90:93]
	v_mfma_f32_16x16x32_bf16 v[86:89], v[218:221], v[162:165], v[86:89]
	v_mfma_f32_16x16x32_bf16 v[82:85], v[210:213], v[194:197], v[82:85]
	v_mfma_f32_16x16x32_bf16 v[78:81], v[218:221], v[194:197], v[78:81]
	v_mfma_f32_16x16x32_bf16 v[74:77], v[210:213], v[202:205], v[74:77]
	v_mfma_f32_16x16x32_bf16 v[70:73], v[218:221], v[202:205], v[70:73]
	s_barrier
	s_setprio 0
	s_mov_b32 m0, s58
	v_lshl_add_u64 v[188:189], s[28:29], 0, v[178:179]
	ds_read_b128 v[150:153], v193 offset:16384
	ds_read_b128 v[154:157], v193 offset:17408
	ds_read_b128 v[158:161], v193 offset:18432
	ds_read_b128 v[162:165], v193 offset:19456
	ds_read_b128 v[184:187], v193 offset:20480
	ds_read_b128 v[194:197], v193 offset:21504
	ds_read_b128 v[198:201], v193 offset:22528
	ds_read_b128 v[202:205], v193 offset:23552
	global_load_lds_dwordx4 v[188:189], off
	v_lshl_add_u64 v[222:223], s[28:29], 0, v[174:175]
	s_mov_b32 m0, s59
	s_nop 0
	global_load_lds_dwordx4 v[222:223], off
	s_setprio 1
	s_barrier
	s_waitcnt lgkmcnt(0)
	v_mfma_f32_16x16x32_bf16 v[66:69], v[134:137], v[150:153], v[66:69]
	v_mfma_f32_16x16x32_bf16 v[62:65], v[142:145], v[150:153], v[62:65]
	v_mfma_f32_16x16x32_bf16 v[58:61], v[134:137], v[158:161], v[58:61]
	v_mfma_f32_16x16x32_bf16 v[54:57], v[142:145], v[158:161], v[54:57]
	v_mfma_f32_16x16x32_bf16 v[50:53], v[134:137], v[184:187], v[50:53]
	v_mfma_f32_16x16x32_bf16 v[46:49], v[142:145], v[184:187], v[46:49]
	v_mfma_f32_16x16x32_bf16 v[42:45], v[134:137], v[198:201], v[42:45]
	v_mfma_f32_16x16x32_bf16 v[38:41], v[142:145], v[198:201], v[38:41]
	v_mfma_f32_16x16x32_bf16 v[66:69], v[138:141], v[154:157], v[66:69]
	v_mfma_f32_16x16x32_bf16 v[62:65], v[146:149], v[154:157], v[62:65]
	v_mfma_f32_16x16x32_bf16 v[58:61], v[138:141], v[162:165], v[58:61]
	v_mfma_f32_16x16x32_bf16 v[54:57], v[146:149], v[162:165], v[54:57]
	v_mfma_f32_16x16x32_bf16 v[50:53], v[138:141], v[194:197], v[50:53]
	v_mfma_f32_16x16x32_bf16 v[46:49], v[146:149], v[194:197], v[46:49]
	v_mfma_f32_16x16x32_bf16 v[42:45], v[138:141], v[202:205], v[42:45]
	v_mfma_f32_16x16x32_bf16 v[38:41], v[146:149], v[202:205], v[38:41]
	s_barrier
	s_setprio 0
	s_add_u32 s0, s26, 0x20000
	s_addc_u32 s1, s27, 0
	s_add_i32 s22, s22, s55
	v_lshl_add_u64 v[28:29], s[0:1], 0, v[176:177]
	s_mov_b32 m0, s22
	s_nop 0
	global_load_lds_dwordx4 v[28:29], off
	v_lshl_add_u64 v[28:29], s[0:1], 0, v[172:173]
	s_add_i32 m0, s22, 0x2000
	s_nop 0
	global_load_lds_dwordx4 v[28:29], off
	s_waitcnt vmcnt(10)
	s_setprio 1
	s_barrier
	v_mfma_f32_16x16x32_bf16 v[34:37], v[206:209], v[150:153], v[34:37]
	v_mfma_f32_16x16x32_bf16 v[28:31], v[214:217], v[150:153], v[30:33]
	v_mfma_f32_16x16x32_bf16 v[22:25], v[206:209], v[158:161], v[22:25]
	v_mfma_f32_16x16x32_bf16 v[18:21], v[214:217], v[158:161], v[18:21]
	v_mfma_f32_16x16x32_bf16 v[14:17], v[206:209], v[184:187], v[14:17]
	v_mfma_f32_16x16x32_bf16 v[10:13], v[214:217], v[184:187], v[10:13]
	v_mfma_f32_16x16x32_bf16 v[6:9], v[206:209], v[198:201], v[6:9]
	v_mfma_f32_16x16x32_bf16 v[2:5], v[214:217], v[198:201], v[2:5]
	v_mfma_f32_16x16x32_bf16 v[34:37], v[210:213], v[154:157], v[34:37]
	v_mfma_f32_16x16x32_bf16 v[28:31], v[218:221], v[154:157], v[28:31]
	v_mfma_f32_16x16x32_bf16 v[22:25], v[210:213], v[162:165], v[22:25]
	v_mfma_f32_16x16x32_bf16 v[18:21], v[218:221], v[162:165], v[18:21]
	v_mfma_f32_16x16x32_bf16 v[14:17], v[210:213], v[194:197], v[14:17]
	v_mfma_f32_16x16x32_bf16 v[10:13], v[218:221], v[194:197], v[10:13]
	v_mfma_f32_16x16x32_bf16 v[6:9], v[210:213], v[202:205], v[6:9]
	v_mfma_f32_16x16x32_bf16 v[2:5], v[218:221], v[202:205], v[2:5]
	s_barrier
	s_setprio 0
	s_add_i32 s22, 0, 0x18000
	v_add_u32_e32 v26, s22, v191
	ds_read_b128 v[134:137], v26
	ds_read_b128 v[138:141], v26 offset:1024
	ds_read_b128 v[142:145], v26 offset:2048
	ds_read_b128 v[146:149], v26 offset:3072
	s_add_u32 s0, s28, 0x140000
	s_addc_u32 s1, s29, 0
	s_mov_b32 m0, s68
	v_lshl_add_u64 v[32:33], s[0:1], 0, v[178:179]
	ds_read_b128 v[150:153], v193 offset:32768
	ds_read_b128 v[154:157], v193 offset:33792
	ds_read_b128 v[158:161], v193 offset:34816
	ds_read_b128 v[162:165], v193 offset:35840
	ds_read_b128 v[184:187], v193 offset:36864
	ds_read_b128 v[194:197], v193 offset:37888
	ds_read_b128 v[198:201], v193 offset:38912
	ds_read_b128 v[202:205], v193 offset:39936
	global_load_lds_dwordx4 v[32:33], off
	v_lshl_add_u64 v[32:33], s[0:1], 0, v[174:175]
	s_mov_b32 m0, s69
	s_nop 0
	global_load_lds_dwordx4 v[32:33], off
	s_waitcnt vmcnt(10) lgkmcnt(8)
	s_setprio 1
	s_barrier
	s_waitcnt lgkmcnt(0)
	v_mfma_f32_16x16x32_bf16 v[130:133], v[134:137], v[150:153], v[130:133]
	v_mfma_f32_16x16x32_bf16 v[126:129], v[142:145], v[150:153], v[126:129]
	v_mfma_f32_16x16x32_bf16 v[122:125], v[134:137], v[158:161], v[122:125]
	v_mfma_f32_16x16x32_bf16 v[118:121], v[142:145], v[158:161], v[118:121]
	v_mfma_f32_16x16x32_bf16 v[114:117], v[134:137], v[184:187], v[114:117]
	v_mfma_f32_16x16x32_bf16 v[110:113], v[142:145], v[184:187], v[110:113]
	v_mfma_f32_16x16x32_bf16 v[106:109], v[134:137], v[198:201], v[106:109]
	v_mfma_f32_16x16x32_bf16 v[102:105], v[142:145], v[198:201], v[102:105]
	v_mfma_f32_16x16x32_bf16 v[130:133], v[138:141], v[154:157], v[130:133]
	v_mfma_f32_16x16x32_bf16 v[126:129], v[146:149], v[154:157], v[126:129]
	v_mfma_f32_16x16x32_bf16 v[122:125], v[138:141], v[162:165], v[122:125]
	v_mfma_f32_16x16x32_bf16 v[118:121], v[146:149], v[162:165], v[118:121]
	v_mfma_f32_16x16x32_bf16 v[114:117], v[138:141], v[194:197], v[114:117]
	v_mfma_f32_16x16x32_bf16 v[110:113], v[146:149], v[194:197], v[110:113]
	v_mfma_f32_16x16x32_bf16 v[106:109], v[138:141], v[202:205], v[106:109]
	v_mfma_f32_16x16x32_bf16 v[102:105], v[146:149], v[202:205], v[102:105]
	s_barrier
	s_setprio 0
	s_add_i32 s23, 0, 0x1c000
	s_add_i32 s0, s22, s55
	v_add_u32_e32 v26, s23, v191
	v_lshl_add_u64 v[32:33], v[166:167], 0, s[12:13]
	s_mov_b32 m0, s0
	ds_read_b128 v[206:209], v26
	ds_read_b128 v[210:213], v26 offset:1024
	ds_read_b128 v[214:217], v26 offset:2048
	ds_read_b128 v[218:221], v26 offset:3072
	global_load_lds_dwordx4 v[32:33], off
	v_lshl_add_u64 v[32:33], v[168:169], 0, s[12:13]
	s_add_i32 m0, s0, 0x2000
	s_nop 0
	global_load_lds_dwordx4 v[32:33], off
	s_waitcnt vmcnt(10)
	s_setprio 1
	s_barrier
	s_waitcnt lgkmcnt(0)
	v_mfma_f32_16x16x32_bf16 v[98:101], v[206:209], v[150:153], v[98:101]
	v_mfma_f32_16x16x32_bf16 v[94:97], v[214:217], v[150:153], v[94:97]
	v_mfma_f32_16x16x32_bf16 v[90:93], v[206:209], v[158:161], v[90:93]
	v_mfma_f32_16x16x32_bf16 v[86:89], v[214:217], v[158:161], v[86:89]
	v_mfma_f32_16x16x32_bf16 v[82:85], v[206:209], v[184:187], v[82:85]
	v_mfma_f32_16x16x32_bf16 v[78:81], v[214:217], v[184:187], v[78:81]
	v_mfma_f32_16x16x32_bf16 v[74:77], v[206:209], v[198:201], v[74:77]
	v_mfma_f32_16x16x32_bf16 v[70:73], v[214:217], v[198:201], v[70:73]
	v_mfma_f32_16x16x32_bf16 v[98:101], v[210:213], v[154:157], v[98:101]
	v_mfma_f32_16x16x32_bf16 v[94:97], v[218:221], v[154:157], v[94:97]
	v_mfma_f32_16x16x32_bf16 v[90:93], v[210:213], v[162:165], v[90:93]
	v_mfma_f32_16x16x32_bf16 v[86:89], v[218:221], v[162:165], v[86:89]
	v_mfma_f32_16x16x32_bf16 v[82:85], v[210:213], v[194:197], v[82:85]
	v_mfma_f32_16x16x32_bf16 v[78:81], v[218:221], v[194:197], v[78:81]
	v_mfma_f32_16x16x32_bf16 v[74:77], v[210:213], v[202:205], v[74:77]
	v_mfma_f32_16x16x32_bf16 v[70:73], v[218:221], v[202:205], v[70:73]
	s_barrier
	s_setprio 0
	s_mov_b32 m0, s30
	v_lshl_add_u64 v[32:33], v[188:189], 0, s[12:13]
	ds_read_b128 v[150:153], v193 offset:49152
	ds_read_b128 v[154:157], v193 offset:50176
	ds_read_b128 v[158:161], v193 offset:51200
	ds_read_b128 v[162:165], v193 offset:52224
	ds_read_b128 v[184:187], v193 offset:53248
	ds_read_b128 v[194:197], v193 offset:54272
	ds_read_b128 v[198:201], v193 offset:55296
	ds_read_b128 v[202:205], v193 offset:56320
	global_load_lds_dwordx4 v[32:33], off
	v_lshl_add_u64 v[32:33], v[222:223], 0, s[12:13]
	s_mov_b32 m0, s34
	s_nop 0
	global_load_lds_dwordx4 v[32:33], off
	s_setprio 1
	s_barrier
	s_waitcnt lgkmcnt(0)
	v_mfma_f32_16x16x32_bf16 v[66:69], v[134:137], v[150:153], v[66:69]
	v_mfma_f32_16x16x32_bf16 v[62:65], v[142:145], v[150:153], v[62:65]
	v_mfma_f32_16x16x32_bf16 v[58:61], v[134:137], v[158:161], v[58:61]
	v_mfma_f32_16x16x32_bf16 v[54:57], v[142:145], v[158:161], v[54:57]
	v_mfma_f32_16x16x32_bf16 v[50:53], v[134:137], v[184:187], v[50:53]
	v_mfma_f32_16x16x32_bf16 v[46:49], v[142:145], v[184:187], v[46:49]
	v_mfma_f32_16x16x32_bf16 v[42:45], v[134:137], v[198:201], v[42:45]
	v_mfma_f32_16x16x32_bf16 v[38:41], v[142:145], v[198:201], v[38:41]
	v_mfma_f32_16x16x32_bf16 v[66:69], v[138:141], v[154:157], v[66:69]
	v_mfma_f32_16x16x32_bf16 v[62:65], v[146:149], v[154:157], v[62:65]
	v_mfma_f32_16x16x32_bf16 v[58:61], v[138:141], v[162:165], v[58:61]
	v_mfma_f32_16x16x32_bf16 v[54:57], v[146:149], v[162:165], v[54:57]
	v_mfma_f32_16x16x32_bf16 v[50:53], v[138:141], v[194:197], v[50:53]
	v_mfma_f32_16x16x32_bf16 v[46:49], v[146:149], v[194:197], v[46:49]
	v_mfma_f32_16x16x32_bf16 v[42:45], v[138:141], v[202:205], v[42:45]
	v_mfma_f32_16x16x32_bf16 v[38:41], v[146:149], v[202:205], v[38:41]
	s_barrier
	s_setprio 0
	s_add_u32 s0, s26, 0x20080
	s_addc_u32 s1, s27, 0
	s_add_i32 s22, s23, s55
	v_lshl_add_u64 v[32:33], s[0:1], 0, v[176:177]
	s_mov_b32 m0, s22
	s_nop 0
	global_load_lds_dwordx4 v[32:33], off
	v_lshl_add_u64 v[32:33], s[0:1], 0, v[172:173]
	s_add_i32 m0, s22, 0x2000
	s_nop 0
	global_load_lds_dwordx4 v[32:33], off
	s_waitcnt vmcnt(10)
	s_setprio 1
	s_barrier
	v_mfma_f32_16x16x32_bf16 v[32:35], v[206:209], v[150:153], v[34:37]
	v_mfma_f32_16x16x32_bf16 v[28:31], v[214:217], v[150:153], v[28:31]
	v_mfma_f32_16x16x32_bf16 v[22:25], v[206:209], v[158:161], v[22:25]
	v_mfma_f32_16x16x32_bf16 v[18:21], v[214:217], v[158:161], v[18:21]
	v_mfma_f32_16x16x32_bf16 v[14:17], v[206:209], v[184:187], v[14:17]
	v_mfma_f32_16x16x32_bf16 v[10:13], v[214:217], v[184:187], v[10:13]
	v_mfma_f32_16x16x32_bf16 v[6:9], v[206:209], v[198:201], v[6:9]
	v_mfma_f32_16x16x32_bf16 v[2:5], v[214:217], v[198:201], v[2:5]
	v_mfma_f32_16x16x32_bf16 v[34:37], v[210:213], v[154:157], v[32:35]
	v_mfma_f32_16x16x32_bf16 v[30:33], v[218:221], v[154:157], v[28:31]
	v_mfma_f32_16x16x32_bf16 v[22:25], v[210:213], v[162:165], v[22:25]
	v_mfma_f32_16x16x32_bf16 v[18:21], v[218:221], v[162:165], v[18:21]
	v_mfma_f32_16x16x32_bf16 v[14:17], v[210:213], v[194:197], v[14:17]
	v_mfma_f32_16x16x32_bf16 v[10:13], v[218:221], v[194:197], v[10:13]
	v_mfma_f32_16x16x32_bf16 v[6:9], v[210:213], v[202:205], v[6:9]
	v_mfma_f32_16x16x32_bf16 v[2:5], v[218:221], v[202:205], v[2:5]
	s_barrier
	s_setprio 0
	s_add_i32 s51, s51, 2
	s_add_u32 s45, s45, 0x100
	s_addc_u32 s50, s50, 0
	s_cmp_gt_u32 s51, 5
	s_mov_b64 s[22:23], s[24:25]
	s_cbranch_scc0 .LBB0_887
	v_lshl_or_b32 v186, s17, 8, v192
	v_ashrrev_i32_e32 v187, 31, v186
	v_lshl_add_u32 v26, s16, 8, v190
	s_cmp_lg_u32 s81, 0
	v_lshl_add_u64 v[28:29], v[186:187], 1, s[40:41]
	s_cselect_b64 s[50:51], -1, 0
	s_cmp_eq_u32 s81, 0
	v_mad_i64_i32 v[184:185], s[0:1], v26, s78, v[28:29]
	v_or_b32_e32 v198, 16, v26
	v_or_b32_e32 v197, 32, v26
	v_or_b32_e32 v196, 48, v26
	v_add_u32_e32 v195, 0x80, v26
	v_add_u32_e32 v194, 0x90, v26
	s_cbranch_scc1 .LBB0_894
	v_add_co_u32_e32 v134, vcc, 0x2000, v184
	v_mad_i64_i32 v[166:167], s[0:1], v26, s78, 0
	s_nop 0
	v_addc_co_u32_e32 v135, vcc, 0, v185, vcc
	global_load_dwordx4 v[162:165], v[134:135], off
	global_load_dwordx4 v[158:161], v[134:135], off offset:256
	v_mad_i64_i32 v[134:135], s[0:1], v198, s78, v[28:29]
	v_add_co_u32_e32 v134, vcc, 0x2000, v134
	v_lshlrev_b64 v[186:187], 1, v[186:187]
	s_nop 0
	v_addc_co_u32_e32 v135, vcc, 0, v135, vcc
	global_load_dwordx4 v[154:157], v[134:135], off
	global_load_dwordx4 v[150:153], v[134:135], off offset:256
	v_mad_i64_i32 v[134:135], s[0:1], v197, s78, v[28:29]
	v_add_co_u32_e32 v134, vcc, 0x2000, v134
	s_movk_i32 s16, 0x2000
	s_nop 0
	v_addc_co_u32_e32 v135, vcc, 0, v135, vcc
	global_load_dwordx4 v[146:149], v[134:135], off
	global_load_dwordx4 v[142:145], v[134:135], off offset:256
	v_mad_i64_i32 v[134:135], s[0:1], v196, s78, v[28:29]
	v_add_co_u32_e32 v134, vcc, 0x2000, v134
	s_nop 1
	v_addc_co_u32_e32 v135, vcc, 0, v135, vcc
	global_load_dwordx4 v[138:141], v[134:135], off
	s_nop 0
	global_load_dwordx4 v[134:137], v[134:135], off offset:256
	s_waitcnt vmcnt(0)
	v_lshlrev_b32_e32 v168, 16, v162
	v_and_b32_e32 v162, 0xffff0000, v162
	v_mul_f32_e32 v162, 0xbfb8aa3b, v162
	v_exp_f32_e32 v162, v162
	v_mul_f32_e32 v168, 0xbfb8aa3b, v168
	v_exp_f32_e32 v168, v168
	v_add_f32_e32 v162, 1.0, v162
	v_rcp_f32_e32 v169, v162
	v_lshlrev_b32_e32 v162, 16, v163
	v_and_b32_e32 v163, 0xffff0000, v163
	v_mul_f32_e32 v162, 0xbfb8aa3b, v162
	v_mul_f32_e32 v163, 0xbfb8aa3b, v163
	v_exp_f32_e32 v162, v162
	v_exp_f32_e32 v163, v163
	v_add_f32_e32 v168, 1.0, v168
	v_rcp_f32_e32 v168, v168
	v_add_f32_e32 v162, 1.0, v162
	v_add_f32_e32 v163, 1.0, v163
	v_rcp_f32_e32 v162, v162
	v_rcp_f32_e32 v163, v163
	v_pk_mul_f32 v[168:169], v[130:131], v[168:169]
	v_pk_mul_f32 v[188:189], v[132:133], v[162:163]
	v_lshlrev_b32_e32 v162, 16, v164
	v_and_b32_e32 v163, 0xffff0000, v164
	v_mul_f32_e32 v162, 0xbfb8aa3b, v162
	v_mul_f32_e32 v163, 0xbfb8aa3b, v163
	v_exp_f32_e32 v162, v162
	v_exp_f32_e32 v163, v163
	v_add_f32_e32 v162, 1.0, v162
	v_add_f32_e32 v163, 1.0, v163
	v_rcp_f32_e32 v162, v162
	v_rcp_f32_e32 v163, v163
	s_nop 0
	v_pk_mul_f32 v[200:201], v[126:127], v[162:163]
	v_lshlrev_b32_e32 v162, 16, v165
	v_and_b32_e32 v163, 0xffff0000, v165
	v_mul_f32_e32 v162, 0xbfb8aa3b, v162
	v_mul_f32_e32 v163, 0xbfb8aa3b, v163
	v_exp_f32_e32 v162, v162
	v_exp_f32_e32 v163, v163
	v_cvt_pk_bf16_f32 v164, v200, v201
	v_add_f32_e32 v162, 1.0, v162
	v_add_f32_e32 v163, 1.0, v163
	v_rcp_f32_e32 v162, v162
	v_rcp_f32_e32 v163, v163
	s_nop 0
	v_pk_mul_f32 v[202:203], v[128:129], v[162:163]
	v_cvt_pk_bf16_f32 v163, v188, v189
	v_lshl_add_u64 v[188:189], s[42:43], 0, v[166:167]
	v_cvt_pk_bf16_f32 v162, v168, v169
	v_cvt_pk_bf16_f32 v165, v202, v203
	v_lshl_add_u64 v[188:189], v[188:189], 0, v[186:187]
	global_store_dwordx4 v[188:189], v[162:165], off
	s_nop 1
	v_lshlrev_b32_e32 v162, 16, v158
	v_and_b32_e32 v158, 0xffff0000, v158
	v_mul_f32_e32 v158, 0xbfb8aa3b, v158
	v_exp_f32_e32 v158, v158
	v_mul_f32_e32 v162, 0xbfb8aa3b, v162
	v_exp_f32_e32 v162, v162
	v_add_f32_e32 v158, 1.0, v158
	v_rcp_f32_e32 v163, v158
	v_lshlrev_b32_e32 v158, 16, v159
	v_and_b32_e32 v159, 0xffff0000, v159
	v_mul_f32_e32 v158, 0xbfb8aa3b, v158
	v_mul_f32_e32 v159, 0xbfb8aa3b, v159
	v_exp_f32_e32 v158, v158
	v_exp_f32_e32 v159, v159
	v_add_f32_e32 v162, 1.0, v162
	v_rcp_f32_e32 v162, v162
	v_add_f32_e32 v158, 1.0, v158
	v_add_f32_e32 v159, 1.0, v159
	v_rcp_f32_e32 v158, v158
	v_rcp_f32_e32 v159, v159
	v_pk_mul_f32 v[162:163], v[98:99], v[162:163]
	v_pk_mul_f32 v[164:165], v[100:101], v[158:159]
	v_lshlrev_b32_e32 v158, 16, v160
	v_and_b32_e32 v159, 0xffff0000, v160
	v_mul_f32_e32 v158, 0xbfb8aa3b, v158
	v_mul_f32_e32 v159, 0xbfb8aa3b, v159
	v_exp_f32_e32 v158, v158
	v_exp_f32_e32 v159, v159
	v_add_f32_e32 v158, 1.0, v158
	v_add_f32_e32 v159, 1.0, v159
	v_rcp_f32_e32 v158, v158
	v_rcp_f32_e32 v159, v159
	s_nop 0
	v_pk_mul_f32 v[166:167], v[94:95], v[158:159]
	v_lshlrev_b32_e32 v158, 16, v161
	v_and_b32_e32 v159, 0xffff0000, v161
	v_mul_f32_e32 v158, 0xbfb8aa3b, v158
	v_mul_f32_e32 v159, 0xbfb8aa3b, v159
	v_exp_f32_e32 v158, v158
	v_exp_f32_e32 v159, v159
	v_cvt_pk_bf16_f32 v160, v166, v167
	v_add_f32_e32 v158, 1.0, v158
	v_add_f32_e32 v159, 1.0, v159
	v_rcp_f32_e32 v158, v158
	v_rcp_f32_e32 v159, v159
	s_nop 0
	v_pk_mul_f32 v[168:169], v[96:97], v[158:159]
	v_cvt_pk_bf16_f32 v158, v162, v163
	v_cvt_pk_bf16_f32 v159, v164, v165
	v_cvt_pk_bf16_f32 v161, v168, v169
	global_store_dwordx4 v[188:189], v[158:161], off offset:256
	s_nop 1
	v_lshlrev_b32_e32 v158, 16, v154
	v_and_b32_e32 v154, 0xffff0000, v154
	v_mul_f32_e32 v154, 0xbfb8aa3b, v154
	v_exp_f32_e32 v154, v154
	v_mul_f32_e32 v158, 0xbfb8aa3b, v158
	v_exp_f32_e32 v158, v158
	v_add_f32_e32 v154, 1.0, v154
	v_rcp_f32_e32 v159, v154
	v_lshlrev_b32_e32 v154, 16, v155
	v_and_b32_e32 v155, 0xffff0000, v155
	v_mul_f32_e32 v154, 0xbfb8aa3b, v154
	v_mul_f32_e32 v155, 0xbfb8aa3b, v155
	v_exp_f32_e32 v154, v154
	v_exp_f32_e32 v155, v155
	v_add_f32_e32 v158, 1.0, v158
	v_rcp_f32_e32 v158, v158
	v_add_f32_e32 v154, 1.0, v154
	v_add_f32_e32 v155, 1.0, v155
	v_rcp_f32_e32 v154, v154
	v_rcp_f32_e32 v155, v155
	v_pk_mul_f32 v[158:159], v[122:123], v[158:159]
	v_pk_mul_f32 v[160:161], v[124:125], v[154:155]
	v_lshlrev_b32_e32 v154, 16, v156
	v_and_b32_e32 v155, 0xffff0000, v156
	v_mul_f32_e32 v154, 0xbfb8aa3b, v154
	v_mul_f32_e32 v155, 0xbfb8aa3b, v155
	v_exp_f32_e32 v154, v154
	v_exp_f32_e32 v155, v155
	v_add_f32_e32 v154, 1.0, v154
	v_add_f32_e32 v155, 1.0, v155
	v_rcp_f32_e32 v154, v154
	v_rcp_f32_e32 v155, v155
	s_nop 0
	v_pk_mul_f32 v[162:163], v[118:119], v[154:155]
	v_lshlrev_b32_e32 v154, 16, v157
	v_and_b32_e32 v155, 0xffff0000, v157
	v_mul_f32_e32 v154, 0xbfb8aa3b, v154
	v_mul_f32_e32 v155, 0xbfb8aa3b, v155
	v_exp_f32_e32 v154, v154
	v_exp_f32_e32 v155, v155
	v_cvt_pk_bf16_f32 v156, v162, v163
	v_mov_b64_e32 v[162:163], s[42:43]
	v_add_f32_e32 v154, 1.0, v154
	v_add_f32_e32 v155, 1.0, v155
	v_rcp_f32_e32 v154, v154
	v_rcp_f32_e32 v155, v155
	s_nop 0
	v_pk_mul_f32 v[164:165], v[120:121], v[154:155]
	v_cvt_pk_bf16_f32 v154, v158, v159
	v_mad_i64_i32 v[158:159], s[0:1], v198, s78, v[162:163]
	v_cvt_pk_bf16_f32 v155, v160, v161
	v_cvt_pk_bf16_f32 v157, v164, v165
	v_lshl_add_u64 v[158:159], v[158:159], 0, v[186:187]
	global_store_dwordx4 v[158:159], v[154:157], off
	s_nop 1
	v_lshlrev_b32_e32 v154, 16, v150
	v_and_b32_e32 v150, 0xffff0000, v150
	v_mul_f32_e32 v150, 0xbfb8aa3b, v150
	v_exp_f32_e32 v150, v150
	v_mul_f32_e32 v154, 0xbfb8aa3b, v154
	v_exp_f32_e32 v154, v154
	v_add_f32_e32 v150, 1.0, v150
	v_rcp_f32_e32 v155, v150
	v_lshlrev_b32_e32 v150, 16, v151
	v_and_b32_e32 v151, 0xffff0000, v151
	v_mul_f32_e32 v150, 0xbfb8aa3b, v150
	v_mul_f32_e32 v151, 0xbfb8aa3b, v151
	v_exp_f32_e32 v150, v150
	v_exp_f32_e32 v151, v151
	v_add_f32_e32 v154, 1.0, v154
	v_rcp_f32_e32 v154, v154
	v_add_f32_e32 v150, 1.0, v150
	v_add_f32_e32 v151, 1.0, v151
	v_rcp_f32_e32 v150, v150
	v_rcp_f32_e32 v151, v151
	v_pk_mul_f32 v[154:155], v[90:91], v[154:155]
	v_pk_mul_f32 v[156:157], v[92:93], v[150:151]
	v_lshlrev_b32_e32 v150, 16, v152
	v_and_b32_e32 v151, 0xffff0000, v152
	v_mul_f32_e32 v150, 0xbfb8aa3b, v150
	v_mul_f32_e32 v151, 0xbfb8aa3b, v151
	v_exp_f32_e32 v150, v150
	v_exp_f32_e32 v151, v151
	v_add_f32_e32 v150, 1.0, v150
	v_add_f32_e32 v151, 1.0, v151
	v_rcp_f32_e32 v150, v150
	v_rcp_f32_e32 v151, v151
	s_nop 0
	v_pk_mul_f32 v[160:161], v[86:87], v[150:151]
	v_lshlrev_b32_e32 v150, 16, v153
	v_and_b32_e32 v151, 0xffff0000, v153
	v_mul_f32_e32 v150, 0xbfb8aa3b, v150
	v_mul_f32_e32 v151, 0xbfb8aa3b, v151
	v_exp_f32_e32 v150, v150
	v_exp_f32_e32 v151, v151
	v_cvt_pk_bf16_f32 v152, v160, v161
	v_add_f32_e32 v150, 1.0, v150
	v_add_f32_e32 v151, 1.0, v151
	v_rcp_f32_e32 v150, v150
	v_rcp_f32_e32 v151, v151
	s_nop 0
	v_pk_mul_f32 v[164:165], v[88:89], v[150:151]
	v_cvt_pk_bf16_f32 v150, v154, v155
	v_cvt_pk_bf16_f32 v151, v156, v157
	v_cvt_pk_bf16_f32 v153, v164, v165
	global_store_dwordx4 v[158:159], v[150:153], off offset:256
	v_add_u32_e32 v165, 0xa0, v26
	v_add_u32_e32 v164, 0xb0, v26
	v_lshlrev_b32_e32 v150, 16, v146
	v_and_b32_e32 v146, 0xffff0000, v146
	v_mul_f32_e32 v146, 0xbfb8aa3b, v146
	v_exp_f32_e32 v146, v146
	v_mul_f32_e32 v150, 0xbfb8aa3b, v150
	v_exp_f32_e32 v150, v150
	v_add_f32_e32 v146, 1.0, v146
	v_rcp_f32_e32 v151, v146
	v_lshlrev_b32_e32 v146, 16, v147
	v_and_b32_e32 v147, 0xffff0000, v147
	v_mul_f32_e32 v146, 0xbfb8aa3b, v146
	v_mul_f32_e32 v147, 0xbfb8aa3b, v147
	v_exp_f32_e32 v146, v146
	v_exp_f32_e32 v147, v147
	v_add_f32_e32 v150, 1.0, v150
	v_rcp_f32_e32 v150, v150
	v_add_f32_e32 v146, 1.0, v146
	v_add_f32_e32 v147, 1.0, v147
	v_rcp_f32_e32 v146, v146
	v_rcp_f32_e32 v147, v147
	v_pk_mul_f32 v[150:151], v[114:115], v[150:151]
	v_pk_mul_f32 v[152:153], v[116:117], v[146:147]
	v_lshlrev_b32_e32 v146, 16, v148
	v_and_b32_e32 v147, 0xffff0000, v148
	v_mul_f32_e32 v146, 0xbfb8aa3b, v146
	v_mul_f32_e32 v147, 0xbfb8aa3b, v147
	v_exp_f32_e32 v146, v146
	v_exp_f32_e32 v147, v147
	v_add_f32_e32 v146, 1.0, v146
	v_add_f32_e32 v147, 1.0, v147
	v_rcp_f32_e32 v146, v146
	v_rcp_f32_e32 v147, v147
	s_nop 0
	v_pk_mul_f32 v[154:155], v[110:111], v[146:147]
	v_lshlrev_b32_e32 v146, 16, v149
	v_and_b32_e32 v147, 0xffff0000, v149
	v_mul_f32_e32 v146, 0xbfb8aa3b, v146
	v_mul_f32_e32 v147, 0xbfb8aa3b, v147
	v_exp_f32_e32 v146, v146
	v_exp_f32_e32 v147, v147
	v_cvt_pk_bf16_f32 v148, v154, v155
	v_add_f32_e32 v146, 1.0, v146
	v_add_f32_e32 v147, 1.0, v147
	v_rcp_f32_e32 v146, v146
	v_rcp_f32_e32 v147, v147
	s_nop 0
	v_pk_mul_f32 v[156:157], v[112:113], v[146:147]
	v_cvt_pk_bf16_f32 v146, v150, v151
	v_mad_i64_i32 v[150:151], s[0:1], v197, s78, v[162:163]
	v_cvt_pk_bf16_f32 v147, v152, v153
	v_cvt_pk_bf16_f32 v149, v156, v157
	v_lshl_add_u64 v[150:151], v[150:151], 0, v[186:187]
	global_store_dwordx4 v[150:151], v[146:149], off
	s_nop 1
	v_lshlrev_b32_e32 v146, 16, v142
	v_and_b32_e32 v142, 0xffff0000, v142
	v_mul_f32_e32 v142, 0xbfb8aa3b, v142
	v_exp_f32_e32 v142, v142
	v_mul_f32_e32 v146, 0xbfb8aa3b, v146
	v_exp_f32_e32 v146, v146
	v_add_f32_e32 v142, 1.0, v142
	v_rcp_f32_e32 v147, v142
	v_lshlrev_b32_e32 v142, 16, v143
	v_and_b32_e32 v143, 0xffff0000, v143
	v_mul_f32_e32 v142, 0xbfb8aa3b, v142
	v_mul_f32_e32 v143, 0xbfb8aa3b, v143
	v_exp_f32_e32 v142, v142
	v_exp_f32_e32 v143, v143
	v_add_f32_e32 v146, 1.0, v146
	v_rcp_f32_e32 v146, v146
	v_add_f32_e32 v142, 1.0, v142
	v_add_f32_e32 v143, 1.0, v143
	v_rcp_f32_e32 v142, v142
	v_rcp_f32_e32 v143, v143
	v_pk_mul_f32 v[146:147], v[82:83], v[146:147]
	v_pk_mul_f32 v[148:149], v[84:85], v[142:143]
	v_lshlrev_b32_e32 v142, 16, v144
	v_and_b32_e32 v143, 0xffff0000, v144
	v_mul_f32_e32 v142, 0xbfb8aa3b, v142
	v_mul_f32_e32 v143, 0xbfb8aa3b, v143
	v_exp_f32_e32 v142, v142
	v_exp_f32_e32 v143, v143
	v_add_f32_e32 v142, 1.0, v142
	v_add_f32_e32 v143, 1.0, v143
	v_rcp_f32_e32 v142, v142
	v_rcp_f32_e32 v143, v143
	s_nop 0
	v_pk_mul_f32 v[152:153], v[78:79], v[142:143]
	v_lshlrev_b32_e32 v142, 16, v145
	v_and_b32_e32 v143, 0xffff0000, v145
	v_mul_f32_e32 v142, 0xbfb8aa3b, v142
	v_mul_f32_e32 v143, 0xbfb8aa3b, v143
	v_exp_f32_e32 v142, v142
	v_exp_f32_e32 v143, v143
	v_cvt_pk_bf16_f32 v144, v152, v153
	v_add_f32_e32 v142, 1.0, v142
	v_add_f32_e32 v143, 1.0, v143
	v_rcp_f32_e32 v142, v142
	v_rcp_f32_e32 v143, v143
	s_nop 0
	v_pk_mul_f32 v[154:155], v[80:81], v[142:143]
	v_cvt_pk_bf16_f32 v142, v146, v147
	v_cvt_pk_bf16_f32 v143, v148, v149
	v_cvt_pk_bf16_f32 v145, v154, v155
	global_store_dwordx4 v[150:151], v[142:145], off offset:256
	s_nop 1
	v_lshlrev_b32_e32 v142, 16, v138
	v_and_b32_e32 v138, 0xffff0000, v138
	v_mul_f32_e32 v138, 0xbfb8aa3b, v138
	v_exp_f32_e32 v138, v138
	v_mul_f32_e32 v142, 0xbfb8aa3b, v142
	v_exp_f32_e32 v142, v142
	v_add_f32_e32 v138, 1.0, v138
	v_rcp_f32_e32 v143, v138
	v_lshlrev_b32_e32 v138, 16, v139
	v_and_b32_e32 v139, 0xffff0000, v139
	v_mul_f32_e32 v138, 0xbfb8aa3b, v138
	v_mul_f32_e32 v139, 0xbfb8aa3b, v139
	v_exp_f32_e32 v138, v138
	v_exp_f32_e32 v139, v139
	v_add_f32_e32 v142, 1.0, v142
	v_rcp_f32_e32 v142, v142
	v_add_f32_e32 v138, 1.0, v138
	v_add_f32_e32 v139, 1.0, v139
	v_rcp_f32_e32 v138, v138
	v_rcp_f32_e32 v139, v139
	v_pk_mul_f32 v[142:143], v[106:107], v[142:143]
	v_pk_mul_f32 v[144:145], v[108:109], v[138:139]
	v_lshlrev_b32_e32 v138, 16, v140
	v_and_b32_e32 v139, 0xffff0000, v140
	v_mul_f32_e32 v138, 0xbfb8aa3b, v138
	v_mul_f32_e32 v139, 0xbfb8aa3b, v139
	v_exp_f32_e32 v138, v138
	v_exp_f32_e32 v139, v139
	v_add_f32_e32 v138, 1.0, v138
	v_add_f32_e32 v139, 1.0, v139
	v_rcp_f32_e32 v138, v138
	v_rcp_f32_e32 v139, v139
	s_nop 0
	v_pk_mul_f32 v[146:147], v[102:103], v[138:139]
	v_lshlrev_b32_e32 v138, 16, v141
	v_and_b32_e32 v139, 0xffff0000, v141
	v_mul_f32_e32 v138, 0xbfb8aa3b, v138
	v_mul_f32_e32 v139, 0xbfb8aa3b, v139
	v_exp_f32_e32 v138, v138
	v_exp_f32_e32 v139, v139
	v_cvt_pk_bf16_f32 v140, v146, v147
	v_add_f32_e32 v138, 1.0, v138
	v_add_f32_e32 v139, 1.0, v139
	v_rcp_f32_e32 v138, v138
	v_rcp_f32_e32 v139, v139
	s_nop 0
	v_pk_mul_f32 v[148:149], v[104:105], v[138:139]
	v_cvt_pk_bf16_f32 v138, v142, v143
	v_mad_i64_i32 v[142:143], s[0:1], v196, s78, v[162:163]
	v_cvt_pk_bf16_f32 v139, v144, v145
	v_cvt_pk_bf16_f32 v141, v148, v149
	v_lshl_add_u64 v[142:143], v[142:143], 0, v[186:187]
	global_store_dwordx4 v[142:143], v[138:141], off
	s_nop 1
	v_lshlrev_b32_e32 v138, 16, v134
	v_and_b32_e32 v134, 0xffff0000, v134
	v_mul_f32_e32 v134, 0xbfb8aa3b, v134
	v_exp_f32_e32 v134, v134
	v_mul_f32_e32 v138, 0xbfb8aa3b, v138
	v_exp_f32_e32 v138, v138
	v_add_f32_e32 v134, 1.0, v134
	v_rcp_f32_e32 v139, v134
	v_lshlrev_b32_e32 v134, 16, v135
	v_and_b32_e32 v135, 0xffff0000, v135
	v_mul_f32_e32 v134, 0xbfb8aa3b, v134
	v_mul_f32_e32 v135, 0xbfb8aa3b, v135
	v_exp_f32_e32 v134, v134
	v_exp_f32_e32 v135, v135
	v_add_f32_e32 v138, 1.0, v138
	v_rcp_f32_e32 v138, v138
	v_add_f32_e32 v134, 1.0, v134
	v_add_f32_e32 v135, 1.0, v135
	v_rcp_f32_e32 v134, v134
	v_rcp_f32_e32 v135, v135
	v_pk_mul_f32 v[138:139], v[74:75], v[138:139]
	v_pk_mul_f32 v[140:141], v[76:77], v[134:135]
	v_lshlrev_b32_e32 v134, 16, v136
	v_and_b32_e32 v135, 0xffff0000, v136
	v_mul_f32_e32 v134, 0xbfb8aa3b, v134
	v_mul_f32_e32 v135, 0xbfb8aa3b, v135
	v_exp_f32_e32 v134, v134
	v_exp_f32_e32 v135, v135
	v_add_f32_e32 v134, 1.0, v134
	v_add_f32_e32 v135, 1.0, v135
	v_rcp_f32_e32 v134, v134
	v_rcp_f32_e32 v135, v135
	s_nop 0
	v_pk_mul_f32 v[144:145], v[70:71], v[134:135]
	v_lshlrev_b32_e32 v134, 16, v137
	v_and_b32_e32 v135, 0xffff0000, v137
	v_mul_f32_e32 v134, 0xbfb8aa3b, v134
	v_mul_f32_e32 v135, 0xbfb8aa3b, v135
	v_exp_f32_e32 v134, v134
	v_exp_f32_e32 v135, v135
	v_cvt_pk_bf16_f32 v136, v144, v145
	v_add_f32_e32 v134, 1.0, v134
	v_add_f32_e32 v135, 1.0, v135
	v_rcp_f32_e32 v134, v134
	v_rcp_f32_e32 v135, v135
	s_nop 0
	v_pk_mul_f32 v[146:147], v[72:73], v[134:135]
	v_cvt_pk_bf16_f32 v134, v138, v139
	v_cvt_pk_bf16_f32 v135, v140, v141
	v_cvt_pk_bf16_f32 v137, v146, v147
	global_store_dwordx4 v[142:143], v[134:137], off offset:256
	s_nop 1
	v_mad_i64_i32 v[134:135], s[0:1], v195, s78, v[28:29]
	v_add_co_u32_e32 v134, vcc, s16, v134
	s_nop 1
	v_addc_co_u32_e32 v135, vcc, 0, v135, vcc
	global_load_dwordx4 v[200:203], v[134:135], off
	global_load_dwordx4 v[158:161], v[134:135], off offset:256
	v_mad_i64_i32 v[134:135], s[0:1], v194, s78, v[28:29]
	v_add_co_u32_e32 v134, vcc, s16, v134
	s_waitcnt vmcnt(0)
	v_lshlrev_b32_e32 v199, 16, v203
	v_addc_co_u32_e32 v135, vcc, 0, v135, vcc
	global_load_dwordx4 v[154:157], v[134:135], off
	global_load_dwordx4 v[150:153], v[134:135], off offset:256
	v_mul_f32_e32 v199, 0xbfb8aa3b, v199
	v_exp_f32_e32 v199, v199
	v_lshlrev_b32_e32 v168, 16, v201
	v_and_b32_e32 v169, 0xffff0000, v201
	v_lshlrev_b32_e32 v166, 16, v200
	v_add_f32_e32 v199, 1.0, v199
	v_and_b32_e32 v167, 0xffff0000, v200
	v_mul_f32_e32 v168, 0xbfb8aa3b, v168
	v_mul_f32_e32 v169, 0xbfb8aa3b, v169
	v_rcp_f32_e32 v200, v199
	v_and_b32_e32 v199, 0xffff0000, v203
	v_exp_f32_e32 v168, v168
	v_exp_f32_e32 v169, v169
	v_mul_f32_e32 v199, 0xbfb8aa3b, v199
	v_exp_f32_e32 v199, v199
	v_add_f32_e32 v168, 1.0, v168
	v_add_f32_e32 v169, 1.0, v169
	v_rcp_f32_e32 v168, v168
	v_rcp_f32_e32 v169, v169
	v_add_f32_e32 v199, 1.0, v199
	v_rcp_f32_e32 v201, v199
	v_lshlrev_b32_e32 v188, 16, v202
	v_pk_mul_f32 v[168:169], v[68:69], v[168:169]
	v_and_b32_e32 v189, 0xffff0000, v202
	v_pk_mul_f32 v[204:205], v[64:65], v[200:201]
	v_cvt_pk_bf16_f32 v201, v168, v169
	v_lshlrev_b32_e32 v168, 16, v158
	v_and_b32_e32 v158, 0xffff0000, v158
	v_mul_f32_e32 v158, 0xbfb8aa3b, v158
	v_exp_f32_e32 v158, v158
	v_mul_f32_e32 v188, 0xbfb8aa3b, v188
	v_mul_f32_e32 v189, 0xbfb8aa3b, v189
	v_exp_f32_e32 v188, v188
	v_add_f32_e32 v158, 1.0, v158
	v_rcp_f32_e32 v169, v158
	v_lshlrev_b32_e32 v158, 16, v159
	v_and_b32_e32 v159, 0xffff0000, v159
	v_exp_f32_e32 v189, v189
	v_mul_f32_e32 v158, 0xbfb8aa3b, v158
	v_mul_f32_e32 v159, 0xbfb8aa3b, v159
	v_exp_f32_e32 v158, v158
	v_exp_f32_e32 v159, v159
	v_add_f32_e32 v188, 1.0, v188
	v_add_f32_e32 v189, 1.0, v189
	v_rcp_f32_e32 v188, v188
	v_rcp_f32_e32 v189, v189
	v_add_f32_e32 v158, 1.0, v158
	v_add_f32_e32 v159, 1.0, v159
	v_rcp_f32_e32 v158, v158
	v_rcp_f32_e32 v159, v159
	v_mul_f32_e32 v166, 0xbfb8aa3b, v166
	v_mul_f32_e32 v167, 0xbfb8aa3b, v167
	v_exp_f32_e32 v166, v166
	v_exp_f32_e32 v167, v167
	v_pk_mul_f32 v[188:189], v[62:63], v[188:189]
	v_mad_i64_i32 v[134:135], s[0:1], v165, s78, v[28:29]
	v_cvt_pk_bf16_f32 v202, v188, v189
	v_pk_mul_f32 v[188:189], v[36:37], v[158:159]
	v_lshlrev_b32_e32 v158, 16, v160
	v_and_b32_e32 v159, 0xffff0000, v160
	v_mul_f32_e32 v158, 0xbfb8aa3b, v158
	v_mul_f32_e32 v159, 0xbfb8aa3b, v159
	v_exp_f32_e32 v158, v158
	v_exp_f32_e32 v159, v159
	v_add_f32_e32 v166, 1.0, v166
	v_add_f32_e32 v167, 1.0, v167
	v_rcp_f32_e32 v166, v166
	v_rcp_f32_e32 v167, v167
	v_add_co_u32_e32 v134, vcc, s16, v134
	v_add_f32_e32 v158, 1.0, v158
	v_add_f32_e32 v159, 1.0, v159
	v_addc_co_u32_e32 v135, vcc, 0, v135, vcc
	v_rcp_f32_e32 v158, v158
	v_rcp_f32_e32 v159, v159
	global_load_dwordx4 v[146:149], v[134:135], off
	global_load_dwordx4 v[142:145], v[134:135], off offset:256
	v_mad_i64_i32 v[134:135], s[0:1], v164, s78, v[28:29]
	v_pk_mul_f32 v[166:167], v[66:67], v[166:167]
	v_add_co_u32_e32 v134, vcc, s16, v134
	v_cvt_pk_bf16_f32 v200, v166, v167
	v_mad_i64_i32 v[166:167], s[0:1], v195, s78, v[162:163]
	v_addc_co_u32_e32 v135, vcc, 0, v135, vcc
	v_cvt_pk_bf16_f32 v203, v204, v205
	v_lshl_add_u64 v[166:167], v[166:167], 0, v[186:187]
	global_load_dwordx4 v[138:141], v[134:135], off
	s_nop 0
	global_load_dwordx4 v[134:137], v[134:135], off offset:256
	v_mul_f32_e32 v168, 0xbfb8aa3b, v168
	global_store_dwordx4 v[166:167], v[200:203], off
	v_exp_f32_e32 v168, v168
	s_nop 0
	v_pk_mul_f32 v[200:201], v[30:31], v[158:159]
	v_lshlrev_b32_e32 v158, 16, v161
	v_and_b32_e32 v159, 0xffff0000, v161
	v_mul_f32_e32 v158, 0xbfb8aa3b, v158
	v_mul_f32_e32 v159, 0xbfb8aa3b, v159
	v_exp_f32_e32 v158, v158
	v_exp_f32_e32 v159, v159
	v_add_f32_e32 v168, 1.0, v168
	v_rcp_f32_e32 v168, v168
	v_add_f32_e32 v158, 1.0, v158
	v_add_f32_e32 v159, 1.0, v159
	v_rcp_f32_e32 v158, v158
	v_rcp_f32_e32 v159, v159
	v_pk_mul_f32 v[168:169], v[34:35], v[168:169]
	v_cvt_pk_bf16_f32 v160, v200, v201
	v_pk_mul_f32 v[202:203], v[32:33], v[158:159]
	v_cvt_pk_bf16_f32 v158, v168, v169
	v_cvt_pk_bf16_f32 v159, v188, v189
	v_cvt_pk_bf16_f32 v161, v202, v203
	global_store_dwordx4 v[166:167], v[158:161], off offset:256
	s_waitcnt vmcnt(0)
	s_nop 0
	v_lshlrev_b32_e32 v158, 16, v154
	v_and_b32_e32 v154, 0xffff0000, v154
	v_mul_f32_e32 v154, 0xbfb8aa3b, v154
	v_exp_f32_e32 v154, v154
	v_mul_f32_e32 v158, 0xbfb8aa3b, v158
	v_exp_f32_e32 v158, v158
	v_add_f32_e32 v154, 1.0, v154
	v_rcp_f32_e32 v159, v154
	v_lshlrev_b32_e32 v154, 16, v155
	v_and_b32_e32 v155, 0xffff0000, v155
	v_mul_f32_e32 v154, 0xbfb8aa3b, v154
	v_mul_f32_e32 v155, 0xbfb8aa3b, v155
	v_exp_f32_e32 v154, v154
	v_exp_f32_e32 v155, v155
	v_add_f32_e32 v158, 1.0, v158
	v_rcp_f32_e32 v158, v158
	v_add_f32_e32 v154, 1.0, v154
	v_add_f32_e32 v155, 1.0, v155
	v_rcp_f32_e32 v154, v154
	v_rcp_f32_e32 v155, v155
	v_pk_mul_f32 v[158:159], v[58:59], v[158:159]
	v_pk_mul_f32 v[160:161], v[60:61], v[154:155]
	v_lshlrev_b32_e32 v154, 16, v156
	v_and_b32_e32 v155, 0xffff0000, v156
	v_mul_f32_e32 v154, 0xbfb8aa3b, v154
	v_mul_f32_e32 v155, 0xbfb8aa3b, v155
	v_exp_f32_e32 v154, v154
	v_exp_f32_e32 v155, v155
	v_add_f32_e32 v154, 1.0, v154
	v_add_f32_e32 v155, 1.0, v155
	v_rcp_f32_e32 v154, v154
	v_rcp_f32_e32 v155, v155
	s_nop 0
	v_pk_mul_f32 v[166:167], v[54:55], v[154:155]
	v_lshlrev_b32_e32 v154, 16, v157
	v_and_b32_e32 v155, 0xffff0000, v157
	v_mul_f32_e32 v154, 0xbfb8aa3b, v154
	v_mul_f32_e32 v155, 0xbfb8aa3b, v155
	v_exp_f32_e32 v154, v154
	v_exp_f32_e32 v155, v155
	v_cvt_pk_bf16_f32 v156, v166, v167
	v_add_f32_e32 v154, 1.0, v154
	v_add_f32_e32 v155, 1.0, v155
	v_rcp_f32_e32 v154, v154
	v_rcp_f32_e32 v155, v155
	s_nop 0
	v_pk_mul_f32 v[168:169], v[56:57], v[154:155]
	v_cvt_pk_bf16_f32 v154, v158, v159
	v_mad_i64_i32 v[158:159], s[0:1], v194, s78, v[162:163]
	v_cvt_pk_bf16_f32 v155, v160, v161
	v_cvt_pk_bf16_f32 v157, v168, v169
	v_lshl_add_u64 v[158:159], v[158:159], 0, v[186:187]
	global_store_dwordx4 v[158:159], v[154:157], off
	s_nop 1
	v_lshlrev_b32_e32 v154, 16, v150
	v_and_b32_e32 v150, 0xffff0000, v150
	v_mul_f32_e32 v150, 0xbfb8aa3b, v150
	v_exp_f32_e32 v150, v150
	v_mul_f32_e32 v154, 0xbfb8aa3b, v154
	v_exp_f32_e32 v154, v154
	v_add_f32_e32 v150, 1.0, v150
	v_rcp_f32_e32 v155, v150
	v_lshlrev_b32_e32 v150, 16, v151
	v_and_b32_e32 v151, 0xffff0000, v151
	v_mul_f32_e32 v150, 0xbfb8aa3b, v150
	v_mul_f32_e32 v151, 0xbfb8aa3b, v151
	v_exp_f32_e32 v150, v150
	v_exp_f32_e32 v151, v151
	v_add_f32_e32 v154, 1.0, v154
	v_rcp_f32_e32 v154, v154
	v_add_f32_e32 v150, 1.0, v150
	v_add_f32_e32 v151, 1.0, v151
	v_rcp_f32_e32 v150, v150
	v_rcp_f32_e32 v151, v151
	v_pk_mul_f32 v[154:155], v[22:23], v[154:155]
	v_pk_mul_f32 v[156:157], v[24:25], v[150:151]
	v_lshlrev_b32_e32 v150, 16, v152
	v_and_b32_e32 v151, 0xffff0000, v152
	v_mul_f32_e32 v150, 0xbfb8aa3b, v150
	v_mul_f32_e32 v151, 0xbfb8aa3b, v151
	v_exp_f32_e32 v150, v150
	v_exp_f32_e32 v151, v151
	v_add_f32_e32 v150, 1.0, v150
	v_add_f32_e32 v151, 1.0, v151
	v_rcp_f32_e32 v150, v150
	v_rcp_f32_e32 v151, v151
	s_nop 0
	v_pk_mul_f32 v[160:161], v[18:19], v[150:151]
	v_lshlrev_b32_e32 v150, 16, v153
	v_and_b32_e32 v151, 0xffff0000, v153
	v_mul_f32_e32 v150, 0xbfb8aa3b, v150
	v_mul_f32_e32 v151, 0xbfb8aa3b, v151
	v_exp_f32_e32 v150, v150
	v_exp_f32_e32 v151, v151
	v_cvt_pk_bf16_f32 v152, v160, v161
	v_add_f32_e32 v150, 1.0, v150
	v_add_f32_e32 v151, 1.0, v151
	v_rcp_f32_e32 v150, v150
	v_rcp_f32_e32 v151, v151
	s_nop 0
	v_pk_mul_f32 v[166:167], v[20:21], v[150:151]
	v_cvt_pk_bf16_f32 v150, v154, v155
	v_cvt_pk_bf16_f32 v151, v156, v157
	v_cvt_pk_bf16_f32 v153, v166, v167
	global_store_dwordx4 v[158:159], v[150:153], off offset:256
	s_nop 1
	v_lshlrev_b32_e32 v150, 16, v146
	v_and_b32_e32 v146, 0xffff0000, v146
	v_mul_f32_e32 v146, 0xbfb8aa3b, v146
	v_exp_f32_e32 v146, v146
	v_mul_f32_e32 v150, 0xbfb8aa3b, v150
	v_exp_f32_e32 v150, v150
	v_add_f32_e32 v146, 1.0, v146
	v_rcp_f32_e32 v151, v146
	v_lshlrev_b32_e32 v146, 16, v147
	v_and_b32_e32 v147, 0xffff0000, v147
	v_mul_f32_e32 v146, 0xbfb8aa3b, v146
	v_mul_f32_e32 v147, 0xbfb8aa3b, v147
	v_exp_f32_e32 v146, v146
	v_exp_f32_e32 v147, v147
	v_add_f32_e32 v150, 1.0, v150
	v_rcp_f32_e32 v150, v150
	v_add_f32_e32 v146, 1.0, v146
	v_add_f32_e32 v147, 1.0, v147
	v_rcp_f32_e32 v146, v146
	v_rcp_f32_e32 v147, v147
	v_pk_mul_f32 v[150:151], v[50:51], v[150:151]
	v_pk_mul_f32 v[152:153], v[52:53], v[146:147]
	v_lshlrev_b32_e32 v146, 16, v148
	v_and_b32_e32 v147, 0xffff0000, v148
	v_mul_f32_e32 v146, 0xbfb8aa3b, v146
	v_mul_f32_e32 v147, 0xbfb8aa3b, v147
	v_exp_f32_e32 v146, v146
	v_exp_f32_e32 v147, v147
	v_add_f32_e32 v146, 1.0, v146
	v_add_f32_e32 v147, 1.0, v147
	v_rcp_f32_e32 v146, v146
	v_rcp_f32_e32 v147, v147
	s_nop 0
	v_pk_mul_f32 v[154:155], v[46:47], v[146:147]
	v_lshlrev_b32_e32 v146, 16, v149
	v_and_b32_e32 v147, 0xffff0000, v149
	v_mul_f32_e32 v146, 0xbfb8aa3b, v146
	v_mul_f32_e32 v147, 0xbfb8aa3b, v147
	v_exp_f32_e32 v146, v146
	v_exp_f32_e32 v147, v147
	v_cvt_pk_bf16_f32 v148, v154, v155
	v_add_f32_e32 v146, 1.0, v146
	v_add_f32_e32 v147, 1.0, v147
	v_rcp_f32_e32 v146, v146
	v_rcp_f32_e32 v147, v147
	s_nop 0
	v_pk_mul_f32 v[156:157], v[48:49], v[146:147]
	v_cvt_pk_bf16_f32 v146, v150, v151
	v_mad_i64_i32 v[150:151], s[0:1], v165, s78, v[162:163]
	v_cvt_pk_bf16_f32 v147, v152, v153
	v_cvt_pk_bf16_f32 v149, v156, v157
	v_lshl_add_u64 v[150:151], v[150:151], 0, v[186:187]
	global_store_dwordx4 v[150:151], v[146:149], off
	s_nop 1
	v_lshlrev_b32_e32 v146, 16, v142
	v_and_b32_e32 v142, 0xffff0000, v142
	v_mul_f32_e32 v142, 0xbfb8aa3b, v142
	v_exp_f32_e32 v142, v142
	v_mul_f32_e32 v146, 0xbfb8aa3b, v146
	v_exp_f32_e32 v146, v146
	v_add_f32_e32 v142, 1.0, v142
	v_rcp_f32_e32 v147, v142
	v_lshlrev_b32_e32 v142, 16, v143
	v_and_b32_e32 v143, 0xffff0000, v143
	v_mul_f32_e32 v142, 0xbfb8aa3b, v142
	v_mul_f32_e32 v143, 0xbfb8aa3b, v143
	v_exp_f32_e32 v142, v142
	v_exp_f32_e32 v143, v143
	v_add_f32_e32 v146, 1.0, v146
	v_rcp_f32_e32 v146, v146
	v_add_f32_e32 v142, 1.0, v142
	v_add_f32_e32 v143, 1.0, v143
	v_rcp_f32_e32 v142, v142
	v_rcp_f32_e32 v143, v143
	v_pk_mul_f32 v[146:147], v[14:15], v[146:147]
	v_pk_mul_f32 v[148:149], v[16:17], v[142:143]
	v_lshlrev_b32_e32 v142, 16, v144
	v_and_b32_e32 v143, 0xffff0000, v144
	v_mul_f32_e32 v142, 0xbfb8aa3b, v142
	v_mul_f32_e32 v143, 0xbfb8aa3b, v143
	v_exp_f32_e32 v142, v142
	v_exp_f32_e32 v143, v143
	v_add_f32_e32 v142, 1.0, v142
	v_add_f32_e32 v143, 1.0, v143
	v_rcp_f32_e32 v142, v142
	v_rcp_f32_e32 v143, v143
	s_nop 0
	v_pk_mul_f32 v[152:153], v[10:11], v[142:143]
	v_lshlrev_b32_e32 v142, 16, v145
	v_and_b32_e32 v143, 0xffff0000, v145
	v_mul_f32_e32 v142, 0xbfb8aa3b, v142
	v_mul_f32_e32 v143, 0xbfb8aa3b, v143
	v_exp_f32_e32 v142, v142
	v_exp_f32_e32 v143, v143
	v_cvt_pk_bf16_f32 v144, v152, v153
	v_add_f32_e32 v142, 1.0, v142
	v_add_f32_e32 v143, 1.0, v143
	v_rcp_f32_e32 v142, v142
	v_rcp_f32_e32 v143, v143
	s_nop 0
	v_pk_mul_f32 v[154:155], v[12:13], v[142:143]
	v_cvt_pk_bf16_f32 v142, v146, v147
	v_cvt_pk_bf16_f32 v143, v148, v149
	v_cvt_pk_bf16_f32 v145, v154, v155
	global_store_dwordx4 v[150:151], v[142:145], off offset:256
	s_nop 1
	v_lshlrev_b32_e32 v142, 16, v138
	v_and_b32_e32 v138, 0xffff0000, v138
	v_mul_f32_e32 v138, 0xbfb8aa3b, v138
	v_exp_f32_e32 v138, v138
	v_mul_f32_e32 v142, 0xbfb8aa3b, v142
	v_exp_f32_e32 v142, v142
	v_add_f32_e32 v138, 1.0, v138
	v_rcp_f32_e32 v143, v138
	v_lshlrev_b32_e32 v138, 16, v139
	v_and_b32_e32 v139, 0xffff0000, v139
	v_mul_f32_e32 v138, 0xbfb8aa3b, v138
	v_mul_f32_e32 v139, 0xbfb8aa3b, v139
	v_exp_f32_e32 v138, v138
	v_exp_f32_e32 v139, v139
	v_add_f32_e32 v142, 1.0, v142
	v_rcp_f32_e32 v142, v142
	v_add_f32_e32 v138, 1.0, v138
	v_add_f32_e32 v139, 1.0, v139
	v_rcp_f32_e32 v138, v138
	v_rcp_f32_e32 v139, v139
	v_pk_mul_f32 v[142:143], v[42:43], v[142:143]
	v_pk_mul_f32 v[144:145], v[44:45], v[138:139]
	v_lshlrev_b32_e32 v138, 16, v140
	v_and_b32_e32 v139, 0xffff0000, v140
	v_mul_f32_e32 v138, 0xbfb8aa3b, v138
	v_mul_f32_e32 v139, 0xbfb8aa3b, v139
	v_exp_f32_e32 v138, v138
	v_exp_f32_e32 v139, v139
	v_add_f32_e32 v138, 1.0, v138
	v_add_f32_e32 v139, 1.0, v139
	v_rcp_f32_e32 v138, v138
	v_rcp_f32_e32 v139, v139
	s_nop 0
	v_pk_mul_f32 v[146:147], v[38:39], v[138:139]
	v_lshlrev_b32_e32 v138, 16, v141
	v_and_b32_e32 v139, 0xffff0000, v141
	v_mul_f32_e32 v138, 0xbfb8aa3b, v138
	v_mul_f32_e32 v139, 0xbfb8aa3b, v139
	v_exp_f32_e32 v138, v138
	v_exp_f32_e32 v139, v139
	v_cvt_pk_bf16_f32 v140, v146, v147
	v_add_f32_e32 v138, 1.0, v138
	v_add_f32_e32 v139, 1.0, v139
	v_rcp_f32_e32 v138, v138
	v_rcp_f32_e32 v139, v139
	s_nop 0
	v_pk_mul_f32 v[148:149], v[40:41], v[138:139]
	v_cvt_pk_bf16_f32 v138, v142, v143
	v_mad_i64_i32 v[142:143], s[0:1], v164, s78, v[162:163]
	v_cvt_pk_bf16_f32 v139, v144, v145
	v_cvt_pk_bf16_f32 v141, v148, v149
	v_lshl_add_u64 v[142:143], v[142:143], 0, v[186:187]
	global_store_dwordx4 v[142:143], v[138:141], off
	s_nop 1
	v_lshlrev_b32_e32 v138, 16, v134
	v_and_b32_e32 v134, 0xffff0000, v134
	v_mul_f32_e32 v134, 0xbfb8aa3b, v134
	v_exp_f32_e32 v134, v134
	v_mul_f32_e32 v138, 0xbfb8aa3b, v138
	v_exp_f32_e32 v138, v138
	v_add_f32_e32 v134, 1.0, v134
	v_rcp_f32_e32 v139, v134
	v_lshlrev_b32_e32 v134, 16, v135
	v_and_b32_e32 v135, 0xffff0000, v135
	v_mul_f32_e32 v134, 0xbfb8aa3b, v134
	v_mul_f32_e32 v135, 0xbfb8aa3b, v135
	v_exp_f32_e32 v134, v134
	v_exp_f32_e32 v135, v135
	v_add_f32_e32 v138, 1.0, v138
	v_rcp_f32_e32 v138, v138
	v_add_f32_e32 v134, 1.0, v134
	v_add_f32_e32 v135, 1.0, v135
	v_rcp_f32_e32 v134, v134
	v_rcp_f32_e32 v135, v135
	v_pk_mul_f32 v[138:139], v[6:7], v[138:139]
	v_pk_mul_f32 v[140:141], v[8:9], v[134:135]
	v_lshlrev_b32_e32 v134, 16, v136
	v_and_b32_e32 v135, 0xffff0000, v136
	v_mul_f32_e32 v134, 0xbfb8aa3b, v134
	v_mul_f32_e32 v135, 0xbfb8aa3b, v135
	v_exp_f32_e32 v134, v134
	v_exp_f32_e32 v135, v135
	v_add_f32_e32 v134, 1.0, v134
	v_add_f32_e32 v135, 1.0, v135
	v_rcp_f32_e32 v134, v134
	v_rcp_f32_e32 v135, v135
	s_nop 0
	v_pk_mul_f32 v[144:145], v[2:3], v[134:135]
	v_lshlrev_b32_e32 v134, 16, v137
	v_and_b32_e32 v135, 0xffff0000, v137
	v_mul_f32_e32 v134, 0xbfb8aa3b, v134
	v_mul_f32_e32 v135, 0xbfb8aa3b, v135
	v_exp_f32_e32 v134, v134
	v_exp_f32_e32 v135, v135
	v_cvt_pk_bf16_f32 v136, v144, v145
	v_add_f32_e32 v134, 1.0, v134
	v_add_f32_e32 v135, 1.0, v135
	v_rcp_f32_e32 v134, v134
	v_rcp_f32_e32 v135, v135
	s_nop 0
	v_pk_mul_f32 v[146:147], v[4:5], v[134:135]
	v_cvt_pk_bf16_f32 v134, v138, v139
	v_cvt_pk_bf16_f32 v135, v140, v141
	v_cvt_pk_bf16_f32 v137, v146, v147
	global_store_dwordx4 v[142:143], v[134:137], off offset:256
	s_cbranch_execnz .LBB0_891

.LBB0_965:
	s_add_u32 s36, s34, 0x100
	s_addc_u32 s37, s35, 0
	s_add_i32 s0, 0, 0x10000
	v_add_u32_e32 v144, s0, v222
	ds_read_b128 v[100:103], v144
	ds_read_b128 v[104:107], v144 offset:1024
	ds_read_b128 v[140:143], v144 offset:2048
	ds_read_b128 v[144:147], v144 offset:3072
	s_cmp_eq_u32 s31, 12
	s_cselect_b32 s47, s25, s37
	s_cselect_b32 s46, s24, s36
	s_cselect_b32 s43, s18, s29
	s_cselect_b32 s42, s19, s23
	v_lshl_add_u64 v[166:167], s[34:35], 0, v[174:175]
	s_add_i32 m0, s54, 0xc000
	ds_read_b128 v[148:151], v224
	ds_read_b128 v[152:155], v224 offset:1024
	ds_read_b128 v[178:181], v224 offset:2048
	ds_read_b128 v[182:185], v224 offset:3072
	ds_read_b128 v[186:189], v224 offset:4096
	ds_read_b128 v[190:193], v224 offset:5120
	ds_read_b128 v[194:197], v224 offset:6144
	ds_read_b128 v[198:201], v224 offset:7168
	global_load_lds_dwordx4 v[166:167], off
	v_lshl_add_u64 v[166:167], s[34:35], 0, v[176:177]
	s_add_i32 m0, s54, 0xe000
	s_nop 0
	global_load_lds_dwordx4 v[166:167], off
	s_waitcnt vmcnt(10) lgkmcnt(8)
	s_setprio 1
	s_barrier
	s_waitcnt lgkmcnt(0)
	v_mfma_f32_16x16x32_bf16 v[136:139], v[100:103], v[148:151], v[136:139]
	v_mfma_f32_16x16x32_bf16 v[132:135], v[140:143], v[148:151], v[132:135]
	v_mfma_f32_16x16x32_bf16 v[128:131], v[100:103], v[178:181], v[128:131]
	v_mfma_f32_16x16x32_bf16 v[124:127], v[140:143], v[178:181], v[124:127]
	v_mfma_f32_16x16x32_bf16 v[120:123], v[100:103], v[186:189], v[120:123]
	v_mfma_f32_16x16x32_bf16 v[116:119], v[140:143], v[186:189], v[116:119]
	v_mfma_f32_16x16x32_bf16 v[112:115], v[100:103], v[194:197], v[112:115]
	v_mfma_f32_16x16x32_bf16 v[108:111], v[140:143], v[194:197], v[108:111]
	v_mfma_f32_16x16x32_bf16 v[136:139], v[104:107], v[152:155], v[136:139]
	v_mfma_f32_16x16x32_bf16 v[132:135], v[144:147], v[152:155], v[132:135]
	v_mfma_f32_16x16x32_bf16 v[128:131], v[104:107], v[182:185], v[128:131]
	v_mfma_f32_16x16x32_bf16 v[124:127], v[144:147], v[182:185], v[124:127]
	v_mfma_f32_16x16x32_bf16 v[120:123], v[104:107], v[190:193], v[120:123]
	v_mfma_f32_16x16x32_bf16 v[116:119], v[144:147], v[190:193], v[116:119]
	v_mfma_f32_16x16x32_bf16 v[112:115], v[104:107], v[198:201], v[112:115]
	v_mfma_f32_16x16x32_bf16 v[108:111], v[144:147], v[198:201], v[108:111]
	s_barrier
	s_setprio 0
	s_add_i32 s34, 0, 0x14000
	v_add_u32_e32 v166, s34, v222
	s_add_i32 s0, s0, s53
	ds_read_b128 v[202:205], v166
	ds_read_b128 v[206:209], v166 offset:1024
	ds_read_b128 v[210:213], v166 offset:2048
	ds_read_b128 v[214:217], v166 offset:3072
	v_lshl_add_u64 v[166:167], s[42:43], 0, v[26:27]
	s_mov_b32 m0, s0
	v_lshl_add_u64 v[168:169], s[42:43], 0, v[160:161]
	global_load_lds_dwordx4 v[166:167], off
	s_add_i32 m0, s0, 0x2000
	s_nop 0
	global_load_lds_dwordx4 v[168:169], off
	s_waitcnt vmcnt(10)
	s_setprio 1
	s_barrier
	s_waitcnt lgkmcnt(0)
	v_mfma_f32_16x16x32_bf16 v[64:67], v[202:205], v[148:151], v[64:67]
	v_mfma_f32_16x16x32_bf16 v[60:63], v[210:213], v[148:151], v[60:63]
	v_mfma_f32_16x16x32_bf16 v[56:59], v[202:205], v[178:181], v[56:59]
	v_mfma_f32_16x16x32_bf16 v[52:55], v[210:213], v[178:181], v[52:55]
	v_mfma_f32_16x16x32_bf16 v[48:51], v[202:205], v[186:189], v[48:51]
	v_mfma_f32_16x16x32_bf16 v[44:47], v[210:213], v[186:189], v[44:47]
	v_mfma_f32_16x16x32_bf16 v[40:43], v[202:205], v[194:197], v[40:43]
	v_mfma_f32_16x16x32_bf16 v[36:39], v[210:213], v[194:197], v[36:39]
	v_mfma_f32_16x16x32_bf16 v[64:67], v[206:209], v[152:155], v[64:67]
	v_mfma_f32_16x16x32_bf16 v[60:63], v[214:217], v[152:155], v[60:63]
	v_mfma_f32_16x16x32_bf16 v[56:59], v[206:209], v[182:185], v[56:59]
	v_mfma_f32_16x16x32_bf16 v[52:55], v[214:217], v[182:185], v[52:55]
	v_mfma_f32_16x16x32_bf16 v[48:51], v[206:209], v[190:193], v[48:51]
	v_mfma_f32_16x16x32_bf16 v[44:47], v[214:217], v[190:193], v[44:47]
	v_mfma_f32_16x16x32_bf16 v[40:43], v[206:209], v[198:201], v[40:43]
	v_mfma_f32_16x16x32_bf16 v[36:39], v[214:217], v[198:201], v[36:39]
	s_barrier
	s_setprio 0
	s_mov_b32 m0, s54
	v_lshl_add_u64 v[218:219], s[46:47], 0, v[156:157]
	ds_read_b128 v[148:151], v224 offset:16384
	ds_read_b128 v[152:155], v224 offset:17408
	ds_read_b128 v[178:181], v224 offset:18432
	ds_read_b128 v[182:185], v224 offset:19456
	ds_read_b128 v[186:189], v224 offset:20480
	ds_read_b128 v[190:193], v224 offset:21504
	ds_read_b128 v[194:197], v224 offset:22528
	ds_read_b128 v[198:201], v224 offset:23552
	global_load_lds_dwordx4 v[218:219], off
	v_lshl_add_u64 v[220:221], s[46:47], 0, v[158:159]
	s_mov_b32 m0, s55
	s_nop 0
	global_load_lds_dwordx4 v[220:221], off
	s_setprio 1
	s_barrier
	s_waitcnt lgkmcnt(0)
	v_mfma_f32_16x16x32_bf16 v[96:99], v[100:103], v[148:151], v[96:99]
	v_mfma_f32_16x16x32_bf16 v[92:95], v[140:143], v[148:151], v[92:95]
	v_mfma_f32_16x16x32_bf16 v[88:91], v[100:103], v[178:181], v[88:91]
	v_mfma_f32_16x16x32_bf16 v[84:87], v[140:143], v[178:181], v[84:87]
	v_mfma_f32_16x16x32_bf16 v[80:83], v[100:103], v[186:189], v[80:83]
	v_mfma_f32_16x16x32_bf16 v[76:79], v[140:143], v[186:189], v[76:79]
	v_mfma_f32_16x16x32_bf16 v[72:75], v[100:103], v[194:197], v[72:75]
	v_mfma_f32_16x16x32_bf16 v[68:71], v[140:143], v[194:197], v[68:71]
	v_mfma_f32_16x16x32_bf16 v[96:99], v[104:107], v[152:155], v[96:99]
	v_mfma_f32_16x16x32_bf16 v[92:95], v[144:147], v[152:155], v[92:95]
	v_mfma_f32_16x16x32_bf16 v[88:91], v[104:107], v[182:185], v[88:91]
	v_mfma_f32_16x16x32_bf16 v[84:87], v[144:147], v[182:185], v[84:87]
	v_mfma_f32_16x16x32_bf16 v[80:83], v[104:107], v[190:193], v[80:83]
	v_mfma_f32_16x16x32_bf16 v[76:79], v[144:147], v[190:193], v[76:79]
	v_mfma_f32_16x16x32_bf16 v[72:75], v[104:107], v[198:201], v[72:75]
	v_mfma_f32_16x16x32_bf16 v[68:71], v[144:147], v[198:201], v[68:71]
	s_barrier
	s_setprio 0
	s_add_u32 s0, s42, 0x40000
	s_addc_u32 s1, s43, 0
	s_add_i32 s34, s34, s53
	v_lshl_add_u64 v[100:101], s[0:1], 0, v[26:27]
	s_mov_b32 m0, s34
	s_nop 0
	global_load_lds_dwordx4 v[100:101], off
	v_lshl_add_u64 v[100:101], s[0:1], 0, v[160:161]
	s_add_i32 m0, s34, 0x2000
	s_nop 0
	global_load_lds_dwordx4 v[100:101], off
	s_waitcnt vmcnt(10)
	s_setprio 1
	s_barrier
	v_mfma_f32_16x16x32_bf16 v[32:35], v[202:205], v[148:151], v[32:35]
	v_mfma_f32_16x16x32_bf16 v[28:31], v[210:213], v[148:151], v[28:31]
	v_mfma_f32_16x16x32_bf16 v[22:25], v[202:205], v[178:181], v[22:25]
	v_mfma_f32_16x16x32_bf16 v[18:21], v[210:213], v[178:181], v[18:21]
	v_mfma_f32_16x16x32_bf16 v[14:17], v[202:205], v[186:189], v[14:17]
	v_mfma_f32_16x16x32_bf16 v[10:13], v[210:213], v[186:189], v[10:13]
	v_mfma_f32_16x16x32_bf16 v[6:9], v[202:205], v[194:197], v[6:9]
	v_mfma_f32_16x16x32_bf16 v[2:5], v[210:213], v[194:197], v[2:5]
	v_mfma_f32_16x16x32_bf16 v[32:35], v[206:209], v[152:155], v[32:35]
	v_mfma_f32_16x16x32_bf16 v[28:31], v[214:217], v[152:155], v[28:31]
	v_mfma_f32_16x16x32_bf16 v[22:25], v[206:209], v[182:185], v[22:25]
	v_mfma_f32_16x16x32_bf16 v[18:21], v[214:217], v[182:185], v[18:21]
	v_mfma_f32_16x16x32_bf16 v[14:17], v[206:209], v[190:193], v[14:17]
	v_mfma_f32_16x16x32_bf16 v[10:13], v[214:217], v[190:193], v[10:13]
	v_mfma_f32_16x16x32_bf16 v[6:9], v[206:209], v[198:201], v[6:9]
	v_mfma_f32_16x16x32_bf16 v[2:5], v[214:217], v[198:201], v[2:5]
	s_barrier
	s_setprio 0
	s_add_i32 s34, 0, 0x18000
	v_add_u32_e32 v144, s34, v222
	ds_read_b128 v[100:103], v144
	ds_read_b128 v[104:107], v144 offset:1024
	ds_read_b128 v[140:143], v144 offset:2048
	ds_read_b128 v[144:147], v144 offset:3072
	s_add_u32 s0, s46, 0x140000
	s_addc_u32 s1, s47, 0
	s_mov_b32 m0, s56
	v_lshl_add_u64 v[202:203], s[0:1], 0, v[156:157]
	ds_read_b128 v[148:151], v224 offset:32768
	ds_read_b128 v[152:155], v224 offset:33792
	ds_read_b128 v[178:181], v224 offset:34816
	ds_read_b128 v[182:185], v224 offset:35840
	ds_read_b128 v[186:189], v224 offset:36864
	ds_read_b128 v[190:193], v224 offset:37888
	ds_read_b128 v[194:197], v224 offset:38912
	ds_read_b128 v[198:201], v224 offset:39936
	global_load_lds_dwordx4 v[202:203], off
	v_lshl_add_u64 v[202:203], s[0:1], 0, v[158:159]
	s_mov_b32 m0, s57
	s_nop 0
	global_load_lds_dwordx4 v[202:203], off
	s_waitcnt vmcnt(10) lgkmcnt(8)
	s_setprio 1
	s_barrier
	s_waitcnt lgkmcnt(0)
	v_mfma_f32_16x16x32_bf16 v[136:139], v[100:103], v[148:151], v[136:139]
	v_mfma_f32_16x16x32_bf16 v[132:135], v[140:143], v[148:151], v[132:135]
	v_mfma_f32_16x16x32_bf16 v[128:131], v[100:103], v[178:181], v[128:131]
	v_mfma_f32_16x16x32_bf16 v[124:127], v[140:143], v[178:181], v[124:127]
	v_mfma_f32_16x16x32_bf16 v[120:123], v[100:103], v[186:189], v[120:123]
	v_mfma_f32_16x16x32_bf16 v[116:119], v[140:143], v[186:189], v[116:119]
	v_mfma_f32_16x16x32_bf16 v[112:115], v[100:103], v[194:197], v[112:115]
	v_mfma_f32_16x16x32_bf16 v[108:111], v[140:143], v[194:197], v[108:111]
	v_mfma_f32_16x16x32_bf16 v[136:139], v[104:107], v[152:155], v[136:139]
	v_mfma_f32_16x16x32_bf16 v[132:135], v[144:147], v[152:155], v[132:135]
	v_mfma_f32_16x16x32_bf16 v[128:131], v[104:107], v[182:185], v[128:131]
	v_mfma_f32_16x16x32_bf16 v[124:127], v[144:147], v[182:185], v[124:127]
	v_mfma_f32_16x16x32_bf16 v[120:123], v[104:107], v[190:193], v[120:123]
	v_mfma_f32_16x16x32_bf16 v[116:119], v[144:147], v[190:193], v[116:119]
	v_mfma_f32_16x16x32_bf16 v[112:115], v[104:107], v[198:201], v[112:115]
	v_mfma_f32_16x16x32_bf16 v[108:111], v[144:147], v[198:201], v[108:111]
	s_barrier
	s_setprio 0
	s_add_i32 s35, 0, 0x1c000
	s_add_i32 s0, s34, s53
	v_add_u32_e32 v214, s35, v222
	v_lshl_add_u64 v[166:167], v[166:167], 0, s[12:13]
	s_mov_b32 m0, s0
	ds_read_b128 v[202:205], v214
	ds_read_b128 v[206:209], v214 offset:1024
	ds_read_b128 v[210:213], v214 offset:2048
	ds_read_b128 v[214:217], v214 offset:3072
	global_load_lds_dwordx4 v[166:167], off
	v_lshl_add_u64 v[166:167], v[168:169], 0, s[12:13]
	s_add_i32 m0, s0, 0x2000
	s_nop 0
	global_load_lds_dwordx4 v[166:167], off
	s_waitcnt vmcnt(10)
	s_setprio 1
	s_barrier
	s_waitcnt lgkmcnt(0)
	v_mfma_f32_16x16x32_bf16 v[64:67], v[202:205], v[148:151], v[64:67]
	v_mfma_f32_16x16x32_bf16 v[60:63], v[210:213], v[148:151], v[60:63]
	v_mfma_f32_16x16x32_bf16 v[56:59], v[202:205], v[178:181], v[56:59]
	v_mfma_f32_16x16x32_bf16 v[52:55], v[210:213], v[178:181], v[52:55]
	v_mfma_f32_16x16x32_bf16 v[48:51], v[202:205], v[186:189], v[48:51]
	v_mfma_f32_16x16x32_bf16 v[44:47], v[210:213], v[186:189], v[44:47]
	v_mfma_f32_16x16x32_bf16 v[40:43], v[202:205], v[194:197], v[40:43]
	v_mfma_f32_16x16x32_bf16 v[36:39], v[210:213], v[194:197], v[36:39]
	v_mfma_f32_16x16x32_bf16 v[64:67], v[206:209], v[152:155], v[64:67]
	v_mfma_f32_16x16x32_bf16 v[60:63], v[214:217], v[152:155], v[60:63]
	v_mfma_f32_16x16x32_bf16 v[56:59], v[206:209], v[182:185], v[56:59]
	v_mfma_f32_16x16x32_bf16 v[52:55], v[214:217], v[182:185], v[52:55]
	v_mfma_f32_16x16x32_bf16 v[48:51], v[206:209], v[190:193], v[48:51]
	v_mfma_f32_16x16x32_bf16 v[44:47], v[214:217], v[190:193], v[44:47]
	v_mfma_f32_16x16x32_bf16 v[40:43], v[206:209], v[198:201], v[40:43]
	v_mfma_f32_16x16x32_bf16 v[36:39], v[214:217], v[198:201], v[36:39]
	s_barrier
	s_setprio 0
	s_mov_b32 m0, s81
	v_lshl_add_u64 v[166:167], v[218:219], 0, s[12:13]
	ds_read_b128 v[148:151], v224 offset:49152
	ds_read_b128 v[152:155], v224 offset:50176
	ds_read_b128 v[178:181], v224 offset:51200
	ds_read_b128 v[182:185], v224 offset:52224
	ds_read_b128 v[186:189], v224 offset:53248
	ds_read_b128 v[190:193], v224 offset:54272
	ds_read_b128 v[194:197], v224 offset:55296
	ds_read_b128 v[198:201], v224 offset:56320
	global_load_lds_dwordx4 v[166:167], off
	v_lshl_add_u64 v[166:167], v[220:221], 0, s[12:13]
	s_mov_b32 m0, s17
	s_nop 0
	global_load_lds_dwordx4 v[166:167], off
	s_setprio 1
	s_barrier
	s_waitcnt lgkmcnt(0)
	v_mfma_f32_16x16x32_bf16 v[96:99], v[100:103], v[148:151], v[96:99]
	v_mfma_f32_16x16x32_bf16 v[92:95], v[140:143], v[148:151], v[92:95]
	v_mfma_f32_16x16x32_bf16 v[88:91], v[100:103], v[178:181], v[88:91]
	v_mfma_f32_16x16x32_bf16 v[84:87], v[140:143], v[178:181], v[84:87]
	v_mfma_f32_16x16x32_bf16 v[80:83], v[100:103], v[186:189], v[80:83]
	v_mfma_f32_16x16x32_bf16 v[76:79], v[140:143], v[186:189], v[76:79]
	v_mfma_f32_16x16x32_bf16 v[72:75], v[100:103], v[194:197], v[72:75]
	v_mfma_f32_16x16x32_bf16 v[68:71], v[140:143], v[194:197], v[68:71]
	v_mfma_f32_16x16x32_bf16 v[96:99], v[104:107], v[152:155], v[96:99]
	v_mfma_f32_16x16x32_bf16 v[92:95], v[144:147], v[152:155], v[92:95]
	v_mfma_f32_16x16x32_bf16 v[88:91], v[104:107], v[182:185], v[88:91]
	v_mfma_f32_16x16x32_bf16 v[84:87], v[144:147], v[182:185], v[84:87]
	v_mfma_f32_16x16x32_bf16 v[80:83], v[104:107], v[190:193], v[80:83]
	v_mfma_f32_16x16x32_bf16 v[76:79], v[144:147], v[190:193], v[76:79]
	v_mfma_f32_16x16x32_bf16 v[72:75], v[104:107], v[198:201], v[72:75]
	v_mfma_f32_16x16x32_bf16 v[68:71], v[144:147], v[198:201], v[68:71]
	s_barrier
	s_setprio 0
	s_add_u32 s0, s42, 0x40080
	s_addc_u32 s1, s43, 0
	s_add_i32 s34, s35, s53
	v_lshl_add_u64 v[100:101], s[0:1], 0, v[26:27]
	s_mov_b32 m0, s34
	s_nop 0
	global_load_lds_dwordx4 v[100:101], off
	v_lshl_add_u64 v[100:101], s[0:1], 0, v[160:161]
	s_add_i32 m0, s34, 0x2000
	s_nop 0
	global_load_lds_dwordx4 v[100:101], off
	s_waitcnt vmcnt(10)
	s_setprio 1
	s_barrier
	v_mfma_f32_16x16x32_bf16 v[32:35], v[202:205], v[148:151], v[32:35]
	v_mfma_f32_16x16x32_bf16 v[28:31], v[210:213], v[148:151], v[28:31]
	v_mfma_f32_16x16x32_bf16 v[22:25], v[202:205], v[178:181], v[22:25]
	v_mfma_f32_16x16x32_bf16 v[18:21], v[210:213], v[178:181], v[18:21]
	v_mfma_f32_16x16x32_bf16 v[14:17], v[202:205], v[186:189], v[14:17]
	v_mfma_f32_16x16x32_bf16 v[10:13], v[210:213], v[186:189], v[10:13]
	v_mfma_f32_16x16x32_bf16 v[6:9], v[202:205], v[194:197], v[6:9]
	v_mfma_f32_16x16x32_bf16 v[2:5], v[210:213], v[194:197], v[2:5]
	v_mfma_f32_16x16x32_bf16 v[32:35], v[206:209], v[152:155], v[32:35]
	v_mfma_f32_16x16x32_bf16 v[28:31], v[214:217], v[152:155], v[28:31]
	v_mfma_f32_16x16x32_bf16 v[22:25], v[206:209], v[182:185], v[22:25]
	v_mfma_f32_16x16x32_bf16 v[18:21], v[214:217], v[182:185], v[18:21]
	v_mfma_f32_16x16x32_bf16 v[14:17], v[206:209], v[190:193], v[14:17]
	v_mfma_f32_16x16x32_bf16 v[10:13], v[214:217], v[190:193], v[10:13]
	v_mfma_f32_16x16x32_bf16 v[6:9], v[206:209], v[198:201], v[6:9]
	v_mfma_f32_16x16x32_bf16 v[2:5], v[214:217], v[198:201], v[2:5]
	s_barrier
	s_setprio 0
	s_add_i32 s31, s31, 2
	s_add_u32 s23, s23, 0x100
	s_addc_u32 s29, s29, 0
	s_cmp_gt_u32 s31, 13
	s_mov_b64 s[34:35], s[36:37]
	s_cbranch_scc0 .LBB0_965
	s_min_i32 s0, s28, 0x100
	s_ashr_i32 s0, s0, 5
	s_ashr_i32 s1, s0, 31
	s_add_i32 s18, s28, 0xffffff00
	s_cmpk_lt_i32 s28, 0x100
	s_cselect_b32 s18, s28, s18
	s_cselect_b32 s23, 0, s59
	s_cselect_b32 s29, 0, s58
	s_ashr_i32 s19, s18, 31
	s_lshl_b64 s[18:19], s[18:19], 19
	v_lshl_or_b32 v148, s30, 8, v223
	s_add_u32 s30, s44, s29
	s_addc_u32 s31, s45, s23
	s_ashr_i32 s29, s28, 31
	v_lshl_add_u64 v[100:101], s[18:19], 0, v[162:163]
	s_lshl_b64 s[18:19], s[28:29], 19
	v_lshl_add_u64 v[152:153], v[164:165], 0, s[18:19]
	s_lshl_b64 s[28:29], s[28:29], 10
	s_mul_i32 s18, s0, 0x9000
	s_mul_hi_i32 s19, s0, 0x9000
	s_add_u32 s18, s68, s18
	s_addc_u32 s19, s69, s19
	s_lshl_b64 s[0:1], s[0:1], 12
	v_ashrrev_i32_e32 v149, 31, v148
	s_add_u32 s0, s72, s0
	v_lshlrev_b64 v[154:155], 2, v[148:149]
	s_addc_u32 s1, s73, s1
	v_lshl_add_u64 v[150:151], v[100:101], 0, v[148:149]
	v_lshl_add_u64 v[104:105], s[18:19], 0, v[154:155]
	v_lshlrev_b64 v[168:169], 1, v[148:149]
	v_lshl_add_u64 v[180:181], s[0:1], 0, v[154:155]
	v_lshl_add_u64 v[166:167], v[100:101], 1, s[30:31]
	global_load_dwordx4 v[140:143], v[104:105], off offset:16
	global_load_dwordx4 v[144:147], v[104:105], off
	global_load_dwordx4 v[100:103], v[104:105], off offset:528
	s_nop 0
	global_load_dwordx4 v[104:107], v[104:105], off offset:512
	v_lshl_add_u64 v[196:197], v[150:151], 1, s[30:31]
	v_lshl_add_u64 v[178:179], v[152:153], 0, v[168:169]
	global_load_dwordx4 v[148:151], v[180:181], off offset:16
	global_load_dwordx4 v[152:155], v[180:181], off
	global_load_dwordx4 v[190:193], v[196:197], off offset:2048
	v_add_co_u32_e32 v210, vcc, s65, v196
	s_mov_b32 s1, 0x20000
	s_nop 0
	v_addc_co_u32_e32 v211, vcc, 0, v197, vcc
	global_load_dwordx4 v[198:201], v[210:211], off offset:2048
	v_add_co_u32_e32 v184, vcc, s1, v196
	s_mov_b32 s18, 0x30000
	s_nop 0
	v_addc_co_u32_e32 v185, vcc, 0, v197, vcc
	global_load_dwordx4 v[202:205], v[184:185], off offset:2048
	v_add_co_u32_e32 v188, vcc, s18, v196
	v_lshl_add_u64 v[182:183], v[166:167], 0, v[168:169]
	s_nop 0
	v_addc_co_u32_e32 v189, vcc, 0, v197, vcc
	global_load_dwordx4 v[206:209], v[188:189], off offset:2048
	s_mov_b32 s0, 0x8000
	s_mov_b32 s19, 0x80000
	s_mov_b32 s23, 0x90000
	s_waitcnt vmcnt(0)
	v_lshlrev_b32_e32 v166, 16, v190
	v_and_b32_e32 v167, 0xffff0000, v190
	v_lshlrev_b32_e32 v168, 16, v191
	v_and_b32_e32 v169, 0xffff0000, v191
	v_lshlrev_b32_e32 v186, 16, v192
	v_and_b32_e32 v187, 0xffff0000, v192
	v_lshlrev_b32_e32 v190, 16, v193
	v_and_b32_e32 v191, 0xffff0000, v193
	v_pk_fma_f32 v[138:139], v[138:139], v[146:147], v[168:169]
	v_pk_fma_f32 v[136:137], v[136:137], v[144:145], v[166:167]
	v_pk_fma_f32 v[134:135], v[134:135], v[142:143], v[190:191]
	v_pk_fma_f32 v[132:133], v[132:133], v[140:141], v[186:187]
	v_cvt_pk_bf16_f32 v190, v136, v137
	v_cvt_pk_bf16_f32 v191, v138, v139
	v_cvt_pk_bf16_f32 v192, v132, v133
	v_cvt_pk_bf16_f32 v193, v134, v135
	v_lshlrev_b32_e32 v138, 16, v190
	v_and_b32_e32 v139, 0xffff0000, v190
	v_lshlrev_b32_e32 v136, 16, v191
	v_and_b32_e32 v137, 0xffff0000, v191
	v_lshlrev_b32_e32 v134, 16, v192
	v_and_b32_e32 v135, 0xffff0000, v192
	v_lshlrev_b32_e32 v132, 16, v193
	v_and_b32_e32 v133, 0xffff0000, v193
	v_lshlrev_b32_e32 v212, 16, v200
	v_and_b32_e32 v213, 0xffff0000, v200
	v_lshlrev_b32_e32 v200, 16, v201
	v_and_b32_e32 v201, 0xffff0000, v201
	global_store_dwordx4 v[182:183], v[190:193], off offset:2048
	v_pk_mul_f32 v[166:167], v[154:155], v[136:137]
	v_pk_mul_f32 v[168:169], v[152:153], v[138:139]
	v_pk_mul_f32 v[186:187], v[150:151], v[132:133]
	v_pk_mul_f32 v[192:193], v[148:149], v[134:135]
	v_lshlrev_b32_e32 v194, 16, v198
	v_and_b32_e32 v195, 0xffff0000, v198
	v_lshlrev_b32_e32 v198, 16, v199
	v_and_b32_e32 v199, 0xffff0000, v199
	v_cvt_pk_bf16_f32 v190, v168, v169
	v_cvt_pk_bf16_f32 v191, v166, v167
	v_cvt_pk_bf16_f32 v192, v192, v193
	v_cvt_pk_bf16_f32 v193, v186, v187
	v_pk_fma_f32 v[126:127], v[126:127], v[142:143], v[200:201]
	v_pk_fma_f32 v[124:125], v[124:125], v[140:141], v[212:213]
	global_store_dwordx4 v[178:179], v[190:193], off
	v_pk_fma_f32 v[130:131], v[130:131], v[146:147], v[198:199]
	v_pk_fma_f32 v[128:129], v[128:129], v[144:145], v[194:195]
	v_cvt_pk_bf16_f32 v192, v124, v125
	v_cvt_pk_bf16_f32 v193, v126, v127
	v_add_co_u32_e32 v186, vcc, s65, v182
	v_cvt_pk_bf16_f32 v190, v128, v129
	v_cvt_pk_bf16_f32 v191, v130, v131
	v_addc_co_u32_e32 v187, vcc, 0, v183, vcc
	v_lshlrev_b32_e32 v126, 16, v192
	v_and_b32_e32 v127, 0xffff0000, v192
	v_lshlrev_b32_e32 v124, 16, v193
	v_and_b32_e32 v125, 0xffff0000, v193
	global_store_dwordx4 v[186:187], v[190:193], off offset:2048
	v_lshlrev_b32_e32 v130, 16, v190
	v_and_b32_e32 v131, 0xffff0000, v190
	v_lshlrev_b32_e32 v128, 16, v191
	v_and_b32_e32 v129, 0xffff0000, v191
	v_pk_mul_f32 v[190:191], v[150:151], v[124:125]
	v_pk_mul_f32 v[194:195], v[148:149], v[126:127]
	v_pk_mul_f32 v[166:167], v[154:155], v[128:129]
	v_pk_mul_f32 v[168:169], v[152:153], v[130:131]
	v_cvt_pk_bf16_f32 v194, v194, v195
	v_cvt_pk_bf16_f32 v195, v190, v191
	v_add_co_u32_e32 v190, vcc, s0, v178
	v_cvt_pk_bf16_f32 v192, v168, v169
	v_cvt_pk_bf16_f32 v193, v166, v167
	v_addc_co_u32_e32 v191, vcc, 0, v179, vcc
	global_store_dwordx4 v[190:191], v[192:195], off
	v_lshlrev_b32_e32 v198, 16, v204
	v_and_b32_e32 v199, 0xffff0000, v204
	v_add_co_u32_e32 v192, vcc, s19, v196
	v_lshlrev_b32_e32 v200, 16, v205
	s_nop 0
	v_addc_co_u32_e32 v193, vcc, 0, v197, vcc
	v_add_co_u32_e32 v194, vcc, s23, v196
	v_and_b32_e32 v201, 0xffff0000, v205
	global_load_dwordx4 v[212:215], v[192:193], off offset:2048
	v_addc_co_u32_e32 v195, vcc, 0, v197, vcc
	v_lshlrev_b32_e32 v166, 16, v202
	v_and_b32_e32 v167, 0xffff0000, v202
	v_lshlrev_b32_e32 v168, 16, v203
	v_and_b32_e32 v169, 0xffff0000, v203
	v_pk_fma_f32 v[118:119], v[118:119], v[142:143], v[200:201]
	v_pk_fma_f32 v[116:117], v[116:117], v[140:141], v[198:199]
	v_pk_fma_f32 v[122:123], v[122:123], v[146:147], v[168:169]
	v_pk_fma_f32 v[120:121], v[120:121], v[144:145], v[166:167]
	v_cvt_pk_bf16_f32 v202, v116, v117
	v_cvt_pk_bf16_f32 v203, v118, v119
	v_add_co_u32_e32 v198, vcc, s1, v182
	global_load_dwordx4 v[216:219], v[194:195], off offset:2048
	v_cvt_pk_bf16_f32 v200, v120, v121
	v_cvt_pk_bf16_f32 v201, v122, v123
	v_addc_co_u32_e32 v199, vcc, 0, v183, vcc
	v_lshlrev_b32_e32 v118, 16, v202
	v_and_b32_e32 v119, 0xffff0000, v202
	v_lshlrev_b32_e32 v116, 16, v203
	v_and_b32_e32 v117, 0xffff0000, v203
	global_store_dwordx4 v[198:199], v[200:203], off offset:2048
	v_lshlrev_b32_e32 v122, 16, v200
	v_and_b32_e32 v123, 0xffff0000, v200
	v_lshlrev_b32_e32 v120, 16, v201
	v_and_b32_e32 v121, 0xffff0000, v201
	v_pk_mul_f32 v[200:201], v[150:151], v[116:117]
	v_pk_mul_f32 v[204:205], v[148:149], v[118:119]
	v_lshlrev_b32_e32 v234, 16, v208
	v_and_b32_e32 v235, 0xffff0000, v208
	v_lshlrev_b32_e32 v208, 16, v209
	v_and_b32_e32 v209, 0xffff0000, v209
	v_pk_mul_f32 v[166:167], v[154:155], v[120:121]
	v_pk_mul_f32 v[168:169], v[152:153], v[122:123]
	v_cvt_pk_bf16_f32 v204, v204, v205
	v_cvt_pk_bf16_f32 v205, v200, v201
	v_add_co_u32_e32 v200, vcc, s65, v178
	v_lshlrev_b32_e32 v220, 16, v206
	v_and_b32_e32 v221, 0xffff0000, v206
	v_lshlrev_b32_e32 v206, 16, v207
	v_and_b32_e32 v207, 0xffff0000, v207
	v_cvt_pk_bf16_f32 v202, v168, v169
	v_cvt_pk_bf16_f32 v203, v166, v167
	v_addc_co_u32_e32 v201, vcc, 0, v179, vcc
	v_pk_fma_f32 v[110:111], v[110:111], v[142:143], v[208:209]
	v_pk_fma_f32 v[108:109], v[108:109], v[140:141], v[234:235]
	global_store_dwordx4 v[200:201], v[202:205], off
	v_pk_fma_f32 v[114:115], v[114:115], v[146:147], v[206:207]
	v_pk_fma_f32 v[112:113], v[112:113], v[144:145], v[220:221]
	v_cvt_pk_bf16_f32 v206, v108, v109
	v_cvt_pk_bf16_f32 v207, v110, v111
	v_add_co_u32_e32 v202, vcc, s18, v182
	v_cvt_pk_bf16_f32 v204, v112, v113
	v_cvt_pk_bf16_f32 v205, v114, v115
	v_addc_co_u32_e32 v203, vcc, 0, v183, vcc
	v_lshlrev_b32_e32 v110, 16, v206
	v_and_b32_e32 v111, 0xffff0000, v206
	v_lshlrev_b32_e32 v108, 16, v207
	v_and_b32_e32 v109, 0xffff0000, v207
	global_store_dwordx4 v[202:203], v[204:207], off offset:2048
	v_lshlrev_b32_e32 v114, 16, v204
	v_and_b32_e32 v115, 0xffff0000, v204
	v_lshlrev_b32_e32 v112, 16, v205
	v_and_b32_e32 v113, 0xffff0000, v205
	v_pk_mul_f32 v[204:205], v[150:151], v[108:109]
	v_pk_mul_f32 v[208:209], v[148:149], v[110:111]
	s_mov_b32 s0, 0x18000
	v_pk_mul_f32 v[166:167], v[154:155], v[112:113]
	v_pk_mul_f32 v[168:169], v[152:153], v[114:115]
	v_cvt_pk_bf16_f32 v208, v208, v209
	v_cvt_pk_bf16_f32 v209, v204, v205
	v_add_co_u32_e32 v204, vcc, s0, v178
	v_cvt_pk_bf16_f32 v206, v168, v169
	v_cvt_pk_bf16_f32 v207, v166, v167
	v_addc_co_u32_e32 v205, vcc, 0, v179, vcc
	global_store_dwordx4 v[204:205], v[206:209], off
	s_mov_b32 s0, 0xb0000
	s_waitcnt vmcnt(0)
	v_lshlrev_b32_e32 v166, 16, v212
	v_add_co_u32_e32 v206, vcc, s76, v196
	v_and_b32_e32 v167, 0xffff0000, v212
	s_nop 0
	v_addc_co_u32_e32 v207, vcc, 0, v197, vcc
	global_load_dwordx4 v[238:241], v[206:207], off offset:2048
	v_add_co_u32_e32 v208, vcc, s0, v196
	v_lshlrev_b32_e32 v168, 16, v213
	s_nop 0
	v_addc_co_u32_e32 v209, vcc, 0, v197, vcc
	global_load_dwordx4 v[242:245], v[208:209], off offset:2048
	v_and_b32_e32 v169, 0xffff0000, v213
	v_lshlrev_b32_e32 v212, 16, v214
	v_and_b32_e32 v213, 0xffff0000, v214
	v_lshlrev_b32_e32 v214, 16, v215
	v_and_b32_e32 v215, 0xffff0000, v215
	v_pk_fma_f32 v[94:95], v[94:95], v[142:143], v[214:215]
	v_pk_fma_f32 v[92:93], v[92:93], v[140:141], v[212:213]
	v_lshlrev_b32_e32 v220, 16, v216
	v_and_b32_e32 v221, 0xffff0000, v216
	v_lshlrev_b32_e32 v234, 16, v217
	v_and_b32_e32 v235, 0xffff0000, v217
	v_pk_fma_f32 v[98:99], v[98:99], v[146:147], v[168:169]
	v_pk_fma_f32 v[96:97], v[96:97], v[144:145], v[166:167]
	v_cvt_pk_bf16_f32 v216, v92, v93
	v_cvt_pk_bf16_f32 v217, v94, v95
	v_add_co_u32_e32 v212, vcc, s19, v182
	v_cvt_pk_bf16_f32 v214, v96, v97
	v_cvt_pk_bf16_f32 v215, v98, v99
	v_addc_co_u32_e32 v213, vcc, 0, v183, vcc
	v_lshlrev_b32_e32 v94, 16, v216
	v_and_b32_e32 v95, 0xffff0000, v216
	v_lshlrev_b32_e32 v92, 16, v217
	v_and_b32_e32 v93, 0xffff0000, v217
	v_lshlrev_b32_e32 v246, 16, v218
	v_and_b32_e32 v247, 0xffff0000, v218
	v_lshlrev_b32_e32 v248, 16, v219
	v_and_b32_e32 v249, 0xffff0000, v219
	global_store_dwordx4 v[212:213], v[214:217], off offset:2048
	v_lshlrev_b32_e32 v98, 16, v214
	v_and_b32_e32 v99, 0xffff0000, v214
	v_lshlrev_b32_e32 v96, 16, v215
	v_and_b32_e32 v97, 0xffff0000, v215
	v_pk_mul_f32 v[214:215], v[150:151], v[92:93]
	v_pk_mul_f32 v[218:219], v[148:149], v[94:95]
	s_mov_b32 s1, 0x40000
	v_pk_mul_f32 v[166:167], v[154:155], v[96:97]
	v_pk_mul_f32 v[168:169], v[152:153], v[98:99]
	v_cvt_pk_bf16_f32 v218, v218, v219
	v_cvt_pk_bf16_f32 v219, v214, v215
	v_add_co_u32_e32 v214, vcc, s1, v178
	v_cvt_pk_bf16_f32 v216, v168, v169
	v_cvt_pk_bf16_f32 v217, v166, v167
	v_addc_co_u32_e32 v215, vcc, 0, v179, vcc
	v_pk_fma_f32 v[86:87], v[86:87], v[142:143], v[248:249]
	global_store_dwordx4 v[214:215], v[216:219], off
	v_pk_fma_f32 v[90:91], v[90:91], v[146:147], v[234:235]
	v_pk_fma_f32 v[88:89], v[88:89], v[144:145], v[220:221]
	v_pk_fma_f32 v[84:85], v[84:85], v[140:141], v[246:247]
	v_cvt_pk_bf16_f32 v221, v86, v87
	v_add_co_u32_e32 v216, vcc, s23, v182
	v_cvt_pk_bf16_f32 v218, v88, v89
	v_cvt_pk_bf16_f32 v219, v90, v91
	v_cvt_pk_bf16_f32 v220, v84, v85
	v_addc_co_u32_e32 v217, vcc, 0, v183, vcc
	v_lshlrev_b32_e32 v84, 16, v221
	v_and_b32_e32 v85, 0xffff0000, v221
	global_store_dwordx4 v[216:217], v[218:221], off offset:2048
	v_lshlrev_b32_e32 v90, 16, v218
	v_and_b32_e32 v91, 0xffff0000, v218
	v_lshlrev_b32_e32 v88, 16, v219
	v_and_b32_e32 v89, 0xffff0000, v219
	v_lshlrev_b32_e32 v86, 16, v220
	v_and_b32_e32 v87, 0xffff0000, v220
	v_pk_mul_f32 v[218:219], v[150:151], v[84:85]
	s_mov_b32 s1, 0x48000
	v_pk_mul_f32 v[166:167], v[154:155], v[88:89]
	v_pk_mul_f32 v[168:169], v[152:153], v[90:91]
	v_pk_mul_f32 v[220:221], v[148:149], v[86:87]
	v_cvt_pk_bf16_f32 v249, v218, v219
	v_add_co_u32_e32 v218, vcc, s1, v178
	v_cvt_pk_bf16_f32 v246, v168, v169
	v_cvt_pk_bf16_f32 v247, v166, v167
	v_cvt_pk_bf16_f32 v248, v220, v221
	v_addc_co_u32_e32 v219, vcc, 0, v179, vcc
	global_store_dwordx4 v[218:219], v[246:249], off
	global_load_dwordx4 v[246:249], v[196:197], off offset:2304
	s_nop 0
	global_load_dwordx4 v[250:253], v[210:211], off offset:2304
	s_waitcnt vmcnt(0)
	v_lshlrev_b32_e32 v196, 16, v240
	v_and_b32_e32 v197, 0xffff0000, v240
	v_lshlrev_b32_e32 v210, 16, v241
	v_and_b32_e32 v211, 0xffff0000, v241
	v_lshlrev_b32_e32 v166, 16, v238
	v_and_b32_e32 v167, 0xffff0000, v238
	v_lshlrev_b32_e32 v168, 16, v239
	v_and_b32_e32 v169, 0xffff0000, v239
	v_pk_fma_f32 v[78:79], v[78:79], v[142:143], v[210:211]
	v_pk_fma_f32 v[76:77], v[76:77], v[140:141], v[196:197]
	v_pk_fma_f32 v[82:83], v[82:83], v[146:147], v[168:169]
	v_pk_fma_f32 v[80:81], v[80:81], v[144:145], v[166:167]
	v_cvt_pk_bf16_f32 v240, v76, v77
	v_cvt_pk_bf16_f32 v241, v78, v79
	v_add_co_u32_e32 v196, vcc, s76, v182
	v_cvt_pk_bf16_f32 v238, v80, v81
	v_cvt_pk_bf16_f32 v239, v82, v83
	v_addc_co_u32_e32 v197, vcc, 0, v183, vcc
	v_lshlrev_b32_e32 v78, 16, v240
	v_and_b32_e32 v79, 0xffff0000, v240
	v_lshlrev_b32_e32 v76, 16, v241
	v_and_b32_e32 v77, 0xffff0000, v241
	global_store_dwordx4 v[196:197], v[238:241], off offset:2048
	v_pk_mul_f32 v[210:211], v[150:151], v[76:77]
	v_lshlrev_b32_e32 v220, 16, v242
	v_pk_mul_f32 v[240:241], v[148:149], v[78:79]
	v_and_b32_e32 v221, 0xffff0000, v242
	v_lshlrev_b32_e32 v234, 16, v243
	v_and_b32_e32 v235, 0xffff0000, v243
	v_lshlrev_b32_e32 v242, 16, v244
	v_and_b32_e32 v243, 0xffff0000, v244
	v_lshlrev_b32_e32 v244, 16, v245
	v_and_b32_e32 v245, 0xffff0000, v245
	v_cvt_pk_bf16_f32 v240, v240, v241
	v_cvt_pk_bf16_f32 v241, v210, v211
	v_add_co_u32_e32 v210, vcc, s77, v178
	v_lshlrev_b32_e32 v82, 16, v238
	v_and_b32_e32 v83, 0xffff0000, v238
	v_lshlrev_b32_e32 v80, 16, v239
	v_and_b32_e32 v81, 0xffff0000, v239
	v_addc_co_u32_e32 v211, vcc, 0, v179, vcc
	v_pk_fma_f32 v[74:75], v[74:75], v[146:147], v[234:235]
	v_pk_fma_f32 v[72:73], v[72:73], v[144:145], v[220:221]
	v_pk_fma_f32 v[142:143], v[70:71], v[142:143], v[244:245]
	v_pk_fma_f32 v[70:71], v[68:69], v[140:141], v[242:243]
	v_pk_mul_f32 v[166:167], v[154:155], v[80:81]
	v_pk_mul_f32 v[168:169], v[152:153], v[82:83]
	v_cvt_pk_bf16_f32 v68, v72, v73
	v_cvt_pk_bf16_f32 v69, v74, v75
	v_cvt_pk_bf16_f32 v70, v70, v71
	v_cvt_pk_bf16_f32 v71, v142, v143
	v_add_co_u32_e32 v220, vcc, s0, v182
	v_cvt_pk_bf16_f32 v238, v168, v169
	v_cvt_pk_bf16_f32 v239, v166, v167
	v_addc_co_u32_e32 v221, vcc, 0, v183, vcc
	v_lshlrev_b32_e32 v146, 16, v68
	v_and_b32_e32 v147, 0xffff0000, v68
	v_lshlrev_b32_e32 v144, 16, v69
	v_and_b32_e32 v145, 0xffff0000, v69
	v_lshlrev_b32_e32 v142, 16, v70
	v_and_b32_e32 v143, 0xffff0000, v70
	v_lshlrev_b32_e32 v140, 16, v71
	v_and_b32_e32 v141, 0xffff0000, v71
	s_mov_b32 s0, 0x58000
	global_store_dwordx4 v[210:211], v[238:241], off
	global_store_dwordx4 v[220:221], v[68:71], off offset:2048
	v_pk_mul_f32 v[72:73], v[150:151], v[140:141]
	v_pk_mul_f32 v[74:75], v[148:149], v[142:143]
	v_pk_mul_f32 v[70:71], v[154:155], v[144:145]
	v_pk_mul_f32 v[68:69], v[152:153], v[146:147]
	v_add_co_u32_e32 v148, vcc, s0, v178
	v_cvt_pk_bf16_f32 v68, v68, v69
	v_cvt_pk_bf16_f32 v69, v70, v71
	v_cvt_pk_bf16_f32 v70, v74, v75
	v_cvt_pk_bf16_f32 v71, v72, v73
	v_addc_co_u32_e32 v149, vcc, 0, v179, vcc
	global_store_dwordx4 v[148:149], v[68:71], off
	global_load_dwordx4 v[150:153], v[184:185], off offset:2304
	global_load_dwordx4 v[238:241], v[188:189], off offset:2304
	s_nop 0
	global_load_dwordx4 v[68:71], v[180:181], off offset:528
	global_load_dwordx4 v[72:75], v[180:181], off offset:512
	v_lshlrev_b32_e32 v154, 16, v246
	v_and_b32_e32 v155, 0xffff0000, v246
	v_lshlrev_b32_e32 v166, 16, v247
	v_and_b32_e32 v167, 0xffff0000, v247
	v_lshlrev_b32_e32 v168, 16, v248
	v_and_b32_e32 v169, 0xffff0000, v248
	v_lshlrev_b32_e32 v180, 16, v249
	v_and_b32_e32 v181, 0xffff0000, v249
	v_pk_fma_f32 v[66:67], v[66:67], v[106:107], v[166:167]
	v_pk_fma_f32 v[64:65], v[64:65], v[104:105], v[154:155]
	v_pk_fma_f32 v[62:63], v[62:63], v[102:103], v[180:181]
	v_pk_fma_f32 v[60:61], v[60:61], v[100:101], v[168:169]
	v_cvt_pk_bf16_f32 v242, v64, v65
	v_cvt_pk_bf16_f32 v243, v66, v67
	v_cvt_pk_bf16_f32 v244, v60, v61
	v_cvt_pk_bf16_f32 v245, v62, v63
	v_lshlrev_b32_e32 v66, 16, v242
	v_and_b32_e32 v67, 0xffff0000, v242
	v_lshlrev_b32_e32 v64, 16, v243
	v_and_b32_e32 v65, 0xffff0000, v243
	v_lshlrev_b32_e32 v62, 16, v244
	v_and_b32_e32 v63, 0xffff0000, v244
	v_lshlrev_b32_e32 v60, 16, v245
	v_and_b32_e32 v61, 0xffff0000, v245
	v_lshlrev_b32_e32 v184, 16, v250
	v_and_b32_e32 v185, 0xffff0000, v250
	v_lshlrev_b32_e32 v188, 16, v251
	v_and_b32_e32 v189, 0xffff0000, v251
	v_lshlrev_b32_e32 v234, 16, v252
	v_and_b32_e32 v235, 0xffff0000, v252
	v_lshlrev_b32_e32 v246, 16, v253
	v_and_b32_e32 v247, 0xffff0000, v253
	global_store_dwordx4 v[182:183], v[242:245], off offset:2304
	v_pk_fma_f32 v[58:59], v[58:59], v[106:107], v[188:189]
	v_pk_fma_f32 v[56:57], v[56:57], v[104:105], v[184:185]
	v_pk_fma_f32 v[54:55], v[54:55], v[102:103], v[246:247]
	v_pk_fma_f32 v[52:53], v[52:53], v[100:101], v[234:235]
	s_waitcnt vmcnt(0)
	v_lshlrev_b32_e32 v188, 16, v240
	v_pk_mul_f32 v[168:169], v[70:71], v[60:61]
	v_pk_mul_f32 v[154:155], v[74:75], v[64:65]
	v_pk_mul_f32 v[166:167], v[72:73], v[66:67]
	v_pk_mul_f32 v[182:183], v[68:69], v[62:63]
	v_cvt_pk_bf16_f32 v180, v166, v167
	v_cvt_pk_bf16_f32 v181, v154, v155
	v_cvt_pk_bf16_f32 v182, v182, v183
	v_cvt_pk_bf16_f32 v183, v168, v169
	global_store_dwordx4 v[178:179], v[180:183], off offset:256
	v_cvt_pk_bf16_f32 v178, v56, v57
	v_cvt_pk_bf16_f32 v179, v58, v59
	v_cvt_pk_bf16_f32 v180, v52, v53
	v_cvt_pk_bf16_f32 v181, v54, v55
	v_lshlrev_b32_e32 v58, 16, v178
	v_and_b32_e32 v59, 0xffff0000, v178
	v_lshlrev_b32_e32 v56, 16, v179
	v_and_b32_e32 v57, 0xffff0000, v179
	v_lshlrev_b32_e32 v54, 16, v180
	v_and_b32_e32 v55, 0xffff0000, v180
	v_lshlrev_b32_e32 v52, 16, v181
	v_and_b32_e32 v53, 0xffff0000, v181
	global_store_dwordx4 v[186:187], v[178:181], off offset:2304
	v_pk_mul_f32 v[154:155], v[74:75], v[56:57]
	v_pk_mul_f32 v[166:167], v[72:73], v[58:59]
	v_pk_mul_f32 v[168:169], v[70:71], v[52:53]
	v_pk_mul_f32 v[180:181], v[68:69], v[54:55]
	v_cvt_pk_bf16_f32 v178, v166, v167
	v_cvt_pk_bf16_f32 v179, v154, v155
	v_cvt_pk_bf16_f32 v180, v180, v181
	v_cvt_pk_bf16_f32 v181, v168, v169
	v_lshlrev_b32_e32 v154, 16, v150
	v_and_b32_e32 v155, 0xffff0000, v150
	v_lshlrev_b32_e32 v150, 16, v151
	v_and_b32_e32 v151, 0xffff0000, v151
	v_lshlrev_b32_e32 v166, 16, v152
	v_and_b32_e32 v167, 0xffff0000, v152
	v_lshlrev_b32_e32 v152, 16, v153
	v_and_b32_e32 v153, 0xffff0000, v153
	global_store_dwordx4 v[190:191], v[178:181], off offset:256
	v_pk_fma_f32 v[50:51], v[50:51], v[106:107], v[150:151]
	v_pk_fma_f32 v[48:49], v[48:49], v[104:105], v[154:155]
	v_pk_fma_f32 v[46:47], v[46:47], v[102:103], v[152:153]
	v_pk_fma_f32 v[44:45], v[44:45], v[100:101], v[166:167]
	global_load_dwordx4 v[178:181], v[192:193], off offset:2304
	global_load_dwordx4 v[182:185], v[194:195], off offset:2304
	v_cvt_pk_bf16_f32 v150, v48, v49
	v_cvt_pk_bf16_f32 v151, v50, v51
	v_cvt_pk_bf16_f32 v152, v44, v45
	v_cvt_pk_bf16_f32 v153, v46, v47
	v_lshlrev_b32_e32 v50, 16, v150
	v_and_b32_e32 v51, 0xffff0000, v150
	v_lshlrev_b32_e32 v48, 16, v151
	v_and_b32_e32 v49, 0xffff0000, v151
	v_lshlrev_b32_e32 v46, 16, v152
	v_and_b32_e32 v47, 0xffff0000, v152
	v_lshlrev_b32_e32 v44, 16, v153
	v_and_b32_e32 v45, 0xffff0000, v153
	v_lshlrev_b32_e32 v168, 16, v238
	v_and_b32_e32 v169, 0xffff0000, v238
	v_lshlrev_b32_e32 v186, 16, v239
	v_and_b32_e32 v187, 0xffff0000, v239
	v_and_b32_e32 v189, 0xffff0000, v240
	v_lshlrev_b32_e32 v190, 16, v241
	v_and_b32_e32 v191, 0xffff0000, v241
	global_store_dwordx4 v[198:199], v[150:153], off offset:2304
	v_pk_mul_f32 v[154:155], v[70:71], v[44:45]
	v_pk_mul_f32 v[166:167], v[68:69], v[46:47]
	v_pk_mul_f32 v[152:153], v[74:75], v[48:49]
	v_pk_mul_f32 v[150:151], v[72:73], v[50:51]
	v_pk_fma_f32 v[42:43], v[42:43], v[106:107], v[186:187]
	v_cvt_pk_bf16_f32 v150, v150, v151
	v_cvt_pk_bf16_f32 v151, v152, v153
	v_cvt_pk_bf16_f32 v152, v166, v167
	v_cvt_pk_bf16_f32 v153, v154, v155
	v_pk_fma_f32 v[40:41], v[40:41], v[104:105], v[168:169]
	v_pk_fma_f32 v[38:39], v[38:39], v[102:103], v[190:191]
	v_pk_fma_f32 v[36:37], v[36:37], v[100:101], v[188:189]
	global_store_dwordx4 v[200:201], v[150:153], off offset:256
	v_mul_f32_e32 v67, v67, v67
	v_mul_f32_e32 v65, v65, v65
	v_cvt_pk_bf16_f32 v150, v40, v41
	v_cvt_pk_bf16_f32 v151, v42, v43
	v_cvt_pk_bf16_f32 v152, v36, v37
	v_cvt_pk_bf16_f32 v153, v38, v39
	v_lshlrev_b32_e32 v42, 16, v150
	v_and_b32_e32 v43, 0xffff0000, v150
	v_lshlrev_b32_e32 v40, 16, v151
	v_and_b32_e32 v41, 0xffff0000, v151
	v_lshlrev_b32_e32 v38, 16, v152
	v_and_b32_e32 v39, 0xffff0000, v152
	v_lshlrev_b32_e32 v36, 16, v153
	v_and_b32_e32 v37, 0xffff0000, v153
	global_store_dwordx4 v[202:203], v[150:153], off offset:2304
	v_pk_mul_f32 v[154:155], v[70:71], v[36:37]
	v_pk_mul_f32 v[166:167], v[68:69], v[38:39]
	v_pk_mul_f32 v[152:153], v[74:75], v[40:41]
	v_pk_mul_f32 v[150:151], v[72:73], v[42:43]
	v_fmac_f32_e32 v67, v66, v66
	v_cvt_pk_bf16_f32 v150, v150, v151
	v_cvt_pk_bf16_f32 v151, v152, v153
	v_cvt_pk_bf16_f32 v152, v166, v167
	v_cvt_pk_bf16_f32 v153, v154, v155
	global_store_dwordx4 v[204:205], v[150:153], off offset:256
	global_load_dwordx4 v[150:153], v[206:207], off offset:2304
	s_nop 0
	global_load_dwordx4 v[186:189], v[208:209], off offset:2304
	v_fmac_f32_e32 v65, v64, v64
	v_mul_f32_e32 v63, v63, v63
	v_mul_f32_e32 v61, v61, v61
	v_add_f32_e32 v64, v67, v65
	v_fmac_f32_e32 v63, v62, v62
	v_fmac_f32_e32 v61, v60, v60
	v_add_f32_e32 v60, v63, v61
	s_waitcnt vmcnt(0)
	v_lshlrev_b32_e32 v154, 16, v178
	v_and_b32_e32 v155, 0xffff0000, v178
	v_lshlrev_b32_e32 v166, 16, v179
	v_and_b32_e32 v167, 0xffff0000, v179
	v_lshlrev_b32_e32 v168, 16, v180
	v_and_b32_e32 v169, 0xffff0000, v180
	v_lshlrev_b32_e32 v178, 16, v181
	v_and_b32_e32 v179, 0xffff0000, v181
	v_pk_fma_f32 v[34:35], v[34:35], v[106:107], v[166:167]
	v_pk_fma_f32 v[32:33], v[32:33], v[104:105], v[154:155]
	v_pk_fma_f32 v[30:31], v[30:31], v[102:103], v[178:179]
	v_pk_fma_f32 v[28:29], v[28:29], v[100:101], v[168:169]
	v_cvt_pk_bf16_f32 v178, v32, v33
	v_cvt_pk_bf16_f32 v179, v34, v35
	v_cvt_pk_bf16_f32 v180, v28, v29
	v_cvt_pk_bf16_f32 v181, v30, v31
	v_lshlrev_b32_e32 v34, 16, v178
	v_and_b32_e32 v35, 0xffff0000, v178
	v_lshlrev_b32_e32 v32, 16, v179
	v_and_b32_e32 v33, 0xffff0000, v179
	v_lshlrev_b32_e32 v30, 16, v180
	v_and_b32_e32 v31, 0xffff0000, v180
	v_lshlrev_b32_e32 v28, 16, v181
	v_and_b32_e32 v29, 0xffff0000, v181
	v_lshlrev_b32_e32 v190, 16, v182
	v_and_b32_e32 v191, 0xffff0000, v182
	v_lshlrev_b32_e32 v182, 16, v183
	v_and_b32_e32 v183, 0xffff0000, v183
	global_store_dwordx4 v[212:213], v[178:181], off offset:2304
	v_pk_mul_f32 v[154:155], v[74:75], v[32:33]
	v_pk_mul_f32 v[166:167], v[72:73], v[34:35]
	v_pk_mul_f32 v[168:169], v[70:71], v[28:29]
	v_pk_mul_f32 v[180:181], v[68:69], v[30:31]
	v_lshlrev_b32_e32 v192, 16, v184
	v_and_b32_e32 v193, 0xffff0000, v184
	v_lshlrev_b32_e32 v184, 16, v185
	v_and_b32_e32 v185, 0xffff0000, v185
	v_cvt_pk_bf16_f32 v178, v166, v167
	v_cvt_pk_bf16_f32 v179, v154, v155
	v_cvt_pk_bf16_f32 v180, v180, v181
	v_cvt_pk_bf16_f32 v181, v168, v169
	v_pk_fma_f32 v[24:25], v[24:25], v[106:107], v[182:183]
	v_pk_fma_f32 v[22:23], v[22:23], v[104:105], v[190:191]
	global_store_dwordx4 v[214:215], v[178:181], off offset:256
	v_pk_fma_f32 v[20:21], v[20:21], v[102:103], v[184:185]
	v_pk_fma_f32 v[18:19], v[18:19], v[100:101], v[192:193]
	v_cvt_pk_bf16_f32 v178, v22, v23
	v_cvt_pk_bf16_f32 v179, v24, v25
	v_cvt_pk_bf16_f32 v180, v18, v19
	v_cvt_pk_bf16_f32 v181, v20, v21
	v_lshlrev_b32_e32 v24, 16, v178
	v_and_b32_e32 v25, 0xffff0000, v178
	v_lshlrev_b32_e32 v22, 16, v179
	v_and_b32_e32 v23, 0xffff0000, v179
	v_lshlrev_b32_e32 v20, 16, v180
	v_and_b32_e32 v21, 0xffff0000, v180
	v_lshlrev_b32_e32 v18, 16, v181
	v_and_b32_e32 v19, 0xffff0000, v181
	v_pk_mul_f32 v[154:155], v[74:75], v[22:23]
	v_pk_mul_f32 v[166:167], v[72:73], v[24:25]
	global_store_dwordx4 v[216:217], v[178:181], off offset:2304
	v_pk_mul_f32 v[168:169], v[70:71], v[18:19]
	v_lshlrev_b32_e32 v182, 16, v189
	v_pk_mul_f32 v[180:181], v[68:69], v[20:21]
	v_cvt_pk_bf16_f32 v178, v166, v167
	v_cvt_pk_bf16_f32 v179, v154, v155
	v_lshlrev_b32_e32 v154, 16, v150
	v_and_b32_e32 v155, 0xffff0000, v150
	v_lshlrev_b32_e32 v150, 16, v151
	v_and_b32_e32 v151, 0xffff0000, v151
	v_lshlrev_b32_e32 v166, 16, v152
	v_and_b32_e32 v167, 0xffff0000, v152
	v_lshlrev_b32_e32 v152, 16, v153
	v_and_b32_e32 v153, 0xffff0000, v153
	v_cvt_pk_bf16_f32 v180, v180, v181
	v_cvt_pk_bf16_f32 v181, v168, v169
	v_pk_fma_f32 v[16:17], v[16:17], v[106:107], v[150:151]
	v_pk_fma_f32 v[14:15], v[14:15], v[104:105], v[154:155]
	v_pk_fma_f32 v[12:13], v[12:13], v[102:103], v[152:153]
	v_pk_fma_f32 v[10:11], v[10:11], v[100:101], v[166:167]
	global_store_dwordx4 v[218:219], v[178:181], off offset:256
	v_lshlrev_b32_e32 v168, 16, v186
	v_and_b32_e32 v169, 0xffff0000, v186
	v_lshlrev_b32_e32 v178, 16, v187
	v_and_b32_e32 v179, 0xffff0000, v187
	v_lshlrev_b32_e32 v180, 16, v188
	v_and_b32_e32 v181, 0xffff0000, v188
	v_and_b32_e32 v183, 0xffff0000, v189
	v_cvt_pk_bf16_f32 v150, v14, v15
	v_cvt_pk_bf16_f32 v151, v16, v17
	v_cvt_pk_bf16_f32 v152, v10, v11
	v_cvt_pk_bf16_f32 v153, v12, v13
	v_lshlrev_b32_e32 v16, 16, v150
	v_and_b32_e32 v17, 0xffff0000, v150
	v_lshlrev_b32_e32 v14, 16, v151
	v_and_b32_e32 v15, 0xffff0000, v151
	v_lshlrev_b32_e32 v12, 16, v152
	v_and_b32_e32 v13, 0xffff0000, v152
	v_lshlrev_b32_e32 v10, 16, v153
	v_and_b32_e32 v11, 0xffff0000, v153
	v_pk_fma_f32 v[8:9], v[8:9], v[106:107], v[178:179]
	v_pk_fma_f32 v[6:7], v[6:7], v[104:105], v[168:169]
	v_pk_fma_f32 v[4:5], v[4:5], v[102:103], v[182:183]
	v_pk_fma_f32 v[2:3], v[2:3], v[100:101], v[180:181]
	global_store_dwordx4 v[196:197], v[150:153], off offset:2304
	v_pk_mul_f32 v[154:155], v[70:71], v[10:11]
	v_pk_mul_f32 v[166:167], v[68:69], v[12:13]
	v_pk_mul_f32 v[152:153], v[74:75], v[14:15]
	v_pk_mul_f32 v[150:151], v[72:73], v[16:17]
	v_cvt_pk_bf16_f32 v100, v6, v7
	v_cvt_pk_bf16_f32 v101, v8, v9
	v_cvt_pk_bf16_f32 v102, v2, v3
	v_cvt_pk_bf16_f32 v103, v4, v5
	v_cvt_pk_bf16_f32 v150, v150, v151
	v_cvt_pk_bf16_f32 v151, v152, v153
	v_cvt_pk_bf16_f32 v152, v166, v167
	v_cvt_pk_bf16_f32 v153, v154, v155
	v_lshlrev_b32_e32 v8, 16, v100
	v_and_b32_e32 v9, 0xffff0000, v100
	v_lshlrev_b32_e32 v6, 16, v101
	v_and_b32_e32 v7, 0xffff0000, v101
	v_lshlrev_b32_e32 v4, 16, v102
	v_and_b32_e32 v5, 0xffff0000, v102
	v_lshlrev_b32_e32 v2, 16, v103
	v_and_b32_e32 v3, 0xffff0000, v103
	global_store_dwordx4 v[210:211], v[150:153], off offset:256
	global_store_dwordx4 v[220:221], v[100:103], off offset:2304
	v_pk_mul_f32 v[74:75], v[74:75], v[6:7]
	v_pk_mul_f32 v[72:73], v[72:73], v[8:9]
	v_pk_mul_f32 v[100:101], v[70:71], v[2:3]
	v_pk_mul_f32 v[70:71], v[68:69], v[4:5]
	v_cvt_pk_bf16_f32 v68, v72, v73
	v_cvt_pk_bf16_f32 v69, v74, v75
	v_cvt_pk_bf16_f32 v70, v70, v71
	v_cvt_pk_bf16_f32 v71, v100, v101
	global_store_dwordx4 v[148:149], v[68:71], off offset:256
	v_xor_b32_e32 v72, 32, v227
	v_mul_f32_e32 v73, v137, v137
	v_and_b32_e32 v71, 64, v227
	v_xor_b32_e32 v70, 16, v227
	v_add_u32_e32 v71, 64, v71
	v_cmp_lt_i32_e32 vcc, v70, v71
	v_fmac_f32_e32 v73, v136, v136
	v_mul_f32_e32 v74, v133, v133
	v_cndmask_b32_e32 v70, v227, v70, vcc
	v_cmp_lt_i32_e32 vcc, v72, v71
	v_fmac_f32_e32 v74, v132, v132
	v_lshlrev_b32_e32 v70, 2, v70
	v_cndmask_b32_e32 v71, v227, v72, vcc
	v_mul_f32_e32 v72, v139, v139
	v_fmac_f32_e32 v72, v138, v138
	v_add_f32_e32 v72, v72, v73
	v_mul_f32_e32 v73, v135, v135
	v_fmac_f32_e32 v73, v134, v134
	v_add_f32_e32 v73, v73, v74
	v_add_f32_e32 v72, v72, v73
	v_add_f32_e32 v64, v72, v64
	v_add_f32_e32 v60, v60, v64
	ds_bpermute_b32 v61, v70, v60
	v_lshlrev_b32_e32 v71, 2, v71
	v_lshl_add_u64 v[68:69], v[172:173], 0, s[28:29]
	s_waitcnt lgkmcnt(0)
	v_add_f32_e32 v60, v60, v61
	ds_bpermute_b32 v61, v71, v60
	s_and_saveexec_b64 s[18:19], s[38:39]
	s_cbranch_execz .LBB0_968
	s_waitcnt lgkmcnt(0)
	v_add_f32_e32 v60, v60, v61
	global_atomic_add_f32 v[68:69], v60, off

.LBB0_1048:
	s_add_u32 s0, s24, 0xfffc0080
	s_addc_u32 s1, s25, -1
	s_add_i32 s83, 0, 0x10000
	v_add_u32_e32 v80, s83, v163
	ds_read_b128 v[68:71], v80
	ds_read_b128 v[72:75], v80 offset:1024
	ds_read_b128 v[76:79], v80 offset:2048
	ds_read_b128 v[80:83], v80 offset:3072
	s_cmp_eq_u32 s82, 12
	s_cselect_b32 s29, s43, s1
	s_cselect_b32 s28, s69, s0
	s_cselect_b32 s27, s45, s81
	s_cselect_b32 s26, s72, s73
	v_lshl_add_u64 v[166:167], s[24:25], 0, v[154:155]
	s_add_i32 m0, s23, 0xc000
	ds_read_b128 v[158:161], v165
	ds_read_b128 v[174:177], v165 offset:1024
	ds_read_b128 v[178:181], v165 offset:2048
	ds_read_b128 v[182:185], v165 offset:3072
	ds_read_b128 v[186:189], v165 offset:4096
	ds_read_b128 v[190:193], v165 offset:5120
	ds_read_b128 v[194:197], v165 offset:6144
	ds_read_b128 v[198:201], v165 offset:7168
	global_load_lds_dwordx4 v[166:167], off
	v_lshl_add_u64 v[166:167], s[24:25], 0, v[156:157]
	s_add_i32 m0, s23, 0xe000
	s_nop 0
	global_load_lds_dwordx4 v[166:167], off
	s_waitcnt vmcnt(10) lgkmcnt(8)
	s_setprio 1
	s_barrier
	s_waitcnt lgkmcnt(0)
	v_mfma_f32_16x16x32_bf16 v[144:147], v[68:71], v[158:161], v[144:147]
	v_mfma_f32_16x16x32_bf16 v[140:143], v[76:79], v[158:161], v[140:143]
	v_mfma_f32_16x16x32_bf16 v[128:131], v[68:71], v[178:181], v[128:131]
	v_mfma_f32_16x16x32_bf16 v[124:127], v[76:79], v[178:181], v[124:127]
	v_mfma_f32_16x16x32_bf16 v[112:115], v[68:71], v[186:189], v[112:115]
	v_mfma_f32_16x16x32_bf16 v[108:111], v[76:79], v[186:189], v[108:111]
	v_mfma_f32_16x16x32_bf16 v[96:99], v[68:71], v[194:197], v[96:99]
	v_mfma_f32_16x16x32_bf16 v[92:95], v[76:79], v[194:197], v[92:95]
	v_mfma_f32_16x16x32_bf16 v[144:147], v[72:75], v[174:177], v[144:147]
	v_mfma_f32_16x16x32_bf16 v[140:143], v[80:83], v[174:177], v[140:143]
	v_mfma_f32_16x16x32_bf16 v[128:131], v[72:75], v[182:185], v[128:131]
	v_mfma_f32_16x16x32_bf16 v[124:127], v[80:83], v[182:185], v[124:127]
	v_mfma_f32_16x16x32_bf16 v[112:115], v[72:75], v[190:193], v[112:115]
	v_mfma_f32_16x16x32_bf16 v[108:111], v[80:83], v[190:193], v[108:111]
	v_mfma_f32_16x16x32_bf16 v[96:99], v[72:75], v[198:201], v[96:99]
	v_mfma_f32_16x16x32_bf16 v[92:95], v[80:83], v[198:201], v[92:95]
	s_barrier
	s_setprio 0
	s_add_i32 s84, 0, 0x14000
	v_add_u32_e32 v166, s84, v163
	s_add_i32 s0, s83, s54
	ds_read_b128 v[202:205], v166
	ds_read_b128 v[206:209], v166 offset:1024
	ds_read_b128 v[210:213], v166 offset:2048
	ds_read_b128 v[214:217], v166 offset:3072
	v_lshl_add_u64 v[166:167], s[26:27], 0, v[26:27]
	s_mov_b32 m0, s0
	v_lshl_add_u64 v[168:169], s[26:27], 0, v[148:149]
	global_load_lds_dwordx4 v[166:167], off
	s_add_i32 m0, s0, 0x2000
	s_nop 0
	global_load_lds_dwordx4 v[168:169], off
	s_waitcnt vmcnt(10)
	s_setprio 1
	s_barrier
	s_waitcnt lgkmcnt(0)
	v_mfma_f32_16x16x32_bf16 v[136:139], v[202:205], v[158:161], v[136:139]
	v_mfma_f32_16x16x32_bf16 v[132:135], v[210:213], v[158:161], v[132:135]
	v_mfma_f32_16x16x32_bf16 v[120:123], v[202:205], v[178:181], v[120:123]
	v_mfma_f32_16x16x32_bf16 v[116:119], v[210:213], v[178:181], v[116:119]
	v_mfma_f32_16x16x32_bf16 v[104:107], v[202:205], v[186:189], v[104:107]
	v_mfma_f32_16x16x32_bf16 v[100:103], v[210:213], v[186:189], v[100:103]
	v_mfma_f32_16x16x32_bf16 v[88:91], v[202:205], v[194:197], v[88:91]
	v_mfma_f32_16x16x32_bf16 v[84:87], v[210:213], v[194:197], v[84:87]
	v_mfma_f32_16x16x32_bf16 v[136:139], v[206:209], v[174:177], v[136:139]
	v_mfma_f32_16x16x32_bf16 v[132:135], v[214:217], v[174:177], v[132:135]
	v_mfma_f32_16x16x32_bf16 v[120:123], v[206:209], v[182:185], v[120:123]
	v_mfma_f32_16x16x32_bf16 v[116:119], v[214:217], v[182:185], v[116:119]
	v_mfma_f32_16x16x32_bf16 v[104:107], v[206:209], v[190:193], v[104:107]
	v_mfma_f32_16x16x32_bf16 v[100:103], v[214:217], v[190:193], v[100:103]
	v_mfma_f32_16x16x32_bf16 v[88:91], v[206:209], v[198:201], v[88:91]
	v_mfma_f32_16x16x32_bf16 v[84:87], v[214:217], v[198:201], v[84:87]
	s_barrier
	s_setprio 0
	s_mov_b32 m0, s23
	v_lshl_add_u64 v[218:219], s[28:29], 0, v[152:153]
	ds_read_b128 v[158:161], v165 offset:16384
	ds_read_b128 v[174:177], v165 offset:17408
	ds_read_b128 v[178:181], v165 offset:18432
	ds_read_b128 v[182:185], v165 offset:19456
	ds_read_b128 v[186:189], v165 offset:20480
	ds_read_b128 v[190:193], v165 offset:21504
	ds_read_b128 v[194:197], v165 offset:22528
	ds_read_b128 v[198:201], v165 offset:23552
	global_load_lds_dwordx4 v[218:219], off
	v_lshl_add_u64 v[220:221], s[28:29], 0, v[150:151]
	s_mov_b32 m0, s57
	s_nop 0
	global_load_lds_dwordx4 v[220:221], off
	s_setprio 1
	s_barrier
	s_waitcnt lgkmcnt(0)
	v_mfma_f32_16x16x32_bf16 v[64:67], v[68:71], v[158:161], v[64:67]
	v_mfma_f32_16x16x32_bf16 v[60:63], v[76:79], v[158:161], v[60:63]
	v_mfma_f32_16x16x32_bf16 v[48:51], v[68:71], v[178:181], v[48:51]
	v_mfma_f32_16x16x32_bf16 v[44:47], v[76:79], v[178:181], v[44:47]
	v_mfma_f32_16x16x32_bf16 v[32:35], v[68:71], v[186:189], v[32:35]
	v_mfma_f32_16x16x32_bf16 v[28:31], v[76:79], v[186:189], v[28:31]
	v_mfma_f32_16x16x32_bf16 v[14:17], v[68:71], v[194:197], v[14:17]
	v_mfma_f32_16x16x32_bf16 v[10:13], v[76:79], v[194:197], v[10:13]
	v_mfma_f32_16x16x32_bf16 v[64:67], v[72:75], v[174:177], v[64:67]
	v_mfma_f32_16x16x32_bf16 v[60:63], v[80:83], v[174:177], v[60:63]
	v_mfma_f32_16x16x32_bf16 v[48:51], v[72:75], v[182:185], v[48:51]
	v_mfma_f32_16x16x32_bf16 v[44:47], v[80:83], v[182:185], v[44:47]
	v_mfma_f32_16x16x32_bf16 v[32:35], v[72:75], v[190:193], v[32:35]
	v_mfma_f32_16x16x32_bf16 v[28:31], v[80:83], v[190:193], v[28:31]
	v_mfma_f32_16x16x32_bf16 v[14:17], v[72:75], v[198:201], v[14:17]
	v_mfma_f32_16x16x32_bf16 v[10:13], v[80:83], v[198:201], v[10:13]
	s_barrier
	s_setprio 0
	s_add_u32 s0, s26, 0x40000
	s_addc_u32 s1, s27, 0
	s_add_i32 s83, s84, s54
	v_lshl_add_u64 v[68:69], s[0:1], 0, v[26:27]
	s_mov_b32 m0, s83
	s_nop 0
	global_load_lds_dwordx4 v[68:69], off
	v_lshl_add_u64 v[68:69], s[0:1], 0, v[148:149]
	s_add_i32 m0, s83, 0x2000
	s_nop 0
	global_load_lds_dwordx4 v[68:69], off
	s_waitcnt vmcnt(10)
	s_setprio 1
	s_barrier
	v_mfma_f32_16x16x32_bf16 v[56:59], v[202:205], v[158:161], v[56:59]
	v_mfma_f32_16x16x32_bf16 v[52:55], v[210:213], v[158:161], v[52:55]
	v_mfma_f32_16x16x32_bf16 v[40:43], v[202:205], v[178:181], v[40:43]
	v_mfma_f32_16x16x32_bf16 v[36:39], v[210:213], v[178:181], v[36:39]
	v_mfma_f32_16x16x32_bf16 v[22:25], v[202:205], v[186:189], v[22:25]
	v_mfma_f32_16x16x32_bf16 v[18:21], v[210:213], v[186:189], v[18:21]
	v_mfma_f32_16x16x32_bf16 v[6:9], v[202:205], v[194:197], v[6:9]
	v_mfma_f32_16x16x32_bf16 v[2:5], v[210:213], v[194:197], v[2:5]
	v_mfma_f32_16x16x32_bf16 v[56:59], v[206:209], v[174:177], v[56:59]
	v_mfma_f32_16x16x32_bf16 v[52:55], v[214:217], v[174:177], v[52:55]
	v_mfma_f32_16x16x32_bf16 v[40:43], v[206:209], v[182:185], v[40:43]
	v_mfma_f32_16x16x32_bf16 v[36:39], v[214:217], v[182:185], v[36:39]
	v_mfma_f32_16x16x32_bf16 v[22:25], v[206:209], v[190:193], v[22:25]
	v_mfma_f32_16x16x32_bf16 v[18:21], v[214:217], v[190:193], v[18:21]
	v_mfma_f32_16x16x32_bf16 v[6:9], v[206:209], v[198:201], v[6:9]
	v_mfma_f32_16x16x32_bf16 v[2:5], v[214:217], v[198:201], v[2:5]
	s_barrier
	s_setprio 0
	s_add_i32 s83, 0, 0x18000
	v_add_u32_e32 v80, s83, v163
	ds_read_b128 v[68:71], v80
	ds_read_b128 v[72:75], v80 offset:1024
	ds_read_b128 v[76:79], v80 offset:2048
	ds_read_b128 v[80:83], v80 offset:3072
	s_add_u32 s0, s28, 0x40000
	s_addc_u32 s1, s29, 0
	s_mov_b32 m0, s58
	v_lshl_add_u64 v[202:203], s[0:1], 0, v[152:153]
	ds_read_b128 v[158:161], v165 offset:32768
	ds_read_b128 v[174:177], v165 offset:33792
	ds_read_b128 v[178:181], v165 offset:34816
	ds_read_b128 v[182:185], v165 offset:35840
	ds_read_b128 v[186:189], v165 offset:36864
	ds_read_b128 v[190:193], v165 offset:37888
	ds_read_b128 v[194:197], v165 offset:38912
	ds_read_b128 v[198:201], v165 offset:39936
	global_load_lds_dwordx4 v[202:203], off
	v_lshl_add_u64 v[202:203], s[0:1], 0, v[150:151]
	s_mov_b32 m0, s59
	s_nop 0
	global_load_lds_dwordx4 v[202:203], off
	s_waitcnt vmcnt(10) lgkmcnt(8)
	s_setprio 1
	s_barrier
	s_waitcnt lgkmcnt(0)
	v_mfma_f32_16x16x32_bf16 v[144:147], v[68:71], v[158:161], v[144:147]
	v_mfma_f32_16x16x32_bf16 v[140:143], v[76:79], v[158:161], v[140:143]
	v_mfma_f32_16x16x32_bf16 v[128:131], v[68:71], v[178:181], v[128:131]
	v_mfma_f32_16x16x32_bf16 v[124:127], v[76:79], v[178:181], v[124:127]
	v_mfma_f32_16x16x32_bf16 v[112:115], v[68:71], v[186:189], v[112:115]
	v_mfma_f32_16x16x32_bf16 v[108:111], v[76:79], v[186:189], v[108:111]
	v_mfma_f32_16x16x32_bf16 v[96:99], v[68:71], v[194:197], v[96:99]
	v_mfma_f32_16x16x32_bf16 v[92:95], v[76:79], v[194:197], v[92:95]
	v_mfma_f32_16x16x32_bf16 v[144:147], v[72:75], v[174:177], v[144:147]
	v_mfma_f32_16x16x32_bf16 v[140:143], v[80:83], v[174:177], v[140:143]
	v_mfma_f32_16x16x32_bf16 v[128:131], v[72:75], v[182:185], v[128:131]
	v_mfma_f32_16x16x32_bf16 v[124:127], v[80:83], v[182:185], v[124:127]
	v_mfma_f32_16x16x32_bf16 v[112:115], v[72:75], v[190:193], v[112:115]
	v_mfma_f32_16x16x32_bf16 v[108:111], v[80:83], v[190:193], v[108:111]
	v_mfma_f32_16x16x32_bf16 v[96:99], v[72:75], v[198:201], v[96:99]
	v_mfma_f32_16x16x32_bf16 v[92:95], v[80:83], v[198:201], v[92:95]
	s_barrier
	s_setprio 0
	s_add_i32 s28, 0, 0x1c000
	s_add_i32 s0, s83, s54
	v_add_u32_e32 v173, s28, v163
	v_lshl_add_u64 v[166:167], v[166:167], 0, s[12:13]
	s_mov_b32 m0, s0
	ds_read_b128 v[202:205], v173
	ds_read_b128 v[206:209], v173 offset:1024
	ds_read_b128 v[210:213], v173 offset:2048
	ds_read_b128 v[214:217], v173 offset:3072
	global_load_lds_dwordx4 v[166:167], off
	v_lshl_add_u64 v[166:167], v[168:169], 0, s[12:13]
	s_add_i32 m0, s0, 0x2000
	s_nop 0
	global_load_lds_dwordx4 v[166:167], off
	s_waitcnt vmcnt(10)
	s_setprio 1
	s_barrier
	s_waitcnt lgkmcnt(0)
	v_mfma_f32_16x16x32_bf16 v[136:139], v[202:205], v[158:161], v[136:139]
	v_mfma_f32_16x16x32_bf16 v[132:135], v[210:213], v[158:161], v[132:135]
	v_mfma_f32_16x16x32_bf16 v[120:123], v[202:205], v[178:181], v[120:123]
	v_mfma_f32_16x16x32_bf16 v[116:119], v[210:213], v[178:181], v[116:119]
	v_mfma_f32_16x16x32_bf16 v[104:107], v[202:205], v[186:189], v[104:107]
	v_mfma_f32_16x16x32_bf16 v[100:103], v[210:213], v[186:189], v[100:103]
	v_mfma_f32_16x16x32_bf16 v[88:91], v[202:205], v[194:197], v[88:91]
	v_mfma_f32_16x16x32_bf16 v[84:87], v[210:213], v[194:197], v[84:87]
	v_mfma_f32_16x16x32_bf16 v[136:139], v[206:209], v[174:177], v[136:139]
	v_mfma_f32_16x16x32_bf16 v[132:135], v[214:217], v[174:177], v[132:135]
	v_mfma_f32_16x16x32_bf16 v[120:123], v[206:209], v[182:185], v[120:123]
	v_mfma_f32_16x16x32_bf16 v[116:119], v[214:217], v[182:185], v[116:119]
	v_mfma_f32_16x16x32_bf16 v[104:107], v[206:209], v[190:193], v[104:107]
	v_mfma_f32_16x16x32_bf16 v[100:103], v[214:217], v[190:193], v[100:103]
	v_mfma_f32_16x16x32_bf16 v[88:91], v[206:209], v[198:201], v[88:91]
	v_mfma_f32_16x16x32_bf16 v[84:87], v[214:217], v[198:201], v[84:87]
	s_barrier
	s_setprio 0
	s_mov_b32 m0, s34
	v_lshl_add_u64 v[166:167], v[218:219], 0, s[12:13]
	ds_read_b128 v[158:161], v165 offset:49152
	ds_read_b128 v[174:177], v165 offset:50176
	ds_read_b128 v[178:181], v165 offset:51200
	ds_read_b128 v[182:185], v165 offset:52224
	ds_read_b128 v[186:189], v165 offset:53248
	ds_read_b128 v[190:193], v165 offset:54272
	ds_read_b128 v[194:197], v165 offset:55296
	ds_read_b128 v[198:201], v165 offset:56320
	global_load_lds_dwordx4 v[166:167], off
	v_lshl_add_u64 v[166:167], v[220:221], 0, s[12:13]
	s_mov_b32 m0, s35
	s_nop 0
	global_load_lds_dwordx4 v[166:167], off
	s_setprio 1
	s_barrier
	s_waitcnt lgkmcnt(0)
	v_mfma_f32_16x16x32_bf16 v[64:67], v[68:71], v[158:161], v[64:67]
	v_mfma_f32_16x16x32_bf16 v[60:63], v[76:79], v[158:161], v[60:63]
	v_mfma_f32_16x16x32_bf16 v[48:51], v[68:71], v[178:181], v[48:51]
	v_mfma_f32_16x16x32_bf16 v[44:47], v[76:79], v[178:181], v[44:47]
	v_mfma_f32_16x16x32_bf16 v[32:35], v[68:71], v[186:189], v[32:35]
	v_mfma_f32_16x16x32_bf16 v[28:31], v[76:79], v[186:189], v[28:31]
	v_mfma_f32_16x16x32_bf16 v[14:17], v[68:71], v[194:197], v[14:17]
	v_mfma_f32_16x16x32_bf16 v[10:13], v[76:79], v[194:197], v[10:13]
	v_mfma_f32_16x16x32_bf16 v[64:67], v[72:75], v[174:177], v[64:67]
	v_mfma_f32_16x16x32_bf16 v[60:63], v[80:83], v[174:177], v[60:63]
	v_mfma_f32_16x16x32_bf16 v[48:51], v[72:75], v[182:185], v[48:51]
	v_mfma_f32_16x16x32_bf16 v[44:47], v[80:83], v[182:185], v[44:47]
	v_mfma_f32_16x16x32_bf16 v[32:35], v[72:75], v[190:193], v[32:35]
	v_mfma_f32_16x16x32_bf16 v[28:31], v[80:83], v[190:193], v[28:31]
	v_mfma_f32_16x16x32_bf16 v[14:17], v[72:75], v[198:201], v[14:17]
	v_mfma_f32_16x16x32_bf16 v[10:13], v[80:83], v[198:201], v[10:13]
	s_barrier
	s_setprio 0
	s_add_u32 s0, s26, 0x40080
	s_addc_u32 s1, s27, 0
	s_add_i32 s26, s28, s54
	v_lshl_add_u64 v[68:69], s[0:1], 0, v[26:27]
	s_mov_b32 m0, s26
	s_nop 0
	global_load_lds_dwordx4 v[68:69], off
	v_lshl_add_u64 v[68:69], s[0:1], 0, v[148:149]
	s_add_i32 m0, s26, 0x2000
	s_nop 0
	global_load_lds_dwordx4 v[68:69], off
	s_waitcnt vmcnt(10)
	s_setprio 1
	s_barrier
	v_mfma_f32_16x16x32_bf16 v[56:59], v[202:205], v[158:161], v[56:59]
	v_mfma_f32_16x16x32_bf16 v[52:55], v[210:213], v[158:161], v[52:55]
	v_mfma_f32_16x16x32_bf16 v[40:43], v[202:205], v[178:181], v[40:43]
	v_mfma_f32_16x16x32_bf16 v[36:39], v[210:213], v[178:181], v[36:39]
	v_mfma_f32_16x16x32_bf16 v[22:25], v[202:205], v[186:189], v[22:25]
	v_mfma_f32_16x16x32_bf16 v[18:21], v[210:213], v[186:189], v[18:21]
	v_mfma_f32_16x16x32_bf16 v[6:9], v[202:205], v[194:197], v[6:9]
	v_mfma_f32_16x16x32_bf16 v[2:5], v[210:213], v[194:197], v[2:5]
	v_mfma_f32_16x16x32_bf16 v[56:59], v[206:209], v[174:177], v[56:59]
	v_mfma_f32_16x16x32_bf16 v[52:55], v[214:217], v[174:177], v[52:55]
	v_mfma_f32_16x16x32_bf16 v[40:43], v[206:209], v[182:185], v[40:43]
	v_mfma_f32_16x16x32_bf16 v[36:39], v[214:217], v[182:185], v[36:39]
	v_mfma_f32_16x16x32_bf16 v[22:25], v[206:209], v[190:193], v[22:25]
	v_mfma_f32_16x16x32_bf16 v[18:21], v[214:217], v[190:193], v[18:21]
	v_mfma_f32_16x16x32_bf16 v[6:9], v[206:209], v[198:201], v[6:9]
	v_mfma_f32_16x16x32_bf16 v[2:5], v[214:217], v[198:201], v[2:5]
	s_barrier
	s_setprio 0
	s_add_i32 s82, s82, 2
	s_add_u32 s24, s24, 0x100
	s_addc_u32 s25, s25, 0
	s_add_u32 s73, s73, 0x100
	s_addc_u32 s81, s81, 0
	s_cmp_gt_u32 s82, 13
	s_cbranch_scc0 .LBB0_1048
	v_readlane_b32 s82, v255, 51
	s_cmpk_gt_i32 s22, 0xff
	s_mov_b64 s[24:25], 0xb000
	v_readlane_b32 s83, v255, 52
	s_cbranch_scc1 .LBB0_1044
	s_ashr_i32 s0, s22, 5
	s_mul_hi_i32 s25, s0, 0x1600
	s_mul_i32 s24, s0, 0x1600
	s_branch .LBB0_1044

.LBB0_1122:
	s_add_u32 s26, s24, 0x100
	s_addc_u32 s27, s25, 0
	s_add_i32 s0, 0, 0x10000
	v_add_u32_e32 v158, s0, v186
	ds_read_b128 v[132:135], v158
	ds_read_b128 v[136:139], v158 offset:1024
	ds_read_b128 v[154:157], v158 offset:2048
	ds_read_b128 v[158:161], v158 offset:3072
	s_cmp_eq_u32 s72, 40
	s_cselect_b32 s31, s43, s27
	s_cselect_b32 s30, s42, s26
	s_cselect_b32 s29, s45, s69
	s_cselect_b32 s28, s44, s68
	v_lshl_add_u64 v[166:167], s[24:25], 0, v[150:151]
	s_add_i32 m0, s36, 0xc000
	ds_read_b128 v[162:165], v188
	ds_read_b128 v[172:175], v188 offset:1024
	ds_read_b128 v[176:179], v188 offset:2048
	ds_read_b128 v[180:183], v188 offset:3072
	ds_read_b128 v[190:193], v188 offset:4096
	ds_read_b128 v[194:197], v188 offset:5120
	ds_read_b128 v[198:201], v188 offset:6144
	ds_read_b128 v[202:205], v188 offset:7168
	global_load_lds_dwordx4 v[166:167], off
	v_lshl_add_u64 v[166:167], s[24:25], 0, v[152:153]
	s_add_i32 m0, s36, 0xe000
	s_nop 0
	global_load_lds_dwordx4 v[166:167], off
	s_waitcnt vmcnt(10) lgkmcnt(8)
	s_setprio 1
	s_barrier
	s_waitcnt lgkmcnt(0)
	v_mfma_f32_16x16x32_bf16 v[128:131], v[132:135], v[162:165], v[128:131]
	v_mfma_f32_16x16x32_bf16 v[124:127], v[154:157], v[162:165], v[124:127]
	v_mfma_f32_16x16x32_bf16 v[120:123], v[132:135], v[176:179], v[120:123]
	v_mfma_f32_16x16x32_bf16 v[116:119], v[154:157], v[176:179], v[116:119]
	v_mfma_f32_16x16x32_bf16 v[112:115], v[132:135], v[190:193], v[112:115]
	v_mfma_f32_16x16x32_bf16 v[108:111], v[154:157], v[190:193], v[108:111]
	v_mfma_f32_16x16x32_bf16 v[104:107], v[132:135], v[198:201], v[104:107]
	v_mfma_f32_16x16x32_bf16 v[100:103], v[154:157], v[198:201], v[100:103]
	v_mfma_f32_16x16x32_bf16 v[128:131], v[136:139], v[172:175], v[128:131]
	v_mfma_f32_16x16x32_bf16 v[124:127], v[158:161], v[172:175], v[124:127]
	v_mfma_f32_16x16x32_bf16 v[120:123], v[136:139], v[180:183], v[120:123]
	v_mfma_f32_16x16x32_bf16 v[116:119], v[158:161], v[180:183], v[116:119]
	v_mfma_f32_16x16x32_bf16 v[112:115], v[136:139], v[194:197], v[112:115]
	v_mfma_f32_16x16x32_bf16 v[108:111], v[158:161], v[194:197], v[108:111]
	v_mfma_f32_16x16x32_bf16 v[104:107], v[136:139], v[202:205], v[104:107]
	v_mfma_f32_16x16x32_bf16 v[100:103], v[158:161], v[202:205], v[100:103]
	s_barrier
	s_setprio 0
	s_add_i32 s24, 0, 0x14000
	v_add_u32_e32 v166, s24, v186
	s_add_i32 s0, s0, s17
	ds_read_b128 v[206:209], v166
	ds_read_b128 v[210:213], v166 offset:1024
	ds_read_b128 v[214:217], v166 offset:2048
	ds_read_b128 v[218:221], v166 offset:3072
	v_lshl_add_u64 v[166:167], s[28:29], 0, v[26:27]
	s_mov_b32 m0, s0
	v_lshl_add_u64 v[168:169], s[28:29], 0, v[144:145]
	global_load_lds_dwordx4 v[166:167], off
	s_add_i32 m0, s0, 0x2000
	s_nop 0
	global_load_lds_dwordx4 v[168:169], off
	s_waitcnt vmcnt(10)
	s_setprio 1
	s_barrier
	s_waitcnt lgkmcnt(0)
	v_mfma_f32_16x16x32_bf16 v[68:71], v[206:209], v[162:165], v[68:71]
	v_mfma_f32_16x16x32_bf16 v[60:63], v[214:217], v[162:165], v[60:63]
	v_mfma_f32_16x16x32_bf16 v[56:59], v[206:209], v[176:179], v[56:59]
	v_mfma_f32_16x16x32_bf16 v[52:55], v[214:217], v[176:179], v[52:55]
	v_mfma_f32_16x16x32_bf16 v[48:51], v[206:209], v[190:193], v[48:51]
	v_mfma_f32_16x16x32_bf16 v[44:47], v[214:217], v[190:193], v[44:47]
	v_mfma_f32_16x16x32_bf16 v[40:43], v[206:209], v[198:201], v[40:43]
	v_mfma_f32_16x16x32_bf16 v[36:39], v[214:217], v[198:201], v[36:39]
	v_mfma_f32_16x16x32_bf16 v[68:71], v[210:213], v[172:175], v[68:71]
	v_mfma_f32_16x16x32_bf16 v[60:63], v[218:221], v[172:175], v[60:63]
	v_mfma_f32_16x16x32_bf16 v[56:59], v[210:213], v[180:183], v[56:59]
	v_mfma_f32_16x16x32_bf16 v[52:55], v[218:221], v[180:183], v[52:55]
	v_mfma_f32_16x16x32_bf16 v[48:51], v[210:213], v[194:197], v[48:51]
	v_mfma_f32_16x16x32_bf16 v[44:47], v[218:221], v[194:197], v[44:47]
	v_mfma_f32_16x16x32_bf16 v[40:43], v[210:213], v[202:205], v[40:43]
	v_mfma_f32_16x16x32_bf16 v[36:39], v[218:221], v[202:205], v[36:39]
	s_barrier
	s_setprio 0
	s_mov_b32 m0, s36
	v_lshl_add_u64 v[184:185], s[30:31], 0, v[140:141]
	ds_read_b128 v[162:165], v188 offset:16384
	ds_read_b128 v[172:175], v188 offset:17408
	ds_read_b128 v[176:179], v188 offset:18432
	ds_read_b128 v[180:183], v188 offset:19456
	ds_read_b128 v[190:193], v188 offset:20480
	ds_read_b128 v[194:197], v188 offset:21504
	ds_read_b128 v[198:201], v188 offset:22528
	ds_read_b128 v[202:205], v188 offset:23552
	global_load_lds_dwordx4 v[184:185], off
	v_lshl_add_u64 v[222:223], s[30:31], 0, v[142:143]
	s_mov_b32 m0, s37
	s_nop 0
	global_load_lds_dwordx4 v[222:223], off
	s_setprio 1
	s_barrier
	s_waitcnt lgkmcnt(0)
	v_mfma_f32_16x16x32_bf16 v[96:99], v[132:135], v[162:165], v[96:99]
	v_mfma_f32_16x16x32_bf16 v[92:95], v[154:157], v[162:165], v[92:95]
	v_mfma_f32_16x16x32_bf16 v[88:91], v[132:135], v[176:179], v[88:91]
	v_mfma_f32_16x16x32_bf16 v[84:87], v[154:157], v[176:179], v[84:87]
	v_mfma_f32_16x16x32_bf16 v[80:83], v[132:135], v[190:193], v[80:83]
	v_mfma_f32_16x16x32_bf16 v[76:79], v[154:157], v[190:193], v[76:79]
	v_mfma_f32_16x16x32_bf16 v[72:75], v[132:135], v[198:201], v[72:75]
	v_mfma_f32_16x16x32_bf16 v[64:67], v[154:157], v[198:201], v[64:67]
	v_mfma_f32_16x16x32_bf16 v[96:99], v[136:139], v[172:175], v[96:99]
	v_mfma_f32_16x16x32_bf16 v[92:95], v[158:161], v[172:175], v[92:95]
	v_mfma_f32_16x16x32_bf16 v[88:91], v[136:139], v[180:183], v[88:91]
	v_mfma_f32_16x16x32_bf16 v[84:87], v[158:161], v[180:183], v[84:87]
	v_mfma_f32_16x16x32_bf16 v[80:83], v[136:139], v[194:197], v[80:83]
	v_mfma_f32_16x16x32_bf16 v[76:79], v[158:161], v[194:197], v[76:79]
	v_mfma_f32_16x16x32_bf16 v[72:75], v[136:139], v[202:205], v[72:75]
	v_mfma_f32_16x16x32_bf16 v[64:67], v[158:161], v[202:205], v[64:67]
	s_barrier
	s_setprio 0
	s_add_u32 s0, s28, 0xb0000
	s_addc_u32 s1, s29, 0
	s_add_i32 s24, s24, s17
	v_lshl_add_u64 v[132:133], s[0:1], 0, v[26:27]
	s_mov_b32 m0, s24
	s_nop 0
	global_load_lds_dwordx4 v[132:133], off
	v_lshl_add_u64 v[132:133], s[0:1], 0, v[144:145]
	s_add_i32 m0, s24, 0x2000
	s_nop 0
	global_load_lds_dwordx4 v[132:133], off
	s_waitcnt vmcnt(10)
	s_setprio 1
	s_barrier
	v_mfma_f32_16x16x32_bf16 v[32:35], v[206:209], v[162:165], v[32:35]
	v_mfma_f32_16x16x32_bf16 v[28:31], v[214:217], v[162:165], v[28:31]
	v_mfma_f32_16x16x32_bf16 v[22:25], v[206:209], v[176:179], v[22:25]
	v_mfma_f32_16x16x32_bf16 v[18:21], v[214:217], v[176:179], v[18:21]
	v_mfma_f32_16x16x32_bf16 v[14:17], v[206:209], v[190:193], v[14:17]
	v_mfma_f32_16x16x32_bf16 v[10:13], v[214:217], v[190:193], v[10:13]
	v_mfma_f32_16x16x32_bf16 v[6:9], v[206:209], v[198:201], v[6:9]
	v_mfma_f32_16x16x32_bf16 v[2:5], v[214:217], v[198:201], v[2:5]
	v_mfma_f32_16x16x32_bf16 v[32:35], v[210:213], v[172:175], v[32:35]
	v_mfma_f32_16x16x32_bf16 v[28:31], v[218:221], v[172:175], v[28:31]
	v_mfma_f32_16x16x32_bf16 v[22:25], v[210:213], v[180:183], v[22:25]
	v_mfma_f32_16x16x32_bf16 v[18:21], v[218:221], v[180:183], v[18:21]
	v_mfma_f32_16x16x32_bf16 v[14:17], v[210:213], v[194:197], v[14:17]
	v_mfma_f32_16x16x32_bf16 v[10:13], v[218:221], v[194:197], v[10:13]
	v_mfma_f32_16x16x32_bf16 v[6:9], v[210:213], v[202:205], v[6:9]
	v_mfma_f32_16x16x32_bf16 v[2:5], v[218:221], v[202:205], v[2:5]
	s_barrier
	s_setprio 0
	s_add_i32 s24, 0, 0x18000
	v_add_u32_e32 v158, s24, v186
	ds_read_b128 v[132:135], v158
	ds_read_b128 v[136:139], v158 offset:1024
	ds_read_b128 v[154:157], v158 offset:2048
	ds_read_b128 v[158:161], v158 offset:3072
	s_add_u32 s0, s30, 0xb0000
	s_addc_u32 s1, s31, 0
	s_mov_b32 m0, s52
	v_lshl_add_u64 v[206:207], s[0:1], 0, v[140:141]
	ds_read_b128 v[162:165], v188 offset:32768
	ds_read_b128 v[172:175], v188 offset:33792
	ds_read_b128 v[176:179], v188 offset:34816
	ds_read_b128 v[180:183], v188 offset:35840
	ds_read_b128 v[190:193], v188 offset:36864
	ds_read_b128 v[194:197], v188 offset:37888
	ds_read_b128 v[198:201], v188 offset:38912
	ds_read_b128 v[202:205], v188 offset:39936
	global_load_lds_dwordx4 v[206:207], off
	v_lshl_add_u64 v[206:207], s[0:1], 0, v[142:143]
	s_mov_b32 m0, s54
	s_nop 0
	global_load_lds_dwordx4 v[206:207], off
	s_waitcnt vmcnt(10) lgkmcnt(8)
	s_setprio 1
	s_barrier
	s_waitcnt lgkmcnt(0)
	v_mfma_f32_16x16x32_bf16 v[128:131], v[132:135], v[162:165], v[128:131]
	v_mfma_f32_16x16x32_bf16 v[124:127], v[154:157], v[162:165], v[124:127]
	v_mfma_f32_16x16x32_bf16 v[120:123], v[132:135], v[176:179], v[120:123]
	v_mfma_f32_16x16x32_bf16 v[116:119], v[154:157], v[176:179], v[116:119]
	v_mfma_f32_16x16x32_bf16 v[112:115], v[132:135], v[190:193], v[112:115]
	v_mfma_f32_16x16x32_bf16 v[108:111], v[154:157], v[190:193], v[108:111]
	v_mfma_f32_16x16x32_bf16 v[104:107], v[132:135], v[198:201], v[104:107]
	v_mfma_f32_16x16x32_bf16 v[100:103], v[154:157], v[198:201], v[100:103]
	v_mfma_f32_16x16x32_bf16 v[128:131], v[136:139], v[172:175], v[128:131]
	v_mfma_f32_16x16x32_bf16 v[124:127], v[158:161], v[172:175], v[124:127]
	v_mfma_f32_16x16x32_bf16 v[120:123], v[136:139], v[180:183], v[120:123]
	v_mfma_f32_16x16x32_bf16 v[116:119], v[158:161], v[180:183], v[116:119]
	v_mfma_f32_16x16x32_bf16 v[112:115], v[136:139], v[194:197], v[112:115]
	v_mfma_f32_16x16x32_bf16 v[108:111], v[158:161], v[194:197], v[108:111]
	v_mfma_f32_16x16x32_bf16 v[104:107], v[136:139], v[202:205], v[104:107]
	v_mfma_f32_16x16x32_bf16 v[100:103], v[158:161], v[202:205], v[100:103]
	s_barrier
	s_setprio 0
	s_add_i32 s25, 0, 0x1c000
	s_add_i32 s0, s24, s17
	v_add_u32_e32 v189, s25, v186
	v_lshl_add_u64 v[166:167], v[166:167], 0, s[12:13]
	s_mov_b32 m0, s0
	ds_read_b128 v[206:209], v189
	ds_read_b128 v[210:213], v189 offset:1024
	ds_read_b128 v[214:217], v189 offset:2048
	ds_read_b128 v[218:221], v189 offset:3072
	global_load_lds_dwordx4 v[166:167], off
	v_lshl_add_u64 v[166:167], v[168:169], 0, s[12:13]
	s_add_i32 m0, s0, 0x2000
	s_nop 0
	global_load_lds_dwordx4 v[166:167], off
	s_waitcnt vmcnt(10)
	s_setprio 1
	s_barrier
	s_waitcnt lgkmcnt(0)
	v_mfma_f32_16x16x32_bf16 v[68:71], v[206:209], v[162:165], v[68:71]
	v_mfma_f32_16x16x32_bf16 v[60:63], v[214:217], v[162:165], v[60:63]
	v_mfma_f32_16x16x32_bf16 v[56:59], v[206:209], v[176:179], v[56:59]
	v_mfma_f32_16x16x32_bf16 v[52:55], v[214:217], v[176:179], v[52:55]
	v_mfma_f32_16x16x32_bf16 v[48:51], v[206:209], v[190:193], v[48:51]
	v_mfma_f32_16x16x32_bf16 v[44:47], v[214:217], v[190:193], v[44:47]
	v_mfma_f32_16x16x32_bf16 v[40:43], v[206:209], v[198:201], v[40:43]
	v_mfma_f32_16x16x32_bf16 v[36:39], v[214:217], v[198:201], v[36:39]
	v_mfma_f32_16x16x32_bf16 v[68:71], v[210:213], v[172:175], v[68:71]
	v_mfma_f32_16x16x32_bf16 v[60:63], v[218:221], v[172:175], v[60:63]
	v_mfma_f32_16x16x32_bf16 v[56:59], v[210:213], v[180:183], v[56:59]
	v_mfma_f32_16x16x32_bf16 v[52:55], v[218:221], v[180:183], v[52:55]
	v_mfma_f32_16x16x32_bf16 v[48:51], v[210:213], v[194:197], v[48:51]
	v_mfma_f32_16x16x32_bf16 v[44:47], v[218:221], v[194:197], v[44:47]
	v_mfma_f32_16x16x32_bf16 v[40:43], v[210:213], v[202:205], v[40:43]
	v_mfma_f32_16x16x32_bf16 v[36:39], v[218:221], v[202:205], v[36:39]
	s_barrier
	s_setprio 0
	s_mov_b32 m0, s55
	v_lshl_add_u64 v[166:167], v[184:185], 0, s[12:13]
	ds_read_b128 v[162:165], v188 offset:49152
	ds_read_b128 v[172:175], v188 offset:50176
	ds_read_b128 v[176:179], v188 offset:51200
	ds_read_b128 v[180:183], v188 offset:52224
	ds_read_b128 v[190:193], v188 offset:53248
	ds_read_b128 v[194:197], v188 offset:54272
	ds_read_b128 v[198:201], v188 offset:55296
	ds_read_b128 v[202:205], v188 offset:56320
	global_load_lds_dwordx4 v[166:167], off
	v_lshl_add_u64 v[166:167], v[222:223], 0, s[12:13]
	s_mov_b32 m0, s56
	s_nop 0
	global_load_lds_dwordx4 v[166:167], off
	s_setprio 1
	s_barrier
	s_waitcnt lgkmcnt(0)
	v_mfma_f32_16x16x32_bf16 v[96:99], v[132:135], v[162:165], v[96:99]
	v_mfma_f32_16x16x32_bf16 v[92:95], v[154:157], v[162:165], v[92:95]
	v_mfma_f32_16x16x32_bf16 v[88:91], v[132:135], v[176:179], v[88:91]
	v_mfma_f32_16x16x32_bf16 v[84:87], v[154:157], v[176:179], v[84:87]
	v_mfma_f32_16x16x32_bf16 v[80:83], v[132:135], v[190:193], v[80:83]
	v_mfma_f32_16x16x32_bf16 v[76:79], v[154:157], v[190:193], v[76:79]
	v_mfma_f32_16x16x32_bf16 v[72:75], v[132:135], v[198:201], v[72:75]
	v_mfma_f32_16x16x32_bf16 v[64:67], v[154:157], v[198:201], v[64:67]
	v_mfma_f32_16x16x32_bf16 v[96:99], v[136:139], v[172:175], v[96:99]
	v_mfma_f32_16x16x32_bf16 v[92:95], v[158:161], v[172:175], v[92:95]
	v_mfma_f32_16x16x32_bf16 v[88:91], v[136:139], v[180:183], v[88:91]
	v_mfma_f32_16x16x32_bf16 v[84:87], v[158:161], v[180:183], v[84:87]
	v_mfma_f32_16x16x32_bf16 v[80:83], v[136:139], v[194:197], v[80:83]
	v_mfma_f32_16x16x32_bf16 v[76:79], v[158:161], v[194:197], v[76:79]
	v_mfma_f32_16x16x32_bf16 v[72:75], v[136:139], v[202:205], v[72:75]
	v_mfma_f32_16x16x32_bf16 v[64:67], v[158:161], v[202:205], v[64:67]
	s_barrier
	s_setprio 0
	s_add_u32 s0, s28, 0xb0080
	s_addc_u32 s1, s29, 0
	s_add_i32 s24, s25, s17
	v_lshl_add_u64 v[132:133], s[0:1], 0, v[26:27]
	s_mov_b32 m0, s24
	s_nop 0
	global_load_lds_dwordx4 v[132:133], off
	v_lshl_add_u64 v[132:133], s[0:1], 0, v[144:145]
	s_add_i32 m0, s24, 0x2000
	s_nop 0
	global_load_lds_dwordx4 v[132:133], off
	s_waitcnt vmcnt(10)
	s_setprio 1
	s_barrier
	v_mfma_f32_16x16x32_bf16 v[32:35], v[206:209], v[162:165], v[32:35]
	v_mfma_f32_16x16x32_bf16 v[28:31], v[214:217], v[162:165], v[28:31]
	v_mfma_f32_16x16x32_bf16 v[22:25], v[206:209], v[176:179], v[22:25]
	v_mfma_f32_16x16x32_bf16 v[18:21], v[214:217], v[176:179], v[18:21]
	v_mfma_f32_16x16x32_bf16 v[14:17], v[206:209], v[190:193], v[14:17]
	v_mfma_f32_16x16x32_bf16 v[10:13], v[214:217], v[190:193], v[10:13]
	v_mfma_f32_16x16x32_bf16 v[6:9], v[206:209], v[198:201], v[6:9]
	v_mfma_f32_16x16x32_bf16 v[2:5], v[214:217], v[198:201], v[2:5]
	v_mfma_f32_16x16x32_bf16 v[32:35], v[210:213], v[172:175], v[32:35]
	v_mfma_f32_16x16x32_bf16 v[28:31], v[218:221], v[172:175], v[28:31]
	v_mfma_f32_16x16x32_bf16 v[22:25], v[210:213], v[180:183], v[22:25]
	v_mfma_f32_16x16x32_bf16 v[18:21], v[218:221], v[180:183], v[18:21]
	v_mfma_f32_16x16x32_bf16 v[14:17], v[210:213], v[194:197], v[14:17]
	v_mfma_f32_16x16x32_bf16 v[10:13], v[218:221], v[194:197], v[10:13]
	v_mfma_f32_16x16x32_bf16 v[6:9], v[210:213], v[202:205], v[6:9]
	v_mfma_f32_16x16x32_bf16 v[2:5], v[218:221], v[202:205], v[2:5]
	s_barrier
	s_setprio 0
	s_add_i32 s72, s72, 2
	s_add_u32 s68, s68, 0x100
	s_addc_u32 s69, s69, 0
	s_cmp_gt_u32 s72, 41
	s_mov_b64 s[24:25], s[26:27]
	s_cbranch_scc0 .LBB0_1122
	s_min_i32 s0, s22, 0x100
	s_ashr_i32 s26, s0, 5
	s_add_i32 s0, s22, 0xffffff00
	s_cmpk_lt_i32 s22, 0x100
	s_cselect_b32 s0, s22, s0
	s_cselect_b32 s25, 0, s51
	s_cselect_b32 s24, 0, s50
	s_ashr_i32 s1, s0, 31
	s_lshl_b64 s[0:1], s[0:1], 19
	s_add_u32 s24, s20, s24
	v_lshl_or_b32 v166, s23, 8, v187
	s_addc_u32 s25, s21, s25
	s_ashr_i32 s23, s22, 31
	v_lshl_add_u64 v[132:133], s[0:1], 0, v[146:147]
	s_lshl_b64 s[22:23], s[22:23], 10
	s_mul_hi_i32 s1, s26, 0x9000
	s_mul_i32 s26, s26, 0x9000
	s_add_u32 s0, s34, s26
	v_ashrrev_i32_e32 v167, 31, v166
	s_addc_u32 s1, s35, s1
	v_lshl_add_u64 v[154:155], v[166:167], 2, s[0:1]
	v_lshl_add_u64 v[168:169], v[132:133], 0, v[166:167]
	v_lshl_add_u64 v[176:177], v[132:133], 1, s[24:25]
	global_load_dwordx4 v[132:135], v[154:155], off offset:16
	global_load_dwordx4 v[136:139], v[154:155], off
	v_lshl_add_u64 v[182:183], v[168:169], 1, s[24:25]
	v_add_co_u32_e32 v184, vcc, s65, v182
	s_mov_b32 s0, 0x20000
	s_nop 0
	v_addc_co_u32_e32 v185, vcc, 0, v183, vcc
	v_add_co_u32_e32 v178, vcc, s0, v182
	s_mov_b32 s1, 0x30000
	s_nop 0
	v_addc_co_u32_e32 v179, vcc, 0, v183, vcc
	v_add_co_u32_e32 v180, vcc, s1, v182
	v_lshl_add_u64 v[176:177], v[166:167], 1, v[176:177]
	s_nop 0
	v_addc_co_u32_e32 v181, vcc, 0, v183, vcc
	s_mov_b32 s24, 0x80000
	s_mov_b32 s25, 0x90000
	s_waitcnt vmcnt(0)
	v_pk_mul_f32 v[164:165], v[134:135], 0.5 op_sel_hi:[1,0]
	v_pk_mul_f32 v[174:175], v[138:139], 0.5 op_sel_hi:[1,0]
	v_pk_mul_f32 v[172:173], v[136:137], 0.5 op_sel_hi:[1,0]
	v_pk_mul_f32 v[162:163], v[132:133], 0.5 op_sel_hi:[1,0]
	global_load_dwordx4 v[132:135], v[154:155], off offset:528
	global_load_dwordx4 v[136:139], v[154:155], off offset:512
	global_load_dwordx4 v[190:193], v[182:183], off offset:2048
	global_load_dwordx4 v[194:197], v[184:185], off offset:2048
	s_waitcnt vmcnt(0)
	v_pk_mul_f32 v[156:157], v[134:135], 0.5 op_sel_hi:[1,0]
	v_pk_mul_f32 v[160:161], v[138:139], 0.5 op_sel_hi:[1,0]
	v_pk_mul_f32 v[158:159], v[136:137], 0.5 op_sel_hi:[1,0]
	global_load_dwordx4 v[136:139], v[178:179], off offset:2048
	v_pk_mul_f32 v[154:155], v[132:133], 0.5 op_sel_hi:[1,0]
	global_load_dwordx4 v[132:135], v[180:181], off offset:2048
	v_lshlrev_b32_e32 v166, 16, v190
	v_and_b32_e32 v167, 0xffff0000, v190
	v_lshlrev_b32_e32 v168, 16, v191
	v_and_b32_e32 v169, 0xffff0000, v191
	v_lshlrev_b32_e32 v190, 16, v192
	v_and_b32_e32 v191, 0xffff0000, v192
	v_lshlrev_b32_e32 v192, 16, v193
	v_and_b32_e32 v193, 0xffff0000, v193
	v_pk_fma_f32 v[130:131], v[130:131], v[174:175], v[168:169]
	v_pk_fma_f32 v[128:129], v[128:129], v[172:173], v[166:167]
	v_pk_fma_f32 v[166:167], v[126:127], v[164:165], v[192:193]
	v_pk_fma_f32 v[126:127], v[124:125], v[162:163], v[190:191]
	v_lshlrev_b32_e32 v202, 16, v196
	v_and_b32_e32 v203, 0xffff0000, v196
	v_lshlrev_b32_e32 v204, 16, v197
	v_and_b32_e32 v205, 0xffff0000, v197
	v_cvt_pk_bf16_f32 v124, v128, v129
	v_cvt_pk_bf16_f32 v125, v130, v131
	v_cvt_pk_bf16_f32 v126, v126, v127
	v_cvt_pk_bf16_f32 v127, v166, v167
	v_lshlrev_b32_e32 v200, 16, v195
	v_and_b32_e32 v201, 0xffff0000, v195
	global_store_dwordx4 v[176:177], v[124:127], off offset:2048
	v_lshlrev_b32_e32 v193, 16, v124
	v_and_b32_e32 v196, 0xffff0000, v124
	v_lshlrev_b32_e32 v191, 16, v125
	v_and_b32_e32 v195, 0xffff0000, v125
	v_pk_fma_f32 v[124:125], v[118:119], v[164:165], v[204:205]
	v_pk_fma_f32 v[118:119], v[116:117], v[162:163], v[202:203]
	v_lshlrev_b32_e32 v198, 16, v194
	v_cvt_pk_bf16_f32 v118, v118, v119
	v_cvt_pk_bf16_f32 v119, v124, v125
	v_add_co_u32_e32 v124, vcc, s65, v176
	v_and_b32_e32 v199, 0xffff0000, v194
	s_nop 0
	v_addc_co_u32_e32 v125, vcc, 0, v177, vcc
	v_lshlrev_b32_e32 v190, 16, v126
	v_and_b32_e32 v194, 0xffff0000, v126
	v_add_co_u32_e32 v126, vcc, s24, v182
	v_lshlrev_b32_e32 v189, 16, v127
	v_and_b32_e32 v192, 0xffff0000, v127
	v_addc_co_u32_e32 v127, vcc, 0, v183, vcc
	v_add_co_u32_e32 v128, vcc, s25, v182
	v_pk_fma_f32 v[122:123], v[122:123], v[174:175], v[200:201]
	v_pk_fma_f32 v[120:121], v[120:121], v[172:173], v[198:199]
	v_addc_co_u32_e32 v129, vcc, 0, v183, vcc
	v_cvt_pk_bf16_f32 v116, v120, v121
	v_cvt_pk_bf16_f32 v117, v122, v123
	global_store_dwordx4 v[124:125], v[116:119], off offset:2048
	global_load_dwordx4 v[120:123], v[126:127], off offset:2048
	global_load_dwordx4 v[198:201], v[128:129], off offset:2048
	s_waitcnt vmcnt(0)
	v_lshlrev_b32_e32 v130, 16, v136
	v_and_b32_e32 v131, 0xffff0000, v136
	v_lshlrev_b32_e32 v166, 16, v138
	v_and_b32_e32 v167, 0xffff0000, v138
	v_lshlrev_b32_e32 v138, 16, v139
	v_and_b32_e32 v139, 0xffff0000, v139
	v_pk_fma_f32 v[112:113], v[112:113], v[172:173], v[130:131]
	v_pk_fma_f32 v[130:131], v[110:111], v[164:165], v[138:139]
	v_pk_fma_f32 v[110:111], v[108:109], v[162:163], v[166:167]
	v_lshlrev_b32_e32 v168, 16, v132
	v_cvt_pk_bf16_f32 v110, v110, v111
	v_cvt_pk_bf16_f32 v111, v130, v131
	v_add_co_u32_e32 v130, vcc, s0, v176
	v_and_b32_e32 v169, 0xffff0000, v132
	v_lshlrev_b32_e32 v132, 16, v133
	v_and_b32_e32 v133, 0xffff0000, v133
	v_addc_co_u32_e32 v131, vcc, 0, v177, vcc
	v_lshlrev_b32_e32 v136, 16, v137
	v_and_b32_e32 v137, 0xffff0000, v137
	v_lshlrev_b32_e32 v202, 16, v134
	v_and_b32_e32 v203, 0xffff0000, v134
	v_lshlrev_b32_e32 v134, 16, v135
	v_and_b32_e32 v135, 0xffff0000, v135
	v_pk_fma_f32 v[106:107], v[106:107], v[174:175], v[132:133]
	v_add_co_u32_e32 v132, vcc, s1, v176
	v_pk_fma_f32 v[114:115], v[114:115], v[174:175], v[136:137]
	v_cvt_pk_bf16_f32 v108, v112, v113
	v_pk_fma_f32 v[104:105], v[104:105], v[172:173], v[168:169]
	v_pk_fma_f32 v[112:113], v[102:103], v[164:165], v[134:135]
	v_pk_fma_f32 v[102:103], v[100:101], v[162:163], v[202:203]
	v_addc_co_u32_e32 v133, vcc, 0, v177, vcc
	v_cvt_pk_bf16_f32 v109, v114, v115
	v_cvt_pk_bf16_f32 v100, v104, v105
	v_cvt_pk_bf16_f32 v101, v106, v107
	v_cvt_pk_bf16_f32 v102, v102, v103
	v_cvt_pk_bf16_f32 v103, v112, v113
	v_add_co_u32_e32 v134, vcc, s76, v182
	global_store_dwordx4 v[130:131], v[108:111], off offset:2048
	global_store_dwordx4 v[132:133], v[100:103], off offset:2048
	v_addc_co_u32_e32 v135, vcc, 0, v183, vcc
	s_mov_b32 s0, 0xb0000
	global_load_dwordx4 v[112:115], v[134:135], off offset:2048
	v_add_co_u32_e32 v136, vcc, s0, v182
	v_lshlrev_b32_e32 v138, 16, v120
	s_nop 0
	v_addc_co_u32_e32 v137, vcc, 0, v183, vcc
	global_load_dwordx4 v[104:107], v[136:137], off offset:2048
	v_and_b32_e32 v139, 0xffff0000, v120
	v_lshlrev_b32_e32 v120, 16, v121
	v_and_b32_e32 v121, 0xffff0000, v121
	v_lshlrev_b32_e32 v166, 16, v122
	v_and_b32_e32 v167, 0xffff0000, v122
	v_lshlrev_b32_e32 v122, 16, v123
	v_and_b32_e32 v123, 0xffff0000, v123
	v_pk_fma_f32 v[96:97], v[96:97], v[172:173], v[138:139]
	v_lshlrev_b32_e32 v168, 16, v198
	v_and_b32_e32 v169, 0xffff0000, v198
	v_lshlrev_b32_e32 v198, 16, v199
	v_and_b32_e32 v199, 0xffff0000, v199
	v_pk_fma_f32 v[98:99], v[98:99], v[174:175], v[120:121]
	v_pk_fma_f32 v[120:121], v[94:95], v[164:165], v[122:123]
	v_pk_fma_f32 v[94:95], v[92:93], v[162:163], v[166:167]
	v_cvt_pk_bf16_f32 v92, v96, v97
	v_add_co_u32_e32 v96, vcc, s24, v176
	v_lshlrev_b32_e32 v202, 16, v200
	v_and_b32_e32 v203, 0xffff0000, v200
	v_lshlrev_b32_e32 v200, 16, v201
	v_and_b32_e32 v201, 0xffff0000, v201
	v_addc_co_u32_e32 v97, vcc, 0, v177, vcc
	v_pk_fma_f32 v[90:91], v[90:91], v[174:175], v[198:199]
	v_pk_fma_f32 v[88:89], v[88:89], v[172:173], v[168:169]
	v_cvt_pk_bf16_f32 v93, v98, v99
	v_pk_fma_f32 v[98:99], v[86:87], v[164:165], v[200:201]
	v_pk_fma_f32 v[86:87], v[84:85], v[162:163], v[202:203]
	v_cvt_pk_bf16_f32 v84, v88, v89
	v_cvt_pk_bf16_f32 v85, v90, v91
	v_add_co_u32_e32 v88, vcc, s25, v176
	v_cvt_pk_bf16_f32 v86, v86, v87
	v_cvt_pk_bf16_f32 v87, v98, v99
	v_addc_co_u32_e32 v89, vcc, 0, v177, vcc
	v_cvt_pk_bf16_f32 v94, v94, v95
	v_cvt_pk_bf16_f32 v95, v120, v121
	global_store_dwordx4 v[96:97], v[92:95], off offset:2048
	global_store_dwordx4 v[88:89], v[84:87], off offset:2048
	global_load_dwordx4 v[120:123], v[182:183], off offset:2304
	s_nop 0
	global_load_dwordx4 v[182:185], v[184:185], off offset:2304
	s_waitcnt vmcnt(0)
	v_lshlrev_b32_e32 v90, 16, v112
	v_and_b32_e32 v91, 0xffff0000, v112
	v_lshlrev_b32_e32 v98, 16, v113
	v_and_b32_e32 v99, 0xffff0000, v113
	v_lshlrev_b32_e32 v112, 16, v114
	v_and_b32_e32 v113, 0xffff0000, v114
	v_lshlrev_b32_e32 v114, 16, v115
	v_and_b32_e32 v115, 0xffff0000, v115
	v_pk_fma_f32 v[80:81], v[80:81], v[172:173], v[90:91]
	v_pk_fma_f32 v[90:91], v[78:79], v[164:165], v[114:115]
	v_pk_fma_f32 v[78:79], v[76:77], v[162:163], v[112:113]
	v_cvt_pk_bf16_f32 v76, v80, v81
	v_add_co_u32_e32 v80, vcc, s76, v176
	v_lshlrev_b32_e32 v138, 16, v104
	v_and_b32_e32 v139, 0xffff0000, v104
	v_lshlrev_b32_e32 v104, 16, v105
	v_and_b32_e32 v105, 0xffff0000, v105
	v_lshlrev_b32_e32 v166, 16, v106
	v_and_b32_e32 v167, 0xffff0000, v106
	v_lshlrev_b32_e32 v106, 16, v107
	v_and_b32_e32 v107, 0xffff0000, v107
	v_pk_fma_f32 v[82:83], v[82:83], v[174:175], v[98:99]
	v_addc_co_u32_e32 v81, vcc, 0, v177, vcc
	v_pk_fma_f32 v[72:73], v[72:73], v[172:173], v[138:139]
	v_cvt_pk_bf16_f32 v77, v82, v83
	v_pk_fma_f32 v[74:75], v[74:75], v[174:175], v[104:105]
	v_pk_fma_f32 v[82:83], v[66:67], v[164:165], v[106:107]
	v_pk_fma_f32 v[66:67], v[64:65], v[162:163], v[166:167]
	v_cvt_pk_bf16_f32 v64, v72, v73
	v_add_co_u32_e32 v72, vcc, s0, v176
	v_cvt_pk_bf16_f32 v78, v78, v79
	v_cvt_pk_bf16_f32 v79, v90, v91
	v_cvt_pk_bf16_f32 v65, v74, v75
	v_cvt_pk_bf16_f32 v66, v66, v67
	v_cvt_pk_bf16_f32 v67, v82, v83
	v_addc_co_u32_e32 v73, vcc, 0, v177, vcc
	global_store_dwordx4 v[80:81], v[76:79], off offset:2048
	global_store_dwordx4 v[72:73], v[64:67], off offset:2048
	global_load_dwordx4 v[104:107], v[178:179], off offset:2304
	global_load_dwordx4 v[112:115], v[180:181], off offset:2304
	v_lshlrev_b32_e32 v74, 16, v120
	v_and_b32_e32 v75, 0xffff0000, v120
	v_lshlrev_b32_e32 v82, 16, v121
	v_and_b32_e32 v83, 0xffff0000, v121
	v_lshlrev_b32_e32 v90, 16, v122
	v_and_b32_e32 v91, 0xffff0000, v122
	v_lshlrev_b32_e32 v98, 16, v123
	v_and_b32_e32 v99, 0xffff0000, v123
	v_pk_fma_f32 v[70:71], v[70:71], v[160:161], v[82:83]
	v_pk_fma_f32 v[68:69], v[68:69], v[158:159], v[74:75]
	v_pk_fma_f32 v[74:75], v[62:63], v[156:157], v[98:99]
	v_pk_fma_f32 v[62:63], v[60:61], v[154:155], v[90:91]
	v_lshlrev_b32_e32 v120, 16, v182
	v_and_b32_e32 v121, 0xffff0000, v182
	v_lshlrev_b32_e32 v122, 16, v183
	v_and_b32_e32 v123, 0xffff0000, v183
	v_lshlrev_b32_e32 v138, 16, v184
	v_and_b32_e32 v139, 0xffff0000, v184
	v_lshlrev_b32_e32 v162, 16, v185
	v_and_b32_e32 v163, 0xffff0000, v185
	v_cvt_pk_bf16_f32 v60, v68, v69
	v_cvt_pk_bf16_f32 v61, v70, v71
	v_cvt_pk_bf16_f32 v62, v62, v63
	v_cvt_pk_bf16_f32 v63, v74, v75
	global_store_dwordx4 v[176:177], v[60:63], off offset:2304
	v_lshlrev_b32_e32 v164, 16, v60
	v_and_b32_e32 v165, 0xffff0000, v60
	v_lshlrev_b32_e32 v166, 16, v61
	v_and_b32_e32 v167, 0xffff0000, v61
	v_pk_fma_f32 v[58:59], v[58:59], v[160:161], v[122:123]
	v_pk_fma_f32 v[56:57], v[56:57], v[158:159], v[120:121]
	v_pk_fma_f32 v[60:61], v[54:55], v[156:157], v[162:163]
	v_pk_fma_f32 v[54:55], v[52:53], v[154:155], v[138:139]
	v_cvt_pk_bf16_f32 v52, v56, v57
	v_cvt_pk_bf16_f32 v53, v58, v59
	v_cvt_pk_bf16_f32 v54, v54, v55
	v_cvt_pk_bf16_f32 v55, v60, v61
	global_store_dwordx4 v[124:125], v[52:55], off offset:2304
	v_lshlrev_b32_e32 v168, 16, v62
	v_and_b32_e32 v169, 0xffff0000, v62
	v_lshlrev_b32_e32 v172, 16, v63
	v_and_b32_e32 v173, 0xffff0000, v63
	global_load_dwordx4 v[56:59], v[126:127], off offset:2304
	global_load_dwordx4 v[60:63], v[128:129], off offset:2304
	s_waitcnt vmcnt(0)
	v_lshlrev_b32_e32 v68, 16, v104
	v_and_b32_e32 v69, 0xffff0000, v104
	v_lshlrev_b32_e32 v70, 16, v105
	v_and_b32_e32 v71, 0xffff0000, v105
	v_lshlrev_b32_e32 v74, 16, v106
	v_and_b32_e32 v75, 0xffff0000, v106
	v_lshlrev_b32_e32 v82, 16, v107
	v_and_b32_e32 v83, 0xffff0000, v107
	v_lshlrev_b32_e32 v90, 16, v112
	v_and_b32_e32 v91, 0xffff0000, v112
	v_lshlrev_b32_e32 v98, 16, v113
	v_and_b32_e32 v99, 0xffff0000, v113
	v_lshlrev_b32_e32 v104, 16, v114
	v_and_b32_e32 v105, 0xffff0000, v114
	v_lshlrev_b32_e32 v106, 16, v115
	v_and_b32_e32 v107, 0xffff0000, v115
	v_pk_fma_f32 v[48:49], v[48:49], v[158:159], v[68:69]
	v_pk_fma_f32 v[50:51], v[50:51], v[160:161], v[70:71]
	v_pk_fma_f32 v[68:69], v[46:47], v[156:157], v[82:83]
	v_pk_fma_f32 v[46:47], v[44:45], v[154:155], v[74:75]
	v_cvt_pk_bf16_f32 v44, v48, v49
	v_pk_fma_f32 v[42:43], v[42:43], v[160:161], v[98:99]
	v_pk_fma_f32 v[40:41], v[40:41], v[158:159], v[90:91]
	v_pk_fma_f32 v[48:49], v[38:39], v[156:157], v[106:107]
	v_pk_fma_f32 v[38:39], v[36:37], v[154:155], v[104:105]
	v_cvt_pk_bf16_f32 v45, v50, v51
	v_cvt_pk_bf16_f32 v46, v46, v47
	v_cvt_pk_bf16_f32 v47, v68, v69
	v_cvt_pk_bf16_f32 v36, v40, v41
	v_cvt_pk_bf16_f32 v37, v42, v43
	v_cvt_pk_bf16_f32 v38, v38, v39
	v_cvt_pk_bf16_f32 v39, v48, v49
	global_store_dwordx4 v[130:131], v[44:47], off offset:2304
	global_store_dwordx4 v[132:133], v[36:39], off offset:2304
	global_load_dwordx4 v[40:43], v[134:135], off offset:2304
	global_load_dwordx4 v[48:51], v[136:137], off offset:2304
	v_lshlrev_b32_e32 v68, 16, v56
	v_and_b32_e32 v69, 0xffff0000, v56
	v_lshlrev_b32_e32 v56, 16, v57
	v_and_b32_e32 v57, 0xffff0000, v57
	v_lshlrev_b32_e32 v70, 16, v58
	v_and_b32_e32 v71, 0xffff0000, v58
	v_lshlrev_b32_e32 v58, 16, v59
	v_and_b32_e32 v59, 0xffff0000, v59
	v_lshlrev_b32_e32 v74, 16, v60
	v_and_b32_e32 v75, 0xffff0000, v60
	v_lshlrev_b32_e32 v82, 16, v62
	v_and_b32_e32 v83, 0xffff0000, v62
	v_lshlrev_b32_e32 v62, 16, v63
	v_and_b32_e32 v63, 0xffff0000, v63
	v_pk_fma_f32 v[32:33], v[32:33], v[158:159], v[68:69]
	v_lshlrev_b32_e32 v60, 16, v61
	v_and_b32_e32 v61, 0xffff0000, v61
	v_pk_fma_f32 v[34:35], v[34:35], v[160:161], v[56:57]
	v_pk_fma_f32 v[56:57], v[30:31], v[156:157], v[58:59]
	v_pk_fma_f32 v[30:31], v[28:29], v[154:155], v[70:71]
	v_cvt_pk_bf16_f32 v28, v32, v33
	v_pk_fma_f32 v[22:23], v[22:23], v[158:159], v[74:75]
	v_pk_fma_f32 v[32:33], v[20:21], v[156:157], v[62:63]
	v_pk_fma_f32 v[20:21], v[18:19], v[154:155], v[82:83]
	v_cvt_pk_bf16_f32 v29, v34, v35
	v_pk_fma_f32 v[24:25], v[24:25], v[160:161], v[60:61]
	v_cvt_pk_bf16_f32 v18, v22, v23
	v_cvt_pk_bf16_f32 v20, v20, v21
	v_cvt_pk_bf16_f32 v21, v32, v33
	v_cvt_pk_bf16_f32 v19, v24, v25
	v_cvt_pk_bf16_f32 v30, v30, v31
	v_cvt_pk_bf16_f32 v31, v56, v57
	global_store_dwordx4 v[96:97], v[28:31], off offset:2304
	global_store_dwordx4 v[88:89], v[18:21], off offset:2304
	s_waitcnt vmcnt(0)
	v_lshlrev_b32_e32 v22, 16, v40
	v_and_b32_e32 v23, 0xffff0000, v40
	v_lshlrev_b32_e32 v32, 16, v42
	v_and_b32_e32 v33, 0xffff0000, v42
	v_lshlrev_b32_e32 v34, 16, v43
	v_and_b32_e32 v35, 0xffff0000, v43
	v_lshlrev_b32_e32 v42, 16, v49
	v_and_b32_e32 v43, 0xffff0000, v49
	v_lshlrev_b32_e32 v24, 16, v41
	v_and_b32_e32 v25, 0xffff0000, v41
	v_lshlrev_b32_e32 v40, 16, v48
	v_and_b32_e32 v41, 0xffff0000, v48
	v_lshlrev_b32_e32 v48, 16, v50
	v_and_b32_e32 v49, 0xffff0000, v50
	v_lshlrev_b32_e32 v50, 16, v51
	v_and_b32_e32 v51, 0xffff0000, v51
	v_pk_fma_f32 v[14:15], v[14:15], v[158:159], v[22:23]
	v_pk_fma_f32 v[8:9], v[8:9], v[160:161], v[42:43]
	v_pk_fma_f32 v[22:23], v[12:13], v[156:157], v[34:35]
	v_pk_fma_f32 v[12:13], v[10:11], v[154:155], v[32:33]
	v_cvt_pk_bf16_f32 v10, v14, v15
	v_pk_fma_f32 v[14:15], v[4:5], v[156:157], v[50:51]
	v_pk_fma_f32 v[4:5], v[2:3], v[154:155], v[48:49]
	v_cvt_pk_bf16_f32 v3, v8, v9
	v_and_b32_e32 v9, 64, v227
	v_xor_b32_e32 v8, 16, v227
	v_add_u32_e32 v9, 64, v9
	v_cvt_pk_bf16_f32 v4, v4, v5
	v_cvt_pk_bf16_f32 v5, v14, v15
	v_cmp_lt_i32_e32 vcc, v8, v9
	v_xor_b32_e32 v14, 32, v227
	v_mul_f32_e32 v15, v195, v195
	v_cndmask_b32_e32 v8, v227, v8, vcc
	v_cmp_lt_i32_e32 vcc, v14, v9
	v_pk_fma_f32 v[16:17], v[16:17], v[160:161], v[24:25]
	v_fmac_f32_e32 v15, v191, v191
	v_cndmask_b32_e32 v9, v227, v14, vcc
	v_mul_f32_e32 v14, v196, v196
	v_fmac_f32_e32 v14, v193, v193
	v_cvt_pk_bf16_f32 v11, v16, v17
	v_add_f32_e32 v14, v14, v15
	v_mul_f32_e32 v15, v194, v194
	v_mul_f32_e32 v16, v192, v192
	v_fmac_f32_e32 v15, v190, v190
	v_fmac_f32_e32 v16, v189, v189
	v_add_f32_e32 v15, v15, v16
	v_add_f32_e32 v14, v14, v15
	v_mul_f32_e32 v15, v165, v165
	v_mul_f32_e32 v16, v167, v167
	v_fmac_f32_e32 v15, v164, v164
	v_fmac_f32_e32 v16, v166, v166
	v_add_f32_e32 v15, v15, v16
	v_add_f32_e32 v14, v14, v15
	v_mul_f32_e32 v15, v169, v169
	v_mul_f32_e32 v16, v173, v173
	v_fmac_f32_e32 v15, v168, v168
	v_fmac_f32_e32 v16, v172, v172
	v_add_f32_e32 v15, v15, v16
	v_lshlrev_b32_e32 v8, 2, v8
	v_add_f32_e32 v14, v15, v14
	ds_bpermute_b32 v15, v8, v14
	v_lshlrev_b32_e32 v9, 2, v9
	v_pk_fma_f32 v[6:7], v[6:7], v[158:159], v[40:41]
	v_cvt_pk_bf16_f32 v12, v12, v13
	v_cvt_pk_bf16_f32 v13, v22, v23
	s_waitcnt lgkmcnt(0)
	v_add_f32_e32 v14, v14, v15
	ds_bpermute_b32 v15, v9, v14
	v_cvt_pk_bf16_f32 v2, v6, v7
	v_lshl_add_u64 v[6:7], v[148:149], 0, s[22:23]
	global_store_dwordx4 v[80:81], v[10:13], off offset:2304
	global_store_dwordx4 v[72:73], v[2:5], off offset:2304
	s_and_saveexec_b64 s[22:23], s[38:39]
	s_cbranch_execz .LBB0_1125
	s_waitcnt lgkmcnt(0)
	v_add_f32_e32 v14, v14, v15
	global_atomic_add_f32 v[6:7], v14, off

.LBB0_1156:
	s_add_u32 s28, s26, 0x100
	s_addc_u32 s29, s27, 0
	s_add_i32 s0, 0, 0x10000
	v_add_u32_e32 v160, s0, v222
	ds_read_b128 v[132:135], v160
	ds_read_b128 v[136:139], v160 offset:1024
	ds_read_b128 v[156:159], v160 offset:2048
	ds_read_b128 v[160:163], v160 offset:3072
	s_cmp_eq_u32 s81, 40
	s_cselect_b32 s35, s43, s29
	s_cselect_b32 s34, s42, s28
	s_cselect_b32 s31, s23, s45
	s_cselect_b32 s30, s22, s44
	v_lshl_add_u64 v[164:165], s[26:27], 0, v[152:153]
	s_add_i32 m0, s52, 0xc000
	ds_read_b128 v[172:175], v224
	ds_read_b128 v[176:179], v224 offset:1024
	ds_read_b128 v[180:183], v224 offset:2048
	ds_read_b128 v[184:187], v224 offset:3072
	ds_read_b128 v[188:191], v224 offset:4096
	ds_read_b128 v[192:195], v224 offset:5120
	ds_read_b128 v[196:199], v224 offset:6144
	ds_read_b128 v[200:203], v224 offset:7168
	global_load_lds_dwordx4 v[164:165], off
	v_lshl_add_u64 v[164:165], s[26:27], 0, v[154:155]
	s_add_i32 m0, s52, 0xe000
	s_nop 0
	global_load_lds_dwordx4 v[164:165], off
	s_waitcnt vmcnt(10) lgkmcnt(8)
	s_setprio 1
	s_barrier
	s_waitcnt lgkmcnt(0)
	v_mfma_f32_16x16x32_bf16 v[128:131], v[132:135], v[172:175], v[128:131]
	v_mfma_f32_16x16x32_bf16 v[124:127], v[156:159], v[172:175], v[124:127]
	v_mfma_f32_16x16x32_bf16 v[120:123], v[132:135], v[180:183], v[120:123]
	v_mfma_f32_16x16x32_bf16 v[116:119], v[156:159], v[180:183], v[116:119]
	v_mfma_f32_16x16x32_bf16 v[112:115], v[132:135], v[188:191], v[112:115]
	v_mfma_f32_16x16x32_bf16 v[108:111], v[156:159], v[188:191], v[108:111]
	v_mfma_f32_16x16x32_bf16 v[104:107], v[132:135], v[196:199], v[104:107]
	v_mfma_f32_16x16x32_bf16 v[100:103], v[156:159], v[196:199], v[100:103]
	v_mfma_f32_16x16x32_bf16 v[128:131], v[136:139], v[176:179], v[128:131]
	v_mfma_f32_16x16x32_bf16 v[124:127], v[160:163], v[176:179], v[124:127]
	v_mfma_f32_16x16x32_bf16 v[120:123], v[136:139], v[184:187], v[120:123]
	v_mfma_f32_16x16x32_bf16 v[116:119], v[160:163], v[184:187], v[116:119]
	v_mfma_f32_16x16x32_bf16 v[112:115], v[136:139], v[192:195], v[112:115]
	v_mfma_f32_16x16x32_bf16 v[108:111], v[160:163], v[192:195], v[108:111]
	v_mfma_f32_16x16x32_bf16 v[104:107], v[136:139], v[200:203], v[104:107]
	v_mfma_f32_16x16x32_bf16 v[100:103], v[160:163], v[200:203], v[100:103]
	s_barrier
	s_setprio 0
	s_add_i32 s26, 0, 0x14000
	v_add_u32_e32 v164, s26, v222
	s_add_i32 s0, s0, s17
	ds_read_b128 v[204:207], v164
	ds_read_b128 v[208:211], v164 offset:1024
	ds_read_b128 v[212:215], v164 offset:2048
	ds_read_b128 v[216:219], v164 offset:3072
	v_lshl_add_u64 v[164:165], s[30:31], 0, v[26:27]
	s_mov_b32 m0, s0
	v_lshl_add_u64 v[166:167], s[30:31], 0, v[144:145]
	global_load_lds_dwordx4 v[164:165], off
	s_add_i32 m0, s0, 0x2000
	s_nop 0
	global_load_lds_dwordx4 v[166:167], off
	s_waitcnt vmcnt(10)
	s_setprio 1
	s_barrier
	s_waitcnt lgkmcnt(0)
	v_mfma_f32_16x16x32_bf16 v[64:67], v[204:207], v[172:175], v[64:67]
	v_mfma_f32_16x16x32_bf16 v[60:63], v[212:215], v[172:175], v[60:63]
	v_mfma_f32_16x16x32_bf16 v[56:59], v[204:207], v[180:183], v[56:59]
	v_mfma_f32_16x16x32_bf16 v[52:55], v[212:215], v[180:183], v[52:55]
	v_mfma_f32_16x16x32_bf16 v[48:51], v[204:207], v[188:191], v[48:51]
	v_mfma_f32_16x16x32_bf16 v[44:47], v[212:215], v[188:191], v[44:47]
	v_mfma_f32_16x16x32_bf16 v[40:43], v[204:207], v[196:199], v[40:43]
	v_mfma_f32_16x16x32_bf16 v[36:39], v[212:215], v[196:199], v[36:39]
	v_mfma_f32_16x16x32_bf16 v[64:67], v[208:211], v[176:179], v[64:67]
	v_mfma_f32_16x16x32_bf16 v[60:63], v[216:219], v[176:179], v[60:63]
	v_mfma_f32_16x16x32_bf16 v[56:59], v[208:211], v[184:187], v[56:59]
	v_mfma_f32_16x16x32_bf16 v[52:55], v[216:219], v[184:187], v[52:55]
	v_mfma_f32_16x16x32_bf16 v[48:51], v[208:211], v[192:195], v[48:51]
	v_mfma_f32_16x16x32_bf16 v[44:47], v[216:219], v[192:195], v[44:47]
	v_mfma_f32_16x16x32_bf16 v[40:43], v[208:211], v[200:203], v[40:43]
	v_mfma_f32_16x16x32_bf16 v[36:39], v[216:219], v[200:203], v[36:39]
	s_barrier
	s_setprio 0
	s_mov_b32 m0, s52
	v_lshl_add_u64 v[168:169], s[34:35], 0, v[140:141]
	ds_read_b128 v[172:175], v224 offset:16384
	ds_read_b128 v[176:179], v224 offset:17408
	ds_read_b128 v[180:183], v224 offset:18432
	ds_read_b128 v[184:187], v224 offset:19456
	ds_read_b128 v[188:191], v224 offset:20480
	ds_read_b128 v[192:195], v224 offset:21504
	ds_read_b128 v[196:199], v224 offset:22528
	ds_read_b128 v[200:203], v224 offset:23552
	global_load_lds_dwordx4 v[168:169], off
	v_lshl_add_u64 v[220:221], s[34:35], 0, v[142:143]
	s_mov_b32 m0, s54
	s_nop 0
	global_load_lds_dwordx4 v[220:221], off
	s_setprio 1
	s_barrier
	s_waitcnt lgkmcnt(0)
	v_mfma_f32_16x16x32_bf16 v[96:99], v[132:135], v[172:175], v[96:99]
	v_mfma_f32_16x16x32_bf16 v[92:95], v[156:159], v[172:175], v[92:95]
	v_mfma_f32_16x16x32_bf16 v[88:91], v[132:135], v[180:183], v[88:91]
	v_mfma_f32_16x16x32_bf16 v[84:87], v[156:159], v[180:183], v[84:87]
	v_mfma_f32_16x16x32_bf16 v[80:83], v[132:135], v[188:191], v[80:83]
	v_mfma_f32_16x16x32_bf16 v[76:79], v[156:159], v[188:191], v[76:79]
	v_mfma_f32_16x16x32_bf16 v[72:75], v[132:135], v[196:199], v[72:75]
	v_mfma_f32_16x16x32_bf16 v[68:71], v[156:159], v[196:199], v[68:71]
	v_mfma_f32_16x16x32_bf16 v[96:99], v[136:139], v[176:179], v[96:99]
	v_mfma_f32_16x16x32_bf16 v[92:95], v[160:163], v[176:179], v[92:95]
	v_mfma_f32_16x16x32_bf16 v[88:91], v[136:139], v[184:187], v[88:91]
	v_mfma_f32_16x16x32_bf16 v[84:87], v[160:163], v[184:187], v[84:87]
	v_mfma_f32_16x16x32_bf16 v[80:83], v[136:139], v[192:195], v[80:83]
	v_mfma_f32_16x16x32_bf16 v[76:79], v[160:163], v[192:195], v[76:79]
	v_mfma_f32_16x16x32_bf16 v[72:75], v[136:139], v[200:203], v[72:75]
	v_mfma_f32_16x16x32_bf16 v[68:71], v[160:163], v[200:203], v[68:71]
	s_barrier
	s_setprio 0
	s_add_u32 s0, s30, 0xb0000
	s_addc_u32 s1, s31, 0
	s_add_i32 s26, s26, s17
	v_lshl_add_u64 v[132:133], s[0:1], 0, v[26:27]
	s_mov_b32 m0, s26
	s_nop 0
	global_load_lds_dwordx4 v[132:133], off
	v_lshl_add_u64 v[132:133], s[0:1], 0, v[144:145]
	s_add_i32 m0, s26, 0x2000
	s_nop 0
	global_load_lds_dwordx4 v[132:133], off
	s_waitcnt vmcnt(10)
	s_setprio 1
	s_barrier
	v_mfma_f32_16x16x32_bf16 v[32:35], v[204:207], v[172:175], v[32:35]
	v_mfma_f32_16x16x32_bf16 v[28:31], v[212:215], v[172:175], v[28:31]
	v_mfma_f32_16x16x32_bf16 v[22:25], v[204:207], v[180:183], v[22:25]
	v_mfma_f32_16x16x32_bf16 v[18:21], v[212:215], v[180:183], v[18:21]
	v_mfma_f32_16x16x32_bf16 v[14:17], v[204:207], v[188:191], v[14:17]
	v_mfma_f32_16x16x32_bf16 v[10:13], v[212:215], v[188:191], v[10:13]
	v_mfma_f32_16x16x32_bf16 v[6:9], v[204:207], v[196:199], v[6:9]
	v_mfma_f32_16x16x32_bf16 v[2:5], v[212:215], v[196:199], v[2:5]
	v_mfma_f32_16x16x32_bf16 v[32:35], v[208:211], v[176:179], v[32:35]
	v_mfma_f32_16x16x32_bf16 v[28:31], v[216:219], v[176:179], v[28:31]
	v_mfma_f32_16x16x32_bf16 v[22:25], v[208:211], v[184:187], v[22:25]
	v_mfma_f32_16x16x32_bf16 v[18:21], v[216:219], v[184:187], v[18:21]
	v_mfma_f32_16x16x32_bf16 v[14:17], v[208:211], v[192:195], v[14:17]
	v_mfma_f32_16x16x32_bf16 v[10:13], v[216:219], v[192:195], v[10:13]
	v_mfma_f32_16x16x32_bf16 v[6:9], v[208:211], v[200:203], v[6:9]
	v_mfma_f32_16x16x32_bf16 v[2:5], v[216:219], v[200:203], v[2:5]
	s_barrier
	s_setprio 0
	s_add_i32 s26, 0, 0x18000
	v_add_u32_e32 v160, s26, v222
	ds_read_b128 v[132:135], v160
	ds_read_b128 v[136:139], v160 offset:1024
	ds_read_b128 v[156:159], v160 offset:2048
	ds_read_b128 v[160:163], v160 offset:3072
	s_add_u32 s0, s34, 0xb0000
	s_addc_u32 s1, s35, 0
	s_mov_b32 m0, s55
	v_lshl_add_u64 v[204:205], s[0:1], 0, v[140:141]
	ds_read_b128 v[172:175], v224 offset:32768
	ds_read_b128 v[176:179], v224 offset:33792
	ds_read_b128 v[180:183], v224 offset:34816
	ds_read_b128 v[184:187], v224 offset:35840
	ds_read_b128 v[188:191], v224 offset:36864
	ds_read_b128 v[192:195], v224 offset:37888
	ds_read_b128 v[196:199], v224 offset:38912
	ds_read_b128 v[200:203], v224 offset:39936
	global_load_lds_dwordx4 v[204:205], off
	v_lshl_add_u64 v[204:205], s[0:1], 0, v[142:143]
	s_mov_b32 m0, s56
	s_nop 0
	global_load_lds_dwordx4 v[204:205], off
	s_waitcnt vmcnt(10) lgkmcnt(8)
	s_setprio 1
	s_barrier
	s_waitcnt lgkmcnt(0)
	v_mfma_f32_16x16x32_bf16 v[128:131], v[132:135], v[172:175], v[128:131]
	v_mfma_f32_16x16x32_bf16 v[124:127], v[156:159], v[172:175], v[124:127]
	v_mfma_f32_16x16x32_bf16 v[120:123], v[132:135], v[180:183], v[120:123]
	v_mfma_f32_16x16x32_bf16 v[116:119], v[156:159], v[180:183], v[116:119]
	v_mfma_f32_16x16x32_bf16 v[112:115], v[132:135], v[188:191], v[112:115]
	v_mfma_f32_16x16x32_bf16 v[108:111], v[156:159], v[188:191], v[108:111]
	v_mfma_f32_16x16x32_bf16 v[104:107], v[132:135], v[196:199], v[104:107]
	v_mfma_f32_16x16x32_bf16 v[100:103], v[156:159], v[196:199], v[100:103]
	v_mfma_f32_16x16x32_bf16 v[128:131], v[136:139], v[176:179], v[128:131]
	v_mfma_f32_16x16x32_bf16 v[124:127], v[160:163], v[176:179], v[124:127]
	v_mfma_f32_16x16x32_bf16 v[120:123], v[136:139], v[184:187], v[120:123]
	v_mfma_f32_16x16x32_bf16 v[116:119], v[160:163], v[184:187], v[116:119]
	v_mfma_f32_16x16x32_bf16 v[112:115], v[136:139], v[192:195], v[112:115]
	v_mfma_f32_16x16x32_bf16 v[108:111], v[160:163], v[192:195], v[108:111]
	v_mfma_f32_16x16x32_bf16 v[104:107], v[136:139], v[200:203], v[104:107]
	v_mfma_f32_16x16x32_bf16 v[100:103], v[160:163], v[200:203], v[100:103]
	s_barrier
	s_setprio 0
	s_add_i32 s27, 0, 0x1c000
	s_add_i32 s0, s26, s17
	v_add_u32_e32 v216, s27, v222
	v_lshl_add_u64 v[164:165], v[164:165], 0, s[12:13]
	s_mov_b32 m0, s0
	ds_read_b128 v[204:207], v216
	ds_read_b128 v[208:211], v216 offset:1024
	ds_read_b128 v[212:215], v216 offset:2048
	ds_read_b128 v[216:219], v216 offset:3072
	global_load_lds_dwordx4 v[164:165], off
	v_lshl_add_u64 v[164:165], v[166:167], 0, s[12:13]
	s_add_i32 m0, s0, 0x2000
	s_nop 0
	global_load_lds_dwordx4 v[164:165], off
	s_waitcnt vmcnt(10)
	s_setprio 1
	s_barrier
	s_waitcnt lgkmcnt(0)
	v_mfma_f32_16x16x32_bf16 v[64:67], v[204:207], v[172:175], v[64:67]
	v_mfma_f32_16x16x32_bf16 v[60:63], v[212:215], v[172:175], v[60:63]
	v_mfma_f32_16x16x32_bf16 v[56:59], v[204:207], v[180:183], v[56:59]
	v_mfma_f32_16x16x32_bf16 v[52:55], v[212:215], v[180:183], v[52:55]
	v_mfma_f32_16x16x32_bf16 v[48:51], v[204:207], v[188:191], v[48:51]
	v_mfma_f32_16x16x32_bf16 v[44:47], v[212:215], v[188:191], v[44:47]
	v_mfma_f32_16x16x32_bf16 v[40:43], v[204:207], v[196:199], v[40:43]
	v_mfma_f32_16x16x32_bf16 v[36:39], v[212:215], v[196:199], v[36:39]
	v_mfma_f32_16x16x32_bf16 v[64:67], v[208:211], v[176:179], v[64:67]
	v_mfma_f32_16x16x32_bf16 v[60:63], v[216:219], v[176:179], v[60:63]
	v_mfma_f32_16x16x32_bf16 v[56:59], v[208:211], v[184:187], v[56:59]
	v_mfma_f32_16x16x32_bf16 v[52:55], v[216:219], v[184:187], v[52:55]
	v_mfma_f32_16x16x32_bf16 v[48:51], v[208:211], v[192:195], v[48:51]
	v_mfma_f32_16x16x32_bf16 v[44:47], v[216:219], v[192:195], v[44:47]
	v_mfma_f32_16x16x32_bf16 v[40:43], v[208:211], v[200:203], v[40:43]
	v_mfma_f32_16x16x32_bf16 v[36:39], v[216:219], v[200:203], v[36:39]
	s_barrier
	s_setprio 0
	s_mov_b32 m0, s59
	v_lshl_add_u64 v[164:165], v[168:169], 0, s[12:13]
	ds_read_b128 v[172:175], v224 offset:49152
	ds_read_b128 v[176:179], v224 offset:50176
	ds_read_b128 v[180:183], v224 offset:51200
	ds_read_b128 v[184:187], v224 offset:52224
	ds_read_b128 v[188:191], v224 offset:53248
	ds_read_b128 v[192:195], v224 offset:54272
	ds_read_b128 v[196:199], v224 offset:55296
	ds_read_b128 v[200:203], v224 offset:56320
	global_load_lds_dwordx4 v[164:165], off
	v_lshl_add_u64 v[164:165], v[220:221], 0, s[12:13]
	s_mov_b32 m0, s68
	s_nop 0
	global_load_lds_dwordx4 v[164:165], off
	s_setprio 1
	s_barrier
	s_waitcnt lgkmcnt(0)
	v_mfma_f32_16x16x32_bf16 v[96:99], v[132:135], v[172:175], v[96:99]
	v_mfma_f32_16x16x32_bf16 v[92:95], v[156:159], v[172:175], v[92:95]
	v_mfma_f32_16x16x32_bf16 v[88:91], v[132:135], v[180:183], v[88:91]
	v_mfma_f32_16x16x32_bf16 v[84:87], v[156:159], v[180:183], v[84:87]
	v_mfma_f32_16x16x32_bf16 v[80:83], v[132:135], v[188:191], v[80:83]
	v_mfma_f32_16x16x32_bf16 v[76:79], v[156:159], v[188:191], v[76:79]
	v_mfma_f32_16x16x32_bf16 v[72:75], v[132:135], v[196:199], v[72:75]
	v_mfma_f32_16x16x32_bf16 v[68:71], v[156:159], v[196:199], v[68:71]
	v_mfma_f32_16x16x32_bf16 v[96:99], v[136:139], v[176:179], v[96:99]
	v_mfma_f32_16x16x32_bf16 v[92:95], v[160:163], v[176:179], v[92:95]
	v_mfma_f32_16x16x32_bf16 v[88:91], v[136:139], v[184:187], v[88:91]
	v_mfma_f32_16x16x32_bf16 v[84:87], v[160:163], v[184:187], v[84:87]
	v_mfma_f32_16x16x32_bf16 v[80:83], v[136:139], v[192:195], v[80:83]
	v_mfma_f32_16x16x32_bf16 v[76:79], v[160:163], v[192:195], v[76:79]
	v_mfma_f32_16x16x32_bf16 v[72:75], v[136:139], v[200:203], v[72:75]
	v_mfma_f32_16x16x32_bf16 v[68:71], v[160:163], v[200:203], v[68:71]
	s_barrier
	s_setprio 0
	s_add_u32 s0, s30, 0xb0080
	s_addc_u32 s1, s31, 0
	s_add_i32 s26, s27, s17
	v_lshl_add_u64 v[132:133], s[0:1], 0, v[26:27]
	s_mov_b32 m0, s26
	s_nop 0
	global_load_lds_dwordx4 v[132:133], off
	v_lshl_add_u64 v[132:133], s[0:1], 0, v[144:145]
	s_add_i32 m0, s26, 0x2000
	s_nop 0
	global_load_lds_dwordx4 v[132:133], off
	s_waitcnt vmcnt(10)
	s_setprio 1
	s_barrier
	v_mfma_f32_16x16x32_bf16 v[32:35], v[204:207], v[172:175], v[32:35]
	v_mfma_f32_16x16x32_bf16 v[28:31], v[212:215], v[172:175], v[28:31]
	v_mfma_f32_16x16x32_bf16 v[22:25], v[204:207], v[180:183], v[22:25]
	v_mfma_f32_16x16x32_bf16 v[18:21], v[212:215], v[180:183], v[18:21]
	v_mfma_f32_16x16x32_bf16 v[14:17], v[204:207], v[188:191], v[14:17]
	v_mfma_f32_16x16x32_bf16 v[10:13], v[212:215], v[188:191], v[10:13]
	v_mfma_f32_16x16x32_bf16 v[6:9], v[204:207], v[196:199], v[6:9]
	v_mfma_f32_16x16x32_bf16 v[2:5], v[212:215], v[196:199], v[2:5]
	v_mfma_f32_16x16x32_bf16 v[32:35], v[208:211], v[176:179], v[32:35]
	v_mfma_f32_16x16x32_bf16 v[28:31], v[216:219], v[176:179], v[28:31]
	v_mfma_f32_16x16x32_bf16 v[22:25], v[208:211], v[184:187], v[22:25]
	v_mfma_f32_16x16x32_bf16 v[18:21], v[216:219], v[184:187], v[18:21]
	v_mfma_f32_16x16x32_bf16 v[14:17], v[208:211], v[192:195], v[14:17]
	v_mfma_f32_16x16x32_bf16 v[10:13], v[216:219], v[192:195], v[10:13]
	v_mfma_f32_16x16x32_bf16 v[6:9], v[208:211], v[200:203], v[6:9]
	v_mfma_f32_16x16x32_bf16 v[2:5], v[216:219], v[200:203], v[2:5]
	s_barrier
	s_setprio 0
	s_add_i32 s81, s81, 2
	s_add_u32 s44, s44, 0x100
	s_addc_u32 s45, s45, 0
	s_cmp_gt_u32 s81, 41
	s_mov_b64 s[26:27], s[28:29]
	s_cbranch_scc0 .LBB0_1156
	s_min_i32 s0, s24, 0x100
	s_ashr_i32 s0, s0, 5
	s_ashr_i32 s1, s0, 31
	s_add_i32 s26, s24, 0xffffff00
	s_cmpk_lt_i32 s24, 0x100
	s_cselect_b32 s26, s24, s26
	s_cselect_b32 s28, 0, s51
	s_cselect_b32 s29, 0, s50
	s_ashr_i32 s27, s26, 31
	s_lshl_b64 s[26:27], s[26:27], 19
	v_lshl_add_u64 v[132:133], s[26:27], 0, v[146:147]
	s_add_u32 s26, s20, s29
	v_lshl_or_b32 v166, s25, 8, v223
	s_addc_u32 s27, s21, s28
	s_ashr_i32 s25, s24, 31
	s_lshl_b64 s[28:29], s[24:25], 19
	v_lshl_add_u64 v[178:179], v[148:149], 0, s[28:29]
	s_lshl_b64 s[24:25], s[24:25], 10
	s_mul_i32 s28, s0, 0x9000
	v_ashrrev_i32_e32 v167, 31, v166
	s_mul_hi_i32 s29, s0, 0x9000
	s_add_u32 s28, s36, s28
	s_addc_u32 s29, s37, s29
	v_lshlrev_b64 v[180:181], 2, v[166:167]
	v_lshl_add_u64 v[156:157], s[28:29], 0, v[180:181]
	v_lshl_add_u64 v[168:169], v[132:133], 0, v[166:167]
	v_lshl_add_u64 v[182:183], v[132:133], 1, s[26:27]
	global_load_dwordx4 v[132:135], v[156:157], off offset:16
	global_load_dwordx4 v[136:139], v[156:157], off
	s_lshl_b64 s[0:1], s[0:1], 12
	s_add_u32 s28, s57, s0
	s_addc_u32 s29, s58, s1
	v_lshl_add_u64 v[180:181], s[28:29], 0, v[180:181]
	v_lshl_add_u64 v[196:197], v[168:169], 1, s[26:27]
	v_add_co_u32_e32 v210, vcc, s65, v196
	s_mov_b32 s1, 0x20000
	s_nop 0
	v_addc_co_u32_e32 v211, vcc, 0, v197, vcc
	v_add_co_u32_e32 v184, vcc, s1, v196
	s_mov_b32 s26, 0x30000
	s_nop 0
	v_addc_co_u32_e32 v185, vcc, 0, v197, vcc
	v_add_co_u32_e32 v188, vcc, s26, v196
	v_lshlrev_b64 v[166:167], 1, v[166:167]
	s_nop 0
	v_addc_co_u32_e32 v189, vcc, 0, v197, vcc
	v_lshl_add_u64 v[178:179], v[178:179], 0, v[166:167]
	v_lshl_add_u64 v[182:183], v[182:183], 0, v[166:167]
	s_mov_b32 s0, 0x8000
	s_mov_b32 s27, 0x80000
	s_mov_b32 s28, 0x90000
	s_waitcnt vmcnt(0)
	v_pk_mul_f32 v[172:173], v[134:135], 0.5 op_sel_hi:[1,0]
	v_pk_mul_f32 v[176:177], v[138:139], 0.5 op_sel_hi:[1,0]
	v_pk_mul_f32 v[174:175], v[136:137], 0.5 op_sel_hi:[1,0]
	v_pk_mul_f32 v[164:165], v[132:133], 0.5 op_sel_hi:[1,0]
	global_load_dwordx4 v[132:135], v[156:157], off offset:528
	global_load_dwordx4 v[136:139], v[156:157], off offset:512
	s_waitcnt vmcnt(0)
	v_pk_mul_f32 v[158:159], v[134:135], 0.5 op_sel_hi:[1,0]
	v_pk_mul_f32 v[162:163], v[138:139], 0.5 op_sel_hi:[1,0]
	v_pk_mul_f32 v[160:161], v[136:137], 0.5 op_sel_hi:[1,0]
	v_pk_mul_f32 v[156:157], v[132:133], 0.5 op_sel_hi:[1,0]
	global_load_dwordx4 v[132:135], v[180:181], off offset:16
	global_load_dwordx4 v[136:139], v[180:181], off
	global_load_dwordx4 v[190:193], v[196:197], off offset:2048
	global_load_dwordx4 v[198:201], v[210:211], off offset:2048
	global_load_dwordx4 v[202:205], v[184:185], off offset:2048
	global_load_dwordx4 v[206:209], v[188:189], off offset:2048
	s_waitcnt vmcnt(0)
	v_lshlrev_b32_e32 v166, 16, v190
	v_and_b32_e32 v167, 0xffff0000, v190
	v_lshlrev_b32_e32 v168, 16, v191
	v_and_b32_e32 v169, 0xffff0000, v191
	v_lshlrev_b32_e32 v186, 16, v192
	v_and_b32_e32 v187, 0xffff0000, v192
	v_lshlrev_b32_e32 v190, 16, v193
	v_and_b32_e32 v191, 0xffff0000, v193
	v_pk_fma_f32 v[130:131], v[130:131], v[176:177], v[168:169]
	v_pk_fma_f32 v[128:129], v[128:129], v[174:175], v[166:167]
	v_pk_fma_f32 v[126:127], v[126:127], v[172:173], v[190:191]
	v_pk_fma_f32 v[124:125], v[124:125], v[164:165], v[186:187]
	v_cvt_pk_bf16_f32 v190, v128, v129
	v_cvt_pk_bf16_f32 v191, v130, v131
	v_cvt_pk_bf16_f32 v192, v124, v125
	v_cvt_pk_bf16_f32 v193, v126, v127
	v_lshlrev_b32_e32 v130, 16, v190
	v_and_b32_e32 v131, 0xffff0000, v190
	v_lshlrev_b32_e32 v128, 16, v191
	v_and_b32_e32 v129, 0xffff0000, v191
	v_lshlrev_b32_e32 v126, 16, v192
	v_and_b32_e32 v127, 0xffff0000, v192
	v_lshlrev_b32_e32 v124, 16, v193
	v_and_b32_e32 v125, 0xffff0000, v193
	v_lshlrev_b32_e32 v212, 16, v200
	v_and_b32_e32 v213, 0xffff0000, v200
	v_lshlrev_b32_e32 v200, 16, v201
	v_and_b32_e32 v201, 0xffff0000, v201
	global_store_dwordx4 v[182:183], v[190:193], off offset:2048
	v_pk_mul_f32 v[166:167], v[138:139], v[128:129]
	v_pk_mul_f32 v[168:169], v[136:137], v[130:131]
	v_pk_mul_f32 v[186:187], v[134:135], v[124:125]
	v_pk_mul_f32 v[192:193], v[132:133], v[126:127]
	v_lshlrev_b32_e32 v194, 16, v198
	v_and_b32_e32 v195, 0xffff0000, v198
	v_lshlrev_b32_e32 v198, 16, v199
	v_and_b32_e32 v199, 0xffff0000, v199
	v_cvt_pk_bf16_f32 v190, v168, v169
	v_cvt_pk_bf16_f32 v191, v166, v167
	v_cvt_pk_bf16_f32 v192, v192, v193
	v_cvt_pk_bf16_f32 v193, v186, v187
	v_pk_fma_f32 v[118:119], v[118:119], v[172:173], v[200:201]
	v_pk_fma_f32 v[116:117], v[116:117], v[164:165], v[212:213]
	global_store_dwordx4 v[178:179], v[190:193], off
	v_pk_fma_f32 v[122:123], v[122:123], v[176:177], v[198:199]
	v_pk_fma_f32 v[120:121], v[120:121], v[174:175], v[194:195]
	v_cvt_pk_bf16_f32 v192, v116, v117
	v_cvt_pk_bf16_f32 v193, v118, v119
	v_add_co_u32_e32 v186, vcc, s65, v182
	v_cvt_pk_bf16_f32 v190, v120, v121
	v_cvt_pk_bf16_f32 v191, v122, v123
	v_addc_co_u32_e32 v187, vcc, 0, v183, vcc
	v_lshlrev_b32_e32 v118, 16, v192
	v_and_b32_e32 v119, 0xffff0000, v192
	v_lshlrev_b32_e32 v116, 16, v193
	v_and_b32_e32 v117, 0xffff0000, v193
	global_store_dwordx4 v[186:187], v[190:193], off offset:2048
	v_lshlrev_b32_e32 v122, 16, v190
	v_and_b32_e32 v123, 0xffff0000, v190
	v_lshlrev_b32_e32 v120, 16, v191
	v_and_b32_e32 v121, 0xffff0000, v191
	v_pk_mul_f32 v[190:191], v[134:135], v[116:117]
	v_pk_mul_f32 v[194:195], v[132:133], v[118:119]
	v_pk_mul_f32 v[166:167], v[138:139], v[120:121]
	v_pk_mul_f32 v[168:169], v[136:137], v[122:123]
	v_cvt_pk_bf16_f32 v194, v194, v195
	v_cvt_pk_bf16_f32 v195, v190, v191
	v_add_co_u32_e32 v190, vcc, s0, v178
	v_cvt_pk_bf16_f32 v192, v168, v169
	v_cvt_pk_bf16_f32 v193, v166, v167
	v_addc_co_u32_e32 v191, vcc, 0, v179, vcc
	global_store_dwordx4 v[190:191], v[192:195], off
	v_lshlrev_b32_e32 v198, 16, v204
	v_and_b32_e32 v199, 0xffff0000, v204
	v_add_co_u32_e32 v192, vcc, s27, v196
	v_lshlrev_b32_e32 v200, 16, v205
	s_nop 0
	v_addc_co_u32_e32 v193, vcc, 0, v197, vcc
	v_add_co_u32_e32 v194, vcc, s28, v196
	v_and_b32_e32 v201, 0xffff0000, v205
	global_load_dwordx4 v[212:215], v[192:193], off offset:2048
	v_addc_co_u32_e32 v195, vcc, 0, v197, vcc
	v_lshlrev_b32_e32 v166, 16, v202
	v_and_b32_e32 v167, 0xffff0000, v202
	v_lshlrev_b32_e32 v168, 16, v203
	v_and_b32_e32 v169, 0xffff0000, v203
	v_pk_fma_f32 v[110:111], v[110:111], v[172:173], v[200:201]
	v_pk_fma_f32 v[108:109], v[108:109], v[164:165], v[198:199]
	v_pk_fma_f32 v[114:115], v[114:115], v[176:177], v[168:169]
	v_pk_fma_f32 v[112:113], v[112:113], v[174:175], v[166:167]
	v_cvt_pk_bf16_f32 v202, v108, v109
	v_cvt_pk_bf16_f32 v203, v110, v111
	v_add_co_u32_e32 v198, vcc, s1, v182
	global_load_dwordx4 v[216:219], v[194:195], off offset:2048
	v_cvt_pk_bf16_f32 v200, v112, v113
	v_cvt_pk_bf16_f32 v201, v114, v115
	v_addc_co_u32_e32 v199, vcc, 0, v183, vcc
	v_lshlrev_b32_e32 v110, 16, v202
	v_and_b32_e32 v111, 0xffff0000, v202
	v_lshlrev_b32_e32 v108, 16, v203
	v_and_b32_e32 v109, 0xffff0000, v203
	global_store_dwordx4 v[198:199], v[200:203], off offset:2048
	v_lshlrev_b32_e32 v114, 16, v200
	v_and_b32_e32 v115, 0xffff0000, v200
	v_lshlrev_b32_e32 v112, 16, v201
	v_and_b32_e32 v113, 0xffff0000, v201
	v_pk_mul_f32 v[200:201], v[134:135], v[108:109]
	v_pk_mul_f32 v[204:205], v[132:133], v[110:111]
	v_lshlrev_b32_e32 v234, 16, v208
	v_and_b32_e32 v235, 0xffff0000, v208
	v_lshlrev_b32_e32 v208, 16, v209
	v_and_b32_e32 v209, 0xffff0000, v209
	v_pk_mul_f32 v[166:167], v[138:139], v[112:113]
	v_pk_mul_f32 v[168:169], v[136:137], v[114:115]
	v_cvt_pk_bf16_f32 v204, v204, v205
	v_cvt_pk_bf16_f32 v205, v200, v201
	v_add_co_u32_e32 v200, vcc, s65, v178
	v_lshlrev_b32_e32 v220, 16, v206
	v_and_b32_e32 v221, 0xffff0000, v206
	v_lshlrev_b32_e32 v206, 16, v207
	v_and_b32_e32 v207, 0xffff0000, v207
	v_cvt_pk_bf16_f32 v202, v168, v169
	v_cvt_pk_bf16_f32 v203, v166, v167
	v_addc_co_u32_e32 v201, vcc, 0, v179, vcc
	v_pk_fma_f32 v[102:103], v[102:103], v[172:173], v[208:209]
	v_pk_fma_f32 v[100:101], v[100:101], v[164:165], v[234:235]
	global_store_dwordx4 v[200:201], v[202:205], off
	v_pk_fma_f32 v[106:107], v[106:107], v[176:177], v[206:207]
	v_pk_fma_f32 v[104:105], v[104:105], v[174:175], v[220:221]
	v_cvt_pk_bf16_f32 v206, v100, v101
	v_cvt_pk_bf16_f32 v207, v102, v103
	v_add_co_u32_e32 v202, vcc, s26, v182
	v_cvt_pk_bf16_f32 v204, v104, v105
	v_cvt_pk_bf16_f32 v205, v106, v107
	v_addc_co_u32_e32 v203, vcc, 0, v183, vcc
	v_lshlrev_b32_e32 v102, 16, v206
	v_and_b32_e32 v103, 0xffff0000, v206
	v_lshlrev_b32_e32 v100, 16, v207
	v_and_b32_e32 v101, 0xffff0000, v207
	global_store_dwordx4 v[202:203], v[204:207], off offset:2048
	v_lshlrev_b32_e32 v106, 16, v204
	v_and_b32_e32 v107, 0xffff0000, v204
	v_lshlrev_b32_e32 v104, 16, v205
	v_and_b32_e32 v105, 0xffff0000, v205
	v_pk_mul_f32 v[204:205], v[134:135], v[100:101]
	v_pk_mul_f32 v[208:209], v[132:133], v[102:103]
	s_mov_b32 s0, 0x18000
	v_pk_mul_f32 v[166:167], v[138:139], v[104:105]
	v_pk_mul_f32 v[168:169], v[136:137], v[106:107]
	v_cvt_pk_bf16_f32 v208, v208, v209
	v_cvt_pk_bf16_f32 v209, v204, v205
	v_add_co_u32_e32 v204, vcc, s0, v178
	v_cvt_pk_bf16_f32 v206, v168, v169
	v_cvt_pk_bf16_f32 v207, v166, v167
	v_addc_co_u32_e32 v205, vcc, 0, v179, vcc
	global_store_dwordx4 v[204:205], v[206:209], off
	s_mov_b32 s0, 0xb0000
	s_waitcnt vmcnt(0)
	v_lshlrev_b32_e32 v166, 16, v212
	v_add_co_u32_e32 v206, vcc, s76, v196
	v_and_b32_e32 v167, 0xffff0000, v212
	s_nop 0
	v_addc_co_u32_e32 v207, vcc, 0, v197, vcc
	global_load_dwordx4 v[238:241], v[206:207], off offset:2048
	v_add_co_u32_e32 v208, vcc, s0, v196
	v_lshlrev_b32_e32 v168, 16, v213
	s_nop 0
	v_addc_co_u32_e32 v209, vcc, 0, v197, vcc
	global_load_dwordx4 v[242:245], v[208:209], off offset:2048
	v_and_b32_e32 v169, 0xffff0000, v213
	v_lshlrev_b32_e32 v212, 16, v214
	v_and_b32_e32 v213, 0xffff0000, v214
	v_lshlrev_b32_e32 v214, 16, v215
	v_and_b32_e32 v215, 0xffff0000, v215
	v_pk_fma_f32 v[94:95], v[94:95], v[172:173], v[214:215]
	v_pk_fma_f32 v[92:93], v[92:93], v[164:165], v[212:213]
	v_lshlrev_b32_e32 v220, 16, v216
	v_and_b32_e32 v221, 0xffff0000, v216
	v_lshlrev_b32_e32 v234, 16, v217
	v_and_b32_e32 v235, 0xffff0000, v217
	v_pk_fma_f32 v[98:99], v[98:99], v[176:177], v[168:169]
	v_pk_fma_f32 v[96:97], v[96:97], v[174:175], v[166:167]
	v_cvt_pk_bf16_f32 v216, v92, v93
	v_cvt_pk_bf16_f32 v217, v94, v95
	v_add_co_u32_e32 v212, vcc, s27, v182
	v_cvt_pk_bf16_f32 v214, v96, v97
	v_cvt_pk_bf16_f32 v215, v98, v99
	v_addc_co_u32_e32 v213, vcc, 0, v183, vcc
	v_lshlrev_b32_e32 v94, 16, v216
	v_and_b32_e32 v95, 0xffff0000, v216
	v_lshlrev_b32_e32 v92, 16, v217
	v_and_b32_e32 v93, 0xffff0000, v217
	v_lshlrev_b32_e32 v246, 16, v218
	v_and_b32_e32 v247, 0xffff0000, v218
	v_lshlrev_b32_e32 v248, 16, v219
	v_and_b32_e32 v249, 0xffff0000, v219
	global_store_dwordx4 v[212:213], v[214:217], off offset:2048
	v_lshlrev_b32_e32 v98, 16, v214
	v_and_b32_e32 v99, 0xffff0000, v214
	v_lshlrev_b32_e32 v96, 16, v215
	v_and_b32_e32 v97, 0xffff0000, v215
	v_pk_mul_f32 v[214:215], v[134:135], v[92:93]
	v_pk_mul_f32 v[218:219], v[132:133], v[94:95]
	s_mov_b32 s1, 0x40000
	v_pk_mul_f32 v[166:167], v[138:139], v[96:97]
	v_pk_mul_f32 v[168:169], v[136:137], v[98:99]
	v_cvt_pk_bf16_f32 v218, v218, v219
	v_cvt_pk_bf16_f32 v219, v214, v215
	v_add_co_u32_e32 v214, vcc, s1, v178
	v_cvt_pk_bf16_f32 v216, v168, v169
	v_cvt_pk_bf16_f32 v217, v166, v167
	v_addc_co_u32_e32 v215, vcc, 0, v179, vcc
	v_pk_fma_f32 v[86:87], v[86:87], v[172:173], v[248:249]
	global_store_dwordx4 v[214:215], v[216:219], off
	v_pk_fma_f32 v[90:91], v[90:91], v[176:177], v[234:235]
	v_pk_fma_f32 v[88:89], v[88:89], v[174:175], v[220:221]
	v_pk_fma_f32 v[84:85], v[84:85], v[164:165], v[246:247]
	v_cvt_pk_bf16_f32 v221, v86, v87
	v_add_co_u32_e32 v216, vcc, s28, v182
	v_cvt_pk_bf16_f32 v218, v88, v89
	v_cvt_pk_bf16_f32 v219, v90, v91
	v_cvt_pk_bf16_f32 v220, v84, v85
	v_addc_co_u32_e32 v217, vcc, 0, v183, vcc
	v_lshlrev_b32_e32 v84, 16, v221
	v_and_b32_e32 v85, 0xffff0000, v221
	global_store_dwordx4 v[216:217], v[218:221], off offset:2048
	v_lshlrev_b32_e32 v90, 16, v218
	v_and_b32_e32 v91, 0xffff0000, v218
	v_lshlrev_b32_e32 v88, 16, v219
	v_and_b32_e32 v89, 0xffff0000, v219
	v_lshlrev_b32_e32 v86, 16, v220
	v_and_b32_e32 v87, 0xffff0000, v220
	v_pk_mul_f32 v[218:219], v[134:135], v[84:85]
	s_mov_b32 s1, 0x48000
	v_pk_mul_f32 v[166:167], v[138:139], v[88:89]
	v_pk_mul_f32 v[168:169], v[136:137], v[90:91]
	v_pk_mul_f32 v[220:221], v[132:133], v[86:87]
	v_cvt_pk_bf16_f32 v249, v218, v219
	v_add_co_u32_e32 v218, vcc, s1, v178
	v_cvt_pk_bf16_f32 v246, v168, v169
	v_cvt_pk_bf16_f32 v247, v166, v167
	v_cvt_pk_bf16_f32 v248, v220, v221
	v_addc_co_u32_e32 v219, vcc, 0, v179, vcc
	global_store_dwordx4 v[218:219], v[246:249], off
	global_load_dwordx4 v[246:249], v[196:197], off offset:2304
	s_nop 0
	global_load_dwordx4 v[250:253], v[210:211], off offset:2304
	s_waitcnt vmcnt(0)
	v_lshlrev_b32_e32 v196, 16, v240
	v_and_b32_e32 v197, 0xffff0000, v240
	v_lshlrev_b32_e32 v210, 16, v241
	v_and_b32_e32 v211, 0xffff0000, v241
	v_lshlrev_b32_e32 v166, 16, v238
	v_and_b32_e32 v167, 0xffff0000, v238
	v_lshlrev_b32_e32 v168, 16, v239
	v_and_b32_e32 v169, 0xffff0000, v239
	v_pk_fma_f32 v[78:79], v[78:79], v[172:173], v[210:211]
	v_pk_fma_f32 v[76:77], v[76:77], v[164:165], v[196:197]
	v_pk_fma_f32 v[82:83], v[82:83], v[176:177], v[168:169]
	v_pk_fma_f32 v[80:81], v[80:81], v[174:175], v[166:167]
	v_cvt_pk_bf16_f32 v240, v76, v77
	v_cvt_pk_bf16_f32 v241, v78, v79
	v_add_co_u32_e32 v196, vcc, s76, v182
	v_cvt_pk_bf16_f32 v238, v80, v81
	v_cvt_pk_bf16_f32 v239, v82, v83
	v_addc_co_u32_e32 v197, vcc, 0, v183, vcc
	v_lshlrev_b32_e32 v78, 16, v240
	v_and_b32_e32 v79, 0xffff0000, v240
	v_lshlrev_b32_e32 v76, 16, v241
	v_and_b32_e32 v77, 0xffff0000, v241
	global_store_dwordx4 v[196:197], v[238:241], off offset:2048
	v_lshlrev_b32_e32 v80, 16, v239
	v_and_b32_e32 v81, 0xffff0000, v239
	v_pk_mul_f32 v[210:211], v[134:135], v[76:77]
	v_pk_mul_f32 v[240:241], v[132:133], v[78:79]
	v_lshlrev_b32_e32 v220, 16, v242
	v_and_b32_e32 v221, 0xffff0000, v242
	v_lshlrev_b32_e32 v234, 16, v243
	v_and_b32_e32 v235, 0xffff0000, v243
	v_lshlrev_b32_e32 v242, 16, v244
	v_and_b32_e32 v243, 0xffff0000, v244
	v_lshlrev_b32_e32 v244, 16, v245
	v_and_b32_e32 v245, 0xffff0000, v245
	v_pk_mul_f32 v[166:167], v[138:139], v[80:81]
	v_cvt_pk_bf16_f32 v240, v240, v241
	v_cvt_pk_bf16_f32 v241, v210, v211
	v_add_co_u32_e32 v210, vcc, s77, v178
	v_lshlrev_b32_e32 v82, 16, v238
	v_and_b32_e32 v83, 0xffff0000, v238
	v_cvt_pk_bf16_f32 v239, v166, v167
	v_addc_co_u32_e32 v211, vcc, 0, v179, vcc
	v_pk_fma_f32 v[74:75], v[74:75], v[176:177], v[234:235]
	v_pk_fma_f32 v[72:73], v[72:73], v[174:175], v[220:221]
	v_pk_fma_f32 v[166:167], v[70:71], v[172:173], v[244:245]
	v_pk_fma_f32 v[70:71], v[68:69], v[164:165], v[242:243]
	v_pk_mul_f32 v[168:169], v[136:137], v[82:83]
	v_cvt_pk_bf16_f32 v68, v72, v73
	v_cvt_pk_bf16_f32 v69, v74, v75
	v_cvt_pk_bf16_f32 v70, v70, v71
	v_cvt_pk_bf16_f32 v71, v166, v167
	v_add_co_u32_e32 v220, vcc, s0, v182
	v_cvt_pk_bf16_f32 v238, v168, v169
	s_nop 0
	v_addc_co_u32_e32 v221, vcc, 0, v183, vcc
	v_lshlrev_b32_e32 v176, 16, v68
	v_and_b32_e32 v177, 0xffff0000, v68
	v_lshlrev_b32_e32 v174, 16, v69
	v_and_b32_e32 v175, 0xffff0000, v69
	v_lshlrev_b32_e32 v172, 16, v70
	v_and_b32_e32 v173, 0xffff0000, v70
	v_lshlrev_b32_e32 v164, 16, v71
	v_and_b32_e32 v165, 0xffff0000, v71
	s_mov_b32 s0, 0x58000
	global_store_dwordx4 v[210:211], v[238:241], off
	global_store_dwordx4 v[220:221], v[68:71], off offset:2048
	v_pk_mul_f32 v[72:73], v[134:135], v[164:165]
	v_pk_mul_f32 v[74:75], v[132:133], v[172:173]
	v_pk_mul_f32 v[70:71], v[138:139], v[174:175]
	v_pk_mul_f32 v[68:69], v[136:137], v[176:177]
	v_add_co_u32_e32 v132, vcc, s0, v178
	v_cvt_pk_bf16_f32 v68, v68, v69
	v_cvt_pk_bf16_f32 v69, v70, v71
	v_cvt_pk_bf16_f32 v70, v74, v75
	v_cvt_pk_bf16_f32 v71, v72, v73
	v_addc_co_u32_e32 v133, vcc, 0, v179, vcc
	global_store_dwordx4 v[132:133], v[68:71], off
	global_load_dwordx4 v[134:137], v[184:185], off offset:2304
	global_load_dwordx4 v[238:241], v[188:189], off offset:2304
	s_nop 0
	global_load_dwordx4 v[68:71], v[180:181], off offset:528
	global_load_dwordx4 v[72:75], v[180:181], off offset:512
	v_lshlrev_b32_e32 v138, 16, v246
	v_and_b32_e32 v139, 0xffff0000, v246
	v_lshlrev_b32_e32 v166, 16, v247
	v_and_b32_e32 v167, 0xffff0000, v247
	v_lshlrev_b32_e32 v168, 16, v248
	v_and_b32_e32 v169, 0xffff0000, v248
	v_lshlrev_b32_e32 v180, 16, v249
	v_and_b32_e32 v181, 0xffff0000, v249
	v_pk_fma_f32 v[66:67], v[66:67], v[162:163], v[166:167]
	v_pk_fma_f32 v[64:65], v[64:65], v[160:161], v[138:139]
	v_pk_fma_f32 v[62:63], v[62:63], v[158:159], v[180:181]
	v_pk_fma_f32 v[60:61], v[60:61], v[156:157], v[168:169]
	v_cvt_pk_bf16_f32 v242, v64, v65
	v_cvt_pk_bf16_f32 v243, v66, v67
	v_cvt_pk_bf16_f32 v244, v60, v61
	v_cvt_pk_bf16_f32 v245, v62, v63
	v_lshlrev_b32_e32 v66, 16, v242
	v_and_b32_e32 v67, 0xffff0000, v242
	v_lshlrev_b32_e32 v64, 16, v243
	v_and_b32_e32 v65, 0xffff0000, v243
	v_lshlrev_b32_e32 v62, 16, v244
	v_and_b32_e32 v63, 0xffff0000, v244
	v_lshlrev_b32_e32 v60, 16, v245
	v_and_b32_e32 v61, 0xffff0000, v245
	v_lshlrev_b32_e32 v184, 16, v250
	v_and_b32_e32 v185, 0xffff0000, v250
	v_lshlrev_b32_e32 v188, 16, v251
	v_and_b32_e32 v189, 0xffff0000, v251
	v_lshlrev_b32_e32 v234, 16, v252
	v_and_b32_e32 v235, 0xffff0000, v252
	v_lshlrev_b32_e32 v246, 16, v253
	v_and_b32_e32 v247, 0xffff0000, v253
	global_store_dwordx4 v[182:183], v[242:245], off offset:2304
	v_pk_fma_f32 v[58:59], v[58:59], v[162:163], v[188:189]
	v_pk_fma_f32 v[56:57], v[56:57], v[160:161], v[184:185]
	v_pk_fma_f32 v[54:55], v[54:55], v[158:159], v[246:247]
	v_pk_fma_f32 v[52:53], v[52:53], v[156:157], v[234:235]
	s_waitcnt vmcnt(0)
	v_lshlrev_b32_e32 v188, 16, v240
	v_pk_mul_f32 v[168:169], v[70:71], v[60:61]
	v_pk_mul_f32 v[138:139], v[74:75], v[64:65]
	v_pk_mul_f32 v[166:167], v[72:73], v[66:67]
	v_pk_mul_f32 v[182:183], v[68:69], v[62:63]
	v_cvt_pk_bf16_f32 v180, v166, v167
	v_cvt_pk_bf16_f32 v181, v138, v139
	v_cvt_pk_bf16_f32 v182, v182, v183
	v_cvt_pk_bf16_f32 v183, v168, v169
	global_store_dwordx4 v[178:179], v[180:183], off offset:256
	v_cvt_pk_bf16_f32 v178, v56, v57
	v_cvt_pk_bf16_f32 v179, v58, v59
	v_cvt_pk_bf16_f32 v180, v52, v53
	v_cvt_pk_bf16_f32 v181, v54, v55
	v_lshlrev_b32_e32 v58, 16, v178
	v_and_b32_e32 v59, 0xffff0000, v178
	v_lshlrev_b32_e32 v56, 16, v179
	v_and_b32_e32 v57, 0xffff0000, v179
	v_lshlrev_b32_e32 v54, 16, v180
	v_and_b32_e32 v55, 0xffff0000, v180
	v_lshlrev_b32_e32 v52, 16, v181
	v_and_b32_e32 v53, 0xffff0000, v181
	global_store_dwordx4 v[186:187], v[178:181], off offset:2304
	v_pk_mul_f32 v[138:139], v[74:75], v[56:57]
	v_pk_mul_f32 v[166:167], v[72:73], v[58:59]
	v_pk_mul_f32 v[168:169], v[70:71], v[52:53]
	v_pk_mul_f32 v[180:181], v[68:69], v[54:55]
	v_cvt_pk_bf16_f32 v178, v166, v167
	v_cvt_pk_bf16_f32 v179, v138, v139
	v_cvt_pk_bf16_f32 v180, v180, v181
	v_cvt_pk_bf16_f32 v181, v168, v169
	v_lshlrev_b32_e32 v138, 16, v134
	v_and_b32_e32 v139, 0xffff0000, v134
	v_lshlrev_b32_e32 v134, 16, v135
	v_and_b32_e32 v135, 0xffff0000, v135
	v_lshlrev_b32_e32 v166, 16, v136
	v_and_b32_e32 v167, 0xffff0000, v136
	v_lshlrev_b32_e32 v136, 16, v137
	v_and_b32_e32 v137, 0xffff0000, v137
	global_store_dwordx4 v[190:191], v[178:181], off offset:256
	v_pk_fma_f32 v[50:51], v[50:51], v[162:163], v[134:135]
	v_pk_fma_f32 v[48:49], v[48:49], v[160:161], v[138:139]
	v_pk_fma_f32 v[46:47], v[46:47], v[158:159], v[136:137]
	v_pk_fma_f32 v[44:45], v[44:45], v[156:157], v[166:167]
	global_load_dwordx4 v[178:181], v[192:193], off offset:2304
	global_load_dwordx4 v[182:185], v[194:195], off offset:2304
	v_cvt_pk_bf16_f32 v134, v48, v49
	v_cvt_pk_bf16_f32 v135, v50, v51
	v_cvt_pk_bf16_f32 v136, v44, v45
	v_cvt_pk_bf16_f32 v137, v46, v47
	v_lshlrev_b32_e32 v50, 16, v134
	v_and_b32_e32 v51, 0xffff0000, v134
	v_lshlrev_b32_e32 v48, 16, v135
	v_and_b32_e32 v49, 0xffff0000, v135
	v_lshlrev_b32_e32 v46, 16, v136
	v_and_b32_e32 v47, 0xffff0000, v136
	v_lshlrev_b32_e32 v44, 16, v137
	v_and_b32_e32 v45, 0xffff0000, v137
	v_lshlrev_b32_e32 v168, 16, v238
	v_and_b32_e32 v169, 0xffff0000, v238
	v_lshlrev_b32_e32 v186, 16, v239
	v_and_b32_e32 v187, 0xffff0000, v239
	v_and_b32_e32 v189, 0xffff0000, v240
	v_lshlrev_b32_e32 v190, 16, v241
	v_and_b32_e32 v191, 0xffff0000, v241
	global_store_dwordx4 v[198:199], v[134:137], off offset:2304
	v_pk_mul_f32 v[138:139], v[70:71], v[44:45]
	v_pk_mul_f32 v[166:167], v[68:69], v[46:47]
	v_pk_mul_f32 v[136:137], v[74:75], v[48:49]
	v_pk_mul_f32 v[134:135], v[72:73], v[50:51]
	v_pk_fma_f32 v[42:43], v[42:43], v[162:163], v[186:187]
	v_cvt_pk_bf16_f32 v134, v134, v135
	v_cvt_pk_bf16_f32 v135, v136, v137
	v_cvt_pk_bf16_f32 v136, v166, v167
	v_cvt_pk_bf16_f32 v137, v138, v139
	v_pk_fma_f32 v[40:41], v[40:41], v[160:161], v[168:169]
	v_pk_fma_f32 v[38:39], v[38:39], v[158:159], v[190:191]
	v_pk_fma_f32 v[36:37], v[36:37], v[156:157], v[188:189]
	global_store_dwordx4 v[200:201], v[134:137], off offset:256
	v_mul_f32_e32 v67, v67, v67
	v_mul_f32_e32 v65, v65, v65
	v_cvt_pk_bf16_f32 v134, v40, v41
	v_cvt_pk_bf16_f32 v135, v42, v43
	v_cvt_pk_bf16_f32 v136, v36, v37
	v_cvt_pk_bf16_f32 v137, v38, v39
	v_lshlrev_b32_e32 v42, 16, v134
	v_and_b32_e32 v43, 0xffff0000, v134
	v_lshlrev_b32_e32 v40, 16, v135
	v_and_b32_e32 v41, 0xffff0000, v135
	v_lshlrev_b32_e32 v38, 16, v136
	v_and_b32_e32 v39, 0xffff0000, v136
	v_lshlrev_b32_e32 v36, 16, v137
	v_and_b32_e32 v37, 0xffff0000, v137
	global_store_dwordx4 v[202:203], v[134:137], off offset:2304
	v_pk_mul_f32 v[138:139], v[70:71], v[36:37]
	v_pk_mul_f32 v[166:167], v[68:69], v[38:39]
	v_pk_mul_f32 v[136:137], v[74:75], v[40:41]
	v_pk_mul_f32 v[134:135], v[72:73], v[42:43]
	v_fmac_f32_e32 v67, v66, v66
	v_cvt_pk_bf16_f32 v134, v134, v135
	v_cvt_pk_bf16_f32 v135, v136, v137
	v_cvt_pk_bf16_f32 v136, v166, v167
	v_cvt_pk_bf16_f32 v137, v138, v139
	global_store_dwordx4 v[204:205], v[134:137], off offset:256
	global_load_dwordx4 v[134:137], v[206:207], off offset:2304
	s_nop 0
	global_load_dwordx4 v[186:189], v[208:209], off offset:2304
	v_fmac_f32_e32 v65, v64, v64
	v_mul_f32_e32 v63, v63, v63
	v_mul_f32_e32 v61, v61, v61
	v_add_f32_e32 v64, v67, v65
	v_fmac_f32_e32 v63, v62, v62
	v_fmac_f32_e32 v61, v60, v60
	v_add_f32_e32 v60, v63, v61
	s_waitcnt vmcnt(0)
	v_lshlrev_b32_e32 v138, 16, v178
	v_and_b32_e32 v139, 0xffff0000, v178
	v_lshlrev_b32_e32 v166, 16, v179
	v_and_b32_e32 v167, 0xffff0000, v179
	v_lshlrev_b32_e32 v168, 16, v180
	v_and_b32_e32 v169, 0xffff0000, v180
	v_lshlrev_b32_e32 v178, 16, v181
	v_and_b32_e32 v179, 0xffff0000, v181
	v_pk_fma_f32 v[34:35], v[34:35], v[162:163], v[166:167]
	v_pk_fma_f32 v[32:33], v[32:33], v[160:161], v[138:139]
	v_pk_fma_f32 v[30:31], v[30:31], v[158:159], v[178:179]
	v_pk_fma_f32 v[28:29], v[28:29], v[156:157], v[168:169]
	v_cvt_pk_bf16_f32 v178, v32, v33
	v_cvt_pk_bf16_f32 v179, v34, v35
	v_cvt_pk_bf16_f32 v180, v28, v29
	v_cvt_pk_bf16_f32 v181, v30, v31
	v_lshlrev_b32_e32 v34, 16, v178
	v_and_b32_e32 v35, 0xffff0000, v178
	v_lshlrev_b32_e32 v32, 16, v179
	v_and_b32_e32 v33, 0xffff0000, v179
	v_lshlrev_b32_e32 v30, 16, v180
	v_and_b32_e32 v31, 0xffff0000, v180
	v_lshlrev_b32_e32 v28, 16, v181
	v_and_b32_e32 v29, 0xffff0000, v181
	v_lshlrev_b32_e32 v190, 16, v182
	v_and_b32_e32 v191, 0xffff0000, v182
	v_lshlrev_b32_e32 v182, 16, v183
	v_and_b32_e32 v183, 0xffff0000, v183
	global_store_dwordx4 v[212:213], v[178:181], off offset:2304
	v_pk_mul_f32 v[138:139], v[74:75], v[32:33]
	v_pk_mul_f32 v[166:167], v[72:73], v[34:35]
	v_pk_mul_f32 v[168:169], v[70:71], v[28:29]
	v_pk_mul_f32 v[180:181], v[68:69], v[30:31]
	v_cvt_pk_bf16_f32 v178, v166, v167
	v_cvt_pk_bf16_f32 v179, v138, v139
	v_cvt_pk_bf16_f32 v180, v180, v181
	v_cvt_pk_bf16_f32 v181, v168, v169
	v_pk_fma_f32 v[24:25], v[24:25], v[162:163], v[182:183]
	v_pk_fma_f32 v[22:23], v[22:23], v[160:161], v[190:191]
	v_lshlrev_b32_e32 v192, 16, v184
	v_and_b32_e32 v193, 0xffff0000, v184
	v_lshlrev_b32_e32 v184, 16, v185
	v_and_b32_e32 v185, 0xffff0000, v185
	global_store_dwordx4 v[214:215], v[178:181], off offset:256
	v_pk_fma_f32 v[20:21], v[20:21], v[158:159], v[184:185]
	v_pk_fma_f32 v[18:19], v[18:19], v[156:157], v[192:193]
	v_cvt_pk_bf16_f32 v178, v22, v23
	v_cvt_pk_bf16_f32 v179, v24, v25
	v_lshlrev_b32_e32 v24, 16, v178
	v_and_b32_e32 v25, 0xffff0000, v178
	v_lshlrev_b32_e32 v22, 16, v179
	v_and_b32_e32 v23, 0xffff0000, v179
	v_cvt_pk_bf16_f32 v180, v18, v19
	v_cvt_pk_bf16_f32 v181, v20, v21
	v_pk_mul_f32 v[138:139], v[74:75], v[22:23]
	v_pk_mul_f32 v[166:167], v[72:73], v[24:25]
	global_store_dwordx4 v[216:217], v[178:181], off offset:2304
	v_lshlrev_b32_e32 v20, 16, v180
	v_and_b32_e32 v21, 0xffff0000, v180
	v_cvt_pk_bf16_f32 v178, v166, v167
	v_cvt_pk_bf16_f32 v179, v138, v139
	v_lshlrev_b32_e32 v138, 16, v134
	v_and_b32_e32 v139, 0xffff0000, v134
	v_lshlrev_b32_e32 v134, 16, v135
	v_and_b32_e32 v135, 0xffff0000, v135
	v_lshlrev_b32_e32 v166, 16, v136
	v_and_b32_e32 v167, 0xffff0000, v136
	v_lshlrev_b32_e32 v136, 16, v137
	v_and_b32_e32 v137, 0xffff0000, v137
	v_lshlrev_b32_e32 v18, 16, v181
	v_and_b32_e32 v19, 0xffff0000, v181
	v_pk_fma_f32 v[16:17], v[16:17], v[162:163], v[134:135]
	v_pk_fma_f32 v[14:15], v[14:15], v[160:161], v[138:139]
	v_pk_fma_f32 v[12:13], v[12:13], v[158:159], v[136:137]
	v_pk_fma_f32 v[10:11], v[10:11], v[156:157], v[166:167]
	v_pk_mul_f32 v[168:169], v[70:71], v[18:19]
	v_pk_mul_f32 v[180:181], v[68:69], v[20:21]
	v_cvt_pk_bf16_f32 v134, v14, v15
	v_cvt_pk_bf16_f32 v135, v16, v17
	v_cvt_pk_bf16_f32 v136, v10, v11
	v_cvt_pk_bf16_f32 v137, v12, v13
	v_cvt_pk_bf16_f32 v180, v180, v181
	v_cvt_pk_bf16_f32 v181, v168, v169
	v_lshlrev_b32_e32 v16, 16, v134
	v_and_b32_e32 v17, 0xffff0000, v134
	v_lshlrev_b32_e32 v14, 16, v135
	v_and_b32_e32 v15, 0xffff0000, v135
	v_lshlrev_b32_e32 v12, 16, v136
	v_and_b32_e32 v13, 0xffff0000, v136
	v_lshlrev_b32_e32 v10, 16, v137
	v_and_b32_e32 v11, 0xffff0000, v137
	global_store_dwordx4 v[218:219], v[178:181], off offset:256
	v_lshlrev_b32_e32 v168, 16, v186
	v_and_b32_e32 v169, 0xffff0000, v186
	v_lshlrev_b32_e32 v178, 16, v187
	v_and_b32_e32 v179, 0xffff0000, v187
	v_lshlrev_b32_e32 v180, 16, v188
	v_and_b32_e32 v181, 0xffff0000, v188
	v_lshlrev_b32_e32 v182, 16, v189
	v_and_b32_e32 v183, 0xffff0000, v189
	global_store_dwordx4 v[196:197], v[134:137], off offset:2304
	v_pk_mul_f32 v[138:139], v[70:71], v[10:11]
	v_pk_mul_f32 v[166:167], v[68:69], v[12:13]
	v_pk_mul_f32 v[136:137], v[74:75], v[14:15]
	v_pk_mul_f32 v[134:135], v[72:73], v[16:17]
	v_pk_fma_f32 v[8:9], v[8:9], v[162:163], v[178:179]
	v_cvt_pk_bf16_f32 v134, v134, v135
	v_cvt_pk_bf16_f32 v135, v136, v137
	v_cvt_pk_bf16_f32 v136, v166, v167
	v_cvt_pk_bf16_f32 v137, v138, v139
	v_pk_fma_f32 v[6:7], v[6:7], v[160:161], v[168:169]
	v_pk_fma_f32 v[4:5], v[4:5], v[158:159], v[182:183]
	v_pk_fma_f32 v[2:3], v[2:3], v[156:157], v[180:181]
	global_store_dwordx4 v[210:211], v[134:137], off offset:256
	s_nop 1
	v_cvt_pk_bf16_f32 v134, v6, v7
	v_cvt_pk_bf16_f32 v135, v8, v9
	v_cvt_pk_bf16_f32 v136, v2, v3
	v_cvt_pk_bf16_f32 v137, v4, v5
	v_lshlrev_b32_e32 v8, 16, v134
	v_and_b32_e32 v9, 0xffff0000, v134
	v_lshlrev_b32_e32 v6, 16, v135
	v_and_b32_e32 v7, 0xffff0000, v135
	v_lshlrev_b32_e32 v4, 16, v136
	v_and_b32_e32 v5, 0xffff0000, v136
	v_lshlrev_b32_e32 v2, 16, v137
	v_and_b32_e32 v3, 0xffff0000, v137
	global_store_dwordx4 v[220:221], v[134:137], off offset:2304
	v_pk_mul_f32 v[74:75], v[74:75], v[6:7]
	v_pk_mul_f32 v[72:73], v[72:73], v[8:9]
	v_pk_mul_f32 v[134:135], v[70:71], v[2:3]
	v_pk_mul_f32 v[70:71], v[68:69], v[4:5]
	v_cvt_pk_bf16_f32 v68, v72, v73
	v_cvt_pk_bf16_f32 v69, v74, v75
	v_cvt_pk_bf16_f32 v70, v70, v71
	v_cvt_pk_bf16_f32 v71, v134, v135
	global_store_dwordx4 v[132:133], v[68:71], off offset:256
	v_xor_b32_e32 v72, 32, v227
	v_mul_f32_e32 v73, v129, v129
	v_and_b32_e32 v71, 64, v227
	v_xor_b32_e32 v70, 16, v227
	v_add_u32_e32 v71, 64, v71
	v_cmp_lt_i32_e32 vcc, v70, v71
	v_fmac_f32_e32 v73, v128, v128
	v_mul_f32_e32 v74, v125, v125
	v_cndmask_b32_e32 v70, v227, v70, vcc
	v_cmp_lt_i32_e32 vcc, v72, v71
	v_fmac_f32_e32 v74, v124, v124
	v_lshlrev_b32_e32 v70, 2, v70
	v_cndmask_b32_e32 v71, v227, v72, vcc
	v_mul_f32_e32 v72, v131, v131
	v_fmac_f32_e32 v72, v130, v130
	v_add_f32_e32 v72, v72, v73
	v_mul_f32_e32 v73, v127, v127
	v_fmac_f32_e32 v73, v126, v126
	v_add_f32_e32 v73, v73, v74
	v_add_f32_e32 v72, v72, v73
	v_add_f32_e32 v64, v72, v64
	v_add_f32_e32 v60, v60, v64
	ds_bpermute_b32 v61, v70, v60
	v_lshlrev_b32_e32 v71, 2, v71
	v_lshl_add_u64 v[68:69], v[150:151], 0, s[24:25]
	s_waitcnt lgkmcnt(0)
	v_add_f32_e32 v60, v60, v61
	ds_bpermute_b32 v61, v71, v60
	s_and_saveexec_b64 s[24:25], s[38:39]
	s_cbranch_execz .LBB0_1159
	s_waitcnt lgkmcnt(0)
	v_add_f32_e32 v60, v60, v61
	global_atomic_add_f32 v[68:69], v60, off
